# as v53 + pool phase output stores write-through (sc1) so less dirty L2 data at the following seam
# speedup vs baseline: 1.0076x; 1.0076x over previous
; __device__ __forceinline__ unsigned cvt_pk_bf16(float lo, float hi) { unsigned r; asm volatile("v_cvt_pk_bf16_f32 %0, %1, %2" : "=v"(r) : "v"(lo), "v"(hi)); return r; }
; __device__ __forceinline__ float bf_lo(unsigned w) { return __uint_as_float(w << 16); }
; __device__ __forceinline__ float bf_hi(unsigned w) { return __uint_as_float(w & 0xffff0000u); }
; __device__ void phase_pool() {
;     ...
;         { u32x4 hv[16];
; #pragma unroll
;           for (int k = 1; k <= 16; ++k) hv[k - 1] = (k <= nh) ? *(const u32x4*)(uz + (size_t)(row0 - k) * DE2 + col) : (u32x4){0u, 0u, 0u, 0u};
; #pragma unroll
;           for (int k = 0; k < 16; ++k) { const u32x4 v = hv[k];
;             s[0] += bf_lo(v.x); s[1] += bf_hi(v.x); s[2] += bf_lo(v.y); s[3] += bf_hi(v.y); s[4] += bf_lo(v.z); s[5] += bf_hi(v.z); s[6] += bf_lo(v.w); s[7] += bf_hi(v.w); } }
; #pragma unroll 1
;         for (int r0 = 0; r0 < RB; r0 += 8) {
;             u32x4 vv[8], ov[8];
; #pragma unroll
;             for (int k = 0; k < 8; ++k) { const int row = row0 + r0 + k, tl = tl0 + r0 + k;
;                 vv[k] = *(const u32x4*)(uz + (size_t)row * DE2 + col);
;                 ov[k] = (tl >= w) ? *(const u32x4*)(uz + (size_t)(row - w) * DE2 + col) : (u32x4){0u, 0u, 0u, 0u}; }
; #pragma unroll
;             for (int k = 0; k < 8; ++k) { const int row = row0 + r0 + k, tl = tl0 + r0 + k; const u32x4 v = vv[k], o2 = ov[k];
;                 s[0] += bf_lo(v.x) - bf_lo(o2.x); s[1] += bf_hi(v.x) - bf_hi(o2.x); s[2] += bf_lo(v.y) - bf_lo(o2.y); s[3] += bf_hi(v.y) - bf_hi(o2.y);
;                 s[4] += bf_lo(v.z) - bf_lo(o2.z); s[5] += bf_hi(v.z) - bf_hi(o2.z); s[6] += bf_lo(v.w) - bf_lo(o2.w); s[7] += bf_hi(v.w) - bf_hi(o2.w);
;                 const float ic = 1.0f / (float)((tl + 1 < w) ? tl + 1 : w);
;                 u32x4 o;
;                 o.x = cvt_pk_bf16(s[0] * ic - bf_lo(v.x), s[1] * ic - bf_hi(v.x)); o.y = cvt_pk_bf16(s[2] * ic - bf_lo(v.y), s[3] * ic - bf_hi(v.y));
;                 o.z = cvt_pk_bf16(s[4] * ic - bf_lo(v.z), s[5] * ic - bf_hi(v.z)); o.w = cvt_pk_bf16(s[6] * ic - bf_lo(v.w), s[7] * ic - bf_hi(v.w));
;                 *(u32x4*)(pg + (size_t)row * DE + col) = o; }
.Lpool_w2_main:
	global_load_dwordx4 v[12:15], v2, s[8:9]
	v_add_u32_e32 v2, 0x4000, v2
	global_load_dwordx4 v[16:19], v2, s[8:9]
	v_add_u32_e32 v2, 0x4000, v2
	global_load_dwordx4 v[20:23], v2, s[8:9]
	v_add_u32_e32 v2, 0x4000, v2
	global_load_dwordx4 v[24:27], v2, s[8:9]
	v_add_u32_e32 v2, 0x4000, v2
	global_load_dwordx4 v[28:31], v2, s[8:9]
	v_add_u32_e32 v2, 0x4000, v2
	global_load_dwordx4 v[32:35], v2, s[8:9]
	v_add_u32_e32 v2, 0x4000, v2
	global_load_dwordx4 v[36:39], v2, s[8:9]
	v_add_u32_e32 v2, 0x4000, v2
	global_load_dwordx4 v[40:43], v2, s[8:9]
	v_add_u32_e32 v2, 0x4000, v2
	global_load_dwordx4 v[44:47], v2, s[8:9]
	v_add_u32_e32 v2, 0x4000, v2
	global_load_dwordx4 v[48:51], v2, s[8:9]
	v_add_u32_e32 v2, 0x4000, v2
	global_load_dwordx4 v[52:55], v2, s[8:9]
	v_add_u32_e32 v2, 0x4000, v2
	global_load_dwordx4 v[56:59], v2, s[8:9]
	v_add_u32_e32 v2, 0x4000, v2
	global_load_dwordx4 v[60:63], v2, s[8:9]
	v_add_u32_e32 v2, 0x4000, v2
	global_load_dwordx4 v[64:67], v2, s[8:9]
	v_add_u32_e32 v2, 0x4000, v2
	global_load_dwordx4 v[68:71], v2, s[8:9]
	v_add_u32_e32 v2, 0x4000, v2
	global_load_dwordx4 v[72:75], v2, s[8:9]
	v_add_u32_e32 v2, 0x4000, v2
	global_load_dwordx4 v[76:79], v2, s[8:9]
	v_add_u32_e32 v2, 0x4000, v2
	global_load_dwordx4 v[80:83], v2, s[8:9]
	v_add_u32_e32 v2, 0x4000, v2
	global_load_dwordx4 v[84:87], v2, s[8:9]
	v_add_u32_e32 v2, 0x4000, v2
	global_load_dwordx4 v[88:91], v2, s[8:9]
	v_add_u32_e32 v2, 0x4000, v2
	global_load_dwordx4 v[92:95], v2, s[8:9]
	v_add_u32_e32 v2, 0x4000, v2
	global_load_dwordx4 v[96:99], v2, s[8:9]
	v_add_u32_e32 v2, 0x4000, v2
	global_load_dwordx4 v[100:103], v2, s[8:9]
	v_add_u32_e32 v2, 0x4000, v2
	global_load_dwordx4 v[104:107], v2, s[8:9]
	v_add_u32_e32 v2, 0x4000, v2
	global_load_dwordx4 v[108:111], v2, s[8:9]
	v_add_u32_e32 v2, 0x4000, v2
	global_load_dwordx4 v[112:115], v2, s[8:9]
	v_add_u32_e32 v2, 0x4000, v2
	global_load_dwordx4 v[116:119], v2, s[8:9]
	v_add_u32_e32 v2, 0x4000, v2
	global_load_dwordx4 v[120:123], v2, s[8:9]
	v_add_u32_e32 v2, 0x4000, v2
	global_load_dwordx4 v[124:127], v2, s[8:9]
	v_add_u32_e32 v2, 0x4000, v2
	global_load_dwordx4 v[128:131], v2, s[8:9]
	v_add_u32_e32 v2, 0x4000, v2
	global_load_dwordx4 v[132:135], v2, s[8:9]
	v_add_u32_e32 v2, 0x4000, v2
	global_load_dwordx4 v[136:139], v2, s[8:9]
	v_mov_b32_e32 v140, 0
	v_mov_b32_e32 v141, 0
	v_mov_b32_e32 v142, 0
	v_mov_b32_e32 v143, 0
	v_mov_b32_e32 v144, 0
	v_mov_b32_e32 v145, 0
	v_mov_b32_e32 v146, 0
	v_mov_b32_e32 v147, 0
	s_mov_b32 s43, 0x3f000000
	s_cmp_eq_u32 s16, 0
	s_waitcnt vmcnt(32)
	v_lshlrev_b32_e32 v152, 16, v8
	v_and_b32_e32 v153, 0xffff0000, v8
	v_lshlrev_b32_e32 v156, 16, v9
	v_and_b32_e32 v157, 0xffff0000, v9
	v_lshlrev_b32_e32 v160, 16, v10
	v_and_b32_e32 v161, 0xffff0000, v10
	v_lshlrev_b32_e32 v164, 16, v11
	v_and_b32_e32 v165, 0xffff0000, v11
	v_pk_add_f32 v[140:141], v[140:141], v[152:153]
	v_pk_add_f32 v[142:143], v[142:143], v[156:157]
	v_pk_add_f32 v[144:145], v[144:145], v[160:161]
	v_pk_add_f32 v[146:147], v[146:147], v[164:165]
	v_lshlrev_b32_e32 v152, 16, v4
	v_and_b32_e32 v153, 0xffff0000, v4
	v_lshlrev_b32_e32 v156, 16, v5
	v_and_b32_e32 v157, 0xffff0000, v5
	v_lshlrev_b32_e32 v160, 16, v6
	v_and_b32_e32 v161, 0xffff0000, v6
	v_lshlrev_b32_e32 v164, 16, v7
	v_and_b32_e32 v165, 0xffff0000, v7
	v_pk_add_f32 v[140:141], v[140:141], v[152:153]
	v_pk_add_f32 v[142:143], v[142:143], v[156:157]
	v_pk_add_f32 v[144:145], v[144:145], v[160:161]
	v_pk_add_f32 v[146:147], v[146:147], v[164:165]
	s_waitcnt vmcnt(31)
	s_cselect_b32 s42, 0x3f800000, s43
	v_lshlrev_b32_e32 v152, 16, v12
	v_and_b32_e32 v153, 0xffff0000, v12
	v_lshlrev_b32_e32 v154, 16, v4
	v_and_b32_e32 v155, 0xffff0000, v4
	v_lshlrev_b32_e32 v156, 16, v13
	v_and_b32_e32 v157, 0xffff0000, v13
	v_lshlrev_b32_e32 v158, 16, v5
	v_and_b32_e32 v159, 0xffff0000, v5
	v_lshlrev_b32_e32 v160, 16, v14
	v_and_b32_e32 v161, 0xffff0000, v14
	v_lshlrev_b32_e32 v162, 16, v6
	v_and_b32_e32 v163, 0xffff0000, v6
	v_lshlrev_b32_e32 v164, 16, v15
	v_and_b32_e32 v165, 0xffff0000, v15
	v_lshlrev_b32_e32 v166, 16, v7
	v_and_b32_e32 v167, 0xffff0000, v7
	v_pk_add_f32 v[154:155], v[152:153], v[154:155] neg_lo:[0,1] neg_hi:[0,1]
	v_pk_add_f32 v[158:159], v[156:157], v[158:159] neg_lo:[0,1] neg_hi:[0,1]
	v_pk_add_f32 v[162:163], v[160:161], v[162:163] neg_lo:[0,1] neg_hi:[0,1]
	v_pk_add_f32 v[166:167], v[164:165], v[166:167] neg_lo:[0,1] neg_hi:[0,1]
	v_pk_add_f32 v[140:141], v[140:141], v[154:155]
	v_pk_add_f32 v[142:143], v[142:143], v[158:159]
	v_pk_add_f32 v[144:145], v[144:145], v[162:163]
	v_pk_add_f32 v[146:147], v[146:147], v[166:167]
	v_fma_f32 v154, s42, v140, -v152
	v_fma_f32 v155, s42, v141, -v153
	v_fma_f32 v158, s42, v142, -v156
	v_fma_f32 v159, s42, v143, -v157
	v_fma_f32 v162, s42, v144, -v160
	v_fma_f32 v163, s42, v145, -v161
	v_fma_f32 v166, s42, v146, -v164
	v_fma_f32 v167, s42, v147, -v165
	v_cvt_pk_bf16_f32 v148, v154, v155
	v_cvt_pk_bf16_f32 v149, v158, v159
	v_cvt_pk_bf16_f32 v150, v162, v163
	v_cvt_pk_bf16_f32 v151, v166, v167
	global_store_dwordx4 v3, v[148:151], s[10:11] sc1
	v_add_u32_e32 v3, 0x2000, v3
	s_waitcnt vmcnt(31)
; __device__ __forceinline__ unsigned cvt_pk_bf16(float lo, float hi) { unsigned r; asm volatile("v_cvt_pk_bf16_f32 %0, %1, %2" : "=v"(r) : "v"(lo), "v"(hi)); return r; }
; __device__ __forceinline__ float bf_lo(unsigned w) { return __uint_as_float(w << 16); }
; __device__ __forceinline__ float bf_hi(unsigned w) { return __uint_as_float(w & 0xffff0000u); }
; __device__ void phase_pool() {
;     ...
;             for (int k = 0; k < 8; ++k) { const int row = row0 + r0 + k, tl = tl0 + r0 + k; const u32x4 v = vv[k], o2 = ov[k];
;                 s[0] += bf_lo(v.x) - bf_lo(o2.x); s[1] += bf_hi(v.x) - bf_hi(o2.x); s[2] += bf_lo(v.y) - bf_lo(o2.y); s[3] += bf_hi(v.y) - bf_hi(o2.y);
;                 s[4] += bf_lo(v.z) - bf_lo(o2.z); s[5] += bf_hi(v.z) - bf_hi(o2.z); s[6] += bf_lo(v.w) - bf_lo(o2.w); s[7] += bf_hi(v.w) - bf_hi(o2.w);
;                 const float ic = 1.0f / (float)((tl + 1 < w) ? tl + 1 : w);
;                 u32x4 o;
;                 o.x = cvt_pk_bf16(s[0] * ic - bf_lo(v.x), s[1] * ic - bf_hi(v.x)); o.y = cvt_pk_bf16(s[2] * ic - bf_lo(v.y), s[3] * ic - bf_hi(v.y));
;                 o.z = cvt_pk_bf16(s[4] * ic - bf_lo(v.z), s[5] * ic - bf_hi(v.z)); o.w = cvt_pk_bf16(s[6] * ic - bf_lo(v.w), s[7] * ic - bf_hi(v.w));
;                 *(u32x4*)(pg + (size_t)row * DE + col) = o; }
	v_lshlrev_b32_e32 v152, 16, v16
	v_and_b32_e32 v153, 0xffff0000, v16
	v_lshlrev_b32_e32 v154, 16, v8
	v_and_b32_e32 v155, 0xffff0000, v8
	v_lshlrev_b32_e32 v156, 16, v17
	v_and_b32_e32 v157, 0xffff0000, v17
	v_lshlrev_b32_e32 v158, 16, v9
	v_and_b32_e32 v159, 0xffff0000, v9
	v_lshlrev_b32_e32 v160, 16, v18
	v_and_b32_e32 v161, 0xffff0000, v18
	v_lshlrev_b32_e32 v162, 16, v10
	v_and_b32_e32 v163, 0xffff0000, v10
	v_lshlrev_b32_e32 v164, 16, v19
	v_and_b32_e32 v165, 0xffff0000, v19
	v_lshlrev_b32_e32 v166, 16, v11
	v_and_b32_e32 v167, 0xffff0000, v11
	v_pk_add_f32 v[154:155], v[152:153], v[154:155] neg_lo:[0,1] neg_hi:[0,1]
	v_pk_add_f32 v[158:159], v[156:157], v[158:159] neg_lo:[0,1] neg_hi:[0,1]
	v_pk_add_f32 v[162:163], v[160:161], v[162:163] neg_lo:[0,1] neg_hi:[0,1]
	v_pk_add_f32 v[166:167], v[164:165], v[166:167] neg_lo:[0,1] neg_hi:[0,1]
	v_pk_add_f32 v[140:141], v[140:141], v[154:155]
	v_pk_add_f32 v[142:143], v[142:143], v[158:159]
	v_pk_add_f32 v[144:145], v[144:145], v[162:163]
	v_pk_add_f32 v[146:147], v[146:147], v[166:167]
	v_fma_f32 v154, s43, v140, -v152
	v_fma_f32 v155, s43, v141, -v153
	v_fma_f32 v158, s43, v142, -v156
	v_fma_f32 v159, s43, v143, -v157
	v_fma_f32 v162, s43, v144, -v160
	v_fma_f32 v163, s43, v145, -v161
	v_fma_f32 v166, s43, v146, -v164
	v_fma_f32 v167, s43, v147, -v165
	v_cvt_pk_bf16_f32 v148, v154, v155
	v_cvt_pk_bf16_f32 v149, v158, v159
	v_cvt_pk_bf16_f32 v150, v162, v163
	v_cvt_pk_bf16_f32 v151, v166, v167
	global_store_dwordx4 v3, v[148:151], s[10:11] sc1
	v_add_u32_e32 v3, 0x2000, v3
	s_waitcnt vmcnt(31)
	v_lshlrev_b32_e32 v152, 16, v20
	v_and_b32_e32 v153, 0xffff0000, v20
	v_lshlrev_b32_e32 v154, 16, v12
	v_and_b32_e32 v155, 0xffff0000, v12
	v_lshlrev_b32_e32 v156, 16, v21
	v_and_b32_e32 v157, 0xffff0000, v21
	v_lshlrev_b32_e32 v158, 16, v13
	v_and_b32_e32 v159, 0xffff0000, v13
	v_lshlrev_b32_e32 v160, 16, v22
	v_and_b32_e32 v161, 0xffff0000, v22
	v_lshlrev_b32_e32 v162, 16, v14
	v_and_b32_e32 v163, 0xffff0000, v14
	v_lshlrev_b32_e32 v164, 16, v23
	v_and_b32_e32 v165, 0xffff0000, v23
	v_lshlrev_b32_e32 v166, 16, v15
	v_and_b32_e32 v167, 0xffff0000, v15
	v_pk_add_f32 v[154:155], v[152:153], v[154:155] neg_lo:[0,1] neg_hi:[0,1]
	v_pk_add_f32 v[158:159], v[156:157], v[158:159] neg_lo:[0,1] neg_hi:[0,1]
	v_pk_add_f32 v[162:163], v[160:161], v[162:163] neg_lo:[0,1] neg_hi:[0,1]
	v_pk_add_f32 v[166:167], v[164:165], v[166:167] neg_lo:[0,1] neg_hi:[0,1]
	v_pk_add_f32 v[140:141], v[140:141], v[154:155]
	v_pk_add_f32 v[142:143], v[142:143], v[158:159]
	v_pk_add_f32 v[144:145], v[144:145], v[162:163]
	v_pk_add_f32 v[146:147], v[146:147], v[166:167]
	v_fma_f32 v154, s43, v140, -v152
	v_fma_f32 v155, s43, v141, -v153
	v_fma_f32 v158, s43, v142, -v156
	v_fma_f32 v159, s43, v143, -v157
	v_fma_f32 v162, s43, v144, -v160
	v_fma_f32 v163, s43, v145, -v161
	v_fma_f32 v166, s43, v146, -v164
	v_fma_f32 v167, s43, v147, -v165
	v_cvt_pk_bf16_f32 v148, v154, v155
	v_cvt_pk_bf16_f32 v149, v158, v159
	v_cvt_pk_bf16_f32 v150, v162, v163
	v_cvt_pk_bf16_f32 v151, v166, v167
	global_store_dwordx4 v3, v[148:151], s[10:11] sc1
	v_add_u32_e32 v3, 0x2000, v3
	s_waitcnt vmcnt(31)
	v_lshlrev_b32_e32 v152, 16, v24
	v_and_b32_e32 v153, 0xffff0000, v24
	v_lshlrev_b32_e32 v154, 16, v16
	v_and_b32_e32 v155, 0xffff0000, v16
	v_lshlrev_b32_e32 v156, 16, v25
	v_and_b32_e32 v157, 0xffff0000, v25
	v_lshlrev_b32_e32 v158, 16, v17
	v_and_b32_e32 v159, 0xffff0000, v17
	v_lshlrev_b32_e32 v160, 16, v26
	v_and_b32_e32 v161, 0xffff0000, v26
	v_lshlrev_b32_e32 v162, 16, v18
	v_and_b32_e32 v163, 0xffff0000, v18
	v_lshlrev_b32_e32 v164, 16, v27
	v_and_b32_e32 v165, 0xffff0000, v27
	v_lshlrev_b32_e32 v166, 16, v19
	v_and_b32_e32 v167, 0xffff0000, v19
	v_pk_add_f32 v[154:155], v[152:153], v[154:155] neg_lo:[0,1] neg_hi:[0,1]
	v_pk_add_f32 v[158:159], v[156:157], v[158:159] neg_lo:[0,1] neg_hi:[0,1]
	v_pk_add_f32 v[162:163], v[160:161], v[162:163] neg_lo:[0,1] neg_hi:[0,1]
	v_pk_add_f32 v[166:167], v[164:165], v[166:167] neg_lo:[0,1] neg_hi:[0,1]
	v_pk_add_f32 v[140:141], v[140:141], v[154:155]
	v_pk_add_f32 v[142:143], v[142:143], v[158:159]
	v_pk_add_f32 v[144:145], v[144:145], v[162:163]
	v_pk_add_f32 v[146:147], v[146:147], v[166:167]
	v_fma_f32 v154, s43, v140, -v152
	v_fma_f32 v155, s43, v141, -v153
	v_fma_f32 v158, s43, v142, -v156
	v_fma_f32 v159, s43, v143, -v157
	v_fma_f32 v162, s43, v144, -v160
	v_fma_f32 v163, s43, v145, -v161
	v_fma_f32 v166, s43, v146, -v164
	v_fma_f32 v167, s43, v147, -v165
	v_cvt_pk_bf16_f32 v148, v154, v155
	v_cvt_pk_bf16_f32 v149, v158, v159
	v_cvt_pk_bf16_f32 v150, v162, v163
	v_cvt_pk_bf16_f32 v151, v166, v167
	global_store_dwordx4 v3, v[148:151], s[10:11] sc1
	v_add_u32_e32 v3, 0x2000, v3
	s_waitcnt vmcnt(31)
	v_lshlrev_b32_e32 v152, 16, v28
	v_and_b32_e32 v153, 0xffff0000, v28
	v_lshlrev_b32_e32 v154, 16, v20
	v_and_b32_e32 v155, 0xffff0000, v20
	v_lshlrev_b32_e32 v156, 16, v29
	v_and_b32_e32 v157, 0xffff0000, v29
	v_lshlrev_b32_e32 v158, 16, v21
	v_and_b32_e32 v159, 0xffff0000, v21
	v_lshlrev_b32_e32 v160, 16, v30
	v_and_b32_e32 v161, 0xffff0000, v30
	v_lshlrev_b32_e32 v162, 16, v22
	v_and_b32_e32 v163, 0xffff0000, v22
	v_lshlrev_b32_e32 v164, 16, v31
	v_and_b32_e32 v165, 0xffff0000, v31
	v_lshlrev_b32_e32 v166, 16, v23
	v_and_b32_e32 v167, 0xffff0000, v23
	v_pk_add_f32 v[154:155], v[152:153], v[154:155] neg_lo:[0,1] neg_hi:[0,1]
	v_pk_add_f32 v[158:159], v[156:157], v[158:159] neg_lo:[0,1] neg_hi:[0,1]
	v_pk_add_f32 v[162:163], v[160:161], v[162:163] neg_lo:[0,1] neg_hi:[0,1]
	v_pk_add_f32 v[166:167], v[164:165], v[166:167] neg_lo:[0,1] neg_hi:[0,1]
	v_pk_add_f32 v[140:141], v[140:141], v[154:155]
	v_pk_add_f32 v[142:143], v[142:143], v[158:159]
	v_pk_add_f32 v[144:145], v[144:145], v[162:163]
	v_pk_add_f32 v[146:147], v[146:147], v[166:167]
	v_fma_f32 v154, s43, v140, -v152
	v_fma_f32 v155, s43, v141, -v153
	v_fma_f32 v158, s43, v142, -v156
	v_fma_f32 v159, s43, v143, -v157
	v_fma_f32 v162, s43, v144, -v160
	v_fma_f32 v163, s43, v145, -v161
	v_fma_f32 v166, s43, v146, -v164
	v_fma_f32 v167, s43, v147, -v165
	v_cvt_pk_bf16_f32 v148, v154, v155
	v_cvt_pk_bf16_f32 v149, v158, v159
	v_cvt_pk_bf16_f32 v150, v162, v163
	v_cvt_pk_bf16_f32 v151, v166, v167
	global_store_dwordx4 v3, v[148:151], s[10:11] sc1
	v_add_u32_e32 v3, 0x2000, v3
	s_waitcnt vmcnt(31)
; __device__ __forceinline__ unsigned cvt_pk_bf16(float lo, float hi) { unsigned r; asm volatile("v_cvt_pk_bf16_f32 %0, %1, %2" : "=v"(r) : "v"(lo), "v"(hi)); return r; }
; __device__ __forceinline__ float bf_lo(unsigned w) { return __uint_as_float(w << 16); }
; __device__ __forceinline__ float bf_hi(unsigned w) { return __uint_as_float(w & 0xffff0000u); }
; __device__ void phase_pool() {
;     ...
;             for (int k = 0; k < 8; ++k) { const int row = row0 + r0 + k, tl = tl0 + r0 + k; const u32x4 v = vv[k], o2 = ov[k];
;                 s[0] += bf_lo(v.x) - bf_lo(o2.x); s[1] += bf_hi(v.x) - bf_hi(o2.x); s[2] += bf_lo(v.y) - bf_lo(o2.y); s[3] += bf_hi(v.y) - bf_hi(o2.y);
;                 s[4] += bf_lo(v.z) - bf_lo(o2.z); s[5] += bf_hi(v.z) - bf_hi(o2.z); s[6] += bf_lo(v.w) - bf_lo(o2.w); s[7] += bf_hi(v.w) - bf_hi(o2.w);
;                 const float ic = 1.0f / (float)((tl + 1 < w) ? tl + 1 : w);
;                 u32x4 o;
;                 o.x = cvt_pk_bf16(s[0] * ic - bf_lo(v.x), s[1] * ic - bf_hi(v.x)); o.y = cvt_pk_bf16(s[2] * ic - bf_lo(v.y), s[3] * ic - bf_hi(v.y));
;                 o.z = cvt_pk_bf16(s[4] * ic - bf_lo(v.z), s[5] * ic - bf_hi(v.z)); o.w = cvt_pk_bf16(s[6] * ic - bf_lo(v.w), s[7] * ic - bf_hi(v.w));
;                 *(u32x4*)(pg + (size_t)row * DE + col) = o; }
	v_lshlrev_b32_e32 v152, 16, v32
	v_and_b32_e32 v153, 0xffff0000, v32
	v_lshlrev_b32_e32 v154, 16, v24
	v_and_b32_e32 v155, 0xffff0000, v24
	v_lshlrev_b32_e32 v156, 16, v33
	v_and_b32_e32 v157, 0xffff0000, v33
	v_lshlrev_b32_e32 v158, 16, v25
	v_and_b32_e32 v159, 0xffff0000, v25
	v_lshlrev_b32_e32 v160, 16, v34
	v_and_b32_e32 v161, 0xffff0000, v34
	v_lshlrev_b32_e32 v162, 16, v26
	v_and_b32_e32 v163, 0xffff0000, v26
	v_lshlrev_b32_e32 v164, 16, v35
	v_and_b32_e32 v165, 0xffff0000, v35
	v_lshlrev_b32_e32 v166, 16, v27
	v_and_b32_e32 v167, 0xffff0000, v27
	v_pk_add_f32 v[154:155], v[152:153], v[154:155] neg_lo:[0,1] neg_hi:[0,1]
	v_pk_add_f32 v[158:159], v[156:157], v[158:159] neg_lo:[0,1] neg_hi:[0,1]
	v_pk_add_f32 v[162:163], v[160:161], v[162:163] neg_lo:[0,1] neg_hi:[0,1]
	v_pk_add_f32 v[166:167], v[164:165], v[166:167] neg_lo:[0,1] neg_hi:[0,1]
	v_pk_add_f32 v[140:141], v[140:141], v[154:155]
	v_pk_add_f32 v[142:143], v[142:143], v[158:159]
	v_pk_add_f32 v[144:145], v[144:145], v[162:163]
	v_pk_add_f32 v[146:147], v[146:147], v[166:167]
	v_fma_f32 v154, s43, v140, -v152
	v_fma_f32 v155, s43, v141, -v153
	v_fma_f32 v158, s43, v142, -v156
	v_fma_f32 v159, s43, v143, -v157
	v_fma_f32 v162, s43, v144, -v160
	v_fma_f32 v163, s43, v145, -v161
	v_fma_f32 v166, s43, v146, -v164
	v_fma_f32 v167, s43, v147, -v165
	v_cvt_pk_bf16_f32 v148, v154, v155
	v_cvt_pk_bf16_f32 v149, v158, v159
	v_cvt_pk_bf16_f32 v150, v162, v163
	v_cvt_pk_bf16_f32 v151, v166, v167
	global_store_dwordx4 v3, v[148:151], s[10:11] sc1
	v_add_u32_e32 v3, 0x2000, v3
	s_waitcnt vmcnt(31)
	v_lshlrev_b32_e32 v152, 16, v36
	v_and_b32_e32 v153, 0xffff0000, v36
	v_lshlrev_b32_e32 v154, 16, v28
	v_and_b32_e32 v155, 0xffff0000, v28
	v_lshlrev_b32_e32 v156, 16, v37
	v_and_b32_e32 v157, 0xffff0000, v37
	v_lshlrev_b32_e32 v158, 16, v29
	v_and_b32_e32 v159, 0xffff0000, v29
	v_lshlrev_b32_e32 v160, 16, v38
	v_and_b32_e32 v161, 0xffff0000, v38
	v_lshlrev_b32_e32 v162, 16, v30
	v_and_b32_e32 v163, 0xffff0000, v30
	v_lshlrev_b32_e32 v164, 16, v39
	v_and_b32_e32 v165, 0xffff0000, v39
	v_lshlrev_b32_e32 v166, 16, v31
	v_and_b32_e32 v167, 0xffff0000, v31
	v_pk_add_f32 v[154:155], v[152:153], v[154:155] neg_lo:[0,1] neg_hi:[0,1]
	v_pk_add_f32 v[158:159], v[156:157], v[158:159] neg_lo:[0,1] neg_hi:[0,1]
	v_pk_add_f32 v[162:163], v[160:161], v[162:163] neg_lo:[0,1] neg_hi:[0,1]
	v_pk_add_f32 v[166:167], v[164:165], v[166:167] neg_lo:[0,1] neg_hi:[0,1]
	v_pk_add_f32 v[140:141], v[140:141], v[154:155]
	v_pk_add_f32 v[142:143], v[142:143], v[158:159]
	v_pk_add_f32 v[144:145], v[144:145], v[162:163]
	v_pk_add_f32 v[146:147], v[146:147], v[166:167]
	v_fma_f32 v154, s43, v140, -v152
	v_fma_f32 v155, s43, v141, -v153
	v_fma_f32 v158, s43, v142, -v156
	v_fma_f32 v159, s43, v143, -v157
	v_fma_f32 v162, s43, v144, -v160
	v_fma_f32 v163, s43, v145, -v161
	v_fma_f32 v166, s43, v146, -v164
	v_fma_f32 v167, s43, v147, -v165
	v_cvt_pk_bf16_f32 v148, v154, v155
	v_cvt_pk_bf16_f32 v149, v158, v159
	v_cvt_pk_bf16_f32 v150, v162, v163
	v_cvt_pk_bf16_f32 v151, v166, v167
	global_store_dwordx4 v3, v[148:151], s[10:11] sc1
	v_add_u32_e32 v3, 0x2000, v3
	s_waitcnt vmcnt(31)
	v_lshlrev_b32_e32 v152, 16, v40
	v_and_b32_e32 v153, 0xffff0000, v40
	v_lshlrev_b32_e32 v154, 16, v32
	v_and_b32_e32 v155, 0xffff0000, v32
	v_lshlrev_b32_e32 v156, 16, v41
	v_and_b32_e32 v157, 0xffff0000, v41
	v_lshlrev_b32_e32 v158, 16, v33
	v_and_b32_e32 v159, 0xffff0000, v33
	v_lshlrev_b32_e32 v160, 16, v42
	v_and_b32_e32 v161, 0xffff0000, v42
	v_lshlrev_b32_e32 v162, 16, v34
	v_and_b32_e32 v163, 0xffff0000, v34
	v_lshlrev_b32_e32 v164, 16, v43
	v_and_b32_e32 v165, 0xffff0000, v43
	v_lshlrev_b32_e32 v166, 16, v35
	v_and_b32_e32 v167, 0xffff0000, v35
	v_pk_add_f32 v[154:155], v[152:153], v[154:155] neg_lo:[0,1] neg_hi:[0,1]
	v_pk_add_f32 v[158:159], v[156:157], v[158:159] neg_lo:[0,1] neg_hi:[0,1]
	v_pk_add_f32 v[162:163], v[160:161], v[162:163] neg_lo:[0,1] neg_hi:[0,1]
	v_pk_add_f32 v[166:167], v[164:165], v[166:167] neg_lo:[0,1] neg_hi:[0,1]
	v_pk_add_f32 v[140:141], v[140:141], v[154:155]
	v_pk_add_f32 v[142:143], v[142:143], v[158:159]
	v_pk_add_f32 v[144:145], v[144:145], v[162:163]
	v_pk_add_f32 v[146:147], v[146:147], v[166:167]
	v_fma_f32 v154, s43, v140, -v152
	v_fma_f32 v155, s43, v141, -v153
	v_fma_f32 v158, s43, v142, -v156
	v_fma_f32 v159, s43, v143, -v157
	v_fma_f32 v162, s43, v144, -v160
	v_fma_f32 v163, s43, v145, -v161
	v_fma_f32 v166, s43, v146, -v164
	v_fma_f32 v167, s43, v147, -v165
	v_cvt_pk_bf16_f32 v148, v154, v155
	v_cvt_pk_bf16_f32 v149, v158, v159
	v_cvt_pk_bf16_f32 v150, v162, v163
	v_cvt_pk_bf16_f32 v151, v166, v167
	global_store_dwordx4 v3, v[148:151], s[10:11] sc1
	v_add_u32_e32 v3, 0x2000, v3
	s_waitcnt vmcnt(31)
	v_lshlrev_b32_e32 v152, 16, v44
	v_and_b32_e32 v153, 0xffff0000, v44
	v_lshlrev_b32_e32 v154, 16, v36
	v_and_b32_e32 v155, 0xffff0000, v36
	v_lshlrev_b32_e32 v156, 16, v45
	v_and_b32_e32 v157, 0xffff0000, v45
	v_lshlrev_b32_e32 v158, 16, v37
	v_and_b32_e32 v159, 0xffff0000, v37
	v_lshlrev_b32_e32 v160, 16, v46
	v_and_b32_e32 v161, 0xffff0000, v46
	v_lshlrev_b32_e32 v162, 16, v38
	v_and_b32_e32 v163, 0xffff0000, v38
	v_lshlrev_b32_e32 v164, 16, v47
	v_and_b32_e32 v165, 0xffff0000, v47
	v_lshlrev_b32_e32 v166, 16, v39
	v_and_b32_e32 v167, 0xffff0000, v39
	v_pk_add_f32 v[154:155], v[152:153], v[154:155] neg_lo:[0,1] neg_hi:[0,1]
	v_pk_add_f32 v[158:159], v[156:157], v[158:159] neg_lo:[0,1] neg_hi:[0,1]
	v_pk_add_f32 v[162:163], v[160:161], v[162:163] neg_lo:[0,1] neg_hi:[0,1]
	v_pk_add_f32 v[166:167], v[164:165], v[166:167] neg_lo:[0,1] neg_hi:[0,1]
	v_pk_add_f32 v[140:141], v[140:141], v[154:155]
	v_pk_add_f32 v[142:143], v[142:143], v[158:159]
	v_pk_add_f32 v[144:145], v[144:145], v[162:163]
	v_pk_add_f32 v[146:147], v[146:147], v[166:167]
	v_fma_f32 v154, s43, v140, -v152
	v_fma_f32 v155, s43, v141, -v153
	v_fma_f32 v158, s43, v142, -v156
	v_fma_f32 v159, s43, v143, -v157
	v_fma_f32 v162, s43, v144, -v160
	v_fma_f32 v163, s43, v145, -v161
	v_fma_f32 v166, s43, v146, -v164
	v_fma_f32 v167, s43, v147, -v165
	v_cvt_pk_bf16_f32 v148, v154, v155
	v_cvt_pk_bf16_f32 v149, v158, v159
	v_cvt_pk_bf16_f32 v150, v162, v163
	v_cvt_pk_bf16_f32 v151, v166, v167
	global_store_dwordx4 v3, v[148:151], s[10:11] sc1
	v_add_u32_e32 v3, 0x2000, v3
	s_waitcnt vmcnt(31)
; __device__ __forceinline__ unsigned cvt_pk_bf16(float lo, float hi) { unsigned r; asm volatile("v_cvt_pk_bf16_f32 %0, %1, %2" : "=v"(r) : "v"(lo), "v"(hi)); return r; }
; __device__ __forceinline__ float bf_lo(unsigned w) { return __uint_as_float(w << 16); }
; __device__ __forceinline__ float bf_hi(unsigned w) { return __uint_as_float(w & 0xffff0000u); }
; __device__ void phase_pool() {
;     ...
;             for (int k = 0; k < 8; ++k) { const int row = row0 + r0 + k, tl = tl0 + r0 + k; const u32x4 v = vv[k], o2 = ov[k];
;                 s[0] += bf_lo(v.x) - bf_lo(o2.x); s[1] += bf_hi(v.x) - bf_hi(o2.x); s[2] += bf_lo(v.y) - bf_lo(o2.y); s[3] += bf_hi(v.y) - bf_hi(o2.y);
;                 s[4] += bf_lo(v.z) - bf_lo(o2.z); s[5] += bf_hi(v.z) - bf_hi(o2.z); s[6] += bf_lo(v.w) - bf_lo(o2.w); s[7] += bf_hi(v.w) - bf_hi(o2.w);
;                 const float ic = 1.0f / (float)((tl + 1 < w) ? tl + 1 : w);
;                 u32x4 o;
;                 o.x = cvt_pk_bf16(s[0] * ic - bf_lo(v.x), s[1] * ic - bf_hi(v.x)); o.y = cvt_pk_bf16(s[2] * ic - bf_lo(v.y), s[3] * ic - bf_hi(v.y));
;                 o.z = cvt_pk_bf16(s[4] * ic - bf_lo(v.z), s[5] * ic - bf_hi(v.z)); o.w = cvt_pk_bf16(s[6] * ic - bf_lo(v.w), s[7] * ic - bf_hi(v.w));
;                 *(u32x4*)(pg + (size_t)row * DE + col) = o; }
	v_lshlrev_b32_e32 v152, 16, v48
	v_and_b32_e32 v153, 0xffff0000, v48
	v_lshlrev_b32_e32 v154, 16, v40
	v_and_b32_e32 v155, 0xffff0000, v40
	v_lshlrev_b32_e32 v156, 16, v49
	v_and_b32_e32 v157, 0xffff0000, v49
	v_lshlrev_b32_e32 v158, 16, v41
	v_and_b32_e32 v159, 0xffff0000, v41
	v_lshlrev_b32_e32 v160, 16, v50
	v_and_b32_e32 v161, 0xffff0000, v50
	v_lshlrev_b32_e32 v162, 16, v42
	v_and_b32_e32 v163, 0xffff0000, v42
	v_lshlrev_b32_e32 v164, 16, v51
	v_and_b32_e32 v165, 0xffff0000, v51
	v_lshlrev_b32_e32 v166, 16, v43
	v_and_b32_e32 v167, 0xffff0000, v43
	v_pk_add_f32 v[154:155], v[152:153], v[154:155] neg_lo:[0,1] neg_hi:[0,1]
	v_pk_add_f32 v[158:159], v[156:157], v[158:159] neg_lo:[0,1] neg_hi:[0,1]
	v_pk_add_f32 v[162:163], v[160:161], v[162:163] neg_lo:[0,1] neg_hi:[0,1]
	v_pk_add_f32 v[166:167], v[164:165], v[166:167] neg_lo:[0,1] neg_hi:[0,1]
	v_pk_add_f32 v[140:141], v[140:141], v[154:155]
	v_pk_add_f32 v[142:143], v[142:143], v[158:159]
	v_pk_add_f32 v[144:145], v[144:145], v[162:163]
	v_pk_add_f32 v[146:147], v[146:147], v[166:167]
	v_fma_f32 v154, s43, v140, -v152
	v_fma_f32 v155, s43, v141, -v153
	v_fma_f32 v158, s43, v142, -v156
	v_fma_f32 v159, s43, v143, -v157
	v_fma_f32 v162, s43, v144, -v160
	v_fma_f32 v163, s43, v145, -v161
	v_fma_f32 v166, s43, v146, -v164
	v_fma_f32 v167, s43, v147, -v165
	v_cvt_pk_bf16_f32 v148, v154, v155
	v_cvt_pk_bf16_f32 v149, v158, v159
	v_cvt_pk_bf16_f32 v150, v162, v163
	v_cvt_pk_bf16_f32 v151, v166, v167
	global_store_dwordx4 v3, v[148:151], s[10:11] sc1
	v_add_u32_e32 v3, 0x2000, v3
	s_waitcnt vmcnt(31)
	v_lshlrev_b32_e32 v152, 16, v52
	v_and_b32_e32 v153, 0xffff0000, v52
	v_lshlrev_b32_e32 v154, 16, v44
	v_and_b32_e32 v155, 0xffff0000, v44
	v_lshlrev_b32_e32 v156, 16, v53
	v_and_b32_e32 v157, 0xffff0000, v53
	v_lshlrev_b32_e32 v158, 16, v45
	v_and_b32_e32 v159, 0xffff0000, v45
	v_lshlrev_b32_e32 v160, 16, v54
	v_and_b32_e32 v161, 0xffff0000, v54
	v_lshlrev_b32_e32 v162, 16, v46
	v_and_b32_e32 v163, 0xffff0000, v46
	v_lshlrev_b32_e32 v164, 16, v55
	v_and_b32_e32 v165, 0xffff0000, v55
	v_lshlrev_b32_e32 v166, 16, v47
	v_and_b32_e32 v167, 0xffff0000, v47
	v_pk_add_f32 v[154:155], v[152:153], v[154:155] neg_lo:[0,1] neg_hi:[0,1]
	v_pk_add_f32 v[158:159], v[156:157], v[158:159] neg_lo:[0,1] neg_hi:[0,1]
	v_pk_add_f32 v[162:163], v[160:161], v[162:163] neg_lo:[0,1] neg_hi:[0,1]
	v_pk_add_f32 v[166:167], v[164:165], v[166:167] neg_lo:[0,1] neg_hi:[0,1]
	v_pk_add_f32 v[140:141], v[140:141], v[154:155]
	v_pk_add_f32 v[142:143], v[142:143], v[158:159]
	v_pk_add_f32 v[144:145], v[144:145], v[162:163]
	v_pk_add_f32 v[146:147], v[146:147], v[166:167]
	v_fma_f32 v154, s43, v140, -v152
	v_fma_f32 v155, s43, v141, -v153
	v_fma_f32 v158, s43, v142, -v156
	v_fma_f32 v159, s43, v143, -v157
	v_fma_f32 v162, s43, v144, -v160
	v_fma_f32 v163, s43, v145, -v161
	v_fma_f32 v166, s43, v146, -v164
	v_fma_f32 v167, s43, v147, -v165
	v_cvt_pk_bf16_f32 v148, v154, v155
	v_cvt_pk_bf16_f32 v149, v158, v159
	v_cvt_pk_bf16_f32 v150, v162, v163
	v_cvt_pk_bf16_f32 v151, v166, v167
	global_store_dwordx4 v3, v[148:151], s[10:11] sc1
	v_add_u32_e32 v3, 0x2000, v3
	s_waitcnt vmcnt(31)
	v_lshlrev_b32_e32 v152, 16, v56
	v_and_b32_e32 v153, 0xffff0000, v56
	v_lshlrev_b32_e32 v154, 16, v48
	v_and_b32_e32 v155, 0xffff0000, v48
	v_lshlrev_b32_e32 v156, 16, v57
	v_and_b32_e32 v157, 0xffff0000, v57
	v_lshlrev_b32_e32 v158, 16, v49
	v_and_b32_e32 v159, 0xffff0000, v49
	v_lshlrev_b32_e32 v160, 16, v58
	v_and_b32_e32 v161, 0xffff0000, v58
	v_lshlrev_b32_e32 v162, 16, v50
	v_and_b32_e32 v163, 0xffff0000, v50
	v_lshlrev_b32_e32 v164, 16, v59
	v_and_b32_e32 v165, 0xffff0000, v59
	v_lshlrev_b32_e32 v166, 16, v51
	v_and_b32_e32 v167, 0xffff0000, v51
	v_pk_add_f32 v[154:155], v[152:153], v[154:155] neg_lo:[0,1] neg_hi:[0,1]
	v_pk_add_f32 v[158:159], v[156:157], v[158:159] neg_lo:[0,1] neg_hi:[0,1]
	v_pk_add_f32 v[162:163], v[160:161], v[162:163] neg_lo:[0,1] neg_hi:[0,1]
	v_pk_add_f32 v[166:167], v[164:165], v[166:167] neg_lo:[0,1] neg_hi:[0,1]
	v_pk_add_f32 v[140:141], v[140:141], v[154:155]
	v_pk_add_f32 v[142:143], v[142:143], v[158:159]
	v_pk_add_f32 v[144:145], v[144:145], v[162:163]
	v_pk_add_f32 v[146:147], v[146:147], v[166:167]
	v_fma_f32 v154, s43, v140, -v152
	v_fma_f32 v155, s43, v141, -v153
	v_fma_f32 v158, s43, v142, -v156
	v_fma_f32 v159, s43, v143, -v157
	v_fma_f32 v162, s43, v144, -v160
	v_fma_f32 v163, s43, v145, -v161
	v_fma_f32 v166, s43, v146, -v164
	v_fma_f32 v167, s43, v147, -v165
	v_cvt_pk_bf16_f32 v148, v154, v155
	v_cvt_pk_bf16_f32 v149, v158, v159
	v_cvt_pk_bf16_f32 v150, v162, v163
	v_cvt_pk_bf16_f32 v151, v166, v167
	global_store_dwordx4 v3, v[148:151], s[10:11] sc1
	v_add_u32_e32 v3, 0x2000, v3
	s_waitcnt vmcnt(31)
	v_lshlrev_b32_e32 v152, 16, v60
	v_and_b32_e32 v153, 0xffff0000, v60
	v_lshlrev_b32_e32 v154, 16, v52
	v_and_b32_e32 v155, 0xffff0000, v52
	v_lshlrev_b32_e32 v156, 16, v61
	v_and_b32_e32 v157, 0xffff0000, v61
	v_lshlrev_b32_e32 v158, 16, v53
	v_and_b32_e32 v159, 0xffff0000, v53
	v_lshlrev_b32_e32 v160, 16, v62
	v_and_b32_e32 v161, 0xffff0000, v62
	v_lshlrev_b32_e32 v162, 16, v54
	v_and_b32_e32 v163, 0xffff0000, v54
	v_lshlrev_b32_e32 v164, 16, v63
	v_and_b32_e32 v165, 0xffff0000, v63
	v_lshlrev_b32_e32 v166, 16, v55
	v_and_b32_e32 v167, 0xffff0000, v55
	v_pk_add_f32 v[154:155], v[152:153], v[154:155] neg_lo:[0,1] neg_hi:[0,1]
	v_pk_add_f32 v[158:159], v[156:157], v[158:159] neg_lo:[0,1] neg_hi:[0,1]
	v_pk_add_f32 v[162:163], v[160:161], v[162:163] neg_lo:[0,1] neg_hi:[0,1]
	v_pk_add_f32 v[166:167], v[164:165], v[166:167] neg_lo:[0,1] neg_hi:[0,1]
	v_pk_add_f32 v[140:141], v[140:141], v[154:155]
	v_pk_add_f32 v[142:143], v[142:143], v[158:159]
	v_pk_add_f32 v[144:145], v[144:145], v[162:163]
	v_pk_add_f32 v[146:147], v[146:147], v[166:167]
	v_fma_f32 v154, s43, v140, -v152
	v_fma_f32 v155, s43, v141, -v153
	v_fma_f32 v158, s43, v142, -v156
	v_fma_f32 v159, s43, v143, -v157
	v_fma_f32 v162, s43, v144, -v160
	v_fma_f32 v163, s43, v145, -v161
	v_fma_f32 v166, s43, v146, -v164
	v_fma_f32 v167, s43, v147, -v165
	v_cvt_pk_bf16_f32 v148, v154, v155
	v_cvt_pk_bf16_f32 v149, v158, v159
	v_cvt_pk_bf16_f32 v150, v162, v163
	v_cvt_pk_bf16_f32 v151, v166, v167
	global_store_dwordx4 v3, v[148:151], s[10:11] sc1
	v_add_u32_e32 v3, 0x2000, v3
	s_waitcnt vmcnt(31)
; __device__ __forceinline__ unsigned cvt_pk_bf16(float lo, float hi) { unsigned r; asm volatile("v_cvt_pk_bf16_f32 %0, %1, %2" : "=v"(r) : "v"(lo), "v"(hi)); return r; }
; __device__ __forceinline__ float bf_lo(unsigned w) { return __uint_as_float(w << 16); }
; __device__ __forceinline__ float bf_hi(unsigned w) { return __uint_as_float(w & 0xffff0000u); }
; __device__ void phase_pool() {
;     ...
;             for (int k = 0; k < 8; ++k) { const int row = row0 + r0 + k, tl = tl0 + r0 + k; const u32x4 v = vv[k], o2 = ov[k];
;                 s[0] += bf_lo(v.x) - bf_lo(o2.x); s[1] += bf_hi(v.x) - bf_hi(o2.x); s[2] += bf_lo(v.y) - bf_lo(o2.y); s[3] += bf_hi(v.y) - bf_hi(o2.y);
;                 s[4] += bf_lo(v.z) - bf_lo(o2.z); s[5] += bf_hi(v.z) - bf_hi(o2.z); s[6] += bf_lo(v.w) - bf_lo(o2.w); s[7] += bf_hi(v.w) - bf_hi(o2.w);
;                 const float ic = 1.0f / (float)((tl + 1 < w) ? tl + 1 : w);
;                 u32x4 o;
;                 o.x = cvt_pk_bf16(s[0] * ic - bf_lo(v.x), s[1] * ic - bf_hi(v.x)); o.y = cvt_pk_bf16(s[2] * ic - bf_lo(v.y), s[3] * ic - bf_hi(v.y));
;                 o.z = cvt_pk_bf16(s[4] * ic - bf_lo(v.z), s[5] * ic - bf_hi(v.z)); o.w = cvt_pk_bf16(s[6] * ic - bf_lo(v.w), s[7] * ic - bf_hi(v.w));
;                 *(u32x4*)(pg + (size_t)row * DE + col) = o; }
	v_lshlrev_b32_e32 v152, 16, v64
	v_and_b32_e32 v153, 0xffff0000, v64
	v_lshlrev_b32_e32 v154, 16, v56
	v_and_b32_e32 v155, 0xffff0000, v56
	v_lshlrev_b32_e32 v156, 16, v65
	v_and_b32_e32 v157, 0xffff0000, v65
	v_lshlrev_b32_e32 v158, 16, v57
	v_and_b32_e32 v159, 0xffff0000, v57
	v_lshlrev_b32_e32 v160, 16, v66
	v_and_b32_e32 v161, 0xffff0000, v66
	v_lshlrev_b32_e32 v162, 16, v58
	v_and_b32_e32 v163, 0xffff0000, v58
	v_lshlrev_b32_e32 v164, 16, v67
	v_and_b32_e32 v165, 0xffff0000, v67
	v_lshlrev_b32_e32 v166, 16, v59
	v_and_b32_e32 v167, 0xffff0000, v59
	v_pk_add_f32 v[154:155], v[152:153], v[154:155] neg_lo:[0,1] neg_hi:[0,1]
	v_pk_add_f32 v[158:159], v[156:157], v[158:159] neg_lo:[0,1] neg_hi:[0,1]
	v_pk_add_f32 v[162:163], v[160:161], v[162:163] neg_lo:[0,1] neg_hi:[0,1]
	v_pk_add_f32 v[166:167], v[164:165], v[166:167] neg_lo:[0,1] neg_hi:[0,1]
	v_pk_add_f32 v[140:141], v[140:141], v[154:155]
	v_pk_add_f32 v[142:143], v[142:143], v[158:159]
	v_pk_add_f32 v[144:145], v[144:145], v[162:163]
	v_pk_add_f32 v[146:147], v[146:147], v[166:167]
	v_fma_f32 v154, s43, v140, -v152
	v_fma_f32 v155, s43, v141, -v153
	v_fma_f32 v158, s43, v142, -v156
	v_fma_f32 v159, s43, v143, -v157
	v_fma_f32 v162, s43, v144, -v160
	v_fma_f32 v163, s43, v145, -v161
	v_fma_f32 v166, s43, v146, -v164
	v_fma_f32 v167, s43, v147, -v165
	v_cvt_pk_bf16_f32 v148, v154, v155
	v_cvt_pk_bf16_f32 v149, v158, v159
	v_cvt_pk_bf16_f32 v150, v162, v163
	v_cvt_pk_bf16_f32 v151, v166, v167
	global_store_dwordx4 v3, v[148:151], s[10:11] sc1
	v_add_u32_e32 v3, 0x2000, v3
	s_waitcnt vmcnt(31)
	v_lshlrev_b32_e32 v152, 16, v68
	v_and_b32_e32 v153, 0xffff0000, v68
	v_lshlrev_b32_e32 v154, 16, v60
	v_and_b32_e32 v155, 0xffff0000, v60
	v_lshlrev_b32_e32 v156, 16, v69
	v_and_b32_e32 v157, 0xffff0000, v69
	v_lshlrev_b32_e32 v158, 16, v61
	v_and_b32_e32 v159, 0xffff0000, v61
	v_lshlrev_b32_e32 v160, 16, v70
	v_and_b32_e32 v161, 0xffff0000, v70
	v_lshlrev_b32_e32 v162, 16, v62
	v_and_b32_e32 v163, 0xffff0000, v62
	v_lshlrev_b32_e32 v164, 16, v71
	v_and_b32_e32 v165, 0xffff0000, v71
	v_lshlrev_b32_e32 v166, 16, v63
	v_and_b32_e32 v167, 0xffff0000, v63
	v_pk_add_f32 v[154:155], v[152:153], v[154:155] neg_lo:[0,1] neg_hi:[0,1]
	v_pk_add_f32 v[158:159], v[156:157], v[158:159] neg_lo:[0,1] neg_hi:[0,1]
	v_pk_add_f32 v[162:163], v[160:161], v[162:163] neg_lo:[0,1] neg_hi:[0,1]
	v_pk_add_f32 v[166:167], v[164:165], v[166:167] neg_lo:[0,1] neg_hi:[0,1]
	v_pk_add_f32 v[140:141], v[140:141], v[154:155]
	v_pk_add_f32 v[142:143], v[142:143], v[158:159]
	v_pk_add_f32 v[144:145], v[144:145], v[162:163]
	v_pk_add_f32 v[146:147], v[146:147], v[166:167]
	v_fma_f32 v154, s43, v140, -v152
	v_fma_f32 v155, s43, v141, -v153
	v_fma_f32 v158, s43, v142, -v156
	v_fma_f32 v159, s43, v143, -v157
	v_fma_f32 v162, s43, v144, -v160
	v_fma_f32 v163, s43, v145, -v161
	v_fma_f32 v166, s43, v146, -v164
	v_fma_f32 v167, s43, v147, -v165
	v_cvt_pk_bf16_f32 v148, v154, v155
	v_cvt_pk_bf16_f32 v149, v158, v159
	v_cvt_pk_bf16_f32 v150, v162, v163
	v_cvt_pk_bf16_f32 v151, v166, v167
	global_store_dwordx4 v3, v[148:151], s[10:11] sc1
	v_add_u32_e32 v3, 0x2000, v3
	s_waitcnt vmcnt(31)
	v_lshlrev_b32_e32 v152, 16, v72
	v_and_b32_e32 v153, 0xffff0000, v72
	v_lshlrev_b32_e32 v154, 16, v64
	v_and_b32_e32 v155, 0xffff0000, v64
	v_lshlrev_b32_e32 v156, 16, v73
	v_and_b32_e32 v157, 0xffff0000, v73
	v_lshlrev_b32_e32 v158, 16, v65
	v_and_b32_e32 v159, 0xffff0000, v65
	v_lshlrev_b32_e32 v160, 16, v74
	v_and_b32_e32 v161, 0xffff0000, v74
	v_lshlrev_b32_e32 v162, 16, v66
	v_and_b32_e32 v163, 0xffff0000, v66
	v_lshlrev_b32_e32 v164, 16, v75
	v_and_b32_e32 v165, 0xffff0000, v75
	v_lshlrev_b32_e32 v166, 16, v67
	v_and_b32_e32 v167, 0xffff0000, v67
	v_pk_add_f32 v[154:155], v[152:153], v[154:155] neg_lo:[0,1] neg_hi:[0,1]
	v_pk_add_f32 v[158:159], v[156:157], v[158:159] neg_lo:[0,1] neg_hi:[0,1]
	v_pk_add_f32 v[162:163], v[160:161], v[162:163] neg_lo:[0,1] neg_hi:[0,1]
	v_pk_add_f32 v[166:167], v[164:165], v[166:167] neg_lo:[0,1] neg_hi:[0,1]
	v_pk_add_f32 v[140:141], v[140:141], v[154:155]
	v_pk_add_f32 v[142:143], v[142:143], v[158:159]
	v_pk_add_f32 v[144:145], v[144:145], v[162:163]
	v_pk_add_f32 v[146:147], v[146:147], v[166:167]
	v_fma_f32 v154, s43, v140, -v152
	v_fma_f32 v155, s43, v141, -v153
	v_fma_f32 v158, s43, v142, -v156
	v_fma_f32 v159, s43, v143, -v157
	v_fma_f32 v162, s43, v144, -v160
	v_fma_f32 v163, s43, v145, -v161
	v_fma_f32 v166, s43, v146, -v164
	v_fma_f32 v167, s43, v147, -v165
	v_cvt_pk_bf16_f32 v148, v154, v155
	v_cvt_pk_bf16_f32 v149, v158, v159
	v_cvt_pk_bf16_f32 v150, v162, v163
	v_cvt_pk_bf16_f32 v151, v166, v167
	global_store_dwordx4 v3, v[148:151], s[10:11] sc1
	v_add_u32_e32 v3, 0x2000, v3
	s_waitcnt vmcnt(31)
	v_lshlrev_b32_e32 v152, 16, v76
	v_and_b32_e32 v153, 0xffff0000, v76
	v_lshlrev_b32_e32 v154, 16, v68
	v_and_b32_e32 v155, 0xffff0000, v68
	v_lshlrev_b32_e32 v156, 16, v77
	v_and_b32_e32 v157, 0xffff0000, v77
	v_lshlrev_b32_e32 v158, 16, v69
	v_and_b32_e32 v159, 0xffff0000, v69
	v_lshlrev_b32_e32 v160, 16, v78
	v_and_b32_e32 v161, 0xffff0000, v78
	v_lshlrev_b32_e32 v162, 16, v70
	v_and_b32_e32 v163, 0xffff0000, v70
	v_lshlrev_b32_e32 v164, 16, v79
	v_and_b32_e32 v165, 0xffff0000, v79
	v_lshlrev_b32_e32 v166, 16, v71
	v_and_b32_e32 v167, 0xffff0000, v71
	v_pk_add_f32 v[154:155], v[152:153], v[154:155] neg_lo:[0,1] neg_hi:[0,1]
	v_pk_add_f32 v[158:159], v[156:157], v[158:159] neg_lo:[0,1] neg_hi:[0,1]
	v_pk_add_f32 v[162:163], v[160:161], v[162:163] neg_lo:[0,1] neg_hi:[0,1]
	v_pk_add_f32 v[166:167], v[164:165], v[166:167] neg_lo:[0,1] neg_hi:[0,1]
	v_pk_add_f32 v[140:141], v[140:141], v[154:155]
	v_pk_add_f32 v[142:143], v[142:143], v[158:159]
	v_pk_add_f32 v[144:145], v[144:145], v[162:163]
	v_pk_add_f32 v[146:147], v[146:147], v[166:167]
	v_fma_f32 v154, s43, v140, -v152
	v_fma_f32 v155, s43, v141, -v153
	v_fma_f32 v158, s43, v142, -v156
	v_fma_f32 v159, s43, v143, -v157
	v_fma_f32 v162, s43, v144, -v160
	v_fma_f32 v163, s43, v145, -v161
	v_fma_f32 v166, s43, v146, -v164
	v_fma_f32 v167, s43, v147, -v165
	v_cvt_pk_bf16_f32 v148, v154, v155
	v_cvt_pk_bf16_f32 v149, v158, v159
	v_cvt_pk_bf16_f32 v150, v162, v163
	v_cvt_pk_bf16_f32 v151, v166, v167
	global_store_dwordx4 v3, v[148:151], s[10:11] sc1
	v_add_u32_e32 v3, 0x2000, v3
	s_waitcnt vmcnt(31)
; __device__ __forceinline__ unsigned cvt_pk_bf16(float lo, float hi) { unsigned r; asm volatile("v_cvt_pk_bf16_f32 %0, %1, %2" : "=v"(r) : "v"(lo), "v"(hi)); return r; }
; __device__ __forceinline__ float bf_lo(unsigned w) { return __uint_as_float(w << 16); }
; __device__ __forceinline__ float bf_hi(unsigned w) { return __uint_as_float(w & 0xffff0000u); }
; __device__ void phase_pool() {
;     ...
;             for (int k = 0; k < 8; ++k) { const int row = row0 + r0 + k, tl = tl0 + r0 + k; const u32x4 v = vv[k], o2 = ov[k];
;                 s[0] += bf_lo(v.x) - bf_lo(o2.x); s[1] += bf_hi(v.x) - bf_hi(o2.x); s[2] += bf_lo(v.y) - bf_lo(o2.y); s[3] += bf_hi(v.y) - bf_hi(o2.y);
;                 s[4] += bf_lo(v.z) - bf_lo(o2.z); s[5] += bf_hi(v.z) - bf_hi(o2.z); s[6] += bf_lo(v.w) - bf_lo(o2.w); s[7] += bf_hi(v.w) - bf_hi(o2.w);
;                 const float ic = 1.0f / (float)((tl + 1 < w) ? tl + 1 : w);
;                 u32x4 o;
;                 o.x = cvt_pk_bf16(s[0] * ic - bf_lo(v.x), s[1] * ic - bf_hi(v.x)); o.y = cvt_pk_bf16(s[2] * ic - bf_lo(v.y), s[3] * ic - bf_hi(v.y));
;                 o.z = cvt_pk_bf16(s[4] * ic - bf_lo(v.z), s[5] * ic - bf_hi(v.z)); o.w = cvt_pk_bf16(s[6] * ic - bf_lo(v.w), s[7] * ic - bf_hi(v.w));
;                 *(u32x4*)(pg + (size_t)row * DE + col) = o; }
	v_lshlrev_b32_e32 v152, 16, v80
	v_and_b32_e32 v153, 0xffff0000, v80
	v_lshlrev_b32_e32 v154, 16, v72
	v_and_b32_e32 v155, 0xffff0000, v72
	v_lshlrev_b32_e32 v156, 16, v81
	v_and_b32_e32 v157, 0xffff0000, v81
	v_lshlrev_b32_e32 v158, 16, v73
	v_and_b32_e32 v159, 0xffff0000, v73
	v_lshlrev_b32_e32 v160, 16, v82
	v_and_b32_e32 v161, 0xffff0000, v82
	v_lshlrev_b32_e32 v162, 16, v74
	v_and_b32_e32 v163, 0xffff0000, v74
	v_lshlrev_b32_e32 v164, 16, v83
	v_and_b32_e32 v165, 0xffff0000, v83
	v_lshlrev_b32_e32 v166, 16, v75
	v_and_b32_e32 v167, 0xffff0000, v75
	v_pk_add_f32 v[154:155], v[152:153], v[154:155] neg_lo:[0,1] neg_hi:[0,1]
	v_pk_add_f32 v[158:159], v[156:157], v[158:159] neg_lo:[0,1] neg_hi:[0,1]
	v_pk_add_f32 v[162:163], v[160:161], v[162:163] neg_lo:[0,1] neg_hi:[0,1]
	v_pk_add_f32 v[166:167], v[164:165], v[166:167] neg_lo:[0,1] neg_hi:[0,1]
	v_pk_add_f32 v[140:141], v[140:141], v[154:155]
	v_pk_add_f32 v[142:143], v[142:143], v[158:159]
	v_pk_add_f32 v[144:145], v[144:145], v[162:163]
	v_pk_add_f32 v[146:147], v[146:147], v[166:167]
	v_fma_f32 v154, s43, v140, -v152
	v_fma_f32 v155, s43, v141, -v153
	v_fma_f32 v158, s43, v142, -v156
	v_fma_f32 v159, s43, v143, -v157
	v_fma_f32 v162, s43, v144, -v160
	v_fma_f32 v163, s43, v145, -v161
	v_fma_f32 v166, s43, v146, -v164
	v_fma_f32 v167, s43, v147, -v165
	v_cvt_pk_bf16_f32 v148, v154, v155
	v_cvt_pk_bf16_f32 v149, v158, v159
	v_cvt_pk_bf16_f32 v150, v162, v163
	v_cvt_pk_bf16_f32 v151, v166, v167
	global_store_dwordx4 v3, v[148:151], s[10:11] sc1
	v_add_u32_e32 v3, 0x2000, v3
	s_waitcnt vmcnt(31)
	v_lshlrev_b32_e32 v152, 16, v84
	v_and_b32_e32 v153, 0xffff0000, v84
	v_lshlrev_b32_e32 v154, 16, v76
	v_and_b32_e32 v155, 0xffff0000, v76
	v_lshlrev_b32_e32 v156, 16, v85
	v_and_b32_e32 v157, 0xffff0000, v85
	v_lshlrev_b32_e32 v158, 16, v77
	v_and_b32_e32 v159, 0xffff0000, v77
	v_lshlrev_b32_e32 v160, 16, v86
	v_and_b32_e32 v161, 0xffff0000, v86
	v_lshlrev_b32_e32 v162, 16, v78
	v_and_b32_e32 v163, 0xffff0000, v78
	v_lshlrev_b32_e32 v164, 16, v87
	v_and_b32_e32 v165, 0xffff0000, v87
	v_lshlrev_b32_e32 v166, 16, v79
	v_and_b32_e32 v167, 0xffff0000, v79
	v_pk_add_f32 v[154:155], v[152:153], v[154:155] neg_lo:[0,1] neg_hi:[0,1]
	v_pk_add_f32 v[158:159], v[156:157], v[158:159] neg_lo:[0,1] neg_hi:[0,1]
	v_pk_add_f32 v[162:163], v[160:161], v[162:163] neg_lo:[0,1] neg_hi:[0,1]
	v_pk_add_f32 v[166:167], v[164:165], v[166:167] neg_lo:[0,1] neg_hi:[0,1]
	v_pk_add_f32 v[140:141], v[140:141], v[154:155]
	v_pk_add_f32 v[142:143], v[142:143], v[158:159]
	v_pk_add_f32 v[144:145], v[144:145], v[162:163]
	v_pk_add_f32 v[146:147], v[146:147], v[166:167]
	v_fma_f32 v154, s43, v140, -v152
	v_fma_f32 v155, s43, v141, -v153
	v_fma_f32 v158, s43, v142, -v156
	v_fma_f32 v159, s43, v143, -v157
	v_fma_f32 v162, s43, v144, -v160
	v_fma_f32 v163, s43, v145, -v161
	v_fma_f32 v166, s43, v146, -v164
	v_fma_f32 v167, s43, v147, -v165
	v_cvt_pk_bf16_f32 v148, v154, v155
	v_cvt_pk_bf16_f32 v149, v158, v159
	v_cvt_pk_bf16_f32 v150, v162, v163
	v_cvt_pk_bf16_f32 v151, v166, v167
	global_store_dwordx4 v3, v[148:151], s[10:11] sc1
	v_add_u32_e32 v3, 0x2000, v3
	s_waitcnt vmcnt(31)
	v_lshlrev_b32_e32 v152, 16, v88
	v_and_b32_e32 v153, 0xffff0000, v88
	v_lshlrev_b32_e32 v154, 16, v80
	v_and_b32_e32 v155, 0xffff0000, v80
	v_lshlrev_b32_e32 v156, 16, v89
	v_and_b32_e32 v157, 0xffff0000, v89
	v_lshlrev_b32_e32 v158, 16, v81
	v_and_b32_e32 v159, 0xffff0000, v81
	v_lshlrev_b32_e32 v160, 16, v90
	v_and_b32_e32 v161, 0xffff0000, v90
	v_lshlrev_b32_e32 v162, 16, v82
	v_and_b32_e32 v163, 0xffff0000, v82
	v_lshlrev_b32_e32 v164, 16, v91
	v_and_b32_e32 v165, 0xffff0000, v91
	v_lshlrev_b32_e32 v166, 16, v83
	v_and_b32_e32 v167, 0xffff0000, v83
	v_pk_add_f32 v[154:155], v[152:153], v[154:155] neg_lo:[0,1] neg_hi:[0,1]
	v_pk_add_f32 v[158:159], v[156:157], v[158:159] neg_lo:[0,1] neg_hi:[0,1]
	v_pk_add_f32 v[162:163], v[160:161], v[162:163] neg_lo:[0,1] neg_hi:[0,1]
	v_pk_add_f32 v[166:167], v[164:165], v[166:167] neg_lo:[0,1] neg_hi:[0,1]
	v_pk_add_f32 v[140:141], v[140:141], v[154:155]
	v_pk_add_f32 v[142:143], v[142:143], v[158:159]
	v_pk_add_f32 v[144:145], v[144:145], v[162:163]
	v_pk_add_f32 v[146:147], v[146:147], v[166:167]
	v_fma_f32 v154, s43, v140, -v152
	v_fma_f32 v155, s43, v141, -v153
	v_fma_f32 v158, s43, v142, -v156
	v_fma_f32 v159, s43, v143, -v157
	v_fma_f32 v162, s43, v144, -v160
	v_fma_f32 v163, s43, v145, -v161
	v_fma_f32 v166, s43, v146, -v164
	v_fma_f32 v167, s43, v147, -v165
	v_cvt_pk_bf16_f32 v148, v154, v155
	v_cvt_pk_bf16_f32 v149, v158, v159
	v_cvt_pk_bf16_f32 v150, v162, v163
	v_cvt_pk_bf16_f32 v151, v166, v167
	global_store_dwordx4 v3, v[148:151], s[10:11] sc1
	v_add_u32_e32 v3, 0x2000, v3
	s_waitcnt vmcnt(31)
	v_lshlrev_b32_e32 v152, 16, v92
	v_and_b32_e32 v153, 0xffff0000, v92
	v_lshlrev_b32_e32 v154, 16, v84
	v_and_b32_e32 v155, 0xffff0000, v84
	v_lshlrev_b32_e32 v156, 16, v93
	v_and_b32_e32 v157, 0xffff0000, v93
	v_lshlrev_b32_e32 v158, 16, v85
	v_and_b32_e32 v159, 0xffff0000, v85
	v_lshlrev_b32_e32 v160, 16, v94
	v_and_b32_e32 v161, 0xffff0000, v94
	v_lshlrev_b32_e32 v162, 16, v86
	v_and_b32_e32 v163, 0xffff0000, v86
	v_lshlrev_b32_e32 v164, 16, v95
	v_and_b32_e32 v165, 0xffff0000, v95
	v_lshlrev_b32_e32 v166, 16, v87
	v_and_b32_e32 v167, 0xffff0000, v87
	v_pk_add_f32 v[154:155], v[152:153], v[154:155] neg_lo:[0,1] neg_hi:[0,1]
	v_pk_add_f32 v[158:159], v[156:157], v[158:159] neg_lo:[0,1] neg_hi:[0,1]
	v_pk_add_f32 v[162:163], v[160:161], v[162:163] neg_lo:[0,1] neg_hi:[0,1]
	v_pk_add_f32 v[166:167], v[164:165], v[166:167] neg_lo:[0,1] neg_hi:[0,1]
	v_pk_add_f32 v[140:141], v[140:141], v[154:155]
	v_pk_add_f32 v[142:143], v[142:143], v[158:159]
	v_pk_add_f32 v[144:145], v[144:145], v[162:163]
	v_pk_add_f32 v[146:147], v[146:147], v[166:167]
	v_fma_f32 v154, s43, v140, -v152
	v_fma_f32 v155, s43, v141, -v153
	v_fma_f32 v158, s43, v142, -v156
	v_fma_f32 v159, s43, v143, -v157
	v_fma_f32 v162, s43, v144, -v160
	v_fma_f32 v163, s43, v145, -v161
	v_fma_f32 v166, s43, v146, -v164
	v_fma_f32 v167, s43, v147, -v165
	v_cvt_pk_bf16_f32 v148, v154, v155
	v_cvt_pk_bf16_f32 v149, v158, v159
	v_cvt_pk_bf16_f32 v150, v162, v163
	v_cvt_pk_bf16_f32 v151, v166, v167
	global_store_dwordx4 v3, v[148:151], s[10:11] sc1
	v_add_u32_e32 v3, 0x2000, v3
	s_waitcnt vmcnt(31)
; __device__ __forceinline__ unsigned cvt_pk_bf16(float lo, float hi) { unsigned r; asm volatile("v_cvt_pk_bf16_f32 %0, %1, %2" : "=v"(r) : "v"(lo), "v"(hi)); return r; }
; __device__ __forceinline__ float bf_lo(unsigned w) { return __uint_as_float(w << 16); }
; __device__ __forceinline__ float bf_hi(unsigned w) { return __uint_as_float(w & 0xffff0000u); }
; __device__ void phase_pool() {
;     ...
;             for (int k = 0; k < 8; ++k) { const int row = row0 + r0 + k, tl = tl0 + r0 + k; const u32x4 v = vv[k], o2 = ov[k];
;                 s[0] += bf_lo(v.x) - bf_lo(o2.x); s[1] += bf_hi(v.x) - bf_hi(o2.x); s[2] += bf_lo(v.y) - bf_lo(o2.y); s[3] += bf_hi(v.y) - bf_hi(o2.y);
;                 s[4] += bf_lo(v.z) - bf_lo(o2.z); s[5] += bf_hi(v.z) - bf_hi(o2.z); s[6] += bf_lo(v.w) - bf_lo(o2.w); s[7] += bf_hi(v.w) - bf_hi(o2.w);
;                 const float ic = 1.0f / (float)((tl + 1 < w) ? tl + 1 : w);
;                 u32x4 o;
;                 o.x = cvt_pk_bf16(s[0] * ic - bf_lo(v.x), s[1] * ic - bf_hi(v.x)); o.y = cvt_pk_bf16(s[2] * ic - bf_lo(v.y), s[3] * ic - bf_hi(v.y));
;                 o.z = cvt_pk_bf16(s[4] * ic - bf_lo(v.z), s[5] * ic - bf_hi(v.z)); o.w = cvt_pk_bf16(s[6] * ic - bf_lo(v.w), s[7] * ic - bf_hi(v.w));
;                 *(u32x4*)(pg + (size_t)row * DE + col) = o; }
	v_lshlrev_b32_e32 v152, 16, v96
	v_and_b32_e32 v153, 0xffff0000, v96
	v_lshlrev_b32_e32 v154, 16, v88
	v_and_b32_e32 v155, 0xffff0000, v88
	v_lshlrev_b32_e32 v156, 16, v97
	v_and_b32_e32 v157, 0xffff0000, v97
	v_lshlrev_b32_e32 v158, 16, v89
	v_and_b32_e32 v159, 0xffff0000, v89
	v_lshlrev_b32_e32 v160, 16, v98
	v_and_b32_e32 v161, 0xffff0000, v98
	v_lshlrev_b32_e32 v162, 16, v90
	v_and_b32_e32 v163, 0xffff0000, v90
	v_lshlrev_b32_e32 v164, 16, v99
	v_and_b32_e32 v165, 0xffff0000, v99
	v_lshlrev_b32_e32 v166, 16, v91
	v_and_b32_e32 v167, 0xffff0000, v91
	v_pk_add_f32 v[154:155], v[152:153], v[154:155] neg_lo:[0,1] neg_hi:[0,1]
	v_pk_add_f32 v[158:159], v[156:157], v[158:159] neg_lo:[0,1] neg_hi:[0,1]
	v_pk_add_f32 v[162:163], v[160:161], v[162:163] neg_lo:[0,1] neg_hi:[0,1]
	v_pk_add_f32 v[166:167], v[164:165], v[166:167] neg_lo:[0,1] neg_hi:[0,1]
	v_pk_add_f32 v[140:141], v[140:141], v[154:155]
	v_pk_add_f32 v[142:143], v[142:143], v[158:159]
	v_pk_add_f32 v[144:145], v[144:145], v[162:163]
	v_pk_add_f32 v[146:147], v[146:147], v[166:167]
	v_fma_f32 v154, s43, v140, -v152
	v_fma_f32 v155, s43, v141, -v153
	v_fma_f32 v158, s43, v142, -v156
	v_fma_f32 v159, s43, v143, -v157
	v_fma_f32 v162, s43, v144, -v160
	v_fma_f32 v163, s43, v145, -v161
	v_fma_f32 v166, s43, v146, -v164
	v_fma_f32 v167, s43, v147, -v165
	v_cvt_pk_bf16_f32 v148, v154, v155
	v_cvt_pk_bf16_f32 v149, v158, v159
	v_cvt_pk_bf16_f32 v150, v162, v163
	v_cvt_pk_bf16_f32 v151, v166, v167
	global_store_dwordx4 v3, v[148:151], s[10:11] sc1
	v_add_u32_e32 v3, 0x2000, v3
	s_waitcnt vmcnt(31)
	v_lshlrev_b32_e32 v152, 16, v100
	v_and_b32_e32 v153, 0xffff0000, v100
	v_lshlrev_b32_e32 v154, 16, v92
	v_and_b32_e32 v155, 0xffff0000, v92
	v_lshlrev_b32_e32 v156, 16, v101
	v_and_b32_e32 v157, 0xffff0000, v101
	v_lshlrev_b32_e32 v158, 16, v93
	v_and_b32_e32 v159, 0xffff0000, v93
	v_lshlrev_b32_e32 v160, 16, v102
	v_and_b32_e32 v161, 0xffff0000, v102
	v_lshlrev_b32_e32 v162, 16, v94
	v_and_b32_e32 v163, 0xffff0000, v94
	v_lshlrev_b32_e32 v164, 16, v103
	v_and_b32_e32 v165, 0xffff0000, v103
	v_lshlrev_b32_e32 v166, 16, v95
	v_and_b32_e32 v167, 0xffff0000, v95
	v_pk_add_f32 v[154:155], v[152:153], v[154:155] neg_lo:[0,1] neg_hi:[0,1]
	v_pk_add_f32 v[158:159], v[156:157], v[158:159] neg_lo:[0,1] neg_hi:[0,1]
	v_pk_add_f32 v[162:163], v[160:161], v[162:163] neg_lo:[0,1] neg_hi:[0,1]
	v_pk_add_f32 v[166:167], v[164:165], v[166:167] neg_lo:[0,1] neg_hi:[0,1]
	v_pk_add_f32 v[140:141], v[140:141], v[154:155]
	v_pk_add_f32 v[142:143], v[142:143], v[158:159]
	v_pk_add_f32 v[144:145], v[144:145], v[162:163]
	v_pk_add_f32 v[146:147], v[146:147], v[166:167]
	v_fma_f32 v154, s43, v140, -v152
	v_fma_f32 v155, s43, v141, -v153
	v_fma_f32 v158, s43, v142, -v156
	v_fma_f32 v159, s43, v143, -v157
	v_fma_f32 v162, s43, v144, -v160
	v_fma_f32 v163, s43, v145, -v161
	v_fma_f32 v166, s43, v146, -v164
	v_fma_f32 v167, s43, v147, -v165
	v_cvt_pk_bf16_f32 v148, v154, v155
	v_cvt_pk_bf16_f32 v149, v158, v159
	v_cvt_pk_bf16_f32 v150, v162, v163
	v_cvt_pk_bf16_f32 v151, v166, v167
	global_store_dwordx4 v3, v[148:151], s[10:11] sc1
	v_add_u32_e32 v3, 0x2000, v3
	s_waitcnt vmcnt(31)
	v_lshlrev_b32_e32 v152, 16, v104
	v_and_b32_e32 v153, 0xffff0000, v104
	v_lshlrev_b32_e32 v154, 16, v96
	v_and_b32_e32 v155, 0xffff0000, v96
	v_lshlrev_b32_e32 v156, 16, v105
	v_and_b32_e32 v157, 0xffff0000, v105
	v_lshlrev_b32_e32 v158, 16, v97
	v_and_b32_e32 v159, 0xffff0000, v97
	v_lshlrev_b32_e32 v160, 16, v106
	v_and_b32_e32 v161, 0xffff0000, v106
	v_lshlrev_b32_e32 v162, 16, v98
	v_and_b32_e32 v163, 0xffff0000, v98
	v_lshlrev_b32_e32 v164, 16, v107
	v_and_b32_e32 v165, 0xffff0000, v107
	v_lshlrev_b32_e32 v166, 16, v99
	v_and_b32_e32 v167, 0xffff0000, v99
	v_pk_add_f32 v[154:155], v[152:153], v[154:155] neg_lo:[0,1] neg_hi:[0,1]
	v_pk_add_f32 v[158:159], v[156:157], v[158:159] neg_lo:[0,1] neg_hi:[0,1]
	v_pk_add_f32 v[162:163], v[160:161], v[162:163] neg_lo:[0,1] neg_hi:[0,1]
	v_pk_add_f32 v[166:167], v[164:165], v[166:167] neg_lo:[0,1] neg_hi:[0,1]
	v_pk_add_f32 v[140:141], v[140:141], v[154:155]
	v_pk_add_f32 v[142:143], v[142:143], v[158:159]
	v_pk_add_f32 v[144:145], v[144:145], v[162:163]
	v_pk_add_f32 v[146:147], v[146:147], v[166:167]
	v_fma_f32 v154, s43, v140, -v152
	v_fma_f32 v155, s43, v141, -v153
	v_fma_f32 v158, s43, v142, -v156
	v_fma_f32 v159, s43, v143, -v157
	v_fma_f32 v162, s43, v144, -v160
	v_fma_f32 v163, s43, v145, -v161
	v_fma_f32 v166, s43, v146, -v164
	v_fma_f32 v167, s43, v147, -v165
	v_cvt_pk_bf16_f32 v148, v154, v155
	v_cvt_pk_bf16_f32 v149, v158, v159
	v_cvt_pk_bf16_f32 v150, v162, v163
	v_cvt_pk_bf16_f32 v151, v166, v167
	global_store_dwordx4 v3, v[148:151], s[10:11] sc1
	v_add_u32_e32 v3, 0x2000, v3
	s_waitcnt vmcnt(31)
	v_lshlrev_b32_e32 v152, 16, v108
	v_and_b32_e32 v153, 0xffff0000, v108
	v_lshlrev_b32_e32 v154, 16, v100
	v_and_b32_e32 v155, 0xffff0000, v100
	v_lshlrev_b32_e32 v156, 16, v109
	v_and_b32_e32 v157, 0xffff0000, v109
	v_lshlrev_b32_e32 v158, 16, v101
	v_and_b32_e32 v159, 0xffff0000, v101
	v_lshlrev_b32_e32 v160, 16, v110
	v_and_b32_e32 v161, 0xffff0000, v110
	v_lshlrev_b32_e32 v162, 16, v102
	v_and_b32_e32 v163, 0xffff0000, v102
	v_lshlrev_b32_e32 v164, 16, v111
	v_and_b32_e32 v165, 0xffff0000, v111
	v_lshlrev_b32_e32 v166, 16, v103
	v_and_b32_e32 v167, 0xffff0000, v103
	v_pk_add_f32 v[154:155], v[152:153], v[154:155] neg_lo:[0,1] neg_hi:[0,1]
	v_pk_add_f32 v[158:159], v[156:157], v[158:159] neg_lo:[0,1] neg_hi:[0,1]
	v_pk_add_f32 v[162:163], v[160:161], v[162:163] neg_lo:[0,1] neg_hi:[0,1]
	v_pk_add_f32 v[166:167], v[164:165], v[166:167] neg_lo:[0,1] neg_hi:[0,1]
	v_pk_add_f32 v[140:141], v[140:141], v[154:155]
	v_pk_add_f32 v[142:143], v[142:143], v[158:159]
	v_pk_add_f32 v[144:145], v[144:145], v[162:163]
	v_pk_add_f32 v[146:147], v[146:147], v[166:167]
	v_fma_f32 v154, s43, v140, -v152
	v_fma_f32 v155, s43, v141, -v153
	v_fma_f32 v158, s43, v142, -v156
	v_fma_f32 v159, s43, v143, -v157
	v_fma_f32 v162, s43, v144, -v160
	v_fma_f32 v163, s43, v145, -v161
	v_fma_f32 v166, s43, v146, -v164
	v_fma_f32 v167, s43, v147, -v165
	v_cvt_pk_bf16_f32 v148, v154, v155
	v_cvt_pk_bf16_f32 v149, v158, v159
	v_cvt_pk_bf16_f32 v150, v162, v163
	v_cvt_pk_bf16_f32 v151, v166, v167
	global_store_dwordx4 v3, v[148:151], s[10:11] sc1
	v_add_u32_e32 v3, 0x2000, v3
	s_waitcnt vmcnt(31)
; __device__ __forceinline__ unsigned cvt_pk_bf16(float lo, float hi) { unsigned r; asm volatile("v_cvt_pk_bf16_f32 %0, %1, %2" : "=v"(r) : "v"(lo), "v"(hi)); return r; }
; __device__ __forceinline__ float bf_lo(unsigned w) { return __uint_as_float(w << 16); }
; __device__ __forceinline__ float bf_hi(unsigned w) { return __uint_as_float(w & 0xffff0000u); }
; __device__ void phase_pool() {
;     ...
;             for (int k = 0; k < 8; ++k) { const int row = row0 + r0 + k, tl = tl0 + r0 + k; const u32x4 v = vv[k], o2 = ov[k];
;                 s[0] += bf_lo(v.x) - bf_lo(o2.x); s[1] += bf_hi(v.x) - bf_hi(o2.x); s[2] += bf_lo(v.y) - bf_lo(o2.y); s[3] += bf_hi(v.y) - bf_hi(o2.y);
;                 s[4] += bf_lo(v.z) - bf_lo(o2.z); s[5] += bf_hi(v.z) - bf_hi(o2.z); s[6] += bf_lo(v.w) - bf_lo(o2.w); s[7] += bf_hi(v.w) - bf_hi(o2.w);
;                 const float ic = 1.0f / (float)((tl + 1 < w) ? tl + 1 : w);
;                 u32x4 o;
;                 o.x = cvt_pk_bf16(s[0] * ic - bf_lo(v.x), s[1] * ic - bf_hi(v.x)); o.y = cvt_pk_bf16(s[2] * ic - bf_lo(v.y), s[3] * ic - bf_hi(v.y));
;                 o.z = cvt_pk_bf16(s[4] * ic - bf_lo(v.z), s[5] * ic - bf_hi(v.z)); o.w = cvt_pk_bf16(s[6] * ic - bf_lo(v.w), s[7] * ic - bf_hi(v.w));
;                 *(u32x4*)(pg + (size_t)row * DE + col) = o; }
	v_lshlrev_b32_e32 v152, 16, v112
	v_and_b32_e32 v153, 0xffff0000, v112
	v_lshlrev_b32_e32 v154, 16, v104
	v_and_b32_e32 v155, 0xffff0000, v104
	v_lshlrev_b32_e32 v156, 16, v113
	v_and_b32_e32 v157, 0xffff0000, v113
	v_lshlrev_b32_e32 v158, 16, v105
	v_and_b32_e32 v159, 0xffff0000, v105
	v_lshlrev_b32_e32 v160, 16, v114
	v_and_b32_e32 v161, 0xffff0000, v114
	v_lshlrev_b32_e32 v162, 16, v106
	v_and_b32_e32 v163, 0xffff0000, v106
	v_lshlrev_b32_e32 v164, 16, v115
	v_and_b32_e32 v165, 0xffff0000, v115
	v_lshlrev_b32_e32 v166, 16, v107
	v_and_b32_e32 v167, 0xffff0000, v107
	v_pk_add_f32 v[154:155], v[152:153], v[154:155] neg_lo:[0,1] neg_hi:[0,1]
	v_pk_add_f32 v[158:159], v[156:157], v[158:159] neg_lo:[0,1] neg_hi:[0,1]
	v_pk_add_f32 v[162:163], v[160:161], v[162:163] neg_lo:[0,1] neg_hi:[0,1]
	v_pk_add_f32 v[166:167], v[164:165], v[166:167] neg_lo:[0,1] neg_hi:[0,1]
	v_pk_add_f32 v[140:141], v[140:141], v[154:155]
	v_pk_add_f32 v[142:143], v[142:143], v[158:159]
	v_pk_add_f32 v[144:145], v[144:145], v[162:163]
	v_pk_add_f32 v[146:147], v[146:147], v[166:167]
	v_fma_f32 v154, s43, v140, -v152
	v_fma_f32 v155, s43, v141, -v153
	v_fma_f32 v158, s43, v142, -v156
	v_fma_f32 v159, s43, v143, -v157
	v_fma_f32 v162, s43, v144, -v160
	v_fma_f32 v163, s43, v145, -v161
	v_fma_f32 v166, s43, v146, -v164
	v_fma_f32 v167, s43, v147, -v165
	v_cvt_pk_bf16_f32 v148, v154, v155
	v_cvt_pk_bf16_f32 v149, v158, v159
	v_cvt_pk_bf16_f32 v150, v162, v163
	v_cvt_pk_bf16_f32 v151, v166, v167
	global_store_dwordx4 v3, v[148:151], s[10:11] sc1
	v_add_u32_e32 v3, 0x2000, v3
	s_waitcnt vmcnt(31)
	v_lshlrev_b32_e32 v152, 16, v116
	v_and_b32_e32 v153, 0xffff0000, v116
	v_lshlrev_b32_e32 v154, 16, v108
	v_and_b32_e32 v155, 0xffff0000, v108
	v_lshlrev_b32_e32 v156, 16, v117
	v_and_b32_e32 v157, 0xffff0000, v117
	v_lshlrev_b32_e32 v158, 16, v109
	v_and_b32_e32 v159, 0xffff0000, v109
	v_lshlrev_b32_e32 v160, 16, v118
	v_and_b32_e32 v161, 0xffff0000, v118
	v_lshlrev_b32_e32 v162, 16, v110
	v_and_b32_e32 v163, 0xffff0000, v110
	v_lshlrev_b32_e32 v164, 16, v119
	v_and_b32_e32 v165, 0xffff0000, v119
	v_lshlrev_b32_e32 v166, 16, v111
	v_and_b32_e32 v167, 0xffff0000, v111
	v_pk_add_f32 v[154:155], v[152:153], v[154:155] neg_lo:[0,1] neg_hi:[0,1]
	v_pk_add_f32 v[158:159], v[156:157], v[158:159] neg_lo:[0,1] neg_hi:[0,1]
	v_pk_add_f32 v[162:163], v[160:161], v[162:163] neg_lo:[0,1] neg_hi:[0,1]
	v_pk_add_f32 v[166:167], v[164:165], v[166:167] neg_lo:[0,1] neg_hi:[0,1]
	v_pk_add_f32 v[140:141], v[140:141], v[154:155]
	v_pk_add_f32 v[142:143], v[142:143], v[158:159]
	v_pk_add_f32 v[144:145], v[144:145], v[162:163]
	v_pk_add_f32 v[146:147], v[146:147], v[166:167]
	v_fma_f32 v154, s43, v140, -v152
	v_fma_f32 v155, s43, v141, -v153
	v_fma_f32 v158, s43, v142, -v156
	v_fma_f32 v159, s43, v143, -v157
	v_fma_f32 v162, s43, v144, -v160
	v_fma_f32 v163, s43, v145, -v161
	v_fma_f32 v166, s43, v146, -v164
	v_fma_f32 v167, s43, v147, -v165
	v_cvt_pk_bf16_f32 v148, v154, v155
	v_cvt_pk_bf16_f32 v149, v158, v159
	v_cvt_pk_bf16_f32 v150, v162, v163
	v_cvt_pk_bf16_f32 v151, v166, v167
	global_store_dwordx4 v3, v[148:151], s[10:11] sc1
	v_add_u32_e32 v3, 0x2000, v3
	s_waitcnt vmcnt(31)
	v_lshlrev_b32_e32 v152, 16, v120
	v_and_b32_e32 v153, 0xffff0000, v120
	v_lshlrev_b32_e32 v154, 16, v112
	v_and_b32_e32 v155, 0xffff0000, v112
	v_lshlrev_b32_e32 v156, 16, v121
	v_and_b32_e32 v157, 0xffff0000, v121
	v_lshlrev_b32_e32 v158, 16, v113
	v_and_b32_e32 v159, 0xffff0000, v113
	v_lshlrev_b32_e32 v160, 16, v122
	v_and_b32_e32 v161, 0xffff0000, v122
	v_lshlrev_b32_e32 v162, 16, v114
	v_and_b32_e32 v163, 0xffff0000, v114
	v_lshlrev_b32_e32 v164, 16, v123
	v_and_b32_e32 v165, 0xffff0000, v123
	v_lshlrev_b32_e32 v166, 16, v115
	v_and_b32_e32 v167, 0xffff0000, v115
	v_pk_add_f32 v[154:155], v[152:153], v[154:155] neg_lo:[0,1] neg_hi:[0,1]
	v_pk_add_f32 v[158:159], v[156:157], v[158:159] neg_lo:[0,1] neg_hi:[0,1]
	v_pk_add_f32 v[162:163], v[160:161], v[162:163] neg_lo:[0,1] neg_hi:[0,1]
	v_pk_add_f32 v[166:167], v[164:165], v[166:167] neg_lo:[0,1] neg_hi:[0,1]
	v_pk_add_f32 v[140:141], v[140:141], v[154:155]
	v_pk_add_f32 v[142:143], v[142:143], v[158:159]
	v_pk_add_f32 v[144:145], v[144:145], v[162:163]
	v_pk_add_f32 v[146:147], v[146:147], v[166:167]
	v_fma_f32 v154, s43, v140, -v152
	v_fma_f32 v155, s43, v141, -v153
	v_fma_f32 v158, s43, v142, -v156
	v_fma_f32 v159, s43, v143, -v157
	v_fma_f32 v162, s43, v144, -v160
	v_fma_f32 v163, s43, v145, -v161
	v_fma_f32 v166, s43, v146, -v164
	v_fma_f32 v167, s43, v147, -v165
	v_cvt_pk_bf16_f32 v148, v154, v155
	v_cvt_pk_bf16_f32 v149, v158, v159
	v_cvt_pk_bf16_f32 v150, v162, v163
	v_cvt_pk_bf16_f32 v151, v166, v167
	global_store_dwordx4 v3, v[148:151], s[10:11] sc1
	v_add_u32_e32 v3, 0x2000, v3
	s_waitcnt vmcnt(31)
; __device__ __forceinline__ unsigned cvt_pk_bf16(float lo, float hi) { unsigned r; asm volatile("v_cvt_pk_bf16_f32 %0, %1, %2" : "=v"(r) : "v"(lo), "v"(hi)); return r; }
; __device__ __forceinline__ float bf_lo(unsigned w) { return __uint_as_float(w << 16); }
; __device__ __forceinline__ float bf_hi(unsigned w) { return __uint_as_float(w & 0xffff0000u); }
; __device__ void phase_pool() {
;     ...
;             for (int k = 0; k < 8; ++k) { const int row = row0 + r0 + k, tl = tl0 + r0 + k; const u32x4 v = vv[k], o2 = ov[k];
;                 s[0] += bf_lo(v.x) - bf_lo(o2.x); s[1] += bf_hi(v.x) - bf_hi(o2.x); s[2] += bf_lo(v.y) - bf_lo(o2.y); s[3] += bf_hi(v.y) - bf_hi(o2.y);
;                 s[4] += bf_lo(v.z) - bf_lo(o2.z); s[5] += bf_hi(v.z) - bf_hi(o2.z); s[6] += bf_lo(v.w) - bf_lo(o2.w); s[7] += bf_hi(v.w) - bf_hi(o2.w);
;                 const float ic = 1.0f / (float)((tl + 1 < w) ? tl + 1 : w);
;                 u32x4 o;
;                 o.x = cvt_pk_bf16(s[0] * ic - bf_lo(v.x), s[1] * ic - bf_hi(v.x)); o.y = cvt_pk_bf16(s[2] * ic - bf_lo(v.y), s[3] * ic - bf_hi(v.y));
;                 o.z = cvt_pk_bf16(s[4] * ic - bf_lo(v.z), s[5] * ic - bf_hi(v.z)); o.w = cvt_pk_bf16(s[6] * ic - bf_lo(v.w), s[7] * ic - bf_hi(v.w));
;                 *(u32x4*)(pg + (size_t)row * DE + col) = o; }
	v_lshlrev_b32_e32 v152, 16, v124
	v_and_b32_e32 v153, 0xffff0000, v124
	v_lshlrev_b32_e32 v154, 16, v116
	v_and_b32_e32 v155, 0xffff0000, v116
	v_lshlrev_b32_e32 v156, 16, v125
	v_and_b32_e32 v157, 0xffff0000, v125
	v_lshlrev_b32_e32 v158, 16, v117
	v_and_b32_e32 v159, 0xffff0000, v117
	v_lshlrev_b32_e32 v160, 16, v126
	v_and_b32_e32 v161, 0xffff0000, v126
	v_lshlrev_b32_e32 v162, 16, v118
	v_and_b32_e32 v163, 0xffff0000, v118
	v_lshlrev_b32_e32 v164, 16, v127
	v_and_b32_e32 v165, 0xffff0000, v127
	v_lshlrev_b32_e32 v166, 16, v119
	v_and_b32_e32 v167, 0xffff0000, v119
	v_pk_add_f32 v[154:155], v[152:153], v[154:155] neg_lo:[0,1] neg_hi:[0,1]
	v_pk_add_f32 v[158:159], v[156:157], v[158:159] neg_lo:[0,1] neg_hi:[0,1]
	v_pk_add_f32 v[162:163], v[160:161], v[162:163] neg_lo:[0,1] neg_hi:[0,1]
	v_pk_add_f32 v[166:167], v[164:165], v[166:167] neg_lo:[0,1] neg_hi:[0,1]
	v_pk_add_f32 v[140:141], v[140:141], v[154:155]
	v_pk_add_f32 v[142:143], v[142:143], v[158:159]
	v_pk_add_f32 v[144:145], v[144:145], v[162:163]
	v_pk_add_f32 v[146:147], v[146:147], v[166:167]
	v_fma_f32 v154, s43, v140, -v152
	v_fma_f32 v155, s43, v141, -v153
	v_fma_f32 v158, s43, v142, -v156
	v_fma_f32 v159, s43, v143, -v157
	v_fma_f32 v162, s43, v144, -v160
	v_fma_f32 v163, s43, v145, -v161
	v_fma_f32 v166, s43, v146, -v164
	v_fma_f32 v167, s43, v147, -v165
	v_cvt_pk_bf16_f32 v148, v154, v155
	v_cvt_pk_bf16_f32 v149, v158, v159
	v_cvt_pk_bf16_f32 v150, v162, v163
	v_cvt_pk_bf16_f32 v151, v166, v167
	global_store_dwordx4 v3, v[148:151], s[10:11] sc1
	v_add_u32_e32 v3, 0x2000, v3
	s_waitcnt vmcnt(31)
	v_lshlrev_b32_e32 v152, 16, v128
	v_and_b32_e32 v153, 0xffff0000, v128
	v_lshlrev_b32_e32 v154, 16, v120
	v_and_b32_e32 v155, 0xffff0000, v120
	v_lshlrev_b32_e32 v156, 16, v129
	v_and_b32_e32 v157, 0xffff0000, v129
	v_lshlrev_b32_e32 v158, 16, v121
	v_and_b32_e32 v159, 0xffff0000, v121
	v_lshlrev_b32_e32 v160, 16, v130
	v_and_b32_e32 v161, 0xffff0000, v130
	v_lshlrev_b32_e32 v162, 16, v122
	v_and_b32_e32 v163, 0xffff0000, v122
	v_lshlrev_b32_e32 v164, 16, v131
	v_and_b32_e32 v165, 0xffff0000, v131
	v_lshlrev_b32_e32 v166, 16, v123
	v_and_b32_e32 v167, 0xffff0000, v123
	v_pk_add_f32 v[154:155], v[152:153], v[154:155] neg_lo:[0,1] neg_hi:[0,1]
	v_pk_add_f32 v[158:159], v[156:157], v[158:159] neg_lo:[0,1] neg_hi:[0,1]
	v_pk_add_f32 v[162:163], v[160:161], v[162:163] neg_lo:[0,1] neg_hi:[0,1]
	v_pk_add_f32 v[166:167], v[164:165], v[166:167] neg_lo:[0,1] neg_hi:[0,1]
	v_pk_add_f32 v[140:141], v[140:141], v[154:155]
	v_pk_add_f32 v[142:143], v[142:143], v[158:159]
	v_pk_add_f32 v[144:145], v[144:145], v[162:163]
	v_pk_add_f32 v[146:147], v[146:147], v[166:167]
	v_fma_f32 v154, s43, v140, -v152
	v_fma_f32 v155, s43, v141, -v153
	v_fma_f32 v158, s43, v142, -v156
	v_fma_f32 v159, s43, v143, -v157
	v_fma_f32 v162, s43, v144, -v160
	v_fma_f32 v163, s43, v145, -v161
	v_fma_f32 v166, s43, v146, -v164
	v_fma_f32 v167, s43, v147, -v165
	v_cvt_pk_bf16_f32 v148, v154, v155
	v_cvt_pk_bf16_f32 v149, v158, v159
	v_cvt_pk_bf16_f32 v150, v162, v163
	v_cvt_pk_bf16_f32 v151, v166, v167
	global_store_dwordx4 v3, v[148:151], s[10:11] sc1
	v_add_u32_e32 v3, 0x2000, v3
	s_waitcnt vmcnt(31)
	v_lshlrev_b32_e32 v152, 16, v132
	v_and_b32_e32 v153, 0xffff0000, v132
	v_lshlrev_b32_e32 v154, 16, v124
	v_and_b32_e32 v155, 0xffff0000, v124
	v_lshlrev_b32_e32 v156, 16, v133
	v_and_b32_e32 v157, 0xffff0000, v133
	v_lshlrev_b32_e32 v158, 16, v125
	v_and_b32_e32 v159, 0xffff0000, v125
	v_lshlrev_b32_e32 v160, 16, v134
	v_and_b32_e32 v161, 0xffff0000, v134
	v_lshlrev_b32_e32 v162, 16, v126
	v_and_b32_e32 v163, 0xffff0000, v126
	v_lshlrev_b32_e32 v164, 16, v135
	v_and_b32_e32 v165, 0xffff0000, v135
	v_lshlrev_b32_e32 v166, 16, v127
	v_and_b32_e32 v167, 0xffff0000, v127
	v_pk_add_f32 v[154:155], v[152:153], v[154:155] neg_lo:[0,1] neg_hi:[0,1]
	v_pk_add_f32 v[158:159], v[156:157], v[158:159] neg_lo:[0,1] neg_hi:[0,1]
	v_pk_add_f32 v[162:163], v[160:161], v[162:163] neg_lo:[0,1] neg_hi:[0,1]
	v_pk_add_f32 v[166:167], v[164:165], v[166:167] neg_lo:[0,1] neg_hi:[0,1]
	v_pk_add_f32 v[140:141], v[140:141], v[154:155]
	v_pk_add_f32 v[142:143], v[142:143], v[158:159]
	v_pk_add_f32 v[144:145], v[144:145], v[162:163]
	v_pk_add_f32 v[146:147], v[146:147], v[166:167]
	v_fma_f32 v154, s43, v140, -v152
	v_fma_f32 v155, s43, v141, -v153
	v_fma_f32 v158, s43, v142, -v156
	v_fma_f32 v159, s43, v143, -v157
	v_fma_f32 v162, s43, v144, -v160
	v_fma_f32 v163, s43, v145, -v161
	v_fma_f32 v166, s43, v146, -v164
	v_fma_f32 v167, s43, v147, -v165
	v_cvt_pk_bf16_f32 v148, v154, v155
	v_cvt_pk_bf16_f32 v149, v158, v159
	v_cvt_pk_bf16_f32 v150, v162, v163
	v_cvt_pk_bf16_f32 v151, v166, v167
	global_store_dwordx4 v3, v[148:151], s[10:11] sc1
	v_add_u32_e32 v3, 0x2000, v3
	s_waitcnt vmcnt(31)
	v_lshlrev_b32_e32 v152, 16, v136
	v_and_b32_e32 v153, 0xffff0000, v136
	v_lshlrev_b32_e32 v154, 16, v128
	v_and_b32_e32 v155, 0xffff0000, v128
	v_lshlrev_b32_e32 v156, 16, v137
	v_and_b32_e32 v157, 0xffff0000, v137
	v_lshlrev_b32_e32 v158, 16, v129
	v_and_b32_e32 v159, 0xffff0000, v129
	v_lshlrev_b32_e32 v160, 16, v138
	v_and_b32_e32 v161, 0xffff0000, v138
	v_lshlrev_b32_e32 v162, 16, v130
	v_and_b32_e32 v163, 0xffff0000, v130
	v_lshlrev_b32_e32 v164, 16, v139
	v_and_b32_e32 v165, 0xffff0000, v139
	v_lshlrev_b32_e32 v166, 16, v131
	v_and_b32_e32 v167, 0xffff0000, v131
	v_pk_add_f32 v[154:155], v[152:153], v[154:155] neg_lo:[0,1] neg_hi:[0,1]
	v_pk_add_f32 v[158:159], v[156:157], v[158:159] neg_lo:[0,1] neg_hi:[0,1]
	v_pk_add_f32 v[162:163], v[160:161], v[162:163] neg_lo:[0,1] neg_hi:[0,1]
	v_pk_add_f32 v[166:167], v[164:165], v[166:167] neg_lo:[0,1] neg_hi:[0,1]
	v_pk_add_f32 v[140:141], v[140:141], v[154:155]
	v_pk_add_f32 v[142:143], v[142:143], v[158:159]
	v_pk_add_f32 v[144:145], v[144:145], v[162:163]
	v_pk_add_f32 v[146:147], v[146:147], v[166:167]
	v_fma_f32 v154, s43, v140, -v152
	v_fma_f32 v155, s43, v141, -v153
	v_fma_f32 v158, s43, v142, -v156
	v_fma_f32 v159, s43, v143, -v157
	v_fma_f32 v162, s43, v144, -v160
	v_fma_f32 v163, s43, v145, -v161
	v_fma_f32 v166, s43, v146, -v164
	v_fma_f32 v167, s43, v147, -v165
	v_cvt_pk_bf16_f32 v148, v154, v155
	v_cvt_pk_bf16_f32 v149, v158, v159
	v_cvt_pk_bf16_f32 v150, v162, v163
	v_cvt_pk_bf16_f32 v151, v166, v167
	global_store_dwordx4 v3, v[148:151], s[10:11] sc1
	s_branch .LBB0_441

; __device__ __forceinline__ unsigned cvt_pk_bf16(float lo, float hi) { unsigned r; asm volatile("v_cvt_pk_bf16_f32 %0, %1, %2" : "=v"(r) : "v"(lo), "v"(hi)); return r; }
; __device__ __forceinline__ float bf_lo(unsigned w) { return __uint_as_float(w << 16); }
; __device__ __forceinline__ float bf_hi(unsigned w) { return __uint_as_float(w & 0xffff0000u); }
; __device__ void phase_pool() {
;     ...
;         { u32x4 hv[16];
; #pragma unroll
;           for (int k = 1; k <= 16; ++k) hv[k - 1] = (k <= nh) ? *(const u32x4*)(uz + (size_t)(row0 - k) * DE2 + col) : (u32x4){0u, 0u, 0u, 0u};
; #pragma unroll
;           for (int k = 0; k < 16; ++k) { const u32x4 v = hv[k];
;             s[0] += bf_lo(v.x); s[1] += bf_hi(v.x); s[2] += bf_lo(v.y); s[3] += bf_hi(v.y); s[4] += bf_lo(v.z); s[5] += bf_hi(v.z); s[6] += bf_lo(v.w); s[7] += bf_hi(v.w); } }
; #pragma unroll 1
;         for (int r0 = 0; r0 < RB; r0 += 8) {
;             u32x4 vv[8], ov[8];
; #pragma unroll
;             for (int k = 0; k < 8; ++k) { const int row = row0 + r0 + k, tl = tl0 + r0 + k;
;                 vv[k] = *(const u32x4*)(uz + (size_t)row * DE2 + col);
;                 ov[k] = (tl >= w) ? *(const u32x4*)(uz + (size_t)(row - w) * DE2 + col) : (u32x4){0u, 0u, 0u, 0u}; }
; #pragma unroll
;             for (int k = 0; k < 8; ++k) { const int row = row0 + r0 + k, tl = tl0 + r0 + k; const u32x4 v = vv[k], o2 = ov[k];
;                 s[0] += bf_lo(v.x) - bf_lo(o2.x); s[1] += bf_hi(v.x) - bf_hi(o2.x); s[2] += bf_lo(v.y) - bf_lo(o2.y); s[3] += bf_hi(v.y) - bf_hi(o2.y);
;                 s[4] += bf_lo(v.z) - bf_lo(o2.z); s[5] += bf_hi(v.z) - bf_hi(o2.z); s[6] += bf_lo(v.w) - bf_lo(o2.w); s[7] += bf_hi(v.w) - bf_hi(o2.w);
;                 const float ic = 1.0f / (float)((tl + 1 < w) ? tl + 1 : w);
;                 u32x4 o;
;                 o.x = cvt_pk_bf16(s[0] * ic - bf_lo(v.x), s[1] * ic - bf_hi(v.x)); o.y = cvt_pk_bf16(s[2] * ic - bf_lo(v.y), s[3] * ic - bf_hi(v.y));
;                 o.z = cvt_pk_bf16(s[4] * ic - bf_lo(v.z), s[5] * ic - bf_hi(v.z)); o.w = cvt_pk_bf16(s[6] * ic - bf_lo(v.w), s[7] * ic - bf_hi(v.w));
;                 *(u32x4*)(pg + (size_t)row * DE + col) = o; }
.Lpool_w4_main:
	global_load_dwordx4 v[20:23], v2, s[8:9]
	v_add_u32_e32 v2, 0x4000, v2
	global_load_dwordx4 v[24:27], v2, s[8:9]
	v_add_u32_e32 v2, 0x4000, v2
	global_load_dwordx4 v[28:31], v2, s[8:9]
	v_add_u32_e32 v2, 0x4000, v2
	global_load_dwordx4 v[32:35], v2, s[8:9]
	v_add_u32_e32 v2, 0x4000, v2
	global_load_dwordx4 v[36:39], v2, s[8:9]
	v_add_u32_e32 v2, 0x4000, v2
	global_load_dwordx4 v[40:43], v2, s[8:9]
	v_add_u32_e32 v2, 0x4000, v2
	global_load_dwordx4 v[44:47], v2, s[8:9]
	v_add_u32_e32 v2, 0x4000, v2
	global_load_dwordx4 v[48:51], v2, s[8:9]
	v_add_u32_e32 v2, 0x4000, v2
	global_load_dwordx4 v[52:55], v2, s[8:9]
	v_add_u32_e32 v2, 0x4000, v2
	global_load_dwordx4 v[56:59], v2, s[8:9]
	v_add_u32_e32 v2, 0x4000, v2
	global_load_dwordx4 v[60:63], v2, s[8:9]
	v_add_u32_e32 v2, 0x4000, v2
	global_load_dwordx4 v[64:67], v2, s[8:9]
	v_add_u32_e32 v2, 0x4000, v2
	global_load_dwordx4 v[68:71], v2, s[8:9]
	v_add_u32_e32 v2, 0x4000, v2
	global_load_dwordx4 v[72:75], v2, s[8:9]
	v_add_u32_e32 v2, 0x4000, v2
	global_load_dwordx4 v[76:79], v2, s[8:9]
	v_add_u32_e32 v2, 0x4000, v2
	global_load_dwordx4 v[80:83], v2, s[8:9]
	v_add_u32_e32 v2, 0x4000, v2
	global_load_dwordx4 v[84:87], v2, s[8:9]
	v_add_u32_e32 v2, 0x4000, v2
	global_load_dwordx4 v[88:91], v2, s[8:9]
	v_add_u32_e32 v2, 0x4000, v2
	global_load_dwordx4 v[92:95], v2, s[8:9]
	v_add_u32_e32 v2, 0x4000, v2
	global_load_dwordx4 v[96:99], v2, s[8:9]
	v_add_u32_e32 v2, 0x4000, v2
	global_load_dwordx4 v[100:103], v2, s[8:9]
	v_add_u32_e32 v2, 0x4000, v2
	global_load_dwordx4 v[104:107], v2, s[8:9]
	v_add_u32_e32 v2, 0x4000, v2
	global_load_dwordx4 v[108:111], v2, s[8:9]
	v_add_u32_e32 v2, 0x4000, v2
	global_load_dwordx4 v[112:115], v2, s[8:9]
	v_add_u32_e32 v2, 0x4000, v2
	global_load_dwordx4 v[116:119], v2, s[8:9]
	v_add_u32_e32 v2, 0x4000, v2
	global_load_dwordx4 v[120:123], v2, s[8:9]
	v_add_u32_e32 v2, 0x4000, v2
	global_load_dwordx4 v[124:127], v2, s[8:9]
	v_add_u32_e32 v2, 0x4000, v2
	global_load_dwordx4 v[128:131], v2, s[8:9]
	v_add_u32_e32 v2, 0x4000, v2
	global_load_dwordx4 v[132:135], v2, s[8:9]
	v_add_u32_e32 v2, 0x4000, v2
	global_load_dwordx4 v[136:139], v2, s[8:9]
	v_add_u32_e32 v2, 0x4000, v2
	global_load_dwordx4 v[140:143], v2, s[8:9]
	v_add_u32_e32 v2, 0x4000, v2
	global_load_dwordx4 v[144:147], v2, s[8:9]
	v_mov_b32_e32 v148, 0
	v_mov_b32_e32 v149, 0
	v_mov_b32_e32 v150, 0
	v_mov_b32_e32 v151, 0
	v_mov_b32_e32 v152, 0
	v_mov_b32_e32 v153, 0
	v_mov_b32_e32 v154, 0
	v_mov_b32_e32 v155, 0
	s_mov_b32 s43, 0x3e800000
	s_cmp_eq_u32 s16, 0
	s_waitcnt vmcnt(32)
	v_lshlrev_b32_e32 v160, 16, v16
	v_and_b32_e32 v161, 0xffff0000, v16
	v_lshlrev_b32_e32 v164, 16, v17
	v_and_b32_e32 v165, 0xffff0000, v17
	v_lshlrev_b32_e32 v168, 16, v18
	v_and_b32_e32 v169, 0xffff0000, v18
	v_lshlrev_b32_e32 v172, 16, v19
	v_and_b32_e32 v173, 0xffff0000, v19
	v_pk_add_f32 v[148:149], v[148:149], v[160:161]
	v_pk_add_f32 v[150:151], v[150:151], v[164:165]
	v_pk_add_f32 v[152:153], v[152:153], v[168:169]
	v_pk_add_f32 v[154:155], v[154:155], v[172:173]
	v_lshlrev_b32_e32 v160, 16, v12
	v_and_b32_e32 v161, 0xffff0000, v12
	v_lshlrev_b32_e32 v164, 16, v13
	v_and_b32_e32 v165, 0xffff0000, v13
	v_lshlrev_b32_e32 v168, 16, v14
	v_and_b32_e32 v169, 0xffff0000, v14
	v_lshlrev_b32_e32 v172, 16, v15
	v_and_b32_e32 v173, 0xffff0000, v15
	v_pk_add_f32 v[148:149], v[148:149], v[160:161]
	v_pk_add_f32 v[150:151], v[150:151], v[164:165]
	v_pk_add_f32 v[152:153], v[152:153], v[168:169]
	v_pk_add_f32 v[154:155], v[154:155], v[172:173]
	v_lshlrev_b32_e32 v160, 16, v8
	v_and_b32_e32 v161, 0xffff0000, v8
	v_lshlrev_b32_e32 v164, 16, v9
	v_and_b32_e32 v165, 0xffff0000, v9
	v_lshlrev_b32_e32 v168, 16, v10
	v_and_b32_e32 v169, 0xffff0000, v10
	v_lshlrev_b32_e32 v172, 16, v11
	v_and_b32_e32 v173, 0xffff0000, v11
	v_pk_add_f32 v[148:149], v[148:149], v[160:161]
	v_pk_add_f32 v[150:151], v[150:151], v[164:165]
	v_pk_add_f32 v[152:153], v[152:153], v[168:169]
	v_pk_add_f32 v[154:155], v[154:155], v[172:173]
	v_lshlrev_b32_e32 v160, 16, v4
	v_and_b32_e32 v161, 0xffff0000, v4
	v_lshlrev_b32_e32 v164, 16, v5
	v_and_b32_e32 v165, 0xffff0000, v5
	v_lshlrev_b32_e32 v168, 16, v6
	v_and_b32_e32 v169, 0xffff0000, v6
	v_lshlrev_b32_e32 v172, 16, v7
	v_and_b32_e32 v173, 0xffff0000, v7
	v_pk_add_f32 v[148:149], v[148:149], v[160:161]
	v_pk_add_f32 v[150:151], v[150:151], v[164:165]
	v_pk_add_f32 v[152:153], v[152:153], v[168:169]
	v_pk_add_f32 v[154:155], v[154:155], v[172:173]
	s_waitcnt vmcnt(31)
	s_cselect_b32 s42, 0x3f800000, s43
	v_lshlrev_b32_e32 v160, 16, v20
	v_and_b32_e32 v161, 0xffff0000, v20
	v_lshlrev_b32_e32 v162, 16, v4
	v_and_b32_e32 v163, 0xffff0000, v4
	v_lshlrev_b32_e32 v164, 16, v21
	v_and_b32_e32 v165, 0xffff0000, v21
	v_lshlrev_b32_e32 v166, 16, v5
	v_and_b32_e32 v167, 0xffff0000, v5
	v_lshlrev_b32_e32 v168, 16, v22
	v_and_b32_e32 v169, 0xffff0000, v22
	v_lshlrev_b32_e32 v170, 16, v6
	v_and_b32_e32 v171, 0xffff0000, v6
	v_lshlrev_b32_e32 v172, 16, v23
	v_and_b32_e32 v173, 0xffff0000, v23
	v_lshlrev_b32_e32 v174, 16, v7
	v_and_b32_e32 v175, 0xffff0000, v7
	v_pk_add_f32 v[162:163], v[160:161], v[162:163] neg_lo:[0,1] neg_hi:[0,1]
	v_pk_add_f32 v[166:167], v[164:165], v[166:167] neg_lo:[0,1] neg_hi:[0,1]
	v_pk_add_f32 v[170:171], v[168:169], v[170:171] neg_lo:[0,1] neg_hi:[0,1]
	v_pk_add_f32 v[174:175], v[172:173], v[174:175] neg_lo:[0,1] neg_hi:[0,1]
	v_pk_add_f32 v[148:149], v[148:149], v[162:163]
	v_pk_add_f32 v[150:151], v[150:151], v[166:167]
	v_pk_add_f32 v[152:153], v[152:153], v[170:171]
	v_pk_add_f32 v[154:155], v[154:155], v[174:175]
	v_fma_f32 v162, s42, v148, -v160
	v_fma_f32 v163, s42, v149, -v161
	v_fma_f32 v166, s42, v150, -v164
	v_fma_f32 v167, s42, v151, -v165
	v_fma_f32 v170, s42, v152, -v168
	v_fma_f32 v171, s42, v153, -v169
	v_fma_f32 v174, s42, v154, -v172
	v_fma_f32 v175, s42, v155, -v173
	v_cvt_pk_bf16_f32 v156, v162, v163
	v_cvt_pk_bf16_f32 v157, v166, v167
	v_cvt_pk_bf16_f32 v158, v170, v171
	v_cvt_pk_bf16_f32 v159, v174, v175
	global_store_dwordx4 v3, v[156:159], s[10:11] sc1
	v_add_u32_e32 v3, 0x2000, v3
	s_waitcnt vmcnt(31)
; __device__ __forceinline__ unsigned cvt_pk_bf16(float lo, float hi) { unsigned r; asm volatile("v_cvt_pk_bf16_f32 %0, %1, %2" : "=v"(r) : "v"(lo), "v"(hi)); return r; }
; __device__ __forceinline__ float bf_lo(unsigned w) { return __uint_as_float(w << 16); }
; __device__ __forceinline__ float bf_hi(unsigned w) { return __uint_as_float(w & 0xffff0000u); }
; __device__ void phase_pool() {
;     ...
;             for (int k = 0; k < 8; ++k) { const int row = row0 + r0 + k, tl = tl0 + r0 + k; const u32x4 v = vv[k], o2 = ov[k];
;                 s[0] += bf_lo(v.x) - bf_lo(o2.x); s[1] += bf_hi(v.x) - bf_hi(o2.x); s[2] += bf_lo(v.y) - bf_lo(o2.y); s[3] += bf_hi(v.y) - bf_hi(o2.y);
;                 s[4] += bf_lo(v.z) - bf_lo(o2.z); s[5] += bf_hi(v.z) - bf_hi(o2.z); s[6] += bf_lo(v.w) - bf_lo(o2.w); s[7] += bf_hi(v.w) - bf_hi(o2.w);
;                 const float ic = 1.0f / (float)((tl + 1 < w) ? tl + 1 : w);
;                 u32x4 o;
;                 o.x = cvt_pk_bf16(s[0] * ic - bf_lo(v.x), s[1] * ic - bf_hi(v.x)); o.y = cvt_pk_bf16(s[2] * ic - bf_lo(v.y), s[3] * ic - bf_hi(v.y));
;                 o.z = cvt_pk_bf16(s[4] * ic - bf_lo(v.z), s[5] * ic - bf_hi(v.z)); o.w = cvt_pk_bf16(s[6] * ic - bf_lo(v.w), s[7] * ic - bf_hi(v.w));
;                 *(u32x4*)(pg + (size_t)row * DE + col) = o; }
	s_cselect_b32 s42, 0x3f000000, s43
	v_lshlrev_b32_e32 v160, 16, v24
	v_and_b32_e32 v161, 0xffff0000, v24
	v_lshlrev_b32_e32 v162, 16, v8
	v_and_b32_e32 v163, 0xffff0000, v8
	v_lshlrev_b32_e32 v164, 16, v25
	v_and_b32_e32 v165, 0xffff0000, v25
	v_lshlrev_b32_e32 v166, 16, v9
	v_and_b32_e32 v167, 0xffff0000, v9
	v_lshlrev_b32_e32 v168, 16, v26
	v_and_b32_e32 v169, 0xffff0000, v26
	v_lshlrev_b32_e32 v170, 16, v10
	v_and_b32_e32 v171, 0xffff0000, v10
	v_lshlrev_b32_e32 v172, 16, v27
	v_and_b32_e32 v173, 0xffff0000, v27
	v_lshlrev_b32_e32 v174, 16, v11
	v_and_b32_e32 v175, 0xffff0000, v11
	v_pk_add_f32 v[162:163], v[160:161], v[162:163] neg_lo:[0,1] neg_hi:[0,1]
	v_pk_add_f32 v[166:167], v[164:165], v[166:167] neg_lo:[0,1] neg_hi:[0,1]
	v_pk_add_f32 v[170:171], v[168:169], v[170:171] neg_lo:[0,1] neg_hi:[0,1]
	v_pk_add_f32 v[174:175], v[172:173], v[174:175] neg_lo:[0,1] neg_hi:[0,1]
	v_pk_add_f32 v[148:149], v[148:149], v[162:163]
	v_pk_add_f32 v[150:151], v[150:151], v[166:167]
	v_pk_add_f32 v[152:153], v[152:153], v[170:171]
	v_pk_add_f32 v[154:155], v[154:155], v[174:175]
	v_fma_f32 v162, s42, v148, -v160
	v_fma_f32 v163, s42, v149, -v161
	v_fma_f32 v166, s42, v150, -v164
	v_fma_f32 v167, s42, v151, -v165
	v_fma_f32 v170, s42, v152, -v168
	v_fma_f32 v171, s42, v153, -v169
	v_fma_f32 v174, s42, v154, -v172
	v_fma_f32 v175, s42, v155, -v173
	v_cvt_pk_bf16_f32 v156, v162, v163
	v_cvt_pk_bf16_f32 v157, v166, v167
	v_cvt_pk_bf16_f32 v158, v170, v171
	v_cvt_pk_bf16_f32 v159, v174, v175
	global_store_dwordx4 v3, v[156:159], s[10:11] sc1
	v_add_u32_e32 v3, 0x2000, v3
	s_waitcnt vmcnt(31)
	s_cselect_b32 s42, 0x3eaaaaab, s43
	v_lshlrev_b32_e32 v160, 16, v28
	v_and_b32_e32 v161, 0xffff0000, v28
	v_lshlrev_b32_e32 v162, 16, v12
	v_and_b32_e32 v163, 0xffff0000, v12
	v_lshlrev_b32_e32 v164, 16, v29
	v_and_b32_e32 v165, 0xffff0000, v29
	v_lshlrev_b32_e32 v166, 16, v13
	v_and_b32_e32 v167, 0xffff0000, v13
	v_lshlrev_b32_e32 v168, 16, v30
	v_and_b32_e32 v169, 0xffff0000, v30
	v_lshlrev_b32_e32 v170, 16, v14
	v_and_b32_e32 v171, 0xffff0000, v14
	v_lshlrev_b32_e32 v172, 16, v31
	v_and_b32_e32 v173, 0xffff0000, v31
	v_lshlrev_b32_e32 v174, 16, v15
	v_and_b32_e32 v175, 0xffff0000, v15
	v_pk_add_f32 v[162:163], v[160:161], v[162:163] neg_lo:[0,1] neg_hi:[0,1]
	v_pk_add_f32 v[166:167], v[164:165], v[166:167] neg_lo:[0,1] neg_hi:[0,1]
	v_pk_add_f32 v[170:171], v[168:169], v[170:171] neg_lo:[0,1] neg_hi:[0,1]
	v_pk_add_f32 v[174:175], v[172:173], v[174:175] neg_lo:[0,1] neg_hi:[0,1]
	v_pk_add_f32 v[148:149], v[148:149], v[162:163]
	v_pk_add_f32 v[150:151], v[150:151], v[166:167]
	v_pk_add_f32 v[152:153], v[152:153], v[170:171]
	v_pk_add_f32 v[154:155], v[154:155], v[174:175]
	v_fma_f32 v162, s42, v148, -v160
	v_fma_f32 v163, s42, v149, -v161
	v_fma_f32 v166, s42, v150, -v164
	v_fma_f32 v167, s42, v151, -v165
	v_fma_f32 v170, s42, v152, -v168
	v_fma_f32 v171, s42, v153, -v169
	v_fma_f32 v174, s42, v154, -v172
	v_fma_f32 v175, s42, v155, -v173
	v_cvt_pk_bf16_f32 v156, v162, v163
	v_cvt_pk_bf16_f32 v157, v166, v167
	v_cvt_pk_bf16_f32 v158, v170, v171
	v_cvt_pk_bf16_f32 v159, v174, v175
	global_store_dwordx4 v3, v[156:159], s[10:11] sc1
	v_add_u32_e32 v3, 0x2000, v3
	s_waitcnt vmcnt(31)
	v_lshlrev_b32_e32 v160, 16, v32
	v_and_b32_e32 v161, 0xffff0000, v32
	v_lshlrev_b32_e32 v162, 16, v16
	v_and_b32_e32 v163, 0xffff0000, v16
	v_lshlrev_b32_e32 v164, 16, v33
	v_and_b32_e32 v165, 0xffff0000, v33
	v_lshlrev_b32_e32 v166, 16, v17
	v_and_b32_e32 v167, 0xffff0000, v17
	v_lshlrev_b32_e32 v168, 16, v34
	v_and_b32_e32 v169, 0xffff0000, v34
	v_lshlrev_b32_e32 v170, 16, v18
	v_and_b32_e32 v171, 0xffff0000, v18
	v_lshlrev_b32_e32 v172, 16, v35
	v_and_b32_e32 v173, 0xffff0000, v35
	v_lshlrev_b32_e32 v174, 16, v19
	v_and_b32_e32 v175, 0xffff0000, v19
	v_pk_add_f32 v[162:163], v[160:161], v[162:163] neg_lo:[0,1] neg_hi:[0,1]
	v_pk_add_f32 v[166:167], v[164:165], v[166:167] neg_lo:[0,1] neg_hi:[0,1]
	v_pk_add_f32 v[170:171], v[168:169], v[170:171] neg_lo:[0,1] neg_hi:[0,1]
	v_pk_add_f32 v[174:175], v[172:173], v[174:175] neg_lo:[0,1] neg_hi:[0,1]
	v_pk_add_f32 v[148:149], v[148:149], v[162:163]
	v_pk_add_f32 v[150:151], v[150:151], v[166:167]
	v_pk_add_f32 v[152:153], v[152:153], v[170:171]
	v_pk_add_f32 v[154:155], v[154:155], v[174:175]
	v_fma_f32 v162, s43, v148, -v160
	v_fma_f32 v163, s43, v149, -v161
	v_fma_f32 v166, s43, v150, -v164
	v_fma_f32 v167, s43, v151, -v165
	v_fma_f32 v170, s43, v152, -v168
	v_fma_f32 v171, s43, v153, -v169
	v_fma_f32 v174, s43, v154, -v172
	v_fma_f32 v175, s43, v155, -v173
	v_cvt_pk_bf16_f32 v156, v162, v163
	v_cvt_pk_bf16_f32 v157, v166, v167
	v_cvt_pk_bf16_f32 v158, v170, v171
	v_cvt_pk_bf16_f32 v159, v174, v175
	global_store_dwordx4 v3, v[156:159], s[10:11] sc1
	v_add_u32_e32 v3, 0x2000, v3
	s_waitcnt vmcnt(31)
	v_lshlrev_b32_e32 v160, 16, v36
	v_and_b32_e32 v161, 0xffff0000, v36
	v_lshlrev_b32_e32 v162, 16, v20
	v_and_b32_e32 v163, 0xffff0000, v20
	v_lshlrev_b32_e32 v164, 16, v37
	v_and_b32_e32 v165, 0xffff0000, v37
	v_lshlrev_b32_e32 v166, 16, v21
	v_and_b32_e32 v167, 0xffff0000, v21
	v_lshlrev_b32_e32 v168, 16, v38
	v_and_b32_e32 v169, 0xffff0000, v38
	v_lshlrev_b32_e32 v170, 16, v22
	v_and_b32_e32 v171, 0xffff0000, v22
	v_lshlrev_b32_e32 v172, 16, v39
	v_and_b32_e32 v173, 0xffff0000, v39
	v_lshlrev_b32_e32 v174, 16, v23
	v_and_b32_e32 v175, 0xffff0000, v23
	v_pk_add_f32 v[162:163], v[160:161], v[162:163] neg_lo:[0,1] neg_hi:[0,1]
	v_pk_add_f32 v[166:167], v[164:165], v[166:167] neg_lo:[0,1] neg_hi:[0,1]
	v_pk_add_f32 v[170:171], v[168:169], v[170:171] neg_lo:[0,1] neg_hi:[0,1]
	v_pk_add_f32 v[174:175], v[172:173], v[174:175] neg_lo:[0,1] neg_hi:[0,1]
	v_pk_add_f32 v[148:149], v[148:149], v[162:163]
	v_pk_add_f32 v[150:151], v[150:151], v[166:167]
	v_pk_add_f32 v[152:153], v[152:153], v[170:171]
	v_pk_add_f32 v[154:155], v[154:155], v[174:175]
	v_fma_f32 v162, s43, v148, -v160
	v_fma_f32 v163, s43, v149, -v161
	v_fma_f32 v166, s43, v150, -v164
	v_fma_f32 v167, s43, v151, -v165
	v_fma_f32 v170, s43, v152, -v168
	v_fma_f32 v171, s43, v153, -v169
	v_fma_f32 v174, s43, v154, -v172
	v_fma_f32 v175, s43, v155, -v173
	v_cvt_pk_bf16_f32 v156, v162, v163
	v_cvt_pk_bf16_f32 v157, v166, v167
	v_cvt_pk_bf16_f32 v158, v170, v171
	v_cvt_pk_bf16_f32 v159, v174, v175
	global_store_dwordx4 v3, v[156:159], s[10:11] sc1
	v_add_u32_e32 v3, 0x2000, v3
	s_waitcnt vmcnt(31)
; __device__ __forceinline__ unsigned cvt_pk_bf16(float lo, float hi) { unsigned r; asm volatile("v_cvt_pk_bf16_f32 %0, %1, %2" : "=v"(r) : "v"(lo), "v"(hi)); return r; }
; __device__ __forceinline__ float bf_lo(unsigned w) { return __uint_as_float(w << 16); }
; __device__ __forceinline__ float bf_hi(unsigned w) { return __uint_as_float(w & 0xffff0000u); }
; __device__ void phase_pool() {
;     ...
;             for (int k = 0; k < 8; ++k) { const int row = row0 + r0 + k, tl = tl0 + r0 + k; const u32x4 v = vv[k], o2 = ov[k];
;                 s[0] += bf_lo(v.x) - bf_lo(o2.x); s[1] += bf_hi(v.x) - bf_hi(o2.x); s[2] += bf_lo(v.y) - bf_lo(o2.y); s[3] += bf_hi(v.y) - bf_hi(o2.y);
;                 s[4] += bf_lo(v.z) - bf_lo(o2.z); s[5] += bf_hi(v.z) - bf_hi(o2.z); s[6] += bf_lo(v.w) - bf_lo(o2.w); s[7] += bf_hi(v.w) - bf_hi(o2.w);
;                 const float ic = 1.0f / (float)((tl + 1 < w) ? tl + 1 : w);
;                 u32x4 o;
;                 o.x = cvt_pk_bf16(s[0] * ic - bf_lo(v.x), s[1] * ic - bf_hi(v.x)); o.y = cvt_pk_bf16(s[2] * ic - bf_lo(v.y), s[3] * ic - bf_hi(v.y));
;                 o.z = cvt_pk_bf16(s[4] * ic - bf_lo(v.z), s[5] * ic - bf_hi(v.z)); o.w = cvt_pk_bf16(s[6] * ic - bf_lo(v.w), s[7] * ic - bf_hi(v.w));
;                 *(u32x4*)(pg + (size_t)row * DE + col) = o; }
	v_lshlrev_b32_e32 v160, 16, v40
	v_and_b32_e32 v161, 0xffff0000, v40
	v_lshlrev_b32_e32 v162, 16, v24
	v_and_b32_e32 v163, 0xffff0000, v24
	v_lshlrev_b32_e32 v164, 16, v41
	v_and_b32_e32 v165, 0xffff0000, v41
	v_lshlrev_b32_e32 v166, 16, v25
	v_and_b32_e32 v167, 0xffff0000, v25
	v_lshlrev_b32_e32 v168, 16, v42
	v_and_b32_e32 v169, 0xffff0000, v42
	v_lshlrev_b32_e32 v170, 16, v26
	v_and_b32_e32 v171, 0xffff0000, v26
	v_lshlrev_b32_e32 v172, 16, v43
	v_and_b32_e32 v173, 0xffff0000, v43
	v_lshlrev_b32_e32 v174, 16, v27
	v_and_b32_e32 v175, 0xffff0000, v27
	v_pk_add_f32 v[162:163], v[160:161], v[162:163] neg_lo:[0,1] neg_hi:[0,1]
	v_pk_add_f32 v[166:167], v[164:165], v[166:167] neg_lo:[0,1] neg_hi:[0,1]
	v_pk_add_f32 v[170:171], v[168:169], v[170:171] neg_lo:[0,1] neg_hi:[0,1]
	v_pk_add_f32 v[174:175], v[172:173], v[174:175] neg_lo:[0,1] neg_hi:[0,1]
	v_pk_add_f32 v[148:149], v[148:149], v[162:163]
	v_pk_add_f32 v[150:151], v[150:151], v[166:167]
	v_pk_add_f32 v[152:153], v[152:153], v[170:171]
	v_pk_add_f32 v[154:155], v[154:155], v[174:175]
	v_fma_f32 v162, s43, v148, -v160
	v_fma_f32 v163, s43, v149, -v161
	v_fma_f32 v166, s43, v150, -v164
	v_fma_f32 v167, s43, v151, -v165
	v_fma_f32 v170, s43, v152, -v168
	v_fma_f32 v171, s43, v153, -v169
	v_fma_f32 v174, s43, v154, -v172
	v_fma_f32 v175, s43, v155, -v173
	v_cvt_pk_bf16_f32 v156, v162, v163
	v_cvt_pk_bf16_f32 v157, v166, v167
	v_cvt_pk_bf16_f32 v158, v170, v171
	v_cvt_pk_bf16_f32 v159, v174, v175
	global_store_dwordx4 v3, v[156:159], s[10:11] sc1
	v_add_u32_e32 v3, 0x2000, v3
	s_waitcnt vmcnt(31)
	v_lshlrev_b32_e32 v160, 16, v44
	v_and_b32_e32 v161, 0xffff0000, v44
	v_lshlrev_b32_e32 v162, 16, v28
	v_and_b32_e32 v163, 0xffff0000, v28
	v_lshlrev_b32_e32 v164, 16, v45
	v_and_b32_e32 v165, 0xffff0000, v45
	v_lshlrev_b32_e32 v166, 16, v29
	v_and_b32_e32 v167, 0xffff0000, v29
	v_lshlrev_b32_e32 v168, 16, v46
	v_and_b32_e32 v169, 0xffff0000, v46
	v_lshlrev_b32_e32 v170, 16, v30
	v_and_b32_e32 v171, 0xffff0000, v30
	v_lshlrev_b32_e32 v172, 16, v47
	v_and_b32_e32 v173, 0xffff0000, v47
	v_lshlrev_b32_e32 v174, 16, v31
	v_and_b32_e32 v175, 0xffff0000, v31
	v_pk_add_f32 v[162:163], v[160:161], v[162:163] neg_lo:[0,1] neg_hi:[0,1]
	v_pk_add_f32 v[166:167], v[164:165], v[166:167] neg_lo:[0,1] neg_hi:[0,1]
	v_pk_add_f32 v[170:171], v[168:169], v[170:171] neg_lo:[0,1] neg_hi:[0,1]
	v_pk_add_f32 v[174:175], v[172:173], v[174:175] neg_lo:[0,1] neg_hi:[0,1]
	v_pk_add_f32 v[148:149], v[148:149], v[162:163]
	v_pk_add_f32 v[150:151], v[150:151], v[166:167]
	v_pk_add_f32 v[152:153], v[152:153], v[170:171]
	v_pk_add_f32 v[154:155], v[154:155], v[174:175]
	v_fma_f32 v162, s43, v148, -v160
	v_fma_f32 v163, s43, v149, -v161
	v_fma_f32 v166, s43, v150, -v164
	v_fma_f32 v167, s43, v151, -v165
	v_fma_f32 v170, s43, v152, -v168
	v_fma_f32 v171, s43, v153, -v169
	v_fma_f32 v174, s43, v154, -v172
	v_fma_f32 v175, s43, v155, -v173
	v_cvt_pk_bf16_f32 v156, v162, v163
	v_cvt_pk_bf16_f32 v157, v166, v167
	v_cvt_pk_bf16_f32 v158, v170, v171
	v_cvt_pk_bf16_f32 v159, v174, v175
	global_store_dwordx4 v3, v[156:159], s[10:11] sc1
	v_add_u32_e32 v3, 0x2000, v3
	s_waitcnt vmcnt(31)
	v_lshlrev_b32_e32 v160, 16, v48
	v_and_b32_e32 v161, 0xffff0000, v48
	v_lshlrev_b32_e32 v162, 16, v32
	v_and_b32_e32 v163, 0xffff0000, v32
	v_lshlrev_b32_e32 v164, 16, v49
	v_and_b32_e32 v165, 0xffff0000, v49
	v_lshlrev_b32_e32 v166, 16, v33
	v_and_b32_e32 v167, 0xffff0000, v33
	v_lshlrev_b32_e32 v168, 16, v50
	v_and_b32_e32 v169, 0xffff0000, v50
	v_lshlrev_b32_e32 v170, 16, v34
	v_and_b32_e32 v171, 0xffff0000, v34
	v_lshlrev_b32_e32 v172, 16, v51
	v_and_b32_e32 v173, 0xffff0000, v51
	v_lshlrev_b32_e32 v174, 16, v35
	v_and_b32_e32 v175, 0xffff0000, v35
	v_pk_add_f32 v[162:163], v[160:161], v[162:163] neg_lo:[0,1] neg_hi:[0,1]
	v_pk_add_f32 v[166:167], v[164:165], v[166:167] neg_lo:[0,1] neg_hi:[0,1]
	v_pk_add_f32 v[170:171], v[168:169], v[170:171] neg_lo:[0,1] neg_hi:[0,1]
	v_pk_add_f32 v[174:175], v[172:173], v[174:175] neg_lo:[0,1] neg_hi:[0,1]
	v_pk_add_f32 v[148:149], v[148:149], v[162:163]
	v_pk_add_f32 v[150:151], v[150:151], v[166:167]
	v_pk_add_f32 v[152:153], v[152:153], v[170:171]
	v_pk_add_f32 v[154:155], v[154:155], v[174:175]
	v_fma_f32 v162, s43, v148, -v160
	v_fma_f32 v163, s43, v149, -v161
	v_fma_f32 v166, s43, v150, -v164
	v_fma_f32 v167, s43, v151, -v165
	v_fma_f32 v170, s43, v152, -v168
	v_fma_f32 v171, s43, v153, -v169
	v_fma_f32 v174, s43, v154, -v172
	v_fma_f32 v175, s43, v155, -v173
	v_cvt_pk_bf16_f32 v156, v162, v163
	v_cvt_pk_bf16_f32 v157, v166, v167
	v_cvt_pk_bf16_f32 v158, v170, v171
	v_cvt_pk_bf16_f32 v159, v174, v175
	global_store_dwordx4 v3, v[156:159], s[10:11] sc1
	v_add_u32_e32 v3, 0x2000, v3
	s_waitcnt vmcnt(31)
	v_lshlrev_b32_e32 v160, 16, v52
	v_and_b32_e32 v161, 0xffff0000, v52
	v_lshlrev_b32_e32 v162, 16, v36
	v_and_b32_e32 v163, 0xffff0000, v36
	v_lshlrev_b32_e32 v164, 16, v53
	v_and_b32_e32 v165, 0xffff0000, v53
	v_lshlrev_b32_e32 v166, 16, v37
	v_and_b32_e32 v167, 0xffff0000, v37
	v_lshlrev_b32_e32 v168, 16, v54
	v_and_b32_e32 v169, 0xffff0000, v54
	v_lshlrev_b32_e32 v170, 16, v38
	v_and_b32_e32 v171, 0xffff0000, v38
	v_lshlrev_b32_e32 v172, 16, v55
	v_and_b32_e32 v173, 0xffff0000, v55
	v_lshlrev_b32_e32 v174, 16, v39
	v_and_b32_e32 v175, 0xffff0000, v39
	v_pk_add_f32 v[162:163], v[160:161], v[162:163] neg_lo:[0,1] neg_hi:[0,1]
	v_pk_add_f32 v[166:167], v[164:165], v[166:167] neg_lo:[0,1] neg_hi:[0,1]
	v_pk_add_f32 v[170:171], v[168:169], v[170:171] neg_lo:[0,1] neg_hi:[0,1]
	v_pk_add_f32 v[174:175], v[172:173], v[174:175] neg_lo:[0,1] neg_hi:[0,1]
	v_pk_add_f32 v[148:149], v[148:149], v[162:163]
	v_pk_add_f32 v[150:151], v[150:151], v[166:167]
	v_pk_add_f32 v[152:153], v[152:153], v[170:171]
	v_pk_add_f32 v[154:155], v[154:155], v[174:175]
	v_fma_f32 v162, s43, v148, -v160
	v_fma_f32 v163, s43, v149, -v161
	v_fma_f32 v166, s43, v150, -v164
	v_fma_f32 v167, s43, v151, -v165
	v_fma_f32 v170, s43, v152, -v168
	v_fma_f32 v171, s43, v153, -v169
	v_fma_f32 v174, s43, v154, -v172
	v_fma_f32 v175, s43, v155, -v173
	v_cvt_pk_bf16_f32 v156, v162, v163
	v_cvt_pk_bf16_f32 v157, v166, v167
	v_cvt_pk_bf16_f32 v158, v170, v171
	v_cvt_pk_bf16_f32 v159, v174, v175
	global_store_dwordx4 v3, v[156:159], s[10:11] sc1
	v_add_u32_e32 v3, 0x2000, v3
	s_waitcnt vmcnt(31)
; __device__ __forceinline__ unsigned cvt_pk_bf16(float lo, float hi) { unsigned r; asm volatile("v_cvt_pk_bf16_f32 %0, %1, %2" : "=v"(r) : "v"(lo), "v"(hi)); return r; }
; __device__ __forceinline__ float bf_lo(unsigned w) { return __uint_as_float(w << 16); }
; __device__ __forceinline__ float bf_hi(unsigned w) { return __uint_as_float(w & 0xffff0000u); }
; __device__ void phase_pool() {
;     ...
;             for (int k = 0; k < 8; ++k) { const int row = row0 + r0 + k, tl = tl0 + r0 + k; const u32x4 v = vv[k], o2 = ov[k];
;                 s[0] += bf_lo(v.x) - bf_lo(o2.x); s[1] += bf_hi(v.x) - bf_hi(o2.x); s[2] += bf_lo(v.y) - bf_lo(o2.y); s[3] += bf_hi(v.y) - bf_hi(o2.y);
;                 s[4] += bf_lo(v.z) - bf_lo(o2.z); s[5] += bf_hi(v.z) - bf_hi(o2.z); s[6] += bf_lo(v.w) - bf_lo(o2.w); s[7] += bf_hi(v.w) - bf_hi(o2.w);
;                 const float ic = 1.0f / (float)((tl + 1 < w) ? tl + 1 : w);
;                 u32x4 o;
;                 o.x = cvt_pk_bf16(s[0] * ic - bf_lo(v.x), s[1] * ic - bf_hi(v.x)); o.y = cvt_pk_bf16(s[2] * ic - bf_lo(v.y), s[3] * ic - bf_hi(v.y));
;                 o.z = cvt_pk_bf16(s[4] * ic - bf_lo(v.z), s[5] * ic - bf_hi(v.z)); o.w = cvt_pk_bf16(s[6] * ic - bf_lo(v.w), s[7] * ic - bf_hi(v.w));
;                 *(u32x4*)(pg + (size_t)row * DE + col) = o; }
	v_lshlrev_b32_e32 v160, 16, v56
	v_and_b32_e32 v161, 0xffff0000, v56
	v_lshlrev_b32_e32 v162, 16, v40
	v_and_b32_e32 v163, 0xffff0000, v40
	v_lshlrev_b32_e32 v164, 16, v57
	v_and_b32_e32 v165, 0xffff0000, v57
	v_lshlrev_b32_e32 v166, 16, v41
	v_and_b32_e32 v167, 0xffff0000, v41
	v_lshlrev_b32_e32 v168, 16, v58
	v_and_b32_e32 v169, 0xffff0000, v58
	v_lshlrev_b32_e32 v170, 16, v42
	v_and_b32_e32 v171, 0xffff0000, v42
	v_lshlrev_b32_e32 v172, 16, v59
	v_and_b32_e32 v173, 0xffff0000, v59
	v_lshlrev_b32_e32 v174, 16, v43
	v_and_b32_e32 v175, 0xffff0000, v43
	v_pk_add_f32 v[162:163], v[160:161], v[162:163] neg_lo:[0,1] neg_hi:[0,1]
	v_pk_add_f32 v[166:167], v[164:165], v[166:167] neg_lo:[0,1] neg_hi:[0,1]
	v_pk_add_f32 v[170:171], v[168:169], v[170:171] neg_lo:[0,1] neg_hi:[0,1]
	v_pk_add_f32 v[174:175], v[172:173], v[174:175] neg_lo:[0,1] neg_hi:[0,1]
	v_pk_add_f32 v[148:149], v[148:149], v[162:163]
	v_pk_add_f32 v[150:151], v[150:151], v[166:167]
	v_pk_add_f32 v[152:153], v[152:153], v[170:171]
	v_pk_add_f32 v[154:155], v[154:155], v[174:175]
	v_fma_f32 v162, s43, v148, -v160
	v_fma_f32 v163, s43, v149, -v161
	v_fma_f32 v166, s43, v150, -v164
	v_fma_f32 v167, s43, v151, -v165
	v_fma_f32 v170, s43, v152, -v168
	v_fma_f32 v171, s43, v153, -v169
	v_fma_f32 v174, s43, v154, -v172
	v_fma_f32 v175, s43, v155, -v173
	v_cvt_pk_bf16_f32 v156, v162, v163
	v_cvt_pk_bf16_f32 v157, v166, v167
	v_cvt_pk_bf16_f32 v158, v170, v171
	v_cvt_pk_bf16_f32 v159, v174, v175
	global_store_dwordx4 v3, v[156:159], s[10:11] sc1
	v_add_u32_e32 v3, 0x2000, v3
	s_waitcnt vmcnt(31)
	v_lshlrev_b32_e32 v160, 16, v60
	v_and_b32_e32 v161, 0xffff0000, v60
	v_lshlrev_b32_e32 v162, 16, v44
	v_and_b32_e32 v163, 0xffff0000, v44
	v_lshlrev_b32_e32 v164, 16, v61
	v_and_b32_e32 v165, 0xffff0000, v61
	v_lshlrev_b32_e32 v166, 16, v45
	v_and_b32_e32 v167, 0xffff0000, v45
	v_lshlrev_b32_e32 v168, 16, v62
	v_and_b32_e32 v169, 0xffff0000, v62
	v_lshlrev_b32_e32 v170, 16, v46
	v_and_b32_e32 v171, 0xffff0000, v46
	v_lshlrev_b32_e32 v172, 16, v63
	v_and_b32_e32 v173, 0xffff0000, v63
	v_lshlrev_b32_e32 v174, 16, v47
	v_and_b32_e32 v175, 0xffff0000, v47
	v_pk_add_f32 v[162:163], v[160:161], v[162:163] neg_lo:[0,1] neg_hi:[0,1]
	v_pk_add_f32 v[166:167], v[164:165], v[166:167] neg_lo:[0,1] neg_hi:[0,1]
	v_pk_add_f32 v[170:171], v[168:169], v[170:171] neg_lo:[0,1] neg_hi:[0,1]
	v_pk_add_f32 v[174:175], v[172:173], v[174:175] neg_lo:[0,1] neg_hi:[0,1]
	v_pk_add_f32 v[148:149], v[148:149], v[162:163]
	v_pk_add_f32 v[150:151], v[150:151], v[166:167]
	v_pk_add_f32 v[152:153], v[152:153], v[170:171]
	v_pk_add_f32 v[154:155], v[154:155], v[174:175]
	v_fma_f32 v162, s43, v148, -v160
	v_fma_f32 v163, s43, v149, -v161
	v_fma_f32 v166, s43, v150, -v164
	v_fma_f32 v167, s43, v151, -v165
	v_fma_f32 v170, s43, v152, -v168
	v_fma_f32 v171, s43, v153, -v169
	v_fma_f32 v174, s43, v154, -v172
	v_fma_f32 v175, s43, v155, -v173
	v_cvt_pk_bf16_f32 v156, v162, v163
	v_cvt_pk_bf16_f32 v157, v166, v167
	v_cvt_pk_bf16_f32 v158, v170, v171
	v_cvt_pk_bf16_f32 v159, v174, v175
	global_store_dwordx4 v3, v[156:159], s[10:11] sc1
	v_add_u32_e32 v3, 0x2000, v3
	s_waitcnt vmcnt(31)
	v_lshlrev_b32_e32 v160, 16, v64
	v_and_b32_e32 v161, 0xffff0000, v64
	v_lshlrev_b32_e32 v162, 16, v48
	v_and_b32_e32 v163, 0xffff0000, v48
	v_lshlrev_b32_e32 v164, 16, v65
	v_and_b32_e32 v165, 0xffff0000, v65
	v_lshlrev_b32_e32 v166, 16, v49
	v_and_b32_e32 v167, 0xffff0000, v49
	v_lshlrev_b32_e32 v168, 16, v66
	v_and_b32_e32 v169, 0xffff0000, v66
	v_lshlrev_b32_e32 v170, 16, v50
	v_and_b32_e32 v171, 0xffff0000, v50
	v_lshlrev_b32_e32 v172, 16, v67
	v_and_b32_e32 v173, 0xffff0000, v67
	v_lshlrev_b32_e32 v174, 16, v51
	v_and_b32_e32 v175, 0xffff0000, v51
	v_pk_add_f32 v[162:163], v[160:161], v[162:163] neg_lo:[0,1] neg_hi:[0,1]
	v_pk_add_f32 v[166:167], v[164:165], v[166:167] neg_lo:[0,1] neg_hi:[0,1]
	v_pk_add_f32 v[170:171], v[168:169], v[170:171] neg_lo:[0,1] neg_hi:[0,1]
	v_pk_add_f32 v[174:175], v[172:173], v[174:175] neg_lo:[0,1] neg_hi:[0,1]
	v_pk_add_f32 v[148:149], v[148:149], v[162:163]
	v_pk_add_f32 v[150:151], v[150:151], v[166:167]
	v_pk_add_f32 v[152:153], v[152:153], v[170:171]
	v_pk_add_f32 v[154:155], v[154:155], v[174:175]
	v_fma_f32 v162, s43, v148, -v160
	v_fma_f32 v163, s43, v149, -v161
	v_fma_f32 v166, s43, v150, -v164
	v_fma_f32 v167, s43, v151, -v165
	v_fma_f32 v170, s43, v152, -v168
	v_fma_f32 v171, s43, v153, -v169
	v_fma_f32 v174, s43, v154, -v172
	v_fma_f32 v175, s43, v155, -v173
	v_cvt_pk_bf16_f32 v156, v162, v163
	v_cvt_pk_bf16_f32 v157, v166, v167
	v_cvt_pk_bf16_f32 v158, v170, v171
	v_cvt_pk_bf16_f32 v159, v174, v175
	global_store_dwordx4 v3, v[156:159], s[10:11] sc1
	v_add_u32_e32 v3, 0x2000, v3
	s_waitcnt vmcnt(31)
	v_lshlrev_b32_e32 v160, 16, v68
	v_and_b32_e32 v161, 0xffff0000, v68
	v_lshlrev_b32_e32 v162, 16, v52
	v_and_b32_e32 v163, 0xffff0000, v52
	v_lshlrev_b32_e32 v164, 16, v69
	v_and_b32_e32 v165, 0xffff0000, v69
	v_lshlrev_b32_e32 v166, 16, v53
	v_and_b32_e32 v167, 0xffff0000, v53
	v_lshlrev_b32_e32 v168, 16, v70
	v_and_b32_e32 v169, 0xffff0000, v70
	v_lshlrev_b32_e32 v170, 16, v54
	v_and_b32_e32 v171, 0xffff0000, v54
	v_lshlrev_b32_e32 v172, 16, v71
	v_and_b32_e32 v173, 0xffff0000, v71
	v_lshlrev_b32_e32 v174, 16, v55
	v_and_b32_e32 v175, 0xffff0000, v55
	v_pk_add_f32 v[162:163], v[160:161], v[162:163] neg_lo:[0,1] neg_hi:[0,1]
	v_pk_add_f32 v[166:167], v[164:165], v[166:167] neg_lo:[0,1] neg_hi:[0,1]
	v_pk_add_f32 v[170:171], v[168:169], v[170:171] neg_lo:[0,1] neg_hi:[0,1]
	v_pk_add_f32 v[174:175], v[172:173], v[174:175] neg_lo:[0,1] neg_hi:[0,1]
	v_pk_add_f32 v[148:149], v[148:149], v[162:163]
	v_pk_add_f32 v[150:151], v[150:151], v[166:167]
	v_pk_add_f32 v[152:153], v[152:153], v[170:171]
	v_pk_add_f32 v[154:155], v[154:155], v[174:175]
	v_fma_f32 v162, s43, v148, -v160
	v_fma_f32 v163, s43, v149, -v161
	v_fma_f32 v166, s43, v150, -v164
	v_fma_f32 v167, s43, v151, -v165
	v_fma_f32 v170, s43, v152, -v168
	v_fma_f32 v171, s43, v153, -v169
	v_fma_f32 v174, s43, v154, -v172
	v_fma_f32 v175, s43, v155, -v173
	v_cvt_pk_bf16_f32 v156, v162, v163
	v_cvt_pk_bf16_f32 v157, v166, v167
	v_cvt_pk_bf16_f32 v158, v170, v171
	v_cvt_pk_bf16_f32 v159, v174, v175
	global_store_dwordx4 v3, v[156:159], s[10:11] sc1
	v_add_u32_e32 v3, 0x2000, v3
	s_waitcnt vmcnt(31)
; __device__ __forceinline__ unsigned cvt_pk_bf16(float lo, float hi) { unsigned r; asm volatile("v_cvt_pk_bf16_f32 %0, %1, %2" : "=v"(r) : "v"(lo), "v"(hi)); return r; }
; __device__ __forceinline__ float bf_lo(unsigned w) { return __uint_as_float(w << 16); }
; __device__ __forceinline__ float bf_hi(unsigned w) { return __uint_as_float(w & 0xffff0000u); }
; __device__ void phase_pool() {
;     ...
;             for (int k = 0; k < 8; ++k) { const int row = row0 + r0 + k, tl = tl0 + r0 + k; const u32x4 v = vv[k], o2 = ov[k];
;                 s[0] += bf_lo(v.x) - bf_lo(o2.x); s[1] += bf_hi(v.x) - bf_hi(o2.x); s[2] += bf_lo(v.y) - bf_lo(o2.y); s[3] += bf_hi(v.y) - bf_hi(o2.y);
;                 s[4] += bf_lo(v.z) - bf_lo(o2.z); s[5] += bf_hi(v.z) - bf_hi(o2.z); s[6] += bf_lo(v.w) - bf_lo(o2.w); s[7] += bf_hi(v.w) - bf_hi(o2.w);
;                 const float ic = 1.0f / (float)((tl + 1 < w) ? tl + 1 : w);
;                 u32x4 o;
;                 o.x = cvt_pk_bf16(s[0] * ic - bf_lo(v.x), s[1] * ic - bf_hi(v.x)); o.y = cvt_pk_bf16(s[2] * ic - bf_lo(v.y), s[3] * ic - bf_hi(v.y));
;                 o.z = cvt_pk_bf16(s[4] * ic - bf_lo(v.z), s[5] * ic - bf_hi(v.z)); o.w = cvt_pk_bf16(s[6] * ic - bf_lo(v.w), s[7] * ic - bf_hi(v.w));
;                 *(u32x4*)(pg + (size_t)row * DE + col) = o; }
	v_lshlrev_b32_e32 v160, 16, v72
	v_and_b32_e32 v161, 0xffff0000, v72
	v_lshlrev_b32_e32 v162, 16, v56
	v_and_b32_e32 v163, 0xffff0000, v56
	v_lshlrev_b32_e32 v164, 16, v73
	v_and_b32_e32 v165, 0xffff0000, v73
	v_lshlrev_b32_e32 v166, 16, v57
	v_and_b32_e32 v167, 0xffff0000, v57
	v_lshlrev_b32_e32 v168, 16, v74
	v_and_b32_e32 v169, 0xffff0000, v74
	v_lshlrev_b32_e32 v170, 16, v58
	v_and_b32_e32 v171, 0xffff0000, v58
	v_lshlrev_b32_e32 v172, 16, v75
	v_and_b32_e32 v173, 0xffff0000, v75
	v_lshlrev_b32_e32 v174, 16, v59
	v_and_b32_e32 v175, 0xffff0000, v59
	v_pk_add_f32 v[162:163], v[160:161], v[162:163] neg_lo:[0,1] neg_hi:[0,1]
	v_pk_add_f32 v[166:167], v[164:165], v[166:167] neg_lo:[0,1] neg_hi:[0,1]
	v_pk_add_f32 v[170:171], v[168:169], v[170:171] neg_lo:[0,1] neg_hi:[0,1]
	v_pk_add_f32 v[174:175], v[172:173], v[174:175] neg_lo:[0,1] neg_hi:[0,1]
	v_pk_add_f32 v[148:149], v[148:149], v[162:163]
	v_pk_add_f32 v[150:151], v[150:151], v[166:167]
	v_pk_add_f32 v[152:153], v[152:153], v[170:171]
	v_pk_add_f32 v[154:155], v[154:155], v[174:175]
	v_fma_f32 v162, s43, v148, -v160
	v_fma_f32 v163, s43, v149, -v161
	v_fma_f32 v166, s43, v150, -v164
	v_fma_f32 v167, s43, v151, -v165
	v_fma_f32 v170, s43, v152, -v168
	v_fma_f32 v171, s43, v153, -v169
	v_fma_f32 v174, s43, v154, -v172
	v_fma_f32 v175, s43, v155, -v173
	v_cvt_pk_bf16_f32 v156, v162, v163
	v_cvt_pk_bf16_f32 v157, v166, v167
	v_cvt_pk_bf16_f32 v158, v170, v171
	v_cvt_pk_bf16_f32 v159, v174, v175
	global_store_dwordx4 v3, v[156:159], s[10:11] sc1
	v_add_u32_e32 v3, 0x2000, v3
	s_waitcnt vmcnt(31)
	v_lshlrev_b32_e32 v160, 16, v76
	v_and_b32_e32 v161, 0xffff0000, v76
	v_lshlrev_b32_e32 v162, 16, v60
	v_and_b32_e32 v163, 0xffff0000, v60
	v_lshlrev_b32_e32 v164, 16, v77
	v_and_b32_e32 v165, 0xffff0000, v77
	v_lshlrev_b32_e32 v166, 16, v61
	v_and_b32_e32 v167, 0xffff0000, v61
	v_lshlrev_b32_e32 v168, 16, v78
	v_and_b32_e32 v169, 0xffff0000, v78
	v_lshlrev_b32_e32 v170, 16, v62
	v_and_b32_e32 v171, 0xffff0000, v62
	v_lshlrev_b32_e32 v172, 16, v79
	v_and_b32_e32 v173, 0xffff0000, v79
	v_lshlrev_b32_e32 v174, 16, v63
	v_and_b32_e32 v175, 0xffff0000, v63
	v_pk_add_f32 v[162:163], v[160:161], v[162:163] neg_lo:[0,1] neg_hi:[0,1]
	v_pk_add_f32 v[166:167], v[164:165], v[166:167] neg_lo:[0,1] neg_hi:[0,1]
	v_pk_add_f32 v[170:171], v[168:169], v[170:171] neg_lo:[0,1] neg_hi:[0,1]
	v_pk_add_f32 v[174:175], v[172:173], v[174:175] neg_lo:[0,1] neg_hi:[0,1]
	v_pk_add_f32 v[148:149], v[148:149], v[162:163]
	v_pk_add_f32 v[150:151], v[150:151], v[166:167]
	v_pk_add_f32 v[152:153], v[152:153], v[170:171]
	v_pk_add_f32 v[154:155], v[154:155], v[174:175]
	v_fma_f32 v162, s43, v148, -v160
	v_fma_f32 v163, s43, v149, -v161
	v_fma_f32 v166, s43, v150, -v164
	v_fma_f32 v167, s43, v151, -v165
	v_fma_f32 v170, s43, v152, -v168
	v_fma_f32 v171, s43, v153, -v169
	v_fma_f32 v174, s43, v154, -v172
	v_fma_f32 v175, s43, v155, -v173
	v_cvt_pk_bf16_f32 v156, v162, v163
	v_cvt_pk_bf16_f32 v157, v166, v167
	v_cvt_pk_bf16_f32 v158, v170, v171
	v_cvt_pk_bf16_f32 v159, v174, v175
	global_store_dwordx4 v3, v[156:159], s[10:11] sc1
	v_add_u32_e32 v3, 0x2000, v3
	s_waitcnt vmcnt(31)
	v_lshlrev_b32_e32 v160, 16, v80
	v_and_b32_e32 v161, 0xffff0000, v80
	v_lshlrev_b32_e32 v162, 16, v64
	v_and_b32_e32 v163, 0xffff0000, v64
	v_lshlrev_b32_e32 v164, 16, v81
	v_and_b32_e32 v165, 0xffff0000, v81
	v_lshlrev_b32_e32 v166, 16, v65
	v_and_b32_e32 v167, 0xffff0000, v65
	v_lshlrev_b32_e32 v168, 16, v82
	v_and_b32_e32 v169, 0xffff0000, v82
	v_lshlrev_b32_e32 v170, 16, v66
	v_and_b32_e32 v171, 0xffff0000, v66
	v_lshlrev_b32_e32 v172, 16, v83
	v_and_b32_e32 v173, 0xffff0000, v83
	v_lshlrev_b32_e32 v174, 16, v67
	v_and_b32_e32 v175, 0xffff0000, v67
	v_pk_add_f32 v[162:163], v[160:161], v[162:163] neg_lo:[0,1] neg_hi:[0,1]
	v_pk_add_f32 v[166:167], v[164:165], v[166:167] neg_lo:[0,1] neg_hi:[0,1]
	v_pk_add_f32 v[170:171], v[168:169], v[170:171] neg_lo:[0,1] neg_hi:[0,1]
	v_pk_add_f32 v[174:175], v[172:173], v[174:175] neg_lo:[0,1] neg_hi:[0,1]
	v_pk_add_f32 v[148:149], v[148:149], v[162:163]
	v_pk_add_f32 v[150:151], v[150:151], v[166:167]
	v_pk_add_f32 v[152:153], v[152:153], v[170:171]
	v_pk_add_f32 v[154:155], v[154:155], v[174:175]
	v_fma_f32 v162, s43, v148, -v160
	v_fma_f32 v163, s43, v149, -v161
	v_fma_f32 v166, s43, v150, -v164
	v_fma_f32 v167, s43, v151, -v165
	v_fma_f32 v170, s43, v152, -v168
	v_fma_f32 v171, s43, v153, -v169
	v_fma_f32 v174, s43, v154, -v172
	v_fma_f32 v175, s43, v155, -v173
	v_cvt_pk_bf16_f32 v156, v162, v163
	v_cvt_pk_bf16_f32 v157, v166, v167
	v_cvt_pk_bf16_f32 v158, v170, v171
	v_cvt_pk_bf16_f32 v159, v174, v175
	global_store_dwordx4 v3, v[156:159], s[10:11] sc1
	v_add_u32_e32 v3, 0x2000, v3
	s_waitcnt vmcnt(31)
	v_lshlrev_b32_e32 v160, 16, v84
	v_and_b32_e32 v161, 0xffff0000, v84
	v_lshlrev_b32_e32 v162, 16, v68
	v_and_b32_e32 v163, 0xffff0000, v68
	v_lshlrev_b32_e32 v164, 16, v85
	v_and_b32_e32 v165, 0xffff0000, v85
	v_lshlrev_b32_e32 v166, 16, v69
	v_and_b32_e32 v167, 0xffff0000, v69
	v_lshlrev_b32_e32 v168, 16, v86
	v_and_b32_e32 v169, 0xffff0000, v86
	v_lshlrev_b32_e32 v170, 16, v70
	v_and_b32_e32 v171, 0xffff0000, v70
	v_lshlrev_b32_e32 v172, 16, v87
	v_and_b32_e32 v173, 0xffff0000, v87
	v_lshlrev_b32_e32 v174, 16, v71
	v_and_b32_e32 v175, 0xffff0000, v71
	v_pk_add_f32 v[162:163], v[160:161], v[162:163] neg_lo:[0,1] neg_hi:[0,1]
	v_pk_add_f32 v[166:167], v[164:165], v[166:167] neg_lo:[0,1] neg_hi:[0,1]
	v_pk_add_f32 v[170:171], v[168:169], v[170:171] neg_lo:[0,1] neg_hi:[0,1]
	v_pk_add_f32 v[174:175], v[172:173], v[174:175] neg_lo:[0,1] neg_hi:[0,1]
	v_pk_add_f32 v[148:149], v[148:149], v[162:163]
	v_pk_add_f32 v[150:151], v[150:151], v[166:167]
	v_pk_add_f32 v[152:153], v[152:153], v[170:171]
	v_pk_add_f32 v[154:155], v[154:155], v[174:175]
	v_fma_f32 v162, s43, v148, -v160
	v_fma_f32 v163, s43, v149, -v161
	v_fma_f32 v166, s43, v150, -v164
	v_fma_f32 v167, s43, v151, -v165
	v_fma_f32 v170, s43, v152, -v168
	v_fma_f32 v171, s43, v153, -v169
	v_fma_f32 v174, s43, v154, -v172
	v_fma_f32 v175, s43, v155, -v173
	v_cvt_pk_bf16_f32 v156, v162, v163
	v_cvt_pk_bf16_f32 v157, v166, v167
	v_cvt_pk_bf16_f32 v158, v170, v171
	v_cvt_pk_bf16_f32 v159, v174, v175
	global_store_dwordx4 v3, v[156:159], s[10:11] sc1
	v_add_u32_e32 v3, 0x2000, v3
	s_waitcnt vmcnt(31)
; __device__ __forceinline__ unsigned cvt_pk_bf16(float lo, float hi) { unsigned r; asm volatile("v_cvt_pk_bf16_f32 %0, %1, %2" : "=v"(r) : "v"(lo), "v"(hi)); return r; }
; __device__ __forceinline__ float bf_lo(unsigned w) { return __uint_as_float(w << 16); }
; __device__ __forceinline__ float bf_hi(unsigned w) { return __uint_as_float(w & 0xffff0000u); }
; __device__ void phase_pool() {
;     ...
;             for (int k = 0; k < 8; ++k) { const int row = row0 + r0 + k, tl = tl0 + r0 + k; const u32x4 v = vv[k], o2 = ov[k];
;                 s[0] += bf_lo(v.x) - bf_lo(o2.x); s[1] += bf_hi(v.x) - bf_hi(o2.x); s[2] += bf_lo(v.y) - bf_lo(o2.y); s[3] += bf_hi(v.y) - bf_hi(o2.y);
;                 s[4] += bf_lo(v.z) - bf_lo(o2.z); s[5] += bf_hi(v.z) - bf_hi(o2.z); s[6] += bf_lo(v.w) - bf_lo(o2.w); s[7] += bf_hi(v.w) - bf_hi(o2.w);
;                 const float ic = 1.0f / (float)((tl + 1 < w) ? tl + 1 : w);
;                 u32x4 o;
;                 o.x = cvt_pk_bf16(s[0] * ic - bf_lo(v.x), s[1] * ic - bf_hi(v.x)); o.y = cvt_pk_bf16(s[2] * ic - bf_lo(v.y), s[3] * ic - bf_hi(v.y));
;                 o.z = cvt_pk_bf16(s[4] * ic - bf_lo(v.z), s[5] * ic - bf_hi(v.z)); o.w = cvt_pk_bf16(s[6] * ic - bf_lo(v.w), s[7] * ic - bf_hi(v.w));
;                 *(u32x4*)(pg + (size_t)row * DE + col) = o; }
	v_lshlrev_b32_e32 v160, 16, v88
	v_and_b32_e32 v161, 0xffff0000, v88
	v_lshlrev_b32_e32 v162, 16, v72
	v_and_b32_e32 v163, 0xffff0000, v72
	v_lshlrev_b32_e32 v164, 16, v89
	v_and_b32_e32 v165, 0xffff0000, v89
	v_lshlrev_b32_e32 v166, 16, v73
	v_and_b32_e32 v167, 0xffff0000, v73
	v_lshlrev_b32_e32 v168, 16, v90
	v_and_b32_e32 v169, 0xffff0000, v90
	v_lshlrev_b32_e32 v170, 16, v74
	v_and_b32_e32 v171, 0xffff0000, v74
	v_lshlrev_b32_e32 v172, 16, v91
	v_and_b32_e32 v173, 0xffff0000, v91
	v_lshlrev_b32_e32 v174, 16, v75
	v_and_b32_e32 v175, 0xffff0000, v75
	v_pk_add_f32 v[162:163], v[160:161], v[162:163] neg_lo:[0,1] neg_hi:[0,1]
	v_pk_add_f32 v[166:167], v[164:165], v[166:167] neg_lo:[0,1] neg_hi:[0,1]
	v_pk_add_f32 v[170:171], v[168:169], v[170:171] neg_lo:[0,1] neg_hi:[0,1]
	v_pk_add_f32 v[174:175], v[172:173], v[174:175] neg_lo:[0,1] neg_hi:[0,1]
	v_pk_add_f32 v[148:149], v[148:149], v[162:163]
	v_pk_add_f32 v[150:151], v[150:151], v[166:167]
	v_pk_add_f32 v[152:153], v[152:153], v[170:171]
	v_pk_add_f32 v[154:155], v[154:155], v[174:175]
	v_fma_f32 v162, s43, v148, -v160
	v_fma_f32 v163, s43, v149, -v161
	v_fma_f32 v166, s43, v150, -v164
	v_fma_f32 v167, s43, v151, -v165
	v_fma_f32 v170, s43, v152, -v168
	v_fma_f32 v171, s43, v153, -v169
	v_fma_f32 v174, s43, v154, -v172
	v_fma_f32 v175, s43, v155, -v173
	v_cvt_pk_bf16_f32 v156, v162, v163
	v_cvt_pk_bf16_f32 v157, v166, v167
	v_cvt_pk_bf16_f32 v158, v170, v171
	v_cvt_pk_bf16_f32 v159, v174, v175
	global_store_dwordx4 v3, v[156:159], s[10:11] sc1
	v_add_u32_e32 v3, 0x2000, v3
	s_waitcnt vmcnt(31)
	v_lshlrev_b32_e32 v160, 16, v92
	v_and_b32_e32 v161, 0xffff0000, v92
	v_lshlrev_b32_e32 v162, 16, v76
	v_and_b32_e32 v163, 0xffff0000, v76
	v_lshlrev_b32_e32 v164, 16, v93
	v_and_b32_e32 v165, 0xffff0000, v93
	v_lshlrev_b32_e32 v166, 16, v77
	v_and_b32_e32 v167, 0xffff0000, v77
	v_lshlrev_b32_e32 v168, 16, v94
	v_and_b32_e32 v169, 0xffff0000, v94
	v_lshlrev_b32_e32 v170, 16, v78
	v_and_b32_e32 v171, 0xffff0000, v78
	v_lshlrev_b32_e32 v172, 16, v95
	v_and_b32_e32 v173, 0xffff0000, v95
	v_lshlrev_b32_e32 v174, 16, v79
	v_and_b32_e32 v175, 0xffff0000, v79
	v_pk_add_f32 v[162:163], v[160:161], v[162:163] neg_lo:[0,1] neg_hi:[0,1]
	v_pk_add_f32 v[166:167], v[164:165], v[166:167] neg_lo:[0,1] neg_hi:[0,1]
	v_pk_add_f32 v[170:171], v[168:169], v[170:171] neg_lo:[0,1] neg_hi:[0,1]
	v_pk_add_f32 v[174:175], v[172:173], v[174:175] neg_lo:[0,1] neg_hi:[0,1]
	v_pk_add_f32 v[148:149], v[148:149], v[162:163]
	v_pk_add_f32 v[150:151], v[150:151], v[166:167]
	v_pk_add_f32 v[152:153], v[152:153], v[170:171]
	v_pk_add_f32 v[154:155], v[154:155], v[174:175]
	v_fma_f32 v162, s43, v148, -v160
	v_fma_f32 v163, s43, v149, -v161
	v_fma_f32 v166, s43, v150, -v164
	v_fma_f32 v167, s43, v151, -v165
	v_fma_f32 v170, s43, v152, -v168
	v_fma_f32 v171, s43, v153, -v169
	v_fma_f32 v174, s43, v154, -v172
	v_fma_f32 v175, s43, v155, -v173
	v_cvt_pk_bf16_f32 v156, v162, v163
	v_cvt_pk_bf16_f32 v157, v166, v167
	v_cvt_pk_bf16_f32 v158, v170, v171
	v_cvt_pk_bf16_f32 v159, v174, v175
	global_store_dwordx4 v3, v[156:159], s[10:11] sc1
	v_add_u32_e32 v3, 0x2000, v3
	s_waitcnt vmcnt(31)
	v_lshlrev_b32_e32 v160, 16, v96
	v_and_b32_e32 v161, 0xffff0000, v96
	v_lshlrev_b32_e32 v162, 16, v80
	v_and_b32_e32 v163, 0xffff0000, v80
	v_lshlrev_b32_e32 v164, 16, v97
	v_and_b32_e32 v165, 0xffff0000, v97
	v_lshlrev_b32_e32 v166, 16, v81
	v_and_b32_e32 v167, 0xffff0000, v81
	v_lshlrev_b32_e32 v168, 16, v98
	v_and_b32_e32 v169, 0xffff0000, v98
	v_lshlrev_b32_e32 v170, 16, v82
	v_and_b32_e32 v171, 0xffff0000, v82
	v_lshlrev_b32_e32 v172, 16, v99
	v_and_b32_e32 v173, 0xffff0000, v99
	v_lshlrev_b32_e32 v174, 16, v83
	v_and_b32_e32 v175, 0xffff0000, v83
	v_pk_add_f32 v[162:163], v[160:161], v[162:163] neg_lo:[0,1] neg_hi:[0,1]
	v_pk_add_f32 v[166:167], v[164:165], v[166:167] neg_lo:[0,1] neg_hi:[0,1]
	v_pk_add_f32 v[170:171], v[168:169], v[170:171] neg_lo:[0,1] neg_hi:[0,1]
	v_pk_add_f32 v[174:175], v[172:173], v[174:175] neg_lo:[0,1] neg_hi:[0,1]
	v_pk_add_f32 v[148:149], v[148:149], v[162:163]
	v_pk_add_f32 v[150:151], v[150:151], v[166:167]
	v_pk_add_f32 v[152:153], v[152:153], v[170:171]
	v_pk_add_f32 v[154:155], v[154:155], v[174:175]
	v_fma_f32 v162, s43, v148, -v160
	v_fma_f32 v163, s43, v149, -v161
	v_fma_f32 v166, s43, v150, -v164
	v_fma_f32 v167, s43, v151, -v165
	v_fma_f32 v170, s43, v152, -v168
	v_fma_f32 v171, s43, v153, -v169
	v_fma_f32 v174, s43, v154, -v172
	v_fma_f32 v175, s43, v155, -v173
	v_cvt_pk_bf16_f32 v156, v162, v163
	v_cvt_pk_bf16_f32 v157, v166, v167
	v_cvt_pk_bf16_f32 v158, v170, v171
	v_cvt_pk_bf16_f32 v159, v174, v175
	global_store_dwordx4 v3, v[156:159], s[10:11] sc1
	v_add_u32_e32 v3, 0x2000, v3
	s_waitcnt vmcnt(31)
	v_lshlrev_b32_e32 v160, 16, v100
	v_and_b32_e32 v161, 0xffff0000, v100
	v_lshlrev_b32_e32 v162, 16, v84
	v_and_b32_e32 v163, 0xffff0000, v84
	v_lshlrev_b32_e32 v164, 16, v101
	v_and_b32_e32 v165, 0xffff0000, v101
	v_lshlrev_b32_e32 v166, 16, v85
	v_and_b32_e32 v167, 0xffff0000, v85
	v_lshlrev_b32_e32 v168, 16, v102
	v_and_b32_e32 v169, 0xffff0000, v102
	v_lshlrev_b32_e32 v170, 16, v86
	v_and_b32_e32 v171, 0xffff0000, v86
	v_lshlrev_b32_e32 v172, 16, v103
	v_and_b32_e32 v173, 0xffff0000, v103
	v_lshlrev_b32_e32 v174, 16, v87
	v_and_b32_e32 v175, 0xffff0000, v87
	v_pk_add_f32 v[162:163], v[160:161], v[162:163] neg_lo:[0,1] neg_hi:[0,1]
	v_pk_add_f32 v[166:167], v[164:165], v[166:167] neg_lo:[0,1] neg_hi:[0,1]
	v_pk_add_f32 v[170:171], v[168:169], v[170:171] neg_lo:[0,1] neg_hi:[0,1]
	v_pk_add_f32 v[174:175], v[172:173], v[174:175] neg_lo:[0,1] neg_hi:[0,1]
	v_pk_add_f32 v[148:149], v[148:149], v[162:163]
	v_pk_add_f32 v[150:151], v[150:151], v[166:167]
	v_pk_add_f32 v[152:153], v[152:153], v[170:171]
	v_pk_add_f32 v[154:155], v[154:155], v[174:175]
	v_fma_f32 v162, s43, v148, -v160
	v_fma_f32 v163, s43, v149, -v161
	v_fma_f32 v166, s43, v150, -v164
	v_fma_f32 v167, s43, v151, -v165
	v_fma_f32 v170, s43, v152, -v168
	v_fma_f32 v171, s43, v153, -v169
	v_fma_f32 v174, s43, v154, -v172
	v_fma_f32 v175, s43, v155, -v173
	v_cvt_pk_bf16_f32 v156, v162, v163
	v_cvt_pk_bf16_f32 v157, v166, v167
	v_cvt_pk_bf16_f32 v158, v170, v171
	v_cvt_pk_bf16_f32 v159, v174, v175
	global_store_dwordx4 v3, v[156:159], s[10:11] sc1
	v_add_u32_e32 v3, 0x2000, v3
	s_waitcnt vmcnt(31)
; __device__ __forceinline__ unsigned cvt_pk_bf16(float lo, float hi) { unsigned r; asm volatile("v_cvt_pk_bf16_f32 %0, %1, %2" : "=v"(r) : "v"(lo), "v"(hi)); return r; }
; __device__ __forceinline__ float bf_lo(unsigned w) { return __uint_as_float(w << 16); }
; __device__ __forceinline__ float bf_hi(unsigned w) { return __uint_as_float(w & 0xffff0000u); }
; __device__ void phase_pool() {
;     ...
;             for (int k = 0; k < 8; ++k) { const int row = row0 + r0 + k, tl = tl0 + r0 + k; const u32x4 v = vv[k], o2 = ov[k];
;                 s[0] += bf_lo(v.x) - bf_lo(o2.x); s[1] += bf_hi(v.x) - bf_hi(o2.x); s[2] += bf_lo(v.y) - bf_lo(o2.y); s[3] += bf_hi(v.y) - bf_hi(o2.y);
;                 s[4] += bf_lo(v.z) - bf_lo(o2.z); s[5] += bf_hi(v.z) - bf_hi(o2.z); s[6] += bf_lo(v.w) - bf_lo(o2.w); s[7] += bf_hi(v.w) - bf_hi(o2.w);
;                 const float ic = 1.0f / (float)((tl + 1 < w) ? tl + 1 : w);
;                 u32x4 o;
;                 o.x = cvt_pk_bf16(s[0] * ic - bf_lo(v.x), s[1] * ic - bf_hi(v.x)); o.y = cvt_pk_bf16(s[2] * ic - bf_lo(v.y), s[3] * ic - bf_hi(v.y));
;                 o.z = cvt_pk_bf16(s[4] * ic - bf_lo(v.z), s[5] * ic - bf_hi(v.z)); o.w = cvt_pk_bf16(s[6] * ic - bf_lo(v.w), s[7] * ic - bf_hi(v.w));
;                 *(u32x4*)(pg + (size_t)row * DE + col) = o; }
	v_lshlrev_b32_e32 v160, 16, v104
	v_and_b32_e32 v161, 0xffff0000, v104
	v_lshlrev_b32_e32 v162, 16, v88
	v_and_b32_e32 v163, 0xffff0000, v88
	v_lshlrev_b32_e32 v164, 16, v105
	v_and_b32_e32 v165, 0xffff0000, v105
	v_lshlrev_b32_e32 v166, 16, v89
	v_and_b32_e32 v167, 0xffff0000, v89
	v_lshlrev_b32_e32 v168, 16, v106
	v_and_b32_e32 v169, 0xffff0000, v106
	v_lshlrev_b32_e32 v170, 16, v90
	v_and_b32_e32 v171, 0xffff0000, v90
	v_lshlrev_b32_e32 v172, 16, v107
	v_and_b32_e32 v173, 0xffff0000, v107
	v_lshlrev_b32_e32 v174, 16, v91
	v_and_b32_e32 v175, 0xffff0000, v91
	v_pk_add_f32 v[162:163], v[160:161], v[162:163] neg_lo:[0,1] neg_hi:[0,1]
	v_pk_add_f32 v[166:167], v[164:165], v[166:167] neg_lo:[0,1] neg_hi:[0,1]
	v_pk_add_f32 v[170:171], v[168:169], v[170:171] neg_lo:[0,1] neg_hi:[0,1]
	v_pk_add_f32 v[174:175], v[172:173], v[174:175] neg_lo:[0,1] neg_hi:[0,1]
	v_pk_add_f32 v[148:149], v[148:149], v[162:163]
	v_pk_add_f32 v[150:151], v[150:151], v[166:167]
	v_pk_add_f32 v[152:153], v[152:153], v[170:171]
	v_pk_add_f32 v[154:155], v[154:155], v[174:175]
	v_fma_f32 v162, s43, v148, -v160
	v_fma_f32 v163, s43, v149, -v161
	v_fma_f32 v166, s43, v150, -v164
	v_fma_f32 v167, s43, v151, -v165
	v_fma_f32 v170, s43, v152, -v168
	v_fma_f32 v171, s43, v153, -v169
	v_fma_f32 v174, s43, v154, -v172
	v_fma_f32 v175, s43, v155, -v173
	v_cvt_pk_bf16_f32 v156, v162, v163
	v_cvt_pk_bf16_f32 v157, v166, v167
	v_cvt_pk_bf16_f32 v158, v170, v171
	v_cvt_pk_bf16_f32 v159, v174, v175
	global_store_dwordx4 v3, v[156:159], s[10:11] sc1
	v_add_u32_e32 v3, 0x2000, v3
	s_waitcnt vmcnt(31)
	v_lshlrev_b32_e32 v160, 16, v108
	v_and_b32_e32 v161, 0xffff0000, v108
	v_lshlrev_b32_e32 v162, 16, v92
	v_and_b32_e32 v163, 0xffff0000, v92
	v_lshlrev_b32_e32 v164, 16, v109
	v_and_b32_e32 v165, 0xffff0000, v109
	v_lshlrev_b32_e32 v166, 16, v93
	v_and_b32_e32 v167, 0xffff0000, v93
	v_lshlrev_b32_e32 v168, 16, v110
	v_and_b32_e32 v169, 0xffff0000, v110
	v_lshlrev_b32_e32 v170, 16, v94
	v_and_b32_e32 v171, 0xffff0000, v94
	v_lshlrev_b32_e32 v172, 16, v111
	v_and_b32_e32 v173, 0xffff0000, v111
	v_lshlrev_b32_e32 v174, 16, v95
	v_and_b32_e32 v175, 0xffff0000, v95
	v_pk_add_f32 v[162:163], v[160:161], v[162:163] neg_lo:[0,1] neg_hi:[0,1]
	v_pk_add_f32 v[166:167], v[164:165], v[166:167] neg_lo:[0,1] neg_hi:[0,1]
	v_pk_add_f32 v[170:171], v[168:169], v[170:171] neg_lo:[0,1] neg_hi:[0,1]
	v_pk_add_f32 v[174:175], v[172:173], v[174:175] neg_lo:[0,1] neg_hi:[0,1]
	v_pk_add_f32 v[148:149], v[148:149], v[162:163]
	v_pk_add_f32 v[150:151], v[150:151], v[166:167]
	v_pk_add_f32 v[152:153], v[152:153], v[170:171]
	v_pk_add_f32 v[154:155], v[154:155], v[174:175]
	v_fma_f32 v162, s43, v148, -v160
	v_fma_f32 v163, s43, v149, -v161
	v_fma_f32 v166, s43, v150, -v164
	v_fma_f32 v167, s43, v151, -v165
	v_fma_f32 v170, s43, v152, -v168
	v_fma_f32 v171, s43, v153, -v169
	v_fma_f32 v174, s43, v154, -v172
	v_fma_f32 v175, s43, v155, -v173
	v_cvt_pk_bf16_f32 v156, v162, v163
	v_cvt_pk_bf16_f32 v157, v166, v167
	v_cvt_pk_bf16_f32 v158, v170, v171
	v_cvt_pk_bf16_f32 v159, v174, v175
	global_store_dwordx4 v3, v[156:159], s[10:11] sc1
	v_add_u32_e32 v3, 0x2000, v3
	s_waitcnt vmcnt(31)
	v_lshlrev_b32_e32 v160, 16, v112
	v_and_b32_e32 v161, 0xffff0000, v112
	v_lshlrev_b32_e32 v162, 16, v96
	v_and_b32_e32 v163, 0xffff0000, v96
	v_lshlrev_b32_e32 v164, 16, v113
	v_and_b32_e32 v165, 0xffff0000, v113
	v_lshlrev_b32_e32 v166, 16, v97
	v_and_b32_e32 v167, 0xffff0000, v97
	v_lshlrev_b32_e32 v168, 16, v114
	v_and_b32_e32 v169, 0xffff0000, v114
	v_lshlrev_b32_e32 v170, 16, v98
	v_and_b32_e32 v171, 0xffff0000, v98
	v_lshlrev_b32_e32 v172, 16, v115
	v_and_b32_e32 v173, 0xffff0000, v115
	v_lshlrev_b32_e32 v174, 16, v99
	v_and_b32_e32 v175, 0xffff0000, v99
	v_pk_add_f32 v[162:163], v[160:161], v[162:163] neg_lo:[0,1] neg_hi:[0,1]
	v_pk_add_f32 v[166:167], v[164:165], v[166:167] neg_lo:[0,1] neg_hi:[0,1]
	v_pk_add_f32 v[170:171], v[168:169], v[170:171] neg_lo:[0,1] neg_hi:[0,1]
	v_pk_add_f32 v[174:175], v[172:173], v[174:175] neg_lo:[0,1] neg_hi:[0,1]
	v_pk_add_f32 v[148:149], v[148:149], v[162:163]
	v_pk_add_f32 v[150:151], v[150:151], v[166:167]
	v_pk_add_f32 v[152:153], v[152:153], v[170:171]
	v_pk_add_f32 v[154:155], v[154:155], v[174:175]
	v_fma_f32 v162, s43, v148, -v160
	v_fma_f32 v163, s43, v149, -v161
	v_fma_f32 v166, s43, v150, -v164
	v_fma_f32 v167, s43, v151, -v165
	v_fma_f32 v170, s43, v152, -v168
	v_fma_f32 v171, s43, v153, -v169
	v_fma_f32 v174, s43, v154, -v172
	v_fma_f32 v175, s43, v155, -v173
	v_cvt_pk_bf16_f32 v156, v162, v163
	v_cvt_pk_bf16_f32 v157, v166, v167
	v_cvt_pk_bf16_f32 v158, v170, v171
	v_cvt_pk_bf16_f32 v159, v174, v175
	global_store_dwordx4 v3, v[156:159], s[10:11] sc1
	v_add_u32_e32 v3, 0x2000, v3
	s_waitcnt vmcnt(31)
	v_lshlrev_b32_e32 v160, 16, v116
	v_and_b32_e32 v161, 0xffff0000, v116
	v_lshlrev_b32_e32 v162, 16, v100
	v_and_b32_e32 v163, 0xffff0000, v100
	v_lshlrev_b32_e32 v164, 16, v117
	v_and_b32_e32 v165, 0xffff0000, v117
	v_lshlrev_b32_e32 v166, 16, v101
	v_and_b32_e32 v167, 0xffff0000, v101
	v_lshlrev_b32_e32 v168, 16, v118
	v_and_b32_e32 v169, 0xffff0000, v118
	v_lshlrev_b32_e32 v170, 16, v102
	v_and_b32_e32 v171, 0xffff0000, v102
	v_lshlrev_b32_e32 v172, 16, v119
	v_and_b32_e32 v173, 0xffff0000, v119
	v_lshlrev_b32_e32 v174, 16, v103
	v_and_b32_e32 v175, 0xffff0000, v103
	v_pk_add_f32 v[162:163], v[160:161], v[162:163] neg_lo:[0,1] neg_hi:[0,1]
	v_pk_add_f32 v[166:167], v[164:165], v[166:167] neg_lo:[0,1] neg_hi:[0,1]
	v_pk_add_f32 v[170:171], v[168:169], v[170:171] neg_lo:[0,1] neg_hi:[0,1]
	v_pk_add_f32 v[174:175], v[172:173], v[174:175] neg_lo:[0,1] neg_hi:[0,1]
	v_pk_add_f32 v[148:149], v[148:149], v[162:163]
	v_pk_add_f32 v[150:151], v[150:151], v[166:167]
	v_pk_add_f32 v[152:153], v[152:153], v[170:171]
	v_pk_add_f32 v[154:155], v[154:155], v[174:175]
	v_fma_f32 v162, s43, v148, -v160
	v_fma_f32 v163, s43, v149, -v161
	v_fma_f32 v166, s43, v150, -v164
	v_fma_f32 v167, s43, v151, -v165
	v_fma_f32 v170, s43, v152, -v168
	v_fma_f32 v171, s43, v153, -v169
	v_fma_f32 v174, s43, v154, -v172
	v_fma_f32 v175, s43, v155, -v173
	v_cvt_pk_bf16_f32 v156, v162, v163
	v_cvt_pk_bf16_f32 v157, v166, v167
	v_cvt_pk_bf16_f32 v158, v170, v171
	v_cvt_pk_bf16_f32 v159, v174, v175
	global_store_dwordx4 v3, v[156:159], s[10:11] sc1
	v_add_u32_e32 v3, 0x2000, v3
	s_waitcnt vmcnt(31)
; __device__ __forceinline__ unsigned cvt_pk_bf16(float lo, float hi) { unsigned r; asm volatile("v_cvt_pk_bf16_f32 %0, %1, %2" : "=v"(r) : "v"(lo), "v"(hi)); return r; }
; __device__ __forceinline__ float bf_lo(unsigned w) { return __uint_as_float(w << 16); }
; __device__ __forceinline__ float bf_hi(unsigned w) { return __uint_as_float(w & 0xffff0000u); }
; __device__ void phase_pool() {
;     ...
;             for (int k = 0; k < 8; ++k) { const int row = row0 + r0 + k, tl = tl0 + r0 + k; const u32x4 v = vv[k], o2 = ov[k];
;                 s[0] += bf_lo(v.x) - bf_lo(o2.x); s[1] += bf_hi(v.x) - bf_hi(o2.x); s[2] += bf_lo(v.y) - bf_lo(o2.y); s[3] += bf_hi(v.y) - bf_hi(o2.y);
;                 s[4] += bf_lo(v.z) - bf_lo(o2.z); s[5] += bf_hi(v.z) - bf_hi(o2.z); s[6] += bf_lo(v.w) - bf_lo(o2.w); s[7] += bf_hi(v.w) - bf_hi(o2.w);
;                 const float ic = 1.0f / (float)((tl + 1 < w) ? tl + 1 : w);
;                 u32x4 o;
;                 o.x = cvt_pk_bf16(s[0] * ic - bf_lo(v.x), s[1] * ic - bf_hi(v.x)); o.y = cvt_pk_bf16(s[2] * ic - bf_lo(v.y), s[3] * ic - bf_hi(v.y));
;                 o.z = cvt_pk_bf16(s[4] * ic - bf_lo(v.z), s[5] * ic - bf_hi(v.z)); o.w = cvt_pk_bf16(s[6] * ic - bf_lo(v.w), s[7] * ic - bf_hi(v.w));
;                 *(u32x4*)(pg + (size_t)row * DE + col) = o; }
	v_lshlrev_b32_e32 v160, 16, v120
	v_and_b32_e32 v161, 0xffff0000, v120
	v_lshlrev_b32_e32 v162, 16, v104
	v_and_b32_e32 v163, 0xffff0000, v104
	v_lshlrev_b32_e32 v164, 16, v121
	v_and_b32_e32 v165, 0xffff0000, v121
	v_lshlrev_b32_e32 v166, 16, v105
	v_and_b32_e32 v167, 0xffff0000, v105
	v_lshlrev_b32_e32 v168, 16, v122
	v_and_b32_e32 v169, 0xffff0000, v122
	v_lshlrev_b32_e32 v170, 16, v106
	v_and_b32_e32 v171, 0xffff0000, v106
	v_lshlrev_b32_e32 v172, 16, v123
	v_and_b32_e32 v173, 0xffff0000, v123
	v_lshlrev_b32_e32 v174, 16, v107
	v_and_b32_e32 v175, 0xffff0000, v107
	v_pk_add_f32 v[162:163], v[160:161], v[162:163] neg_lo:[0,1] neg_hi:[0,1]
	v_pk_add_f32 v[166:167], v[164:165], v[166:167] neg_lo:[0,1] neg_hi:[0,1]
	v_pk_add_f32 v[170:171], v[168:169], v[170:171] neg_lo:[0,1] neg_hi:[0,1]
	v_pk_add_f32 v[174:175], v[172:173], v[174:175] neg_lo:[0,1] neg_hi:[0,1]
	v_pk_add_f32 v[148:149], v[148:149], v[162:163]
	v_pk_add_f32 v[150:151], v[150:151], v[166:167]
	v_pk_add_f32 v[152:153], v[152:153], v[170:171]
	v_pk_add_f32 v[154:155], v[154:155], v[174:175]
	v_fma_f32 v162, s43, v148, -v160
	v_fma_f32 v163, s43, v149, -v161
	v_fma_f32 v166, s43, v150, -v164
	v_fma_f32 v167, s43, v151, -v165
	v_fma_f32 v170, s43, v152, -v168
	v_fma_f32 v171, s43, v153, -v169
	v_fma_f32 v174, s43, v154, -v172
	v_fma_f32 v175, s43, v155, -v173
	v_cvt_pk_bf16_f32 v156, v162, v163
	v_cvt_pk_bf16_f32 v157, v166, v167
	v_cvt_pk_bf16_f32 v158, v170, v171
	v_cvt_pk_bf16_f32 v159, v174, v175
	global_store_dwordx4 v3, v[156:159], s[10:11] sc1
	v_add_u32_e32 v3, 0x2000, v3
	s_waitcnt vmcnt(31)
	v_lshlrev_b32_e32 v160, 16, v124
	v_and_b32_e32 v161, 0xffff0000, v124
	v_lshlrev_b32_e32 v162, 16, v108
	v_and_b32_e32 v163, 0xffff0000, v108
	v_lshlrev_b32_e32 v164, 16, v125
	v_and_b32_e32 v165, 0xffff0000, v125
	v_lshlrev_b32_e32 v166, 16, v109
	v_and_b32_e32 v167, 0xffff0000, v109
	v_lshlrev_b32_e32 v168, 16, v126
	v_and_b32_e32 v169, 0xffff0000, v126
	v_lshlrev_b32_e32 v170, 16, v110
	v_and_b32_e32 v171, 0xffff0000, v110
	v_lshlrev_b32_e32 v172, 16, v127
	v_and_b32_e32 v173, 0xffff0000, v127
	v_lshlrev_b32_e32 v174, 16, v111
	v_and_b32_e32 v175, 0xffff0000, v111
	v_pk_add_f32 v[162:163], v[160:161], v[162:163] neg_lo:[0,1] neg_hi:[0,1]
	v_pk_add_f32 v[166:167], v[164:165], v[166:167] neg_lo:[0,1] neg_hi:[0,1]
	v_pk_add_f32 v[170:171], v[168:169], v[170:171] neg_lo:[0,1] neg_hi:[0,1]
	v_pk_add_f32 v[174:175], v[172:173], v[174:175] neg_lo:[0,1] neg_hi:[0,1]
	v_pk_add_f32 v[148:149], v[148:149], v[162:163]
	v_pk_add_f32 v[150:151], v[150:151], v[166:167]
	v_pk_add_f32 v[152:153], v[152:153], v[170:171]
	v_pk_add_f32 v[154:155], v[154:155], v[174:175]
	v_fma_f32 v162, s43, v148, -v160
	v_fma_f32 v163, s43, v149, -v161
	v_fma_f32 v166, s43, v150, -v164
	v_fma_f32 v167, s43, v151, -v165
	v_fma_f32 v170, s43, v152, -v168
	v_fma_f32 v171, s43, v153, -v169
	v_fma_f32 v174, s43, v154, -v172
	v_fma_f32 v175, s43, v155, -v173
	v_cvt_pk_bf16_f32 v156, v162, v163
	v_cvt_pk_bf16_f32 v157, v166, v167
	v_cvt_pk_bf16_f32 v158, v170, v171
	v_cvt_pk_bf16_f32 v159, v174, v175
	global_store_dwordx4 v3, v[156:159], s[10:11] sc1
	v_add_u32_e32 v3, 0x2000, v3
	s_waitcnt vmcnt(31)
	v_lshlrev_b32_e32 v160, 16, v128
	v_and_b32_e32 v161, 0xffff0000, v128
	v_lshlrev_b32_e32 v162, 16, v112
	v_and_b32_e32 v163, 0xffff0000, v112
	v_lshlrev_b32_e32 v164, 16, v129
	v_and_b32_e32 v165, 0xffff0000, v129
	v_lshlrev_b32_e32 v166, 16, v113
	v_and_b32_e32 v167, 0xffff0000, v113
	v_lshlrev_b32_e32 v168, 16, v130
	v_and_b32_e32 v169, 0xffff0000, v130
	v_lshlrev_b32_e32 v170, 16, v114
	v_and_b32_e32 v171, 0xffff0000, v114
	v_lshlrev_b32_e32 v172, 16, v131
	v_and_b32_e32 v173, 0xffff0000, v131
	v_lshlrev_b32_e32 v174, 16, v115
	v_and_b32_e32 v175, 0xffff0000, v115
	v_pk_add_f32 v[162:163], v[160:161], v[162:163] neg_lo:[0,1] neg_hi:[0,1]
	v_pk_add_f32 v[166:167], v[164:165], v[166:167] neg_lo:[0,1] neg_hi:[0,1]
	v_pk_add_f32 v[170:171], v[168:169], v[170:171] neg_lo:[0,1] neg_hi:[0,1]
	v_pk_add_f32 v[174:175], v[172:173], v[174:175] neg_lo:[0,1] neg_hi:[0,1]
	v_pk_add_f32 v[148:149], v[148:149], v[162:163]
	v_pk_add_f32 v[150:151], v[150:151], v[166:167]
	v_pk_add_f32 v[152:153], v[152:153], v[170:171]
	v_pk_add_f32 v[154:155], v[154:155], v[174:175]
	v_fma_f32 v162, s43, v148, -v160
	v_fma_f32 v163, s43, v149, -v161
	v_fma_f32 v166, s43, v150, -v164
	v_fma_f32 v167, s43, v151, -v165
	v_fma_f32 v170, s43, v152, -v168
	v_fma_f32 v171, s43, v153, -v169
	v_fma_f32 v174, s43, v154, -v172
	v_fma_f32 v175, s43, v155, -v173
	v_cvt_pk_bf16_f32 v156, v162, v163
	v_cvt_pk_bf16_f32 v157, v166, v167
	v_cvt_pk_bf16_f32 v158, v170, v171
	v_cvt_pk_bf16_f32 v159, v174, v175
	global_store_dwordx4 v3, v[156:159], s[10:11] sc1
	v_add_u32_e32 v3, 0x2000, v3
	s_waitcnt vmcnt(31)
; __device__ __forceinline__ unsigned cvt_pk_bf16(float lo, float hi) { unsigned r; asm volatile("v_cvt_pk_bf16_f32 %0, %1, %2" : "=v"(r) : "v"(lo), "v"(hi)); return r; }
; __device__ __forceinline__ float bf_lo(unsigned w) { return __uint_as_float(w << 16); }
; __device__ __forceinline__ float bf_hi(unsigned w) { return __uint_as_float(w & 0xffff0000u); }
; __device__ void phase_pool() {
;     ...
;             for (int k = 0; k < 8; ++k) { const int row = row0 + r0 + k, tl = tl0 + r0 + k; const u32x4 v = vv[k], o2 = ov[k];
;                 s[0] += bf_lo(v.x) - bf_lo(o2.x); s[1] += bf_hi(v.x) - bf_hi(o2.x); s[2] += bf_lo(v.y) - bf_lo(o2.y); s[3] += bf_hi(v.y) - bf_hi(o2.y);
;                 s[4] += bf_lo(v.z) - bf_lo(o2.z); s[5] += bf_hi(v.z) - bf_hi(o2.z); s[6] += bf_lo(v.w) - bf_lo(o2.w); s[7] += bf_hi(v.w) - bf_hi(o2.w);
;                 const float ic = 1.0f / (float)((tl + 1 < w) ? tl + 1 : w);
;                 u32x4 o;
;                 o.x = cvt_pk_bf16(s[0] * ic - bf_lo(v.x), s[1] * ic - bf_hi(v.x)); o.y = cvt_pk_bf16(s[2] * ic - bf_lo(v.y), s[3] * ic - bf_hi(v.y));
;                 o.z = cvt_pk_bf16(s[4] * ic - bf_lo(v.z), s[5] * ic - bf_hi(v.z)); o.w = cvt_pk_bf16(s[6] * ic - bf_lo(v.w), s[7] * ic - bf_hi(v.w));
;                 *(u32x4*)(pg + (size_t)row * DE + col) = o; }
	v_lshlrev_b32_e32 v160, 16, v132
	v_and_b32_e32 v161, 0xffff0000, v132
	v_lshlrev_b32_e32 v162, 16, v116
	v_and_b32_e32 v163, 0xffff0000, v116
	v_lshlrev_b32_e32 v164, 16, v133
	v_and_b32_e32 v165, 0xffff0000, v133
	v_lshlrev_b32_e32 v166, 16, v117
	v_and_b32_e32 v167, 0xffff0000, v117
	v_lshlrev_b32_e32 v168, 16, v134
	v_and_b32_e32 v169, 0xffff0000, v134
	v_lshlrev_b32_e32 v170, 16, v118
	v_and_b32_e32 v171, 0xffff0000, v118
	v_lshlrev_b32_e32 v172, 16, v135
	v_and_b32_e32 v173, 0xffff0000, v135
	v_lshlrev_b32_e32 v174, 16, v119
	v_and_b32_e32 v175, 0xffff0000, v119
	v_pk_add_f32 v[162:163], v[160:161], v[162:163] neg_lo:[0,1] neg_hi:[0,1]
	v_pk_add_f32 v[166:167], v[164:165], v[166:167] neg_lo:[0,1] neg_hi:[0,1]
	v_pk_add_f32 v[170:171], v[168:169], v[170:171] neg_lo:[0,1] neg_hi:[0,1]
	v_pk_add_f32 v[174:175], v[172:173], v[174:175] neg_lo:[0,1] neg_hi:[0,1]
	v_pk_add_f32 v[148:149], v[148:149], v[162:163]
	v_pk_add_f32 v[150:151], v[150:151], v[166:167]
	v_pk_add_f32 v[152:153], v[152:153], v[170:171]
	v_pk_add_f32 v[154:155], v[154:155], v[174:175]
	v_fma_f32 v162, s43, v148, -v160
	v_fma_f32 v163, s43, v149, -v161
	v_fma_f32 v166, s43, v150, -v164
	v_fma_f32 v167, s43, v151, -v165
	v_fma_f32 v170, s43, v152, -v168
	v_fma_f32 v171, s43, v153, -v169
	v_fma_f32 v174, s43, v154, -v172
	v_fma_f32 v175, s43, v155, -v173
	v_cvt_pk_bf16_f32 v156, v162, v163
	v_cvt_pk_bf16_f32 v157, v166, v167
	v_cvt_pk_bf16_f32 v158, v170, v171
	v_cvt_pk_bf16_f32 v159, v174, v175
	global_store_dwordx4 v3, v[156:159], s[10:11] sc1
	v_add_u32_e32 v3, 0x2000, v3
	s_waitcnt vmcnt(31)
	v_lshlrev_b32_e32 v160, 16, v136
	v_and_b32_e32 v161, 0xffff0000, v136
	v_lshlrev_b32_e32 v162, 16, v120
	v_and_b32_e32 v163, 0xffff0000, v120
	v_lshlrev_b32_e32 v164, 16, v137
	v_and_b32_e32 v165, 0xffff0000, v137
	v_lshlrev_b32_e32 v166, 16, v121
	v_and_b32_e32 v167, 0xffff0000, v121
	v_lshlrev_b32_e32 v168, 16, v138
	v_and_b32_e32 v169, 0xffff0000, v138
	v_lshlrev_b32_e32 v170, 16, v122
	v_and_b32_e32 v171, 0xffff0000, v122
	v_lshlrev_b32_e32 v172, 16, v139
	v_and_b32_e32 v173, 0xffff0000, v139
	v_lshlrev_b32_e32 v174, 16, v123
	v_and_b32_e32 v175, 0xffff0000, v123
	v_pk_add_f32 v[162:163], v[160:161], v[162:163] neg_lo:[0,1] neg_hi:[0,1]
	v_pk_add_f32 v[166:167], v[164:165], v[166:167] neg_lo:[0,1] neg_hi:[0,1]
	v_pk_add_f32 v[170:171], v[168:169], v[170:171] neg_lo:[0,1] neg_hi:[0,1]
	v_pk_add_f32 v[174:175], v[172:173], v[174:175] neg_lo:[0,1] neg_hi:[0,1]
	v_pk_add_f32 v[148:149], v[148:149], v[162:163]
	v_pk_add_f32 v[150:151], v[150:151], v[166:167]
	v_pk_add_f32 v[152:153], v[152:153], v[170:171]
	v_pk_add_f32 v[154:155], v[154:155], v[174:175]
	v_fma_f32 v162, s43, v148, -v160
	v_fma_f32 v163, s43, v149, -v161
	v_fma_f32 v166, s43, v150, -v164
	v_fma_f32 v167, s43, v151, -v165
	v_fma_f32 v170, s43, v152, -v168
	v_fma_f32 v171, s43, v153, -v169
	v_fma_f32 v174, s43, v154, -v172
	v_fma_f32 v175, s43, v155, -v173
	v_cvt_pk_bf16_f32 v156, v162, v163
	v_cvt_pk_bf16_f32 v157, v166, v167
	v_cvt_pk_bf16_f32 v158, v170, v171
	v_cvt_pk_bf16_f32 v159, v174, v175
	global_store_dwordx4 v3, v[156:159], s[10:11] sc1
	v_add_u32_e32 v3, 0x2000, v3
	s_waitcnt vmcnt(31)
	v_lshlrev_b32_e32 v160, 16, v140
	v_and_b32_e32 v161, 0xffff0000, v140
	v_lshlrev_b32_e32 v162, 16, v124
	v_and_b32_e32 v163, 0xffff0000, v124
	v_lshlrev_b32_e32 v164, 16, v141
	v_and_b32_e32 v165, 0xffff0000, v141
	v_lshlrev_b32_e32 v166, 16, v125
	v_and_b32_e32 v167, 0xffff0000, v125
	v_lshlrev_b32_e32 v168, 16, v142
	v_and_b32_e32 v169, 0xffff0000, v142
	v_lshlrev_b32_e32 v170, 16, v126
	v_and_b32_e32 v171, 0xffff0000, v126
	v_lshlrev_b32_e32 v172, 16, v143
	v_and_b32_e32 v173, 0xffff0000, v143
	v_lshlrev_b32_e32 v174, 16, v127
	v_and_b32_e32 v175, 0xffff0000, v127
	v_pk_add_f32 v[162:163], v[160:161], v[162:163] neg_lo:[0,1] neg_hi:[0,1]
	v_pk_add_f32 v[166:167], v[164:165], v[166:167] neg_lo:[0,1] neg_hi:[0,1]
	v_pk_add_f32 v[170:171], v[168:169], v[170:171] neg_lo:[0,1] neg_hi:[0,1]
	v_pk_add_f32 v[174:175], v[172:173], v[174:175] neg_lo:[0,1] neg_hi:[0,1]
	v_pk_add_f32 v[148:149], v[148:149], v[162:163]
	v_pk_add_f32 v[150:151], v[150:151], v[166:167]
	v_pk_add_f32 v[152:153], v[152:153], v[170:171]
	v_pk_add_f32 v[154:155], v[154:155], v[174:175]
	v_fma_f32 v162, s43, v148, -v160
	v_fma_f32 v163, s43, v149, -v161
	v_fma_f32 v166, s43, v150, -v164
	v_fma_f32 v167, s43, v151, -v165
	v_fma_f32 v170, s43, v152, -v168
	v_fma_f32 v171, s43, v153, -v169
	v_fma_f32 v174, s43, v154, -v172
	v_fma_f32 v175, s43, v155, -v173
	v_cvt_pk_bf16_f32 v156, v162, v163
	v_cvt_pk_bf16_f32 v157, v166, v167
	v_cvt_pk_bf16_f32 v158, v170, v171
	v_cvt_pk_bf16_f32 v159, v174, v175
	global_store_dwordx4 v3, v[156:159], s[10:11] sc1
	v_add_u32_e32 v3, 0x2000, v3
	s_waitcnt vmcnt(31)
	v_lshlrev_b32_e32 v160, 16, v144
	v_and_b32_e32 v161, 0xffff0000, v144
	v_lshlrev_b32_e32 v162, 16, v128
	v_and_b32_e32 v163, 0xffff0000, v128
	v_lshlrev_b32_e32 v164, 16, v145
	v_and_b32_e32 v165, 0xffff0000, v145
	v_lshlrev_b32_e32 v166, 16, v129
	v_and_b32_e32 v167, 0xffff0000, v129
	v_lshlrev_b32_e32 v168, 16, v146
	v_and_b32_e32 v169, 0xffff0000, v146
	v_lshlrev_b32_e32 v170, 16, v130
	v_and_b32_e32 v171, 0xffff0000, v130
	v_lshlrev_b32_e32 v172, 16, v147
	v_and_b32_e32 v173, 0xffff0000, v147
	v_lshlrev_b32_e32 v174, 16, v131
	v_and_b32_e32 v175, 0xffff0000, v131
	v_pk_add_f32 v[162:163], v[160:161], v[162:163] neg_lo:[0,1] neg_hi:[0,1]
	v_pk_add_f32 v[166:167], v[164:165], v[166:167] neg_lo:[0,1] neg_hi:[0,1]
	v_pk_add_f32 v[170:171], v[168:169], v[170:171] neg_lo:[0,1] neg_hi:[0,1]
	v_pk_add_f32 v[174:175], v[172:173], v[174:175] neg_lo:[0,1] neg_hi:[0,1]
	v_pk_add_f32 v[148:149], v[148:149], v[162:163]
	v_pk_add_f32 v[150:151], v[150:151], v[166:167]
	v_pk_add_f32 v[152:153], v[152:153], v[170:171]
	v_pk_add_f32 v[154:155], v[154:155], v[174:175]
	v_fma_f32 v162, s43, v148, -v160
	v_fma_f32 v163, s43, v149, -v161
	v_fma_f32 v166, s43, v150, -v164
	v_fma_f32 v167, s43, v151, -v165
	v_fma_f32 v170, s43, v152, -v168
	v_fma_f32 v171, s43, v153, -v169
	v_fma_f32 v174, s43, v154, -v172
	v_fma_f32 v175, s43, v155, -v173
	v_cvt_pk_bf16_f32 v156, v162, v163
	v_cvt_pk_bf16_f32 v157, v166, v167
	v_cvt_pk_bf16_f32 v158, v170, v171
	v_cvt_pk_bf16_f32 v159, v174, v175
	global_store_dwordx4 v3, v[156:159], s[10:11] sc1
	s_branch .LBB0_441

; __device__ __forceinline__ float bf_lo(unsigned w) { return __uint_as_float(w << 16); }
; __device__ __forceinline__ float bf_hi(unsigned w) { return __uint_as_float(w & 0xffff0000u); }
; __device__ void phase_pool() {
;     ...
;         { u32x4 hv[16];
; #pragma unroll
;           for (int k = 1; k <= 16; ++k) hv[k - 1] = (k <= nh) ? *(const u32x4*)(uz + (size_t)(row0 - k) * DE2 + col) : (u32x4){0u, 0u, 0u, 0u};
; #pragma unroll
;           for (int k = 0; k < 16; ++k) { const u32x4 v = hv[k];
;             s[0] += bf_lo(v.x); s[1] += bf_hi(v.x); s[2] += bf_lo(v.y); s[3] += bf_hi(v.y); s[4] += bf_lo(v.z); s[5] += bf_hi(v.z); s[6] += bf_lo(v.w); s[7] += bf_hi(v.w); } }
; #pragma unroll 1
;         for (int r0 = 0; r0 < RB; r0 += 8) {
;             u32x4 vv[8], ov[8];
; #pragma unroll
;             for (int k = 0; k < 8; ++k) { const int row = row0 + r0 + k, tl = tl0 + r0 + k;
;                 vv[k] = *(const u32x4*)(uz + (size_t)row * DE2 + col);
;                 ov[k] = (tl >= w) ? *(const u32x4*)(uz + (size_t)(row - w) * DE2 + col) : (u32x4){0u, 0u, 0u, 0u}; }
.Lpool_w8_main:
	global_load_dwordx4 v[36:39], v2, s[8:9]
	v_add_u32_e32 v2, 0x4000, v2
	global_load_dwordx4 v[40:43], v2, s[8:9]
	v_add_u32_e32 v2, 0x4000, v2
	global_load_dwordx4 v[44:47], v2, s[8:9]
	v_add_u32_e32 v2, 0x4000, v2
	global_load_dwordx4 v[48:51], v2, s[8:9]
	v_add_u32_e32 v2, 0x4000, v2
	global_load_dwordx4 v[52:55], v2, s[8:9]
	v_add_u32_e32 v2, 0x4000, v2
	global_load_dwordx4 v[56:59], v2, s[8:9]
	v_add_u32_e32 v2, 0x4000, v2
	global_load_dwordx4 v[60:63], v2, s[8:9]
	v_add_u32_e32 v2, 0x4000, v2
	global_load_dwordx4 v[64:67], v2, s[8:9]
	v_add_u32_e32 v2, 0x4000, v2
	global_load_dwordx4 v[68:71], v2, s[8:9]
	v_add_u32_e32 v2, 0x4000, v2
	global_load_dwordx4 v[72:75], v2, s[8:9]
	v_add_u32_e32 v2, 0x4000, v2
	global_load_dwordx4 v[76:79], v2, s[8:9]
	v_add_u32_e32 v2, 0x4000, v2
	global_load_dwordx4 v[80:83], v2, s[8:9]
	v_add_u32_e32 v2, 0x4000, v2
	global_load_dwordx4 v[84:87], v2, s[8:9]
	v_add_u32_e32 v2, 0x4000, v2
	global_load_dwordx4 v[88:91], v2, s[8:9]
	v_add_u32_e32 v2, 0x4000, v2
	global_load_dwordx4 v[92:95], v2, s[8:9]
	v_add_u32_e32 v2, 0x4000, v2
	global_load_dwordx4 v[96:99], v2, s[8:9]
	v_add_u32_e32 v2, 0x4000, v2
	global_load_dwordx4 v[100:103], v2, s[8:9]
	v_add_u32_e32 v2, 0x4000, v2
	global_load_dwordx4 v[104:107], v2, s[8:9]
	v_add_u32_e32 v2, 0x4000, v2
	global_load_dwordx4 v[108:111], v2, s[8:9]
	v_add_u32_e32 v2, 0x4000, v2
	global_load_dwordx4 v[112:115], v2, s[8:9]
	v_add_u32_e32 v2, 0x4000, v2
	global_load_dwordx4 v[116:119], v2, s[8:9]
	v_add_u32_e32 v2, 0x4000, v2
	global_load_dwordx4 v[120:123], v2, s[8:9]
	v_add_u32_e32 v2, 0x4000, v2
	global_load_dwordx4 v[124:127], v2, s[8:9]
	v_add_u32_e32 v2, 0x4000, v2
	global_load_dwordx4 v[128:131], v2, s[8:9]
	v_add_u32_e32 v2, 0x4000, v2
	global_load_dwordx4 v[132:135], v2, s[8:9]
	v_add_u32_e32 v2, 0x4000, v2
	global_load_dwordx4 v[136:139], v2, s[8:9]
	v_add_u32_e32 v2, 0x4000, v2
	global_load_dwordx4 v[140:143], v2, s[8:9]
	v_add_u32_e32 v2, 0x4000, v2
	global_load_dwordx4 v[144:147], v2, s[8:9]
	v_add_u32_e32 v2, 0x4000, v2
	global_load_dwordx4 v[148:151], v2, s[8:9]
	v_add_u32_e32 v2, 0x4000, v2
	global_load_dwordx4 v[152:155], v2, s[8:9]
	v_add_u32_e32 v2, 0x4000, v2
	global_load_dwordx4 v[156:159], v2, s[8:9]
	v_add_u32_e32 v2, 0x4000, v2
	global_load_dwordx4 v[160:163], v2, s[8:9]
	v_mov_b32_e32 v164, 0
	v_mov_b32_e32 v165, 0
	v_mov_b32_e32 v166, 0
	v_mov_b32_e32 v167, 0
	v_mov_b32_e32 v168, 0
	v_mov_b32_e32 v169, 0
	v_mov_b32_e32 v170, 0
	v_mov_b32_e32 v171, 0
	s_mov_b32 s43, 0x3e000000
	s_cmp_eq_u32 s16, 0
	s_waitcnt vmcnt(32)
	v_lshlrev_b32_e32 v184, 16, v32
	v_and_b32_e32 v185, 0xffff0000, v32
	v_lshlrev_b32_e32 v188, 16, v33
	v_and_b32_e32 v189, 0xffff0000, v33
	v_lshlrev_b32_e32 v192, 16, v34
	v_and_b32_e32 v193, 0xffff0000, v34
	v_lshlrev_b32_e32 v196, 16, v35
	v_and_b32_e32 v197, 0xffff0000, v35
	v_pk_add_f32 v[164:165], v[164:165], v[184:185]
	v_pk_add_f32 v[166:167], v[166:167], v[188:189]
	v_pk_add_f32 v[168:169], v[168:169], v[192:193]
	v_pk_add_f32 v[170:171], v[170:171], v[196:197]
	v_lshlrev_b32_e32 v184, 16, v28
	v_and_b32_e32 v185, 0xffff0000, v28
	v_lshlrev_b32_e32 v188, 16, v29
	v_and_b32_e32 v189, 0xffff0000, v29
	v_lshlrev_b32_e32 v192, 16, v30
	v_and_b32_e32 v193, 0xffff0000, v30
	v_lshlrev_b32_e32 v196, 16, v31
	v_and_b32_e32 v197, 0xffff0000, v31
	v_pk_add_f32 v[164:165], v[164:165], v[184:185]
	v_pk_add_f32 v[166:167], v[166:167], v[188:189]
	v_pk_add_f32 v[168:169], v[168:169], v[192:193]
	v_pk_add_f32 v[170:171], v[170:171], v[196:197]
	v_lshlrev_b32_e32 v184, 16, v24
	v_and_b32_e32 v185, 0xffff0000, v24
	v_lshlrev_b32_e32 v188, 16, v25
	v_and_b32_e32 v189, 0xffff0000, v25
	v_lshlrev_b32_e32 v192, 16, v26
	v_and_b32_e32 v193, 0xffff0000, v26
	v_lshlrev_b32_e32 v196, 16, v27
	v_and_b32_e32 v197, 0xffff0000, v27
	v_pk_add_f32 v[164:165], v[164:165], v[184:185]
	v_pk_add_f32 v[166:167], v[166:167], v[188:189]
	v_pk_add_f32 v[168:169], v[168:169], v[192:193]
	v_pk_add_f32 v[170:171], v[170:171], v[196:197]
	v_lshlrev_b32_e32 v184, 16, v20
	v_and_b32_e32 v185, 0xffff0000, v20
	v_lshlrev_b32_e32 v188, 16, v21
	v_and_b32_e32 v189, 0xffff0000, v21
	v_lshlrev_b32_e32 v192, 16, v22
	v_and_b32_e32 v193, 0xffff0000, v22
	v_lshlrev_b32_e32 v196, 16, v23
	v_and_b32_e32 v197, 0xffff0000, v23
	v_pk_add_f32 v[164:165], v[164:165], v[184:185]
	v_pk_add_f32 v[166:167], v[166:167], v[188:189]
	v_pk_add_f32 v[168:169], v[168:169], v[192:193]
	v_pk_add_f32 v[170:171], v[170:171], v[196:197]
	v_lshlrev_b32_e32 v184, 16, v16
	v_and_b32_e32 v185, 0xffff0000, v16
	v_lshlrev_b32_e32 v188, 16, v17
	v_and_b32_e32 v189, 0xffff0000, v17
	v_lshlrev_b32_e32 v192, 16, v18
	v_and_b32_e32 v193, 0xffff0000, v18
	v_lshlrev_b32_e32 v196, 16, v19
	v_and_b32_e32 v197, 0xffff0000, v19
	v_pk_add_f32 v[164:165], v[164:165], v[184:185]
	v_pk_add_f32 v[166:167], v[166:167], v[188:189]
	v_pk_add_f32 v[168:169], v[168:169], v[192:193]
	v_pk_add_f32 v[170:171], v[170:171], v[196:197]
	v_lshlrev_b32_e32 v184, 16, v12
	v_and_b32_e32 v185, 0xffff0000, v12
	v_lshlrev_b32_e32 v188, 16, v13
	v_and_b32_e32 v189, 0xffff0000, v13
	v_lshlrev_b32_e32 v192, 16, v14
	v_and_b32_e32 v193, 0xffff0000, v14
	v_lshlrev_b32_e32 v196, 16, v15
	v_and_b32_e32 v197, 0xffff0000, v15
	v_pk_add_f32 v[164:165], v[164:165], v[184:185]
	v_pk_add_f32 v[166:167], v[166:167], v[188:189]
	v_pk_add_f32 v[168:169], v[168:169], v[192:193]
	v_pk_add_f32 v[170:171], v[170:171], v[196:197]
	v_lshlrev_b32_e32 v184, 16, v8
	v_and_b32_e32 v185, 0xffff0000, v8
	v_lshlrev_b32_e32 v188, 16, v9
	v_and_b32_e32 v189, 0xffff0000, v9
	v_lshlrev_b32_e32 v192, 16, v10
	v_and_b32_e32 v193, 0xffff0000, v10
	v_lshlrev_b32_e32 v196, 16, v11
	v_and_b32_e32 v197, 0xffff0000, v11
	v_pk_add_f32 v[164:165], v[164:165], v[184:185]
	v_pk_add_f32 v[166:167], v[166:167], v[188:189]
	v_pk_add_f32 v[168:169], v[168:169], v[192:193]
	v_pk_add_f32 v[170:171], v[170:171], v[196:197]
	v_lshlrev_b32_e32 v184, 16, v4
	v_and_b32_e32 v185, 0xffff0000, v4
	v_lshlrev_b32_e32 v188, 16, v5
	v_and_b32_e32 v189, 0xffff0000, v5
	v_lshlrev_b32_e32 v192, 16, v6
	v_and_b32_e32 v193, 0xffff0000, v6
	v_lshlrev_b32_e32 v196, 16, v7
	v_and_b32_e32 v197, 0xffff0000, v7
	v_pk_add_f32 v[164:165], v[164:165], v[184:185]
	v_pk_add_f32 v[166:167], v[166:167], v[188:189]
	v_pk_add_f32 v[168:169], v[168:169], v[192:193]
	v_pk_add_f32 v[170:171], v[170:171], v[196:197]
	s_waitcnt vmcnt(31)
; __device__ __forceinline__ unsigned cvt_pk_bf16(float lo, float hi) { unsigned r; asm volatile("v_cvt_pk_bf16_f32 %0, %1, %2" : "=v"(r) : "v"(lo), "v"(hi)); return r; }
; __device__ __forceinline__ float bf_lo(unsigned w) { return __uint_as_float(w << 16); }
; __device__ __forceinline__ float bf_hi(unsigned w) { return __uint_as_float(w & 0xffff0000u); }
; __device__ void phase_pool() {
;     ...
;             for (int k = 0; k < 8; ++k) { const int row = row0 + r0 + k, tl = tl0 + r0 + k; const u32x4 v = vv[k], o2 = ov[k];
;                 s[0] += bf_lo(v.x) - bf_lo(o2.x); s[1] += bf_hi(v.x) - bf_hi(o2.x); s[2] += bf_lo(v.y) - bf_lo(o2.y); s[3] += bf_hi(v.y) - bf_hi(o2.y);
;                 s[4] += bf_lo(v.z) - bf_lo(o2.z); s[5] += bf_hi(v.z) - bf_hi(o2.z); s[6] += bf_lo(v.w) - bf_lo(o2.w); s[7] += bf_hi(v.w) - bf_hi(o2.w);
;                 const float ic = 1.0f / (float)((tl + 1 < w) ? tl + 1 : w);
;                 u32x4 o;
;                 o.x = cvt_pk_bf16(s[0] * ic - bf_lo(v.x), s[1] * ic - bf_hi(v.x)); o.y = cvt_pk_bf16(s[2] * ic - bf_lo(v.y), s[3] * ic - bf_hi(v.y));
;                 o.z = cvt_pk_bf16(s[4] * ic - bf_lo(v.z), s[5] * ic - bf_hi(v.z)); o.w = cvt_pk_bf16(s[6] * ic - bf_lo(v.w), s[7] * ic - bf_hi(v.w));
;                 *(u32x4*)(pg + (size_t)row * DE + col) = o; }
	s_cselect_b32 s42, 0x3f800000, s43
	v_lshlrev_b32_e32 v184, 16, v36
	v_and_b32_e32 v185, 0xffff0000, v36
	v_lshlrev_b32_e32 v186, 16, v4
	v_and_b32_e32 v187, 0xffff0000, v4
	v_lshlrev_b32_e32 v188, 16, v37
	v_and_b32_e32 v189, 0xffff0000, v37
	v_lshlrev_b32_e32 v190, 16, v5
	v_and_b32_e32 v191, 0xffff0000, v5
	v_lshlrev_b32_e32 v192, 16, v38
	v_and_b32_e32 v193, 0xffff0000, v38
	v_lshlrev_b32_e32 v194, 16, v6
	v_and_b32_e32 v195, 0xffff0000, v6
	v_lshlrev_b32_e32 v196, 16, v39
	v_and_b32_e32 v197, 0xffff0000, v39
	v_lshlrev_b32_e32 v198, 16, v7
	v_and_b32_e32 v199, 0xffff0000, v7
	v_pk_add_f32 v[186:187], v[184:185], v[186:187] neg_lo:[0,1] neg_hi:[0,1]
	v_pk_add_f32 v[190:191], v[188:189], v[190:191] neg_lo:[0,1] neg_hi:[0,1]
	v_pk_add_f32 v[194:195], v[192:193], v[194:195] neg_lo:[0,1] neg_hi:[0,1]
	v_pk_add_f32 v[198:199], v[196:197], v[198:199] neg_lo:[0,1] neg_hi:[0,1]
	v_pk_add_f32 v[164:165], v[164:165], v[186:187]
	v_pk_add_f32 v[166:167], v[166:167], v[190:191]
	v_pk_add_f32 v[168:169], v[168:169], v[194:195]
	v_pk_add_f32 v[170:171], v[170:171], v[198:199]
	v_fma_f32 v186, s42, v164, -v184
	v_fma_f32 v187, s42, v165, -v185
	v_fma_f32 v190, s42, v166, -v188
	v_fma_f32 v191, s42, v167, -v189
	v_fma_f32 v194, s42, v168, -v192
	v_fma_f32 v195, s42, v169, -v193
	v_fma_f32 v198, s42, v170, -v196
	v_fma_f32 v199, s42, v171, -v197
	v_cvt_pk_bf16_f32 v172, v186, v187
	v_cvt_pk_bf16_f32 v173, v190, v191
	v_cvt_pk_bf16_f32 v174, v194, v195
	v_cvt_pk_bf16_f32 v175, v198, v199
	global_store_dwordx4 v3, v[172:175], s[10:11] sc1
	v_add_u32_e32 v3, 0x2000, v3
	s_waitcnt vmcnt(31)
	s_cselect_b32 s42, 0x3f000000, s43
	v_lshlrev_b32_e32 v184, 16, v40
	v_and_b32_e32 v185, 0xffff0000, v40
	v_lshlrev_b32_e32 v186, 16, v8
	v_and_b32_e32 v187, 0xffff0000, v8
	v_lshlrev_b32_e32 v188, 16, v41
	v_and_b32_e32 v189, 0xffff0000, v41
	v_lshlrev_b32_e32 v190, 16, v9
	v_and_b32_e32 v191, 0xffff0000, v9
	v_lshlrev_b32_e32 v192, 16, v42
	v_and_b32_e32 v193, 0xffff0000, v42
	v_lshlrev_b32_e32 v194, 16, v10
	v_and_b32_e32 v195, 0xffff0000, v10
	v_lshlrev_b32_e32 v196, 16, v43
	v_and_b32_e32 v197, 0xffff0000, v43
	v_lshlrev_b32_e32 v198, 16, v11
	v_and_b32_e32 v199, 0xffff0000, v11
	v_pk_add_f32 v[186:187], v[184:185], v[186:187] neg_lo:[0,1] neg_hi:[0,1]
	v_pk_add_f32 v[190:191], v[188:189], v[190:191] neg_lo:[0,1] neg_hi:[0,1]
	v_pk_add_f32 v[194:195], v[192:193], v[194:195] neg_lo:[0,1] neg_hi:[0,1]
	v_pk_add_f32 v[198:199], v[196:197], v[198:199] neg_lo:[0,1] neg_hi:[0,1]
	v_pk_add_f32 v[164:165], v[164:165], v[186:187]
	v_pk_add_f32 v[166:167], v[166:167], v[190:191]
	v_pk_add_f32 v[168:169], v[168:169], v[194:195]
	v_pk_add_f32 v[170:171], v[170:171], v[198:199]
	v_fma_f32 v186, s42, v164, -v184
	v_fma_f32 v187, s42, v165, -v185
	v_fma_f32 v190, s42, v166, -v188
	v_fma_f32 v191, s42, v167, -v189
	v_fma_f32 v194, s42, v168, -v192
	v_fma_f32 v195, s42, v169, -v193
	v_fma_f32 v198, s42, v170, -v196
	v_fma_f32 v199, s42, v171, -v197
	v_cvt_pk_bf16_f32 v172, v186, v187
	v_cvt_pk_bf16_f32 v173, v190, v191
	v_cvt_pk_bf16_f32 v174, v194, v195
	v_cvt_pk_bf16_f32 v175, v198, v199
	global_store_dwordx4 v3, v[172:175], s[10:11] sc1
	v_add_u32_e32 v3, 0x2000, v3
	s_waitcnt vmcnt(31)
	s_cselect_b32 s42, 0x3eaaaaab, s43
	v_lshlrev_b32_e32 v184, 16, v44
	v_and_b32_e32 v185, 0xffff0000, v44
	v_lshlrev_b32_e32 v186, 16, v12
	v_and_b32_e32 v187, 0xffff0000, v12
	v_lshlrev_b32_e32 v188, 16, v45
	v_and_b32_e32 v189, 0xffff0000, v45
	v_lshlrev_b32_e32 v190, 16, v13
	v_and_b32_e32 v191, 0xffff0000, v13
	v_lshlrev_b32_e32 v192, 16, v46
	v_and_b32_e32 v193, 0xffff0000, v46
	v_lshlrev_b32_e32 v194, 16, v14
	v_and_b32_e32 v195, 0xffff0000, v14
	v_lshlrev_b32_e32 v196, 16, v47
	v_and_b32_e32 v197, 0xffff0000, v47
	v_lshlrev_b32_e32 v198, 16, v15
	v_and_b32_e32 v199, 0xffff0000, v15
	v_pk_add_f32 v[186:187], v[184:185], v[186:187] neg_lo:[0,1] neg_hi:[0,1]
	v_pk_add_f32 v[190:191], v[188:189], v[190:191] neg_lo:[0,1] neg_hi:[0,1]
	v_pk_add_f32 v[194:195], v[192:193], v[194:195] neg_lo:[0,1] neg_hi:[0,1]
	v_pk_add_f32 v[198:199], v[196:197], v[198:199] neg_lo:[0,1] neg_hi:[0,1]
	v_pk_add_f32 v[164:165], v[164:165], v[186:187]
	v_pk_add_f32 v[166:167], v[166:167], v[190:191]
	v_pk_add_f32 v[168:169], v[168:169], v[194:195]
	v_pk_add_f32 v[170:171], v[170:171], v[198:199]
	v_fma_f32 v186, s42, v164, -v184
	v_fma_f32 v187, s42, v165, -v185
	v_fma_f32 v190, s42, v166, -v188
	v_fma_f32 v191, s42, v167, -v189
	v_fma_f32 v194, s42, v168, -v192
	v_fma_f32 v195, s42, v169, -v193
	v_fma_f32 v198, s42, v170, -v196
	v_fma_f32 v199, s42, v171, -v197
	v_cvt_pk_bf16_f32 v172, v186, v187
	v_cvt_pk_bf16_f32 v173, v190, v191
	v_cvt_pk_bf16_f32 v174, v194, v195
	v_cvt_pk_bf16_f32 v175, v198, v199
	global_store_dwordx4 v3, v[172:175], s[10:11] sc1
	v_add_u32_e32 v3, 0x2000, v3
	s_waitcnt vmcnt(31)
	s_cselect_b32 s42, 0x3e800000, s43
	v_lshlrev_b32_e32 v184, 16, v48
	v_and_b32_e32 v185, 0xffff0000, v48
	v_lshlrev_b32_e32 v186, 16, v16
	v_and_b32_e32 v187, 0xffff0000, v16
	v_lshlrev_b32_e32 v188, 16, v49
	v_and_b32_e32 v189, 0xffff0000, v49
	v_lshlrev_b32_e32 v190, 16, v17
	v_and_b32_e32 v191, 0xffff0000, v17
	v_lshlrev_b32_e32 v192, 16, v50
	v_and_b32_e32 v193, 0xffff0000, v50
	v_lshlrev_b32_e32 v194, 16, v18
	v_and_b32_e32 v195, 0xffff0000, v18
	v_lshlrev_b32_e32 v196, 16, v51
	v_and_b32_e32 v197, 0xffff0000, v51
	v_lshlrev_b32_e32 v198, 16, v19
	v_and_b32_e32 v199, 0xffff0000, v19
	v_pk_add_f32 v[186:187], v[184:185], v[186:187] neg_lo:[0,1] neg_hi:[0,1]
	v_pk_add_f32 v[190:191], v[188:189], v[190:191] neg_lo:[0,1] neg_hi:[0,1]
	v_pk_add_f32 v[194:195], v[192:193], v[194:195] neg_lo:[0,1] neg_hi:[0,1]
	v_pk_add_f32 v[198:199], v[196:197], v[198:199] neg_lo:[0,1] neg_hi:[0,1]
	v_pk_add_f32 v[164:165], v[164:165], v[186:187]
	v_pk_add_f32 v[166:167], v[166:167], v[190:191]
	v_pk_add_f32 v[168:169], v[168:169], v[194:195]
	v_pk_add_f32 v[170:171], v[170:171], v[198:199]
	v_fma_f32 v186, s42, v164, -v184
	v_fma_f32 v187, s42, v165, -v185
	v_fma_f32 v190, s42, v166, -v188
	v_fma_f32 v191, s42, v167, -v189
	v_fma_f32 v194, s42, v168, -v192
	v_fma_f32 v195, s42, v169, -v193
	v_fma_f32 v198, s42, v170, -v196
	v_fma_f32 v199, s42, v171, -v197
	v_cvt_pk_bf16_f32 v172, v186, v187
	v_cvt_pk_bf16_f32 v173, v190, v191
	v_cvt_pk_bf16_f32 v174, v194, v195
	v_cvt_pk_bf16_f32 v175, v198, v199
	global_store_dwordx4 v3, v[172:175], s[10:11] sc1
	v_add_u32_e32 v3, 0x2000, v3
	s_waitcnt vmcnt(31)
; __device__ __forceinline__ unsigned cvt_pk_bf16(float lo, float hi) { unsigned r; asm volatile("v_cvt_pk_bf16_f32 %0, %1, %2" : "=v"(r) : "v"(lo), "v"(hi)); return r; }
; __device__ __forceinline__ float bf_lo(unsigned w) { return __uint_as_float(w << 16); }
; __device__ __forceinline__ float bf_hi(unsigned w) { return __uint_as_float(w & 0xffff0000u); }
; __device__ void phase_pool() {
;     ...
;             for (int k = 0; k < 8; ++k) { const int row = row0 + r0 + k, tl = tl0 + r0 + k; const u32x4 v = vv[k], o2 = ov[k];
;                 s[0] += bf_lo(v.x) - bf_lo(o2.x); s[1] += bf_hi(v.x) - bf_hi(o2.x); s[2] += bf_lo(v.y) - bf_lo(o2.y); s[3] += bf_hi(v.y) - bf_hi(o2.y);
;                 s[4] += bf_lo(v.z) - bf_lo(o2.z); s[5] += bf_hi(v.z) - bf_hi(o2.z); s[6] += bf_lo(v.w) - bf_lo(o2.w); s[7] += bf_hi(v.w) - bf_hi(o2.w);
;                 const float ic = 1.0f / (float)((tl + 1 < w) ? tl + 1 : w);
;                 u32x4 o;
;                 o.x = cvt_pk_bf16(s[0] * ic - bf_lo(v.x), s[1] * ic - bf_hi(v.x)); o.y = cvt_pk_bf16(s[2] * ic - bf_lo(v.y), s[3] * ic - bf_hi(v.y));
;                 o.z = cvt_pk_bf16(s[4] * ic - bf_lo(v.z), s[5] * ic - bf_hi(v.z)); o.w = cvt_pk_bf16(s[6] * ic - bf_lo(v.w), s[7] * ic - bf_hi(v.w));
;                 *(u32x4*)(pg + (size_t)row * DE + col) = o; }
	s_cselect_b32 s42, 0x3e4ccccd, s43
	v_lshlrev_b32_e32 v184, 16, v52
	v_and_b32_e32 v185, 0xffff0000, v52
	v_lshlrev_b32_e32 v186, 16, v20
	v_and_b32_e32 v187, 0xffff0000, v20
	v_lshlrev_b32_e32 v188, 16, v53
	v_and_b32_e32 v189, 0xffff0000, v53
	v_lshlrev_b32_e32 v190, 16, v21
	v_and_b32_e32 v191, 0xffff0000, v21
	v_lshlrev_b32_e32 v192, 16, v54
	v_and_b32_e32 v193, 0xffff0000, v54
	v_lshlrev_b32_e32 v194, 16, v22
	v_and_b32_e32 v195, 0xffff0000, v22
	v_lshlrev_b32_e32 v196, 16, v55
	v_and_b32_e32 v197, 0xffff0000, v55
	v_lshlrev_b32_e32 v198, 16, v23
	v_and_b32_e32 v199, 0xffff0000, v23
	v_pk_add_f32 v[186:187], v[184:185], v[186:187] neg_lo:[0,1] neg_hi:[0,1]
	v_pk_add_f32 v[190:191], v[188:189], v[190:191] neg_lo:[0,1] neg_hi:[0,1]
	v_pk_add_f32 v[194:195], v[192:193], v[194:195] neg_lo:[0,1] neg_hi:[0,1]
	v_pk_add_f32 v[198:199], v[196:197], v[198:199] neg_lo:[0,1] neg_hi:[0,1]
	v_pk_add_f32 v[164:165], v[164:165], v[186:187]
	v_pk_add_f32 v[166:167], v[166:167], v[190:191]
	v_pk_add_f32 v[168:169], v[168:169], v[194:195]
	v_pk_add_f32 v[170:171], v[170:171], v[198:199]
	v_fma_f32 v186, s42, v164, -v184
	v_fma_f32 v187, s42, v165, -v185
	v_fma_f32 v190, s42, v166, -v188
	v_fma_f32 v191, s42, v167, -v189
	v_fma_f32 v194, s42, v168, -v192
	v_fma_f32 v195, s42, v169, -v193
	v_fma_f32 v198, s42, v170, -v196
	v_fma_f32 v199, s42, v171, -v197
	v_cvt_pk_bf16_f32 v172, v186, v187
	v_cvt_pk_bf16_f32 v173, v190, v191
	v_cvt_pk_bf16_f32 v174, v194, v195
	v_cvt_pk_bf16_f32 v175, v198, v199
	global_store_dwordx4 v3, v[172:175], s[10:11] sc1
	v_add_u32_e32 v3, 0x2000, v3
	s_waitcnt vmcnt(31)
	s_cselect_b32 s42, 0x3e2aaaab, s43
	v_lshlrev_b32_e32 v184, 16, v56
	v_and_b32_e32 v185, 0xffff0000, v56
	v_lshlrev_b32_e32 v186, 16, v24
	v_and_b32_e32 v187, 0xffff0000, v24
	v_lshlrev_b32_e32 v188, 16, v57
	v_and_b32_e32 v189, 0xffff0000, v57
	v_lshlrev_b32_e32 v190, 16, v25
	v_and_b32_e32 v191, 0xffff0000, v25
	v_lshlrev_b32_e32 v192, 16, v58
	v_and_b32_e32 v193, 0xffff0000, v58
	v_lshlrev_b32_e32 v194, 16, v26
	v_and_b32_e32 v195, 0xffff0000, v26
	v_lshlrev_b32_e32 v196, 16, v59
	v_and_b32_e32 v197, 0xffff0000, v59
	v_lshlrev_b32_e32 v198, 16, v27
	v_and_b32_e32 v199, 0xffff0000, v27
	v_pk_add_f32 v[186:187], v[184:185], v[186:187] neg_lo:[0,1] neg_hi:[0,1]
	v_pk_add_f32 v[190:191], v[188:189], v[190:191] neg_lo:[0,1] neg_hi:[0,1]
	v_pk_add_f32 v[194:195], v[192:193], v[194:195] neg_lo:[0,1] neg_hi:[0,1]
	v_pk_add_f32 v[198:199], v[196:197], v[198:199] neg_lo:[0,1] neg_hi:[0,1]
	v_pk_add_f32 v[164:165], v[164:165], v[186:187]
	v_pk_add_f32 v[166:167], v[166:167], v[190:191]
	v_pk_add_f32 v[168:169], v[168:169], v[194:195]
	v_pk_add_f32 v[170:171], v[170:171], v[198:199]
	v_fma_f32 v186, s42, v164, -v184
	v_fma_f32 v187, s42, v165, -v185
	v_fma_f32 v190, s42, v166, -v188
	v_fma_f32 v191, s42, v167, -v189
	v_fma_f32 v194, s42, v168, -v192
	v_fma_f32 v195, s42, v169, -v193
	v_fma_f32 v198, s42, v170, -v196
	v_fma_f32 v199, s42, v171, -v197
	v_cvt_pk_bf16_f32 v172, v186, v187
	v_cvt_pk_bf16_f32 v173, v190, v191
	v_cvt_pk_bf16_f32 v174, v194, v195
	v_cvt_pk_bf16_f32 v175, v198, v199
	global_store_dwordx4 v3, v[172:175], s[10:11] sc1
	v_add_u32_e32 v3, 0x2000, v3
	s_waitcnt vmcnt(31)
	s_cselect_b32 s42, 0x3e124925, s43
	v_lshlrev_b32_e32 v184, 16, v60
	v_and_b32_e32 v185, 0xffff0000, v60
	v_lshlrev_b32_e32 v186, 16, v28
	v_and_b32_e32 v187, 0xffff0000, v28
	v_lshlrev_b32_e32 v188, 16, v61
	v_and_b32_e32 v189, 0xffff0000, v61
	v_lshlrev_b32_e32 v190, 16, v29
	v_and_b32_e32 v191, 0xffff0000, v29
	v_lshlrev_b32_e32 v192, 16, v62
	v_and_b32_e32 v193, 0xffff0000, v62
	v_lshlrev_b32_e32 v194, 16, v30
	v_and_b32_e32 v195, 0xffff0000, v30
	v_lshlrev_b32_e32 v196, 16, v63
	v_and_b32_e32 v197, 0xffff0000, v63
	v_lshlrev_b32_e32 v198, 16, v31
	v_and_b32_e32 v199, 0xffff0000, v31
	v_pk_add_f32 v[186:187], v[184:185], v[186:187] neg_lo:[0,1] neg_hi:[0,1]
	v_pk_add_f32 v[190:191], v[188:189], v[190:191] neg_lo:[0,1] neg_hi:[0,1]
	v_pk_add_f32 v[194:195], v[192:193], v[194:195] neg_lo:[0,1] neg_hi:[0,1]
	v_pk_add_f32 v[198:199], v[196:197], v[198:199] neg_lo:[0,1] neg_hi:[0,1]
	v_pk_add_f32 v[164:165], v[164:165], v[186:187]
	v_pk_add_f32 v[166:167], v[166:167], v[190:191]
	v_pk_add_f32 v[168:169], v[168:169], v[194:195]
	v_pk_add_f32 v[170:171], v[170:171], v[198:199]
	v_fma_f32 v186, s42, v164, -v184
	v_fma_f32 v187, s42, v165, -v185
	v_fma_f32 v190, s42, v166, -v188
	v_fma_f32 v191, s42, v167, -v189
	v_fma_f32 v194, s42, v168, -v192
	v_fma_f32 v195, s42, v169, -v193
	v_fma_f32 v198, s42, v170, -v196
	v_fma_f32 v199, s42, v171, -v197
	v_cvt_pk_bf16_f32 v172, v186, v187
	v_cvt_pk_bf16_f32 v173, v190, v191
	v_cvt_pk_bf16_f32 v174, v194, v195
	v_cvt_pk_bf16_f32 v175, v198, v199
	global_store_dwordx4 v3, v[172:175], s[10:11] sc1
	v_add_u32_e32 v3, 0x2000, v3
	s_waitcnt vmcnt(31)
	v_lshlrev_b32_e32 v184, 16, v64
	v_and_b32_e32 v185, 0xffff0000, v64
	v_lshlrev_b32_e32 v186, 16, v32
	v_and_b32_e32 v187, 0xffff0000, v32
	v_lshlrev_b32_e32 v188, 16, v65
	v_and_b32_e32 v189, 0xffff0000, v65
	v_lshlrev_b32_e32 v190, 16, v33
	v_and_b32_e32 v191, 0xffff0000, v33
	v_lshlrev_b32_e32 v192, 16, v66
	v_and_b32_e32 v193, 0xffff0000, v66
	v_lshlrev_b32_e32 v194, 16, v34
	v_and_b32_e32 v195, 0xffff0000, v34
	v_lshlrev_b32_e32 v196, 16, v67
	v_and_b32_e32 v197, 0xffff0000, v67
	v_lshlrev_b32_e32 v198, 16, v35
	v_and_b32_e32 v199, 0xffff0000, v35
	v_pk_add_f32 v[186:187], v[184:185], v[186:187] neg_lo:[0,1] neg_hi:[0,1]
	v_pk_add_f32 v[190:191], v[188:189], v[190:191] neg_lo:[0,1] neg_hi:[0,1]
	v_pk_add_f32 v[194:195], v[192:193], v[194:195] neg_lo:[0,1] neg_hi:[0,1]
	v_pk_add_f32 v[198:199], v[196:197], v[198:199] neg_lo:[0,1] neg_hi:[0,1]
	v_pk_add_f32 v[164:165], v[164:165], v[186:187]
	v_pk_add_f32 v[166:167], v[166:167], v[190:191]
	v_pk_add_f32 v[168:169], v[168:169], v[194:195]
	v_pk_add_f32 v[170:171], v[170:171], v[198:199]
	v_fma_f32 v186, s43, v164, -v184
	v_fma_f32 v187, s43, v165, -v185
	v_fma_f32 v190, s43, v166, -v188
	v_fma_f32 v191, s43, v167, -v189
	v_fma_f32 v194, s43, v168, -v192
	v_fma_f32 v195, s43, v169, -v193
	v_fma_f32 v198, s43, v170, -v196
	v_fma_f32 v199, s43, v171, -v197
	v_cvt_pk_bf16_f32 v172, v186, v187
	v_cvt_pk_bf16_f32 v173, v190, v191
	v_cvt_pk_bf16_f32 v174, v194, v195
	v_cvt_pk_bf16_f32 v175, v198, v199
	global_store_dwordx4 v3, v[172:175], s[10:11] sc1
	v_add_u32_e32 v3, 0x2000, v3
	s_waitcnt vmcnt(31)
; __device__ __forceinline__ unsigned cvt_pk_bf16(float lo, float hi) { unsigned r; asm volatile("v_cvt_pk_bf16_f32 %0, %1, %2" : "=v"(r) : "v"(lo), "v"(hi)); return r; }
; __device__ __forceinline__ float bf_lo(unsigned w) { return __uint_as_float(w << 16); }
; __device__ __forceinline__ float bf_hi(unsigned w) { return __uint_as_float(w & 0xffff0000u); }
; __device__ void phase_pool() {
;     ...
;             for (int k = 0; k < 8; ++k) { const int row = row0 + r0 + k, tl = tl0 + r0 + k; const u32x4 v = vv[k], o2 = ov[k];
;                 s[0] += bf_lo(v.x) - bf_lo(o2.x); s[1] += bf_hi(v.x) - bf_hi(o2.x); s[2] += bf_lo(v.y) - bf_lo(o2.y); s[3] += bf_hi(v.y) - bf_hi(o2.y);
;                 s[4] += bf_lo(v.z) - bf_lo(o2.z); s[5] += bf_hi(v.z) - bf_hi(o2.z); s[6] += bf_lo(v.w) - bf_lo(o2.w); s[7] += bf_hi(v.w) - bf_hi(o2.w);
;                 const float ic = 1.0f / (float)((tl + 1 < w) ? tl + 1 : w);
;                 u32x4 o;
;                 o.x = cvt_pk_bf16(s[0] * ic - bf_lo(v.x), s[1] * ic - bf_hi(v.x)); o.y = cvt_pk_bf16(s[2] * ic - bf_lo(v.y), s[3] * ic - bf_hi(v.y));
;                 o.z = cvt_pk_bf16(s[4] * ic - bf_lo(v.z), s[5] * ic - bf_hi(v.z)); o.w = cvt_pk_bf16(s[6] * ic - bf_lo(v.w), s[7] * ic - bf_hi(v.w));
;                 *(u32x4*)(pg + (size_t)row * DE + col) = o; }
	v_lshlrev_b32_e32 v184, 16, v68
	v_and_b32_e32 v185, 0xffff0000, v68
	v_lshlrev_b32_e32 v186, 16, v36
	v_and_b32_e32 v187, 0xffff0000, v36
	v_lshlrev_b32_e32 v188, 16, v69
	v_and_b32_e32 v189, 0xffff0000, v69
	v_lshlrev_b32_e32 v190, 16, v37
	v_and_b32_e32 v191, 0xffff0000, v37
	v_lshlrev_b32_e32 v192, 16, v70
	v_and_b32_e32 v193, 0xffff0000, v70
	v_lshlrev_b32_e32 v194, 16, v38
	v_and_b32_e32 v195, 0xffff0000, v38
	v_lshlrev_b32_e32 v196, 16, v71
	v_and_b32_e32 v197, 0xffff0000, v71
	v_lshlrev_b32_e32 v198, 16, v39
	v_and_b32_e32 v199, 0xffff0000, v39
	v_pk_add_f32 v[186:187], v[184:185], v[186:187] neg_lo:[0,1] neg_hi:[0,1]
	v_pk_add_f32 v[190:191], v[188:189], v[190:191] neg_lo:[0,1] neg_hi:[0,1]
	v_pk_add_f32 v[194:195], v[192:193], v[194:195] neg_lo:[0,1] neg_hi:[0,1]
	v_pk_add_f32 v[198:199], v[196:197], v[198:199] neg_lo:[0,1] neg_hi:[0,1]
	v_pk_add_f32 v[164:165], v[164:165], v[186:187]
	v_pk_add_f32 v[166:167], v[166:167], v[190:191]
	v_pk_add_f32 v[168:169], v[168:169], v[194:195]
	v_pk_add_f32 v[170:171], v[170:171], v[198:199]
	v_fma_f32 v186, s43, v164, -v184
	v_fma_f32 v187, s43, v165, -v185
	v_fma_f32 v190, s43, v166, -v188
	v_fma_f32 v191, s43, v167, -v189
	v_fma_f32 v194, s43, v168, -v192
	v_fma_f32 v195, s43, v169, -v193
	v_fma_f32 v198, s43, v170, -v196
	v_fma_f32 v199, s43, v171, -v197
	v_cvt_pk_bf16_f32 v172, v186, v187
	v_cvt_pk_bf16_f32 v173, v190, v191
	v_cvt_pk_bf16_f32 v174, v194, v195
	v_cvt_pk_bf16_f32 v175, v198, v199
	global_store_dwordx4 v3, v[172:175], s[10:11] sc1
	v_add_u32_e32 v3, 0x2000, v3
	s_waitcnt vmcnt(31)
	v_lshlrev_b32_e32 v184, 16, v72
	v_and_b32_e32 v185, 0xffff0000, v72
	v_lshlrev_b32_e32 v186, 16, v40
	v_and_b32_e32 v187, 0xffff0000, v40
	v_lshlrev_b32_e32 v188, 16, v73
	v_and_b32_e32 v189, 0xffff0000, v73
	v_lshlrev_b32_e32 v190, 16, v41
	v_and_b32_e32 v191, 0xffff0000, v41
	v_lshlrev_b32_e32 v192, 16, v74
	v_and_b32_e32 v193, 0xffff0000, v74
	v_lshlrev_b32_e32 v194, 16, v42
	v_and_b32_e32 v195, 0xffff0000, v42
	v_lshlrev_b32_e32 v196, 16, v75
	v_and_b32_e32 v197, 0xffff0000, v75
	v_lshlrev_b32_e32 v198, 16, v43
	v_and_b32_e32 v199, 0xffff0000, v43
	v_pk_add_f32 v[186:187], v[184:185], v[186:187] neg_lo:[0,1] neg_hi:[0,1]
	v_pk_add_f32 v[190:191], v[188:189], v[190:191] neg_lo:[0,1] neg_hi:[0,1]
	v_pk_add_f32 v[194:195], v[192:193], v[194:195] neg_lo:[0,1] neg_hi:[0,1]
	v_pk_add_f32 v[198:199], v[196:197], v[198:199] neg_lo:[0,1] neg_hi:[0,1]
	v_pk_add_f32 v[164:165], v[164:165], v[186:187]
	v_pk_add_f32 v[166:167], v[166:167], v[190:191]
	v_pk_add_f32 v[168:169], v[168:169], v[194:195]
	v_pk_add_f32 v[170:171], v[170:171], v[198:199]
	v_fma_f32 v186, s43, v164, -v184
	v_fma_f32 v187, s43, v165, -v185
	v_fma_f32 v190, s43, v166, -v188
	v_fma_f32 v191, s43, v167, -v189
	v_fma_f32 v194, s43, v168, -v192
	v_fma_f32 v195, s43, v169, -v193
	v_fma_f32 v198, s43, v170, -v196
	v_fma_f32 v199, s43, v171, -v197
	v_cvt_pk_bf16_f32 v172, v186, v187
	v_cvt_pk_bf16_f32 v173, v190, v191
	v_cvt_pk_bf16_f32 v174, v194, v195
	v_cvt_pk_bf16_f32 v175, v198, v199
	global_store_dwordx4 v3, v[172:175], s[10:11] sc1
	v_add_u32_e32 v3, 0x2000, v3
	s_waitcnt vmcnt(31)
	v_lshlrev_b32_e32 v184, 16, v76
	v_and_b32_e32 v185, 0xffff0000, v76
	v_lshlrev_b32_e32 v186, 16, v44
	v_and_b32_e32 v187, 0xffff0000, v44
	v_lshlrev_b32_e32 v188, 16, v77
	v_and_b32_e32 v189, 0xffff0000, v77
	v_lshlrev_b32_e32 v190, 16, v45
	v_and_b32_e32 v191, 0xffff0000, v45
	v_lshlrev_b32_e32 v192, 16, v78
	v_and_b32_e32 v193, 0xffff0000, v78
	v_lshlrev_b32_e32 v194, 16, v46
	v_and_b32_e32 v195, 0xffff0000, v46
	v_lshlrev_b32_e32 v196, 16, v79
	v_and_b32_e32 v197, 0xffff0000, v79
	v_lshlrev_b32_e32 v198, 16, v47
	v_and_b32_e32 v199, 0xffff0000, v47
	v_pk_add_f32 v[186:187], v[184:185], v[186:187] neg_lo:[0,1] neg_hi:[0,1]
	v_pk_add_f32 v[190:191], v[188:189], v[190:191] neg_lo:[0,1] neg_hi:[0,1]
	v_pk_add_f32 v[194:195], v[192:193], v[194:195] neg_lo:[0,1] neg_hi:[0,1]
	v_pk_add_f32 v[198:199], v[196:197], v[198:199] neg_lo:[0,1] neg_hi:[0,1]
	v_pk_add_f32 v[164:165], v[164:165], v[186:187]
	v_pk_add_f32 v[166:167], v[166:167], v[190:191]
	v_pk_add_f32 v[168:169], v[168:169], v[194:195]
	v_pk_add_f32 v[170:171], v[170:171], v[198:199]
	v_fma_f32 v186, s43, v164, -v184
	v_fma_f32 v187, s43, v165, -v185
	v_fma_f32 v190, s43, v166, -v188
	v_fma_f32 v191, s43, v167, -v189
	v_fma_f32 v194, s43, v168, -v192
	v_fma_f32 v195, s43, v169, -v193
	v_fma_f32 v198, s43, v170, -v196
	v_fma_f32 v199, s43, v171, -v197
	v_cvt_pk_bf16_f32 v172, v186, v187
	v_cvt_pk_bf16_f32 v173, v190, v191
	v_cvt_pk_bf16_f32 v174, v194, v195
	v_cvt_pk_bf16_f32 v175, v198, v199
	global_store_dwordx4 v3, v[172:175], s[10:11] sc1
	v_add_u32_e32 v3, 0x2000, v3
	s_waitcnt vmcnt(31)
	v_lshlrev_b32_e32 v184, 16, v80
	v_and_b32_e32 v185, 0xffff0000, v80
	v_lshlrev_b32_e32 v186, 16, v48
	v_and_b32_e32 v187, 0xffff0000, v48
	v_lshlrev_b32_e32 v188, 16, v81
	v_and_b32_e32 v189, 0xffff0000, v81
	v_lshlrev_b32_e32 v190, 16, v49
	v_and_b32_e32 v191, 0xffff0000, v49
	v_lshlrev_b32_e32 v192, 16, v82
	v_and_b32_e32 v193, 0xffff0000, v82
	v_lshlrev_b32_e32 v194, 16, v50
	v_and_b32_e32 v195, 0xffff0000, v50
	v_lshlrev_b32_e32 v196, 16, v83
	v_and_b32_e32 v197, 0xffff0000, v83
	v_lshlrev_b32_e32 v198, 16, v51
	v_and_b32_e32 v199, 0xffff0000, v51
	v_pk_add_f32 v[186:187], v[184:185], v[186:187] neg_lo:[0,1] neg_hi:[0,1]
	v_pk_add_f32 v[190:191], v[188:189], v[190:191] neg_lo:[0,1] neg_hi:[0,1]
	v_pk_add_f32 v[194:195], v[192:193], v[194:195] neg_lo:[0,1] neg_hi:[0,1]
	v_pk_add_f32 v[198:199], v[196:197], v[198:199] neg_lo:[0,1] neg_hi:[0,1]
	v_pk_add_f32 v[164:165], v[164:165], v[186:187]
	v_pk_add_f32 v[166:167], v[166:167], v[190:191]
	v_pk_add_f32 v[168:169], v[168:169], v[194:195]
	v_pk_add_f32 v[170:171], v[170:171], v[198:199]
	v_fma_f32 v186, s43, v164, -v184
	v_fma_f32 v187, s43, v165, -v185
	v_fma_f32 v190, s43, v166, -v188
	v_fma_f32 v191, s43, v167, -v189
	v_fma_f32 v194, s43, v168, -v192
	v_fma_f32 v195, s43, v169, -v193
	v_fma_f32 v198, s43, v170, -v196
	v_fma_f32 v199, s43, v171, -v197
	v_cvt_pk_bf16_f32 v172, v186, v187
	v_cvt_pk_bf16_f32 v173, v190, v191
	v_cvt_pk_bf16_f32 v174, v194, v195
	v_cvt_pk_bf16_f32 v175, v198, v199
	global_store_dwordx4 v3, v[172:175], s[10:11] sc1
	v_add_u32_e32 v3, 0x2000, v3
	s_waitcnt vmcnt(31)
; __device__ __forceinline__ unsigned cvt_pk_bf16(float lo, float hi) { unsigned r; asm volatile("v_cvt_pk_bf16_f32 %0, %1, %2" : "=v"(r) : "v"(lo), "v"(hi)); return r; }
; __device__ __forceinline__ float bf_lo(unsigned w) { return __uint_as_float(w << 16); }
; __device__ __forceinline__ float bf_hi(unsigned w) { return __uint_as_float(w & 0xffff0000u); }
; __device__ void phase_pool() {
;     ...
;             for (int k = 0; k < 8; ++k) { const int row = row0 + r0 + k, tl = tl0 + r0 + k; const u32x4 v = vv[k], o2 = ov[k];
;                 s[0] += bf_lo(v.x) - bf_lo(o2.x); s[1] += bf_hi(v.x) - bf_hi(o2.x); s[2] += bf_lo(v.y) - bf_lo(o2.y); s[3] += bf_hi(v.y) - bf_hi(o2.y);
;                 s[4] += bf_lo(v.z) - bf_lo(o2.z); s[5] += bf_hi(v.z) - bf_hi(o2.z); s[6] += bf_lo(v.w) - bf_lo(o2.w); s[7] += bf_hi(v.w) - bf_hi(o2.w);
;                 const float ic = 1.0f / (float)((tl + 1 < w) ? tl + 1 : w);
;                 u32x4 o;
;                 o.x = cvt_pk_bf16(s[0] * ic - bf_lo(v.x), s[1] * ic - bf_hi(v.x)); o.y = cvt_pk_bf16(s[2] * ic - bf_lo(v.y), s[3] * ic - bf_hi(v.y));
;                 o.z = cvt_pk_bf16(s[4] * ic - bf_lo(v.z), s[5] * ic - bf_hi(v.z)); o.w = cvt_pk_bf16(s[6] * ic - bf_lo(v.w), s[7] * ic - bf_hi(v.w));
;                 *(u32x4*)(pg + (size_t)row * DE + col) = o; }
	v_lshlrev_b32_e32 v184, 16, v84
	v_and_b32_e32 v185, 0xffff0000, v84
	v_lshlrev_b32_e32 v186, 16, v52
	v_and_b32_e32 v187, 0xffff0000, v52
	v_lshlrev_b32_e32 v188, 16, v85
	v_and_b32_e32 v189, 0xffff0000, v85
	v_lshlrev_b32_e32 v190, 16, v53
	v_and_b32_e32 v191, 0xffff0000, v53
	v_lshlrev_b32_e32 v192, 16, v86
	v_and_b32_e32 v193, 0xffff0000, v86
	v_lshlrev_b32_e32 v194, 16, v54
	v_and_b32_e32 v195, 0xffff0000, v54
	v_lshlrev_b32_e32 v196, 16, v87
	v_and_b32_e32 v197, 0xffff0000, v87
	v_lshlrev_b32_e32 v198, 16, v55
	v_and_b32_e32 v199, 0xffff0000, v55
	v_pk_add_f32 v[186:187], v[184:185], v[186:187] neg_lo:[0,1] neg_hi:[0,1]
	v_pk_add_f32 v[190:191], v[188:189], v[190:191] neg_lo:[0,1] neg_hi:[0,1]
	v_pk_add_f32 v[194:195], v[192:193], v[194:195] neg_lo:[0,1] neg_hi:[0,1]
	v_pk_add_f32 v[198:199], v[196:197], v[198:199] neg_lo:[0,1] neg_hi:[0,1]
	v_pk_add_f32 v[164:165], v[164:165], v[186:187]
	v_pk_add_f32 v[166:167], v[166:167], v[190:191]
	v_pk_add_f32 v[168:169], v[168:169], v[194:195]
	v_pk_add_f32 v[170:171], v[170:171], v[198:199]
	v_fma_f32 v186, s43, v164, -v184
	v_fma_f32 v187, s43, v165, -v185
	v_fma_f32 v190, s43, v166, -v188
	v_fma_f32 v191, s43, v167, -v189
	v_fma_f32 v194, s43, v168, -v192
	v_fma_f32 v195, s43, v169, -v193
	v_fma_f32 v198, s43, v170, -v196
	v_fma_f32 v199, s43, v171, -v197
	v_cvt_pk_bf16_f32 v172, v186, v187
	v_cvt_pk_bf16_f32 v173, v190, v191
	v_cvt_pk_bf16_f32 v174, v194, v195
	v_cvt_pk_bf16_f32 v175, v198, v199
	global_store_dwordx4 v3, v[172:175], s[10:11] sc1
	v_add_u32_e32 v3, 0x2000, v3
	s_waitcnt vmcnt(31)
	v_lshlrev_b32_e32 v184, 16, v88
	v_and_b32_e32 v185, 0xffff0000, v88
	v_lshlrev_b32_e32 v186, 16, v56
	v_and_b32_e32 v187, 0xffff0000, v56
	v_lshlrev_b32_e32 v188, 16, v89
	v_and_b32_e32 v189, 0xffff0000, v89
	v_lshlrev_b32_e32 v190, 16, v57
	v_and_b32_e32 v191, 0xffff0000, v57
	v_lshlrev_b32_e32 v192, 16, v90
	v_and_b32_e32 v193, 0xffff0000, v90
	v_lshlrev_b32_e32 v194, 16, v58
	v_and_b32_e32 v195, 0xffff0000, v58
	v_lshlrev_b32_e32 v196, 16, v91
	v_and_b32_e32 v197, 0xffff0000, v91
	v_lshlrev_b32_e32 v198, 16, v59
	v_and_b32_e32 v199, 0xffff0000, v59
	v_pk_add_f32 v[186:187], v[184:185], v[186:187] neg_lo:[0,1] neg_hi:[0,1]
	v_pk_add_f32 v[190:191], v[188:189], v[190:191] neg_lo:[0,1] neg_hi:[0,1]
	v_pk_add_f32 v[194:195], v[192:193], v[194:195] neg_lo:[0,1] neg_hi:[0,1]
	v_pk_add_f32 v[198:199], v[196:197], v[198:199] neg_lo:[0,1] neg_hi:[0,1]
	v_pk_add_f32 v[164:165], v[164:165], v[186:187]
	v_pk_add_f32 v[166:167], v[166:167], v[190:191]
	v_pk_add_f32 v[168:169], v[168:169], v[194:195]
	v_pk_add_f32 v[170:171], v[170:171], v[198:199]
	v_fma_f32 v186, s43, v164, -v184
	v_fma_f32 v187, s43, v165, -v185
	v_fma_f32 v190, s43, v166, -v188
	v_fma_f32 v191, s43, v167, -v189
	v_fma_f32 v194, s43, v168, -v192
	v_fma_f32 v195, s43, v169, -v193
	v_fma_f32 v198, s43, v170, -v196
	v_fma_f32 v199, s43, v171, -v197
	v_cvt_pk_bf16_f32 v172, v186, v187
	v_cvt_pk_bf16_f32 v173, v190, v191
	v_cvt_pk_bf16_f32 v174, v194, v195
	v_cvt_pk_bf16_f32 v175, v198, v199
	global_store_dwordx4 v3, v[172:175], s[10:11] sc1
	v_add_u32_e32 v3, 0x2000, v3
	s_waitcnt vmcnt(31)
	v_lshlrev_b32_e32 v184, 16, v92
	v_and_b32_e32 v185, 0xffff0000, v92
	v_lshlrev_b32_e32 v186, 16, v60
	v_and_b32_e32 v187, 0xffff0000, v60
	v_lshlrev_b32_e32 v188, 16, v93
	v_and_b32_e32 v189, 0xffff0000, v93
	v_lshlrev_b32_e32 v190, 16, v61
	v_and_b32_e32 v191, 0xffff0000, v61
	v_lshlrev_b32_e32 v192, 16, v94
	v_and_b32_e32 v193, 0xffff0000, v94
	v_lshlrev_b32_e32 v194, 16, v62
	v_and_b32_e32 v195, 0xffff0000, v62
	v_lshlrev_b32_e32 v196, 16, v95
	v_and_b32_e32 v197, 0xffff0000, v95
	v_lshlrev_b32_e32 v198, 16, v63
	v_and_b32_e32 v199, 0xffff0000, v63
	v_pk_add_f32 v[186:187], v[184:185], v[186:187] neg_lo:[0,1] neg_hi:[0,1]
	v_pk_add_f32 v[190:191], v[188:189], v[190:191] neg_lo:[0,1] neg_hi:[0,1]
	v_pk_add_f32 v[194:195], v[192:193], v[194:195] neg_lo:[0,1] neg_hi:[0,1]
	v_pk_add_f32 v[198:199], v[196:197], v[198:199] neg_lo:[0,1] neg_hi:[0,1]
	v_pk_add_f32 v[164:165], v[164:165], v[186:187]
	v_pk_add_f32 v[166:167], v[166:167], v[190:191]
	v_pk_add_f32 v[168:169], v[168:169], v[194:195]
	v_pk_add_f32 v[170:171], v[170:171], v[198:199]
	v_fma_f32 v186, s43, v164, -v184
	v_fma_f32 v187, s43, v165, -v185
	v_fma_f32 v190, s43, v166, -v188
	v_fma_f32 v191, s43, v167, -v189
	v_fma_f32 v194, s43, v168, -v192
	v_fma_f32 v195, s43, v169, -v193
	v_fma_f32 v198, s43, v170, -v196
	v_fma_f32 v199, s43, v171, -v197
	v_cvt_pk_bf16_f32 v172, v186, v187
	v_cvt_pk_bf16_f32 v173, v190, v191
	v_cvt_pk_bf16_f32 v174, v194, v195
	v_cvt_pk_bf16_f32 v175, v198, v199
	global_store_dwordx4 v3, v[172:175], s[10:11] sc1
	v_add_u32_e32 v3, 0x2000, v3
	s_waitcnt vmcnt(31)
	v_lshlrev_b32_e32 v184, 16, v96
	v_and_b32_e32 v185, 0xffff0000, v96
	v_lshlrev_b32_e32 v186, 16, v64
	v_and_b32_e32 v187, 0xffff0000, v64
	v_lshlrev_b32_e32 v188, 16, v97
	v_and_b32_e32 v189, 0xffff0000, v97
	v_lshlrev_b32_e32 v190, 16, v65
	v_and_b32_e32 v191, 0xffff0000, v65
	v_lshlrev_b32_e32 v192, 16, v98
	v_and_b32_e32 v193, 0xffff0000, v98
	v_lshlrev_b32_e32 v194, 16, v66
	v_and_b32_e32 v195, 0xffff0000, v66
	v_lshlrev_b32_e32 v196, 16, v99
	v_and_b32_e32 v197, 0xffff0000, v99
	v_lshlrev_b32_e32 v198, 16, v67
	v_and_b32_e32 v199, 0xffff0000, v67
	v_pk_add_f32 v[186:187], v[184:185], v[186:187] neg_lo:[0,1] neg_hi:[0,1]
	v_pk_add_f32 v[190:191], v[188:189], v[190:191] neg_lo:[0,1] neg_hi:[0,1]
	v_pk_add_f32 v[194:195], v[192:193], v[194:195] neg_lo:[0,1] neg_hi:[0,1]
	v_pk_add_f32 v[198:199], v[196:197], v[198:199] neg_lo:[0,1] neg_hi:[0,1]
	v_pk_add_f32 v[164:165], v[164:165], v[186:187]
	v_pk_add_f32 v[166:167], v[166:167], v[190:191]
	v_pk_add_f32 v[168:169], v[168:169], v[194:195]
	v_pk_add_f32 v[170:171], v[170:171], v[198:199]
	v_fma_f32 v186, s43, v164, -v184
	v_fma_f32 v187, s43, v165, -v185
	v_fma_f32 v190, s43, v166, -v188
	v_fma_f32 v191, s43, v167, -v189
	v_fma_f32 v194, s43, v168, -v192
	v_fma_f32 v195, s43, v169, -v193
	v_fma_f32 v198, s43, v170, -v196
	v_fma_f32 v199, s43, v171, -v197
	v_cvt_pk_bf16_f32 v172, v186, v187
	v_cvt_pk_bf16_f32 v173, v190, v191
	v_cvt_pk_bf16_f32 v174, v194, v195
	v_cvt_pk_bf16_f32 v175, v198, v199
	global_store_dwordx4 v3, v[172:175], s[10:11] sc1
	v_add_u32_e32 v3, 0x2000, v3
	s_waitcnt vmcnt(31)
; __device__ __forceinline__ unsigned cvt_pk_bf16(float lo, float hi) { unsigned r; asm volatile("v_cvt_pk_bf16_f32 %0, %1, %2" : "=v"(r) : "v"(lo), "v"(hi)); return r; }
; __device__ __forceinline__ float bf_lo(unsigned w) { return __uint_as_float(w << 16); }
; __device__ __forceinline__ float bf_hi(unsigned w) { return __uint_as_float(w & 0xffff0000u); }
; __device__ void phase_pool() {
;     ...
;             for (int k = 0; k < 8; ++k) { const int row = row0 + r0 + k, tl = tl0 + r0 + k; const u32x4 v = vv[k], o2 = ov[k];
;                 s[0] += bf_lo(v.x) - bf_lo(o2.x); s[1] += bf_hi(v.x) - bf_hi(o2.x); s[2] += bf_lo(v.y) - bf_lo(o2.y); s[3] += bf_hi(v.y) - bf_hi(o2.y);
;                 s[4] += bf_lo(v.z) - bf_lo(o2.z); s[5] += bf_hi(v.z) - bf_hi(o2.z); s[6] += bf_lo(v.w) - bf_lo(o2.w); s[7] += bf_hi(v.w) - bf_hi(o2.w);
;                 const float ic = 1.0f / (float)((tl + 1 < w) ? tl + 1 : w);
;                 u32x4 o;
;                 o.x = cvt_pk_bf16(s[0] * ic - bf_lo(v.x), s[1] * ic - bf_hi(v.x)); o.y = cvt_pk_bf16(s[2] * ic - bf_lo(v.y), s[3] * ic - bf_hi(v.y));
;                 o.z = cvt_pk_bf16(s[4] * ic - bf_lo(v.z), s[5] * ic - bf_hi(v.z)); o.w = cvt_pk_bf16(s[6] * ic - bf_lo(v.w), s[7] * ic - bf_hi(v.w));
;                 *(u32x4*)(pg + (size_t)row * DE + col) = o; }
	v_lshlrev_b32_e32 v184, 16, v100
	v_and_b32_e32 v185, 0xffff0000, v100
	v_lshlrev_b32_e32 v186, 16, v68
	v_and_b32_e32 v187, 0xffff0000, v68
	v_lshlrev_b32_e32 v188, 16, v101
	v_and_b32_e32 v189, 0xffff0000, v101
	v_lshlrev_b32_e32 v190, 16, v69
	v_and_b32_e32 v191, 0xffff0000, v69
	v_lshlrev_b32_e32 v192, 16, v102
	v_and_b32_e32 v193, 0xffff0000, v102
	v_lshlrev_b32_e32 v194, 16, v70
	v_and_b32_e32 v195, 0xffff0000, v70
	v_lshlrev_b32_e32 v196, 16, v103
	v_and_b32_e32 v197, 0xffff0000, v103
	v_lshlrev_b32_e32 v198, 16, v71
	v_and_b32_e32 v199, 0xffff0000, v71
	v_pk_add_f32 v[186:187], v[184:185], v[186:187] neg_lo:[0,1] neg_hi:[0,1]
	v_pk_add_f32 v[190:191], v[188:189], v[190:191] neg_lo:[0,1] neg_hi:[0,1]
	v_pk_add_f32 v[194:195], v[192:193], v[194:195] neg_lo:[0,1] neg_hi:[0,1]
	v_pk_add_f32 v[198:199], v[196:197], v[198:199] neg_lo:[0,1] neg_hi:[0,1]
	v_pk_add_f32 v[164:165], v[164:165], v[186:187]
	v_pk_add_f32 v[166:167], v[166:167], v[190:191]
	v_pk_add_f32 v[168:169], v[168:169], v[194:195]
	v_pk_add_f32 v[170:171], v[170:171], v[198:199]
	v_fma_f32 v186, s43, v164, -v184
	v_fma_f32 v187, s43, v165, -v185
	v_fma_f32 v190, s43, v166, -v188
	v_fma_f32 v191, s43, v167, -v189
	v_fma_f32 v194, s43, v168, -v192
	v_fma_f32 v195, s43, v169, -v193
	v_fma_f32 v198, s43, v170, -v196
	v_fma_f32 v199, s43, v171, -v197
	v_cvt_pk_bf16_f32 v172, v186, v187
	v_cvt_pk_bf16_f32 v173, v190, v191
	v_cvt_pk_bf16_f32 v174, v194, v195
	v_cvt_pk_bf16_f32 v175, v198, v199
	global_store_dwordx4 v3, v[172:175], s[10:11] sc1
	v_add_u32_e32 v3, 0x2000, v3
	s_waitcnt vmcnt(31)
	v_lshlrev_b32_e32 v184, 16, v104
	v_and_b32_e32 v185, 0xffff0000, v104
	v_lshlrev_b32_e32 v186, 16, v72
	v_and_b32_e32 v187, 0xffff0000, v72
	v_lshlrev_b32_e32 v188, 16, v105
	v_and_b32_e32 v189, 0xffff0000, v105
	v_lshlrev_b32_e32 v190, 16, v73
	v_and_b32_e32 v191, 0xffff0000, v73
	v_lshlrev_b32_e32 v192, 16, v106
	v_and_b32_e32 v193, 0xffff0000, v106
	v_lshlrev_b32_e32 v194, 16, v74
	v_and_b32_e32 v195, 0xffff0000, v74
	v_lshlrev_b32_e32 v196, 16, v107
	v_and_b32_e32 v197, 0xffff0000, v107
	v_lshlrev_b32_e32 v198, 16, v75
	v_and_b32_e32 v199, 0xffff0000, v75
	v_pk_add_f32 v[186:187], v[184:185], v[186:187] neg_lo:[0,1] neg_hi:[0,1]
	v_pk_add_f32 v[190:191], v[188:189], v[190:191] neg_lo:[0,1] neg_hi:[0,1]
	v_pk_add_f32 v[194:195], v[192:193], v[194:195] neg_lo:[0,1] neg_hi:[0,1]
	v_pk_add_f32 v[198:199], v[196:197], v[198:199] neg_lo:[0,1] neg_hi:[0,1]
	v_pk_add_f32 v[164:165], v[164:165], v[186:187]
	v_pk_add_f32 v[166:167], v[166:167], v[190:191]
	v_pk_add_f32 v[168:169], v[168:169], v[194:195]
	v_pk_add_f32 v[170:171], v[170:171], v[198:199]
	v_fma_f32 v186, s43, v164, -v184
	v_fma_f32 v187, s43, v165, -v185
	v_fma_f32 v190, s43, v166, -v188
	v_fma_f32 v191, s43, v167, -v189
	v_fma_f32 v194, s43, v168, -v192
	v_fma_f32 v195, s43, v169, -v193
	v_fma_f32 v198, s43, v170, -v196
	v_fma_f32 v199, s43, v171, -v197
	v_cvt_pk_bf16_f32 v172, v186, v187
	v_cvt_pk_bf16_f32 v173, v190, v191
	v_cvt_pk_bf16_f32 v174, v194, v195
	v_cvt_pk_bf16_f32 v175, v198, v199
	global_store_dwordx4 v3, v[172:175], s[10:11] sc1
	v_add_u32_e32 v3, 0x2000, v3
	s_waitcnt vmcnt(31)
	v_lshlrev_b32_e32 v184, 16, v108
	v_and_b32_e32 v185, 0xffff0000, v108
	v_lshlrev_b32_e32 v186, 16, v76
	v_and_b32_e32 v187, 0xffff0000, v76
	v_lshlrev_b32_e32 v188, 16, v109
	v_and_b32_e32 v189, 0xffff0000, v109
	v_lshlrev_b32_e32 v190, 16, v77
	v_and_b32_e32 v191, 0xffff0000, v77
	v_lshlrev_b32_e32 v192, 16, v110
	v_and_b32_e32 v193, 0xffff0000, v110
	v_lshlrev_b32_e32 v194, 16, v78
	v_and_b32_e32 v195, 0xffff0000, v78
	v_lshlrev_b32_e32 v196, 16, v111
	v_and_b32_e32 v197, 0xffff0000, v111
	v_lshlrev_b32_e32 v198, 16, v79
	v_and_b32_e32 v199, 0xffff0000, v79
	v_pk_add_f32 v[186:187], v[184:185], v[186:187] neg_lo:[0,1] neg_hi:[0,1]
	v_pk_add_f32 v[190:191], v[188:189], v[190:191] neg_lo:[0,1] neg_hi:[0,1]
	v_pk_add_f32 v[194:195], v[192:193], v[194:195] neg_lo:[0,1] neg_hi:[0,1]
	v_pk_add_f32 v[198:199], v[196:197], v[198:199] neg_lo:[0,1] neg_hi:[0,1]
	v_pk_add_f32 v[164:165], v[164:165], v[186:187]
	v_pk_add_f32 v[166:167], v[166:167], v[190:191]
	v_pk_add_f32 v[168:169], v[168:169], v[194:195]
	v_pk_add_f32 v[170:171], v[170:171], v[198:199]
	v_fma_f32 v186, s43, v164, -v184
	v_fma_f32 v187, s43, v165, -v185
	v_fma_f32 v190, s43, v166, -v188
	v_fma_f32 v191, s43, v167, -v189
	v_fma_f32 v194, s43, v168, -v192
	v_fma_f32 v195, s43, v169, -v193
	v_fma_f32 v198, s43, v170, -v196
	v_fma_f32 v199, s43, v171, -v197
	v_cvt_pk_bf16_f32 v172, v186, v187
	v_cvt_pk_bf16_f32 v173, v190, v191
	v_cvt_pk_bf16_f32 v174, v194, v195
	v_cvt_pk_bf16_f32 v175, v198, v199
	global_store_dwordx4 v3, v[172:175], s[10:11] sc1
	v_add_u32_e32 v3, 0x2000, v3
	s_waitcnt vmcnt(31)
	v_lshlrev_b32_e32 v184, 16, v112
	v_and_b32_e32 v185, 0xffff0000, v112
	v_lshlrev_b32_e32 v186, 16, v80
	v_and_b32_e32 v187, 0xffff0000, v80
	v_lshlrev_b32_e32 v188, 16, v113
	v_and_b32_e32 v189, 0xffff0000, v113
	v_lshlrev_b32_e32 v190, 16, v81
	v_and_b32_e32 v191, 0xffff0000, v81
	v_lshlrev_b32_e32 v192, 16, v114
	v_and_b32_e32 v193, 0xffff0000, v114
	v_lshlrev_b32_e32 v194, 16, v82
	v_and_b32_e32 v195, 0xffff0000, v82
	v_lshlrev_b32_e32 v196, 16, v115
	v_and_b32_e32 v197, 0xffff0000, v115
	v_lshlrev_b32_e32 v198, 16, v83
	v_and_b32_e32 v199, 0xffff0000, v83
	v_pk_add_f32 v[186:187], v[184:185], v[186:187] neg_lo:[0,1] neg_hi:[0,1]
	v_pk_add_f32 v[190:191], v[188:189], v[190:191] neg_lo:[0,1] neg_hi:[0,1]
	v_pk_add_f32 v[194:195], v[192:193], v[194:195] neg_lo:[0,1] neg_hi:[0,1]
	v_pk_add_f32 v[198:199], v[196:197], v[198:199] neg_lo:[0,1] neg_hi:[0,1]
	v_pk_add_f32 v[164:165], v[164:165], v[186:187]
	v_pk_add_f32 v[166:167], v[166:167], v[190:191]
	v_pk_add_f32 v[168:169], v[168:169], v[194:195]
	v_pk_add_f32 v[170:171], v[170:171], v[198:199]
	v_fma_f32 v186, s43, v164, -v184
	v_fma_f32 v187, s43, v165, -v185
	v_fma_f32 v190, s43, v166, -v188
	v_fma_f32 v191, s43, v167, -v189
	v_fma_f32 v194, s43, v168, -v192
	v_fma_f32 v195, s43, v169, -v193
	v_fma_f32 v198, s43, v170, -v196
	v_fma_f32 v199, s43, v171, -v197
	v_cvt_pk_bf16_f32 v172, v186, v187
	v_cvt_pk_bf16_f32 v173, v190, v191
	v_cvt_pk_bf16_f32 v174, v194, v195
	v_cvt_pk_bf16_f32 v175, v198, v199
	global_store_dwordx4 v3, v[172:175], s[10:11] sc1
	v_add_u32_e32 v3, 0x2000, v3
	s_waitcnt vmcnt(31)
; __device__ __forceinline__ unsigned cvt_pk_bf16(float lo, float hi) { unsigned r; asm volatile("v_cvt_pk_bf16_f32 %0, %1, %2" : "=v"(r) : "v"(lo), "v"(hi)); return r; }
; __device__ __forceinline__ float bf_lo(unsigned w) { return __uint_as_float(w << 16); }
; __device__ __forceinline__ float bf_hi(unsigned w) { return __uint_as_float(w & 0xffff0000u); }
; __device__ void phase_pool() {
;     ...
;             for (int k = 0; k < 8; ++k) { const int row = row0 + r0 + k, tl = tl0 + r0 + k; const u32x4 v = vv[k], o2 = ov[k];
;                 s[0] += bf_lo(v.x) - bf_lo(o2.x); s[1] += bf_hi(v.x) - bf_hi(o2.x); s[2] += bf_lo(v.y) - bf_lo(o2.y); s[3] += bf_hi(v.y) - bf_hi(o2.y);
;                 s[4] += bf_lo(v.z) - bf_lo(o2.z); s[5] += bf_hi(v.z) - bf_hi(o2.z); s[6] += bf_lo(v.w) - bf_lo(o2.w); s[7] += bf_hi(v.w) - bf_hi(o2.w);
;                 const float ic = 1.0f / (float)((tl + 1 < w) ? tl + 1 : w);
;                 u32x4 o;
;                 o.x = cvt_pk_bf16(s[0] * ic - bf_lo(v.x), s[1] * ic - bf_hi(v.x)); o.y = cvt_pk_bf16(s[2] * ic - bf_lo(v.y), s[3] * ic - bf_hi(v.y));
;                 o.z = cvt_pk_bf16(s[4] * ic - bf_lo(v.z), s[5] * ic - bf_hi(v.z)); o.w = cvt_pk_bf16(s[6] * ic - bf_lo(v.w), s[7] * ic - bf_hi(v.w));
;                 *(u32x4*)(pg + (size_t)row * DE + col) = o; }
	v_lshlrev_b32_e32 v184, 16, v116
	v_and_b32_e32 v185, 0xffff0000, v116
	v_lshlrev_b32_e32 v186, 16, v84
	v_and_b32_e32 v187, 0xffff0000, v84
	v_lshlrev_b32_e32 v188, 16, v117
	v_and_b32_e32 v189, 0xffff0000, v117
	v_lshlrev_b32_e32 v190, 16, v85
	v_and_b32_e32 v191, 0xffff0000, v85
	v_lshlrev_b32_e32 v192, 16, v118
	v_and_b32_e32 v193, 0xffff0000, v118
	v_lshlrev_b32_e32 v194, 16, v86
	v_and_b32_e32 v195, 0xffff0000, v86
	v_lshlrev_b32_e32 v196, 16, v119
	v_and_b32_e32 v197, 0xffff0000, v119
	v_lshlrev_b32_e32 v198, 16, v87
	v_and_b32_e32 v199, 0xffff0000, v87
	v_pk_add_f32 v[186:187], v[184:185], v[186:187] neg_lo:[0,1] neg_hi:[0,1]
	v_pk_add_f32 v[190:191], v[188:189], v[190:191] neg_lo:[0,1] neg_hi:[0,1]
	v_pk_add_f32 v[194:195], v[192:193], v[194:195] neg_lo:[0,1] neg_hi:[0,1]
	v_pk_add_f32 v[198:199], v[196:197], v[198:199] neg_lo:[0,1] neg_hi:[0,1]
	v_pk_add_f32 v[164:165], v[164:165], v[186:187]
	v_pk_add_f32 v[166:167], v[166:167], v[190:191]
	v_pk_add_f32 v[168:169], v[168:169], v[194:195]
	v_pk_add_f32 v[170:171], v[170:171], v[198:199]
	v_fma_f32 v186, s43, v164, -v184
	v_fma_f32 v187, s43, v165, -v185
	v_fma_f32 v190, s43, v166, -v188
	v_fma_f32 v191, s43, v167, -v189
	v_fma_f32 v194, s43, v168, -v192
	v_fma_f32 v195, s43, v169, -v193
	v_fma_f32 v198, s43, v170, -v196
	v_fma_f32 v199, s43, v171, -v197
	v_cvt_pk_bf16_f32 v172, v186, v187
	v_cvt_pk_bf16_f32 v173, v190, v191
	v_cvt_pk_bf16_f32 v174, v194, v195
	v_cvt_pk_bf16_f32 v175, v198, v199
	global_store_dwordx4 v3, v[172:175], s[10:11] sc1
	v_add_u32_e32 v3, 0x2000, v3
	s_waitcnt vmcnt(31)
	v_lshlrev_b32_e32 v184, 16, v120
	v_and_b32_e32 v185, 0xffff0000, v120
	v_lshlrev_b32_e32 v186, 16, v88
	v_and_b32_e32 v187, 0xffff0000, v88
	v_lshlrev_b32_e32 v188, 16, v121
	v_and_b32_e32 v189, 0xffff0000, v121
	v_lshlrev_b32_e32 v190, 16, v89
	v_and_b32_e32 v191, 0xffff0000, v89
	v_lshlrev_b32_e32 v192, 16, v122
	v_and_b32_e32 v193, 0xffff0000, v122
	v_lshlrev_b32_e32 v194, 16, v90
	v_and_b32_e32 v195, 0xffff0000, v90
	v_lshlrev_b32_e32 v196, 16, v123
	v_and_b32_e32 v197, 0xffff0000, v123
	v_lshlrev_b32_e32 v198, 16, v91
	v_and_b32_e32 v199, 0xffff0000, v91
	v_pk_add_f32 v[186:187], v[184:185], v[186:187] neg_lo:[0,1] neg_hi:[0,1]
	v_pk_add_f32 v[190:191], v[188:189], v[190:191] neg_lo:[0,1] neg_hi:[0,1]
	v_pk_add_f32 v[194:195], v[192:193], v[194:195] neg_lo:[0,1] neg_hi:[0,1]
	v_pk_add_f32 v[198:199], v[196:197], v[198:199] neg_lo:[0,1] neg_hi:[0,1]
	v_pk_add_f32 v[164:165], v[164:165], v[186:187]
	v_pk_add_f32 v[166:167], v[166:167], v[190:191]
	v_pk_add_f32 v[168:169], v[168:169], v[194:195]
	v_pk_add_f32 v[170:171], v[170:171], v[198:199]
	v_fma_f32 v186, s43, v164, -v184
	v_fma_f32 v187, s43, v165, -v185
	v_fma_f32 v190, s43, v166, -v188
	v_fma_f32 v191, s43, v167, -v189
	v_fma_f32 v194, s43, v168, -v192
	v_fma_f32 v195, s43, v169, -v193
	v_fma_f32 v198, s43, v170, -v196
	v_fma_f32 v199, s43, v171, -v197
	v_cvt_pk_bf16_f32 v172, v186, v187
	v_cvt_pk_bf16_f32 v173, v190, v191
	v_cvt_pk_bf16_f32 v174, v194, v195
	v_cvt_pk_bf16_f32 v175, v198, v199
	global_store_dwordx4 v3, v[172:175], s[10:11] sc1
	v_add_u32_e32 v3, 0x2000, v3
	s_waitcnt vmcnt(31)
	v_lshlrev_b32_e32 v184, 16, v124
	v_and_b32_e32 v185, 0xffff0000, v124
	v_lshlrev_b32_e32 v186, 16, v92
	v_and_b32_e32 v187, 0xffff0000, v92
	v_lshlrev_b32_e32 v188, 16, v125
	v_and_b32_e32 v189, 0xffff0000, v125
	v_lshlrev_b32_e32 v190, 16, v93
	v_and_b32_e32 v191, 0xffff0000, v93
	v_lshlrev_b32_e32 v192, 16, v126
	v_and_b32_e32 v193, 0xffff0000, v126
	v_lshlrev_b32_e32 v194, 16, v94
	v_and_b32_e32 v195, 0xffff0000, v94
	v_lshlrev_b32_e32 v196, 16, v127
	v_and_b32_e32 v197, 0xffff0000, v127
	v_lshlrev_b32_e32 v198, 16, v95
	v_and_b32_e32 v199, 0xffff0000, v95
	v_pk_add_f32 v[186:187], v[184:185], v[186:187] neg_lo:[0,1] neg_hi:[0,1]
	v_pk_add_f32 v[190:191], v[188:189], v[190:191] neg_lo:[0,1] neg_hi:[0,1]
	v_pk_add_f32 v[194:195], v[192:193], v[194:195] neg_lo:[0,1] neg_hi:[0,1]
	v_pk_add_f32 v[198:199], v[196:197], v[198:199] neg_lo:[0,1] neg_hi:[0,1]
	v_pk_add_f32 v[164:165], v[164:165], v[186:187]
	v_pk_add_f32 v[166:167], v[166:167], v[190:191]
	v_pk_add_f32 v[168:169], v[168:169], v[194:195]
	v_pk_add_f32 v[170:171], v[170:171], v[198:199]
	v_fma_f32 v186, s43, v164, -v184
	v_fma_f32 v187, s43, v165, -v185
	v_fma_f32 v190, s43, v166, -v188
	v_fma_f32 v191, s43, v167, -v189
	v_fma_f32 v194, s43, v168, -v192
	v_fma_f32 v195, s43, v169, -v193
	v_fma_f32 v198, s43, v170, -v196
	v_fma_f32 v199, s43, v171, -v197
	v_cvt_pk_bf16_f32 v172, v186, v187
	v_cvt_pk_bf16_f32 v173, v190, v191
	v_cvt_pk_bf16_f32 v174, v194, v195
	v_cvt_pk_bf16_f32 v175, v198, v199
	global_store_dwordx4 v3, v[172:175], s[10:11] sc1
	v_add_u32_e32 v3, 0x2000, v3
	s_waitcnt vmcnt(31)
	v_lshlrev_b32_e32 v184, 16, v128
	v_and_b32_e32 v185, 0xffff0000, v128
	v_lshlrev_b32_e32 v186, 16, v96
	v_and_b32_e32 v187, 0xffff0000, v96
	v_lshlrev_b32_e32 v188, 16, v129
	v_and_b32_e32 v189, 0xffff0000, v129
	v_lshlrev_b32_e32 v190, 16, v97
	v_and_b32_e32 v191, 0xffff0000, v97
	v_lshlrev_b32_e32 v192, 16, v130
	v_and_b32_e32 v193, 0xffff0000, v130
	v_lshlrev_b32_e32 v194, 16, v98
	v_and_b32_e32 v195, 0xffff0000, v98
	v_lshlrev_b32_e32 v196, 16, v131
	v_and_b32_e32 v197, 0xffff0000, v131
	v_lshlrev_b32_e32 v198, 16, v99
	v_and_b32_e32 v199, 0xffff0000, v99
	v_pk_add_f32 v[186:187], v[184:185], v[186:187] neg_lo:[0,1] neg_hi:[0,1]
	v_pk_add_f32 v[190:191], v[188:189], v[190:191] neg_lo:[0,1] neg_hi:[0,1]
	v_pk_add_f32 v[194:195], v[192:193], v[194:195] neg_lo:[0,1] neg_hi:[0,1]
	v_pk_add_f32 v[198:199], v[196:197], v[198:199] neg_lo:[0,1] neg_hi:[0,1]
	v_pk_add_f32 v[164:165], v[164:165], v[186:187]
	v_pk_add_f32 v[166:167], v[166:167], v[190:191]
	v_pk_add_f32 v[168:169], v[168:169], v[194:195]
	v_pk_add_f32 v[170:171], v[170:171], v[198:199]
	v_fma_f32 v186, s43, v164, -v184
	v_fma_f32 v187, s43, v165, -v185
	v_fma_f32 v190, s43, v166, -v188
	v_fma_f32 v191, s43, v167, -v189
	v_fma_f32 v194, s43, v168, -v192
	v_fma_f32 v195, s43, v169, -v193
	v_fma_f32 v198, s43, v170, -v196
	v_fma_f32 v199, s43, v171, -v197
	v_cvt_pk_bf16_f32 v172, v186, v187
	v_cvt_pk_bf16_f32 v173, v190, v191
	v_cvt_pk_bf16_f32 v174, v194, v195
	v_cvt_pk_bf16_f32 v175, v198, v199
	global_store_dwordx4 v3, v[172:175], s[10:11] sc1
	v_add_u32_e32 v3, 0x2000, v3
	s_waitcnt vmcnt(31)
; __device__ __forceinline__ unsigned cvt_pk_bf16(float lo, float hi) { unsigned r; asm volatile("v_cvt_pk_bf16_f32 %0, %1, %2" : "=v"(r) : "v"(lo), "v"(hi)); return r; }
; __device__ __forceinline__ float bf_lo(unsigned w) { return __uint_as_float(w << 16); }
; __device__ __forceinline__ float bf_hi(unsigned w) { return __uint_as_float(w & 0xffff0000u); }
; __device__ void phase_pool() {
;     ...
;             for (int k = 0; k < 8; ++k) { const int row = row0 + r0 + k, tl = tl0 + r0 + k; const u32x4 v = vv[k], o2 = ov[k];
;                 s[0] += bf_lo(v.x) - bf_lo(o2.x); s[1] += bf_hi(v.x) - bf_hi(o2.x); s[2] += bf_lo(v.y) - bf_lo(o2.y); s[3] += bf_hi(v.y) - bf_hi(o2.y);
;                 s[4] += bf_lo(v.z) - bf_lo(o2.z); s[5] += bf_hi(v.z) - bf_hi(o2.z); s[6] += bf_lo(v.w) - bf_lo(o2.w); s[7] += bf_hi(v.w) - bf_hi(o2.w);
;                 const float ic = 1.0f / (float)((tl + 1 < w) ? tl + 1 : w);
;                 u32x4 o;
;                 o.x = cvt_pk_bf16(s[0] * ic - bf_lo(v.x), s[1] * ic - bf_hi(v.x)); o.y = cvt_pk_bf16(s[2] * ic - bf_lo(v.y), s[3] * ic - bf_hi(v.y));
;                 o.z = cvt_pk_bf16(s[4] * ic - bf_lo(v.z), s[5] * ic - bf_hi(v.z)); o.w = cvt_pk_bf16(s[6] * ic - bf_lo(v.w), s[7] * ic - bf_hi(v.w));
;                 *(u32x4*)(pg + (size_t)row * DE + col) = o; }
	v_lshlrev_b32_e32 v184, 16, v132
	v_and_b32_e32 v185, 0xffff0000, v132
	v_lshlrev_b32_e32 v186, 16, v100
	v_and_b32_e32 v187, 0xffff0000, v100
	v_lshlrev_b32_e32 v188, 16, v133
	v_and_b32_e32 v189, 0xffff0000, v133
	v_lshlrev_b32_e32 v190, 16, v101
	v_and_b32_e32 v191, 0xffff0000, v101
	v_lshlrev_b32_e32 v192, 16, v134
	v_and_b32_e32 v193, 0xffff0000, v134
	v_lshlrev_b32_e32 v194, 16, v102
	v_and_b32_e32 v195, 0xffff0000, v102
	v_lshlrev_b32_e32 v196, 16, v135
	v_and_b32_e32 v197, 0xffff0000, v135
	v_lshlrev_b32_e32 v198, 16, v103
	v_and_b32_e32 v199, 0xffff0000, v103
	v_pk_add_f32 v[186:187], v[184:185], v[186:187] neg_lo:[0,1] neg_hi:[0,1]
	v_pk_add_f32 v[190:191], v[188:189], v[190:191] neg_lo:[0,1] neg_hi:[0,1]
	v_pk_add_f32 v[194:195], v[192:193], v[194:195] neg_lo:[0,1] neg_hi:[0,1]
	v_pk_add_f32 v[198:199], v[196:197], v[198:199] neg_lo:[0,1] neg_hi:[0,1]
	v_pk_add_f32 v[164:165], v[164:165], v[186:187]
	v_pk_add_f32 v[166:167], v[166:167], v[190:191]
	v_pk_add_f32 v[168:169], v[168:169], v[194:195]
	v_pk_add_f32 v[170:171], v[170:171], v[198:199]
	v_fma_f32 v186, s43, v164, -v184
	v_fma_f32 v187, s43, v165, -v185
	v_fma_f32 v190, s43, v166, -v188
	v_fma_f32 v191, s43, v167, -v189
	v_fma_f32 v194, s43, v168, -v192
	v_fma_f32 v195, s43, v169, -v193
	v_fma_f32 v198, s43, v170, -v196
	v_fma_f32 v199, s43, v171, -v197
	v_cvt_pk_bf16_f32 v172, v186, v187
	v_cvt_pk_bf16_f32 v173, v190, v191
	v_cvt_pk_bf16_f32 v174, v194, v195
	v_cvt_pk_bf16_f32 v175, v198, v199
	global_store_dwordx4 v3, v[172:175], s[10:11] sc1
	v_add_u32_e32 v3, 0x2000, v3
	s_waitcnt vmcnt(31)
	v_lshlrev_b32_e32 v184, 16, v136
	v_and_b32_e32 v185, 0xffff0000, v136
	v_lshlrev_b32_e32 v186, 16, v104
	v_and_b32_e32 v187, 0xffff0000, v104
	v_lshlrev_b32_e32 v188, 16, v137
	v_and_b32_e32 v189, 0xffff0000, v137
	v_lshlrev_b32_e32 v190, 16, v105
	v_and_b32_e32 v191, 0xffff0000, v105
	v_lshlrev_b32_e32 v192, 16, v138
	v_and_b32_e32 v193, 0xffff0000, v138
	v_lshlrev_b32_e32 v194, 16, v106
	v_and_b32_e32 v195, 0xffff0000, v106
	v_lshlrev_b32_e32 v196, 16, v139
	v_and_b32_e32 v197, 0xffff0000, v139
	v_lshlrev_b32_e32 v198, 16, v107
	v_and_b32_e32 v199, 0xffff0000, v107
	v_pk_add_f32 v[186:187], v[184:185], v[186:187] neg_lo:[0,1] neg_hi:[0,1]
	v_pk_add_f32 v[190:191], v[188:189], v[190:191] neg_lo:[0,1] neg_hi:[0,1]
	v_pk_add_f32 v[194:195], v[192:193], v[194:195] neg_lo:[0,1] neg_hi:[0,1]
	v_pk_add_f32 v[198:199], v[196:197], v[198:199] neg_lo:[0,1] neg_hi:[0,1]
	v_pk_add_f32 v[164:165], v[164:165], v[186:187]
	v_pk_add_f32 v[166:167], v[166:167], v[190:191]
	v_pk_add_f32 v[168:169], v[168:169], v[194:195]
	v_pk_add_f32 v[170:171], v[170:171], v[198:199]
	v_fma_f32 v186, s43, v164, -v184
	v_fma_f32 v187, s43, v165, -v185
	v_fma_f32 v190, s43, v166, -v188
	v_fma_f32 v191, s43, v167, -v189
	v_fma_f32 v194, s43, v168, -v192
	v_fma_f32 v195, s43, v169, -v193
	v_fma_f32 v198, s43, v170, -v196
	v_fma_f32 v199, s43, v171, -v197
	v_cvt_pk_bf16_f32 v172, v186, v187
	v_cvt_pk_bf16_f32 v173, v190, v191
	v_cvt_pk_bf16_f32 v174, v194, v195
	v_cvt_pk_bf16_f32 v175, v198, v199
	global_store_dwordx4 v3, v[172:175], s[10:11] sc1
	v_add_u32_e32 v3, 0x2000, v3
	s_waitcnt vmcnt(31)
	v_lshlrev_b32_e32 v184, 16, v140
	v_and_b32_e32 v185, 0xffff0000, v140
	v_lshlrev_b32_e32 v186, 16, v108
	v_and_b32_e32 v187, 0xffff0000, v108
	v_lshlrev_b32_e32 v188, 16, v141
	v_and_b32_e32 v189, 0xffff0000, v141
	v_lshlrev_b32_e32 v190, 16, v109
	v_and_b32_e32 v191, 0xffff0000, v109
	v_lshlrev_b32_e32 v192, 16, v142
	v_and_b32_e32 v193, 0xffff0000, v142
	v_lshlrev_b32_e32 v194, 16, v110
	v_and_b32_e32 v195, 0xffff0000, v110
	v_lshlrev_b32_e32 v196, 16, v143
	v_and_b32_e32 v197, 0xffff0000, v143
	v_lshlrev_b32_e32 v198, 16, v111
	v_and_b32_e32 v199, 0xffff0000, v111
	v_pk_add_f32 v[186:187], v[184:185], v[186:187] neg_lo:[0,1] neg_hi:[0,1]
	v_pk_add_f32 v[190:191], v[188:189], v[190:191] neg_lo:[0,1] neg_hi:[0,1]
	v_pk_add_f32 v[194:195], v[192:193], v[194:195] neg_lo:[0,1] neg_hi:[0,1]
	v_pk_add_f32 v[198:199], v[196:197], v[198:199] neg_lo:[0,1] neg_hi:[0,1]
	v_pk_add_f32 v[164:165], v[164:165], v[186:187]
	v_pk_add_f32 v[166:167], v[166:167], v[190:191]
	v_pk_add_f32 v[168:169], v[168:169], v[194:195]
	v_pk_add_f32 v[170:171], v[170:171], v[198:199]
	v_fma_f32 v186, s43, v164, -v184
	v_fma_f32 v187, s43, v165, -v185
	v_fma_f32 v190, s43, v166, -v188
	v_fma_f32 v191, s43, v167, -v189
	v_fma_f32 v194, s43, v168, -v192
	v_fma_f32 v195, s43, v169, -v193
	v_fma_f32 v198, s43, v170, -v196
	v_fma_f32 v199, s43, v171, -v197
	v_cvt_pk_bf16_f32 v172, v186, v187
	v_cvt_pk_bf16_f32 v173, v190, v191
	v_cvt_pk_bf16_f32 v174, v194, v195
	v_cvt_pk_bf16_f32 v175, v198, v199
	global_store_dwordx4 v3, v[172:175], s[10:11] sc1
	v_add_u32_e32 v3, 0x2000, v3
	s_waitcnt vmcnt(31)
	v_lshlrev_b32_e32 v184, 16, v144
	v_and_b32_e32 v185, 0xffff0000, v144
	v_lshlrev_b32_e32 v186, 16, v112
	v_and_b32_e32 v187, 0xffff0000, v112
	v_lshlrev_b32_e32 v188, 16, v145
	v_and_b32_e32 v189, 0xffff0000, v145
	v_lshlrev_b32_e32 v190, 16, v113
	v_and_b32_e32 v191, 0xffff0000, v113
	v_lshlrev_b32_e32 v192, 16, v146
	v_and_b32_e32 v193, 0xffff0000, v146
	v_lshlrev_b32_e32 v194, 16, v114
	v_and_b32_e32 v195, 0xffff0000, v114
	v_lshlrev_b32_e32 v196, 16, v147
	v_and_b32_e32 v197, 0xffff0000, v147
	v_lshlrev_b32_e32 v198, 16, v115
	v_and_b32_e32 v199, 0xffff0000, v115
	v_pk_add_f32 v[186:187], v[184:185], v[186:187] neg_lo:[0,1] neg_hi:[0,1]
	v_pk_add_f32 v[190:191], v[188:189], v[190:191] neg_lo:[0,1] neg_hi:[0,1]
	v_pk_add_f32 v[194:195], v[192:193], v[194:195] neg_lo:[0,1] neg_hi:[0,1]
	v_pk_add_f32 v[198:199], v[196:197], v[198:199] neg_lo:[0,1] neg_hi:[0,1]
	v_pk_add_f32 v[164:165], v[164:165], v[186:187]
	v_pk_add_f32 v[166:167], v[166:167], v[190:191]
	v_pk_add_f32 v[168:169], v[168:169], v[194:195]
	v_pk_add_f32 v[170:171], v[170:171], v[198:199]
	v_fma_f32 v186, s43, v164, -v184
	v_fma_f32 v187, s43, v165, -v185
	v_fma_f32 v190, s43, v166, -v188
	v_fma_f32 v191, s43, v167, -v189
	v_fma_f32 v194, s43, v168, -v192
	v_fma_f32 v195, s43, v169, -v193
	v_fma_f32 v198, s43, v170, -v196
	v_fma_f32 v199, s43, v171, -v197
	v_cvt_pk_bf16_f32 v172, v186, v187
	v_cvt_pk_bf16_f32 v173, v190, v191
	v_cvt_pk_bf16_f32 v174, v194, v195
	v_cvt_pk_bf16_f32 v175, v198, v199
	global_store_dwordx4 v3, v[172:175], s[10:11] sc1
	v_add_u32_e32 v3, 0x2000, v3
	s_waitcnt vmcnt(31)
; __device__ __forceinline__ unsigned cvt_pk_bf16(float lo, float hi) { unsigned r; asm volatile("v_cvt_pk_bf16_f32 %0, %1, %2" : "=v"(r) : "v"(lo), "v"(hi)); return r; }
; __device__ __forceinline__ float bf_lo(unsigned w) { return __uint_as_float(w << 16); }
; __device__ __forceinline__ float bf_hi(unsigned w) { return __uint_as_float(w & 0xffff0000u); }
; __device__ void phase_pool() {
;     ...
;             for (int k = 0; k < 8; ++k) { const int row = row0 + r0 + k, tl = tl0 + r0 + k; const u32x4 v = vv[k], o2 = ov[k];
;                 s[0] += bf_lo(v.x) - bf_lo(o2.x); s[1] += bf_hi(v.x) - bf_hi(o2.x); s[2] += bf_lo(v.y) - bf_lo(o2.y); s[3] += bf_hi(v.y) - bf_hi(o2.y);
;                 s[4] += bf_lo(v.z) - bf_lo(o2.z); s[5] += bf_hi(v.z) - bf_hi(o2.z); s[6] += bf_lo(v.w) - bf_lo(o2.w); s[7] += bf_hi(v.w) - bf_hi(o2.w);
;                 const float ic = 1.0f / (float)((tl + 1 < w) ? tl + 1 : w);
;                 u32x4 o;
;                 o.x = cvt_pk_bf16(s[0] * ic - bf_lo(v.x), s[1] * ic - bf_hi(v.x)); o.y = cvt_pk_bf16(s[2] * ic - bf_lo(v.y), s[3] * ic - bf_hi(v.y));
;                 o.z = cvt_pk_bf16(s[4] * ic - bf_lo(v.z), s[5] * ic - bf_hi(v.z)); o.w = cvt_pk_bf16(s[6] * ic - bf_lo(v.w), s[7] * ic - bf_hi(v.w));
;                 *(u32x4*)(pg + (size_t)row * DE + col) = o; }
	v_lshlrev_b32_e32 v184, 16, v148
	v_and_b32_e32 v185, 0xffff0000, v148
	v_lshlrev_b32_e32 v186, 16, v116
	v_and_b32_e32 v187, 0xffff0000, v116
	v_lshlrev_b32_e32 v188, 16, v149
	v_and_b32_e32 v189, 0xffff0000, v149
	v_lshlrev_b32_e32 v190, 16, v117
	v_and_b32_e32 v191, 0xffff0000, v117
	v_lshlrev_b32_e32 v192, 16, v150
	v_and_b32_e32 v193, 0xffff0000, v150
	v_lshlrev_b32_e32 v194, 16, v118
	v_and_b32_e32 v195, 0xffff0000, v118
	v_lshlrev_b32_e32 v196, 16, v151
	v_and_b32_e32 v197, 0xffff0000, v151
	v_lshlrev_b32_e32 v198, 16, v119
	v_and_b32_e32 v199, 0xffff0000, v119
	v_pk_add_f32 v[186:187], v[184:185], v[186:187] neg_lo:[0,1] neg_hi:[0,1]
	v_pk_add_f32 v[190:191], v[188:189], v[190:191] neg_lo:[0,1] neg_hi:[0,1]
	v_pk_add_f32 v[194:195], v[192:193], v[194:195] neg_lo:[0,1] neg_hi:[0,1]
	v_pk_add_f32 v[198:199], v[196:197], v[198:199] neg_lo:[0,1] neg_hi:[0,1]
	v_pk_add_f32 v[164:165], v[164:165], v[186:187]
	v_pk_add_f32 v[166:167], v[166:167], v[190:191]
	v_pk_add_f32 v[168:169], v[168:169], v[194:195]
	v_pk_add_f32 v[170:171], v[170:171], v[198:199]
	v_fma_f32 v186, s43, v164, -v184
	v_fma_f32 v187, s43, v165, -v185
	v_fma_f32 v190, s43, v166, -v188
	v_fma_f32 v191, s43, v167, -v189
	v_fma_f32 v194, s43, v168, -v192
	v_fma_f32 v195, s43, v169, -v193
	v_fma_f32 v198, s43, v170, -v196
	v_fma_f32 v199, s43, v171, -v197
	v_cvt_pk_bf16_f32 v172, v186, v187
	v_cvt_pk_bf16_f32 v173, v190, v191
	v_cvt_pk_bf16_f32 v174, v194, v195
	v_cvt_pk_bf16_f32 v175, v198, v199
	global_store_dwordx4 v3, v[172:175], s[10:11] sc1
	v_add_u32_e32 v3, 0x2000, v3
	s_waitcnt vmcnt(31)
	v_lshlrev_b32_e32 v184, 16, v152
	v_and_b32_e32 v185, 0xffff0000, v152
	v_lshlrev_b32_e32 v186, 16, v120
	v_and_b32_e32 v187, 0xffff0000, v120
	v_lshlrev_b32_e32 v188, 16, v153
	v_and_b32_e32 v189, 0xffff0000, v153
	v_lshlrev_b32_e32 v190, 16, v121
	v_and_b32_e32 v191, 0xffff0000, v121
	v_lshlrev_b32_e32 v192, 16, v154
	v_and_b32_e32 v193, 0xffff0000, v154
	v_lshlrev_b32_e32 v194, 16, v122
	v_and_b32_e32 v195, 0xffff0000, v122
	v_lshlrev_b32_e32 v196, 16, v155
	v_and_b32_e32 v197, 0xffff0000, v155
	v_lshlrev_b32_e32 v198, 16, v123
	v_and_b32_e32 v199, 0xffff0000, v123
	v_pk_add_f32 v[186:187], v[184:185], v[186:187] neg_lo:[0,1] neg_hi:[0,1]
	v_pk_add_f32 v[190:191], v[188:189], v[190:191] neg_lo:[0,1] neg_hi:[0,1]
	v_pk_add_f32 v[194:195], v[192:193], v[194:195] neg_lo:[0,1] neg_hi:[0,1]
	v_pk_add_f32 v[198:199], v[196:197], v[198:199] neg_lo:[0,1] neg_hi:[0,1]
	v_pk_add_f32 v[164:165], v[164:165], v[186:187]
	v_pk_add_f32 v[166:167], v[166:167], v[190:191]
	v_pk_add_f32 v[168:169], v[168:169], v[194:195]
	v_pk_add_f32 v[170:171], v[170:171], v[198:199]
	v_fma_f32 v186, s43, v164, -v184
	v_fma_f32 v187, s43, v165, -v185
	v_fma_f32 v190, s43, v166, -v188
	v_fma_f32 v191, s43, v167, -v189
	v_fma_f32 v194, s43, v168, -v192
	v_fma_f32 v195, s43, v169, -v193
	v_fma_f32 v198, s43, v170, -v196
	v_fma_f32 v199, s43, v171, -v197
	v_cvt_pk_bf16_f32 v172, v186, v187
	v_cvt_pk_bf16_f32 v173, v190, v191
	v_cvt_pk_bf16_f32 v174, v194, v195
	v_cvt_pk_bf16_f32 v175, v198, v199
	global_store_dwordx4 v3, v[172:175], s[10:11] sc1
	v_add_u32_e32 v3, 0x2000, v3
	s_waitcnt vmcnt(31)
	v_lshlrev_b32_e32 v184, 16, v156
	v_and_b32_e32 v185, 0xffff0000, v156
	v_lshlrev_b32_e32 v186, 16, v124
	v_and_b32_e32 v187, 0xffff0000, v124
	v_lshlrev_b32_e32 v188, 16, v157
	v_and_b32_e32 v189, 0xffff0000, v157
	v_lshlrev_b32_e32 v190, 16, v125
	v_and_b32_e32 v191, 0xffff0000, v125
	v_lshlrev_b32_e32 v192, 16, v158
	v_and_b32_e32 v193, 0xffff0000, v158
	v_lshlrev_b32_e32 v194, 16, v126
	v_and_b32_e32 v195, 0xffff0000, v126
	v_lshlrev_b32_e32 v196, 16, v159
	v_and_b32_e32 v197, 0xffff0000, v159
	v_lshlrev_b32_e32 v198, 16, v127
	v_and_b32_e32 v199, 0xffff0000, v127
	v_pk_add_f32 v[186:187], v[184:185], v[186:187] neg_lo:[0,1] neg_hi:[0,1]
	v_pk_add_f32 v[190:191], v[188:189], v[190:191] neg_lo:[0,1] neg_hi:[0,1]
	v_pk_add_f32 v[194:195], v[192:193], v[194:195] neg_lo:[0,1] neg_hi:[0,1]
	v_pk_add_f32 v[198:199], v[196:197], v[198:199] neg_lo:[0,1] neg_hi:[0,1]
	v_pk_add_f32 v[164:165], v[164:165], v[186:187]
	v_pk_add_f32 v[166:167], v[166:167], v[190:191]
	v_pk_add_f32 v[168:169], v[168:169], v[194:195]
	v_pk_add_f32 v[170:171], v[170:171], v[198:199]
	v_fma_f32 v186, s43, v164, -v184
	v_fma_f32 v187, s43, v165, -v185
	v_fma_f32 v190, s43, v166, -v188
	v_fma_f32 v191, s43, v167, -v189
	v_fma_f32 v194, s43, v168, -v192
	v_fma_f32 v195, s43, v169, -v193
	v_fma_f32 v198, s43, v170, -v196
	v_fma_f32 v199, s43, v171, -v197
	v_cvt_pk_bf16_f32 v172, v186, v187
	v_cvt_pk_bf16_f32 v173, v190, v191
	v_cvt_pk_bf16_f32 v174, v194, v195
	v_cvt_pk_bf16_f32 v175, v198, v199
	global_store_dwordx4 v3, v[172:175], s[10:11] sc1
	v_add_u32_e32 v3, 0x2000, v3
	s_waitcnt vmcnt(31)
	v_lshlrev_b32_e32 v184, 16, v160
	v_and_b32_e32 v185, 0xffff0000, v160
	v_lshlrev_b32_e32 v186, 16, v128
	v_and_b32_e32 v187, 0xffff0000, v128
	v_lshlrev_b32_e32 v188, 16, v161
	v_and_b32_e32 v189, 0xffff0000, v161
	v_lshlrev_b32_e32 v190, 16, v129
	v_and_b32_e32 v191, 0xffff0000, v129
	v_lshlrev_b32_e32 v192, 16, v162
	v_and_b32_e32 v193, 0xffff0000, v162
	v_lshlrev_b32_e32 v194, 16, v130
	v_and_b32_e32 v195, 0xffff0000, v130
	v_lshlrev_b32_e32 v196, 16, v163
	v_and_b32_e32 v197, 0xffff0000, v163
	v_lshlrev_b32_e32 v198, 16, v131
	v_and_b32_e32 v199, 0xffff0000, v131
	v_pk_add_f32 v[186:187], v[184:185], v[186:187] neg_lo:[0,1] neg_hi:[0,1]
	v_pk_add_f32 v[190:191], v[188:189], v[190:191] neg_lo:[0,1] neg_hi:[0,1]
	v_pk_add_f32 v[194:195], v[192:193], v[194:195] neg_lo:[0,1] neg_hi:[0,1]
	v_pk_add_f32 v[198:199], v[196:197], v[198:199] neg_lo:[0,1] neg_hi:[0,1]
	v_pk_add_f32 v[164:165], v[164:165], v[186:187]
	v_pk_add_f32 v[166:167], v[166:167], v[190:191]
	v_pk_add_f32 v[168:169], v[168:169], v[194:195]
	v_pk_add_f32 v[170:171], v[170:171], v[198:199]
	v_fma_f32 v186, s43, v164, -v184
	v_fma_f32 v187, s43, v165, -v185
	v_fma_f32 v190, s43, v166, -v188
	v_fma_f32 v191, s43, v167, -v189
	v_fma_f32 v194, s43, v168, -v192
	v_fma_f32 v195, s43, v169, -v193
	v_fma_f32 v198, s43, v170, -v196
	v_fma_f32 v199, s43, v171, -v197
	v_cvt_pk_bf16_f32 v172, v186, v187
	v_cvt_pk_bf16_f32 v173, v190, v191
	v_cvt_pk_bf16_f32 v174, v194, v195
	v_cvt_pk_bf16_f32 v175, v198, v199
	global_store_dwordx4 v3, v[172:175], s[10:11] sc1
	s_branch .LBB0_441

; __device__ __forceinline__ float bf_lo(unsigned w) { return __uint_as_float(w << 16); }
; __device__ __forceinline__ float bf_hi(unsigned w) { return __uint_as_float(w & 0xffff0000u); }
; __device__ void phase_pool() {
;     ...
;         { u32x4 hv[16];
; #pragma unroll
;           for (int k = 1; k <= 16; ++k) hv[k - 1] = (k <= nh) ? *(const u32x4*)(uz + (size_t)(row0 - k) * DE2 + col) : (u32x4){0u, 0u, 0u, 0u};
; #pragma unroll
;           for (int k = 0; k < 16; ++k) { const u32x4 v = hv[k];
;             s[0] += bf_lo(v.x); s[1] += bf_hi(v.x); s[2] += bf_lo(v.y); s[3] += bf_hi(v.y); s[4] += bf_lo(v.z); s[5] += bf_hi(v.z); s[6] += bf_lo(v.w); s[7] += bf_hi(v.w); } }
; #pragma unroll 1
;         for (int r0 = 0; r0 < RB; r0 += 8) {
;             u32x4 vv[8], ov[8];
; #pragma unroll
;             for (int k = 0; k < 8; ++k) { const int row = row0 + r0 + k, tl = tl0 + r0 + k;
;                 vv[k] = *(const u32x4*)(uz + (size_t)row * DE2 + col);
;                 ov[k] = (tl >= w) ? *(const u32x4*)(uz + (size_t)(row - w) * DE2 + col) : (u32x4){0u, 0u, 0u, 0u}; }
.Lpool_w16_main:
	global_load_dwordx4 v[68:71], v2, s[8:9]
	v_add_u32_e32 v2, 0x4000, v2
	global_load_dwordx4 v[72:75], v2, s[8:9]
	v_add_u32_e32 v2, 0x4000, v2
	global_load_dwordx4 v[76:79], v2, s[8:9]
	v_add_u32_e32 v2, 0x4000, v2
	global_load_dwordx4 v[80:83], v2, s[8:9]
	v_add_u32_e32 v2, 0x4000, v2
	global_load_dwordx4 v[84:87], v2, s[8:9]
	v_add_u32_e32 v2, 0x4000, v2
	global_load_dwordx4 v[88:91], v2, s[8:9]
	v_add_u32_e32 v2, 0x4000, v2
	global_load_dwordx4 v[92:95], v2, s[8:9]
	v_add_u32_e32 v2, 0x4000, v2
	global_load_dwordx4 v[96:99], v2, s[8:9]
	v_add_u32_e32 v2, 0x4000, v2
	global_load_dwordx4 v[100:103], v2, s[8:9]
	v_add_u32_e32 v2, 0x4000, v2
	global_load_dwordx4 v[104:107], v2, s[8:9]
	v_add_u32_e32 v2, 0x4000, v2
	global_load_dwordx4 v[108:111], v2, s[8:9]
	v_add_u32_e32 v2, 0x4000, v2
	global_load_dwordx4 v[112:115], v2, s[8:9]
	v_add_u32_e32 v2, 0x4000, v2
	global_load_dwordx4 v[116:119], v2, s[8:9]
	v_add_u32_e32 v2, 0x4000, v2
	global_load_dwordx4 v[120:123], v2, s[8:9]
	v_add_u32_e32 v2, 0x4000, v2
	global_load_dwordx4 v[124:127], v2, s[8:9]
	v_add_u32_e32 v2, 0x4000, v2
	global_load_dwordx4 v[128:131], v2, s[8:9]
	v_add_u32_e32 v2, 0x4000, v2
	global_load_dwordx4 v[132:135], v2, s[8:9]
	v_add_u32_e32 v2, 0x4000, v2
	global_load_dwordx4 v[136:139], v2, s[8:9]
	v_add_u32_e32 v2, 0x4000, v2
	global_load_dwordx4 v[140:143], v2, s[8:9]
	v_add_u32_e32 v2, 0x4000, v2
	global_load_dwordx4 v[144:147], v2, s[8:9]
	v_add_u32_e32 v2, 0x4000, v2
	global_load_dwordx4 v[148:151], v2, s[8:9]
	v_add_u32_e32 v2, 0x4000, v2
	global_load_dwordx4 v[152:155], v2, s[8:9]
	v_add_u32_e32 v2, 0x4000, v2
	global_load_dwordx4 v[156:159], v2, s[8:9]
	v_add_u32_e32 v2, 0x4000, v2
	global_load_dwordx4 v[160:163], v2, s[8:9]
	v_add_u32_e32 v2, 0x4000, v2
	global_load_dwordx4 v[164:167], v2, s[8:9]
	v_add_u32_e32 v2, 0x4000, v2
	global_load_dwordx4 v[168:171], v2, s[8:9]
	v_add_u32_e32 v2, 0x4000, v2
	global_load_dwordx4 v[172:175], v2, s[8:9]
	v_add_u32_e32 v2, 0x4000, v2
	global_load_dwordx4 v[184:187], v2, s[8:9]
	v_add_u32_e32 v2, 0x4000, v2
	global_load_dwordx4 v[188:191], v2, s[8:9]
	v_add_u32_e32 v2, 0x4000, v2
	global_load_dwordx4 v[192:195], v2, s[8:9]
	v_add_u32_e32 v2, 0x4000, v2
	global_load_dwordx4 v[196:199], v2, s[8:9]
	v_add_u32_e32 v2, 0x4000, v2
	global_load_dwordx4 v[200:203], v2, s[8:9]
	v_mov_b32_e32 v204, 0
	v_mov_b32_e32 v205, 0
	v_mov_b32_e32 v206, 0
	v_mov_b32_e32 v207, 0
	v_mov_b32_e32 v208, 0
	v_mov_b32_e32 v209, 0
	v_mov_b32_e32 v210, 0
	v_mov_b32_e32 v211, 0
	s_mov_b32 s43, 0x3d800000
	s_cmp_eq_u32 s16, 0
	s_waitcnt vmcnt(32)
	v_lshlrev_b32_e32 v216, 16, v64
	v_and_b32_e32 v217, 0xffff0000, v64
	v_lshlrev_b32_e32 v220, 16, v65
	v_and_b32_e32 v221, 0xffff0000, v65
	v_lshlrev_b32_e32 v224, 16, v66
	v_and_b32_e32 v225, 0xffff0000, v66
	v_lshlrev_b32_e32 v228, 16, v67
	v_and_b32_e32 v229, 0xffff0000, v67
	v_pk_add_f32 v[204:205], v[204:205], v[216:217]
	v_pk_add_f32 v[206:207], v[206:207], v[220:221]
	v_pk_add_f32 v[208:209], v[208:209], v[224:225]
	v_pk_add_f32 v[210:211], v[210:211], v[228:229]
	v_lshlrev_b32_e32 v216, 16, v60
	v_and_b32_e32 v217, 0xffff0000, v60
	v_lshlrev_b32_e32 v220, 16, v61
	v_and_b32_e32 v221, 0xffff0000, v61
	v_lshlrev_b32_e32 v224, 16, v62
	v_and_b32_e32 v225, 0xffff0000, v62
	v_lshlrev_b32_e32 v228, 16, v63
	v_and_b32_e32 v229, 0xffff0000, v63
	v_pk_add_f32 v[204:205], v[204:205], v[216:217]
	v_pk_add_f32 v[206:207], v[206:207], v[220:221]
	v_pk_add_f32 v[208:209], v[208:209], v[224:225]
	v_pk_add_f32 v[210:211], v[210:211], v[228:229]
	v_lshlrev_b32_e32 v216, 16, v56
	v_and_b32_e32 v217, 0xffff0000, v56
	v_lshlrev_b32_e32 v220, 16, v57
	v_and_b32_e32 v221, 0xffff0000, v57
	v_lshlrev_b32_e32 v224, 16, v58
	v_and_b32_e32 v225, 0xffff0000, v58
	v_lshlrev_b32_e32 v228, 16, v59
	v_and_b32_e32 v229, 0xffff0000, v59
	v_pk_add_f32 v[204:205], v[204:205], v[216:217]
	v_pk_add_f32 v[206:207], v[206:207], v[220:221]
	v_pk_add_f32 v[208:209], v[208:209], v[224:225]
	v_pk_add_f32 v[210:211], v[210:211], v[228:229]
	v_lshlrev_b32_e32 v216, 16, v52
	v_and_b32_e32 v217, 0xffff0000, v52
	v_lshlrev_b32_e32 v220, 16, v53
	v_and_b32_e32 v221, 0xffff0000, v53
	v_lshlrev_b32_e32 v224, 16, v54
	v_and_b32_e32 v225, 0xffff0000, v54
	v_lshlrev_b32_e32 v228, 16, v55
	v_and_b32_e32 v229, 0xffff0000, v55
	v_pk_add_f32 v[204:205], v[204:205], v[216:217]
	v_pk_add_f32 v[206:207], v[206:207], v[220:221]
	v_pk_add_f32 v[208:209], v[208:209], v[224:225]
	v_pk_add_f32 v[210:211], v[210:211], v[228:229]
	v_lshlrev_b32_e32 v216, 16, v48
	v_and_b32_e32 v217, 0xffff0000, v48
	v_lshlrev_b32_e32 v220, 16, v49
	v_and_b32_e32 v221, 0xffff0000, v49
	v_lshlrev_b32_e32 v224, 16, v50
	v_and_b32_e32 v225, 0xffff0000, v50
	v_lshlrev_b32_e32 v228, 16, v51
	v_and_b32_e32 v229, 0xffff0000, v51
	v_pk_add_f32 v[204:205], v[204:205], v[216:217]
	v_pk_add_f32 v[206:207], v[206:207], v[220:221]
	v_pk_add_f32 v[208:209], v[208:209], v[224:225]
	v_pk_add_f32 v[210:211], v[210:211], v[228:229]
	v_lshlrev_b32_e32 v216, 16, v44
	v_and_b32_e32 v217, 0xffff0000, v44
	v_lshlrev_b32_e32 v220, 16, v45
	v_and_b32_e32 v221, 0xffff0000, v45
	v_lshlrev_b32_e32 v224, 16, v46
	v_and_b32_e32 v225, 0xffff0000, v46
	v_lshlrev_b32_e32 v228, 16, v47
	v_and_b32_e32 v229, 0xffff0000, v47
	v_pk_add_f32 v[204:205], v[204:205], v[216:217]
	v_pk_add_f32 v[206:207], v[206:207], v[220:221]
	v_pk_add_f32 v[208:209], v[208:209], v[224:225]
	v_pk_add_f32 v[210:211], v[210:211], v[228:229]
	v_lshlrev_b32_e32 v216, 16, v40
	v_and_b32_e32 v217, 0xffff0000, v40
	v_lshlrev_b32_e32 v220, 16, v41
	v_and_b32_e32 v221, 0xffff0000, v41
	v_lshlrev_b32_e32 v224, 16, v42
	v_and_b32_e32 v225, 0xffff0000, v42
; __device__ __forceinline__ unsigned cvt_pk_bf16(float lo, float hi) { unsigned r; asm volatile("v_cvt_pk_bf16_f32 %0, %1, %2" : "=v"(r) : "v"(lo), "v"(hi)); return r; }
; __device__ __forceinline__ float bf_lo(unsigned w) { return __uint_as_float(w << 16); }
; __device__ __forceinline__ float bf_hi(unsigned w) { return __uint_as_float(w & 0xffff0000u); }
; __device__ void phase_pool() {
;     ...
;           for (int k = 0; k < 16; ++k) { const u32x4 v = hv[k];
;             s[0] += bf_lo(v.x); s[1] += bf_hi(v.x); s[2] += bf_lo(v.y); s[3] += bf_hi(v.y); s[4] += bf_lo(v.z); s[5] += bf_hi(v.z); s[6] += bf_lo(v.w); s[7] += bf_hi(v.w); } }
;     ...
;             for (int k = 0; k < 8; ++k) { const int row = row0 + r0 + k, tl = tl0 + r0 + k; const u32x4 v = vv[k], o2 = ov[k];
;                 s[0] += bf_lo(v.x) - bf_lo(o2.x); s[1] += bf_hi(v.x) - bf_hi(o2.x); s[2] += bf_lo(v.y) - bf_lo(o2.y); s[3] += bf_hi(v.y) - bf_hi(o2.y);
;                 s[4] += bf_lo(v.z) - bf_lo(o2.z); s[5] += bf_hi(v.z) - bf_hi(o2.z); s[6] += bf_lo(v.w) - bf_lo(o2.w); s[7] += bf_hi(v.w) - bf_hi(o2.w);
;                 const float ic = 1.0f / (float)((tl + 1 < w) ? tl + 1 : w);
;                 u32x4 o;
;                 o.x = cvt_pk_bf16(s[0] * ic - bf_lo(v.x), s[1] * ic - bf_hi(v.x)); o.y = cvt_pk_bf16(s[2] * ic - bf_lo(v.y), s[3] * ic - bf_hi(v.y));
;                 o.z = cvt_pk_bf16(s[4] * ic - bf_lo(v.z), s[5] * ic - bf_hi(v.z)); o.w = cvt_pk_bf16(s[6] * ic - bf_lo(v.w), s[7] * ic - bf_hi(v.w));
;                 *(u32x4*)(pg + (size_t)row * DE + col) = o; }
	v_lshlrev_b32_e32 v228, 16, v43
	v_and_b32_e32 v229, 0xffff0000, v43
	v_pk_add_f32 v[204:205], v[204:205], v[216:217]
	v_pk_add_f32 v[206:207], v[206:207], v[220:221]
	v_pk_add_f32 v[208:209], v[208:209], v[224:225]
	v_pk_add_f32 v[210:211], v[210:211], v[228:229]
	v_lshlrev_b32_e32 v216, 16, v36
	v_and_b32_e32 v217, 0xffff0000, v36
	v_lshlrev_b32_e32 v220, 16, v37
	v_and_b32_e32 v221, 0xffff0000, v37
	v_lshlrev_b32_e32 v224, 16, v38
	v_and_b32_e32 v225, 0xffff0000, v38
	v_lshlrev_b32_e32 v228, 16, v39
	v_and_b32_e32 v229, 0xffff0000, v39
	v_pk_add_f32 v[204:205], v[204:205], v[216:217]
	v_pk_add_f32 v[206:207], v[206:207], v[220:221]
	v_pk_add_f32 v[208:209], v[208:209], v[224:225]
	v_pk_add_f32 v[210:211], v[210:211], v[228:229]
	v_lshlrev_b32_e32 v216, 16, v32
	v_and_b32_e32 v217, 0xffff0000, v32
	v_lshlrev_b32_e32 v220, 16, v33
	v_and_b32_e32 v221, 0xffff0000, v33
	v_lshlrev_b32_e32 v224, 16, v34
	v_and_b32_e32 v225, 0xffff0000, v34
	v_lshlrev_b32_e32 v228, 16, v35
	v_and_b32_e32 v229, 0xffff0000, v35
	v_pk_add_f32 v[204:205], v[204:205], v[216:217]
	v_pk_add_f32 v[206:207], v[206:207], v[220:221]
	v_pk_add_f32 v[208:209], v[208:209], v[224:225]
	v_pk_add_f32 v[210:211], v[210:211], v[228:229]
	v_lshlrev_b32_e32 v216, 16, v28
	v_and_b32_e32 v217, 0xffff0000, v28
	v_lshlrev_b32_e32 v220, 16, v29
	v_and_b32_e32 v221, 0xffff0000, v29
	v_lshlrev_b32_e32 v224, 16, v30
	v_and_b32_e32 v225, 0xffff0000, v30
	v_lshlrev_b32_e32 v228, 16, v31
	v_and_b32_e32 v229, 0xffff0000, v31
	v_pk_add_f32 v[204:205], v[204:205], v[216:217]
	v_pk_add_f32 v[206:207], v[206:207], v[220:221]
	v_pk_add_f32 v[208:209], v[208:209], v[224:225]
	v_pk_add_f32 v[210:211], v[210:211], v[228:229]
	v_lshlrev_b32_e32 v216, 16, v24
	v_and_b32_e32 v217, 0xffff0000, v24
	v_lshlrev_b32_e32 v220, 16, v25
	v_and_b32_e32 v221, 0xffff0000, v25
	v_lshlrev_b32_e32 v224, 16, v26
	v_and_b32_e32 v225, 0xffff0000, v26
	v_lshlrev_b32_e32 v228, 16, v27
	v_and_b32_e32 v229, 0xffff0000, v27
	v_pk_add_f32 v[204:205], v[204:205], v[216:217]
	v_pk_add_f32 v[206:207], v[206:207], v[220:221]
	v_pk_add_f32 v[208:209], v[208:209], v[224:225]
	v_pk_add_f32 v[210:211], v[210:211], v[228:229]
	v_lshlrev_b32_e32 v216, 16, v20
	v_and_b32_e32 v217, 0xffff0000, v20
	v_lshlrev_b32_e32 v220, 16, v21
	v_and_b32_e32 v221, 0xffff0000, v21
	v_lshlrev_b32_e32 v224, 16, v22
	v_and_b32_e32 v225, 0xffff0000, v22
	v_lshlrev_b32_e32 v228, 16, v23
	v_and_b32_e32 v229, 0xffff0000, v23
	v_pk_add_f32 v[204:205], v[204:205], v[216:217]
	v_pk_add_f32 v[206:207], v[206:207], v[220:221]
	v_pk_add_f32 v[208:209], v[208:209], v[224:225]
	v_pk_add_f32 v[210:211], v[210:211], v[228:229]
	v_lshlrev_b32_e32 v216, 16, v16
	v_and_b32_e32 v217, 0xffff0000, v16
	v_lshlrev_b32_e32 v220, 16, v17
	v_and_b32_e32 v221, 0xffff0000, v17
	v_lshlrev_b32_e32 v224, 16, v18
	v_and_b32_e32 v225, 0xffff0000, v18
	v_lshlrev_b32_e32 v228, 16, v19
	v_and_b32_e32 v229, 0xffff0000, v19
	v_pk_add_f32 v[204:205], v[204:205], v[216:217]
	v_pk_add_f32 v[206:207], v[206:207], v[220:221]
	v_pk_add_f32 v[208:209], v[208:209], v[224:225]
	v_pk_add_f32 v[210:211], v[210:211], v[228:229]
	v_lshlrev_b32_e32 v216, 16, v12
	v_and_b32_e32 v217, 0xffff0000, v12
	v_lshlrev_b32_e32 v220, 16, v13
	v_and_b32_e32 v221, 0xffff0000, v13
	v_lshlrev_b32_e32 v224, 16, v14
	v_and_b32_e32 v225, 0xffff0000, v14
	v_lshlrev_b32_e32 v228, 16, v15
	v_and_b32_e32 v229, 0xffff0000, v15
	v_pk_add_f32 v[204:205], v[204:205], v[216:217]
	v_pk_add_f32 v[206:207], v[206:207], v[220:221]
	v_pk_add_f32 v[208:209], v[208:209], v[224:225]
	v_pk_add_f32 v[210:211], v[210:211], v[228:229]
	v_lshlrev_b32_e32 v216, 16, v8
	v_and_b32_e32 v217, 0xffff0000, v8
	v_lshlrev_b32_e32 v220, 16, v9
	v_and_b32_e32 v221, 0xffff0000, v9
	v_lshlrev_b32_e32 v224, 16, v10
	v_and_b32_e32 v225, 0xffff0000, v10
	v_lshlrev_b32_e32 v228, 16, v11
	v_and_b32_e32 v229, 0xffff0000, v11
	v_pk_add_f32 v[204:205], v[204:205], v[216:217]
	v_pk_add_f32 v[206:207], v[206:207], v[220:221]
	v_pk_add_f32 v[208:209], v[208:209], v[224:225]
	v_pk_add_f32 v[210:211], v[210:211], v[228:229]
	v_lshlrev_b32_e32 v216, 16, v4
	v_and_b32_e32 v217, 0xffff0000, v4
	v_lshlrev_b32_e32 v220, 16, v5
	v_and_b32_e32 v221, 0xffff0000, v5
	v_lshlrev_b32_e32 v224, 16, v6
	v_and_b32_e32 v225, 0xffff0000, v6
	v_lshlrev_b32_e32 v228, 16, v7
	v_and_b32_e32 v229, 0xffff0000, v7
	v_pk_add_f32 v[204:205], v[204:205], v[216:217]
	v_pk_add_f32 v[206:207], v[206:207], v[220:221]
	v_pk_add_f32 v[208:209], v[208:209], v[224:225]
	v_pk_add_f32 v[210:211], v[210:211], v[228:229]
	s_waitcnt vmcnt(31)
	s_cselect_b32 s42, 0x3f800000, s43
	v_lshlrev_b32_e32 v216, 16, v68
	v_and_b32_e32 v217, 0xffff0000, v68
	v_lshlrev_b32_e32 v218, 16, v4
	v_and_b32_e32 v219, 0xffff0000, v4
	v_lshlrev_b32_e32 v220, 16, v69
	v_and_b32_e32 v221, 0xffff0000, v69
	v_lshlrev_b32_e32 v222, 16, v5
	v_and_b32_e32 v223, 0xffff0000, v5
	v_lshlrev_b32_e32 v224, 16, v70
	v_and_b32_e32 v225, 0xffff0000, v70
	v_lshlrev_b32_e32 v226, 16, v6
	v_and_b32_e32 v227, 0xffff0000, v6
	v_lshlrev_b32_e32 v228, 16, v71
	v_and_b32_e32 v229, 0xffff0000, v71
	v_lshlrev_b32_e32 v230, 16, v7
	v_and_b32_e32 v231, 0xffff0000, v7
	v_pk_add_f32 v[218:219], v[216:217], v[218:219] neg_lo:[0,1] neg_hi:[0,1]
	v_pk_add_f32 v[222:223], v[220:221], v[222:223] neg_lo:[0,1] neg_hi:[0,1]
	v_pk_add_f32 v[226:227], v[224:225], v[226:227] neg_lo:[0,1] neg_hi:[0,1]
	v_pk_add_f32 v[230:231], v[228:229], v[230:231] neg_lo:[0,1] neg_hi:[0,1]
	v_pk_add_f32 v[204:205], v[204:205], v[218:219]
	v_pk_add_f32 v[206:207], v[206:207], v[222:223]
	v_pk_add_f32 v[208:209], v[208:209], v[226:227]
	v_pk_add_f32 v[210:211], v[210:211], v[230:231]
	v_fma_f32 v218, s42, v204, -v216
	v_fma_f32 v219, s42, v205, -v217
	v_fma_f32 v222, s42, v206, -v220
	v_fma_f32 v223, s42, v207, -v221
	v_fma_f32 v226, s42, v208, -v224
	v_fma_f32 v227, s42, v209, -v225
	v_fma_f32 v230, s42, v210, -v228
	v_fma_f32 v231, s42, v211, -v229
	v_cvt_pk_bf16_f32 v212, v218, v219
	v_cvt_pk_bf16_f32 v213, v222, v223
	v_cvt_pk_bf16_f32 v214, v226, v227
	v_cvt_pk_bf16_f32 v215, v230, v231
	global_store_dwordx4 v3, v[212:215], s[10:11] sc1
	v_add_u32_e32 v3, 0x2000, v3
	s_waitcnt vmcnt(31)
; __device__ __forceinline__ unsigned cvt_pk_bf16(float lo, float hi) { unsigned r; asm volatile("v_cvt_pk_bf16_f32 %0, %1, %2" : "=v"(r) : "v"(lo), "v"(hi)); return r; }
; __device__ __forceinline__ float bf_lo(unsigned w) { return __uint_as_float(w << 16); }
; __device__ __forceinline__ float bf_hi(unsigned w) { return __uint_as_float(w & 0xffff0000u); }
; __device__ void phase_pool() {
;     ...
;             for (int k = 0; k < 8; ++k) { const int row = row0 + r0 + k, tl = tl0 + r0 + k;
;                 vv[k] = *(const u32x4*)(uz + (size_t)row * DE2 + col);
;                 ov[k] = (tl >= w) ? *(const u32x4*)(uz + (size_t)(row - w) * DE2 + col) : (u32x4){0u, 0u, 0u, 0u}; }
; #pragma unroll
;             for (int k = 0; k < 8; ++k) { const int row = row0 + r0 + k, tl = tl0 + r0 + k; const u32x4 v = vv[k], o2 = ov[k];
;                 s[0] += bf_lo(v.x) - bf_lo(o2.x); s[1] += bf_hi(v.x) - bf_hi(o2.x); s[2] += bf_lo(v.y) - bf_lo(o2.y); s[3] += bf_hi(v.y) - bf_hi(o2.y);
;                 s[4] += bf_lo(v.z) - bf_lo(o2.z); s[5] += bf_hi(v.z) - bf_hi(o2.z); s[6] += bf_lo(v.w) - bf_lo(o2.w); s[7] += bf_hi(v.w) - bf_hi(o2.w);
;                 const float ic = 1.0f / (float)((tl + 1 < w) ? tl + 1 : w);
;                 u32x4 o;
;                 o.x = cvt_pk_bf16(s[0] * ic - bf_lo(v.x), s[1] * ic - bf_hi(v.x)); o.y = cvt_pk_bf16(s[2] * ic - bf_lo(v.y), s[3] * ic - bf_hi(v.y));
;                 o.z = cvt_pk_bf16(s[4] * ic - bf_lo(v.z), s[5] * ic - bf_hi(v.z)); o.w = cvt_pk_bf16(s[6] * ic - bf_lo(v.w), s[7] * ic - bf_hi(v.w));
;                 *(u32x4*)(pg + (size_t)row * DE + col) = o; }
	s_cselect_b32 s42, 0x3f000000, s43
	v_lshlrev_b32_e32 v216, 16, v72
	v_and_b32_e32 v217, 0xffff0000, v72
	v_lshlrev_b32_e32 v218, 16, v8
	v_and_b32_e32 v219, 0xffff0000, v8
	v_lshlrev_b32_e32 v220, 16, v73
	v_and_b32_e32 v221, 0xffff0000, v73
	v_lshlrev_b32_e32 v222, 16, v9
	v_and_b32_e32 v223, 0xffff0000, v9
	v_lshlrev_b32_e32 v224, 16, v74
	v_and_b32_e32 v225, 0xffff0000, v74
	v_lshlrev_b32_e32 v226, 16, v10
	v_and_b32_e32 v227, 0xffff0000, v10
	v_lshlrev_b32_e32 v228, 16, v75
	v_and_b32_e32 v229, 0xffff0000, v75
	v_lshlrev_b32_e32 v230, 16, v11
	v_and_b32_e32 v231, 0xffff0000, v11
	v_pk_add_f32 v[218:219], v[216:217], v[218:219] neg_lo:[0,1] neg_hi:[0,1]
	v_pk_add_f32 v[222:223], v[220:221], v[222:223] neg_lo:[0,1] neg_hi:[0,1]
	v_pk_add_f32 v[226:227], v[224:225], v[226:227] neg_lo:[0,1] neg_hi:[0,1]
	v_pk_add_f32 v[230:231], v[228:229], v[230:231] neg_lo:[0,1] neg_hi:[0,1]
	v_pk_add_f32 v[204:205], v[204:205], v[218:219]
	v_pk_add_f32 v[206:207], v[206:207], v[222:223]
	v_pk_add_f32 v[208:209], v[208:209], v[226:227]
	v_pk_add_f32 v[210:211], v[210:211], v[230:231]
	v_fma_f32 v218, s42, v204, -v216
	v_fma_f32 v219, s42, v205, -v217
	v_fma_f32 v222, s42, v206, -v220
	v_fma_f32 v223, s42, v207, -v221
	v_fma_f32 v226, s42, v208, -v224
	v_fma_f32 v227, s42, v209, -v225
	v_fma_f32 v230, s42, v210, -v228
	v_fma_f32 v231, s42, v211, -v229
	v_cvt_pk_bf16_f32 v212, v218, v219
	v_cvt_pk_bf16_f32 v213, v222, v223
	v_cvt_pk_bf16_f32 v214, v226, v227
	v_cvt_pk_bf16_f32 v215, v230, v231
	global_store_dwordx4 v3, v[212:215], s[10:11] sc1
	v_add_u32_e32 v3, 0x2000, v3
	s_waitcnt vmcnt(31)
	s_cselect_b32 s42, 0x3eaaaaab, s43
	v_lshlrev_b32_e32 v216, 16, v76
	v_and_b32_e32 v217, 0xffff0000, v76
	v_lshlrev_b32_e32 v218, 16, v12
	v_and_b32_e32 v219, 0xffff0000, v12
	v_lshlrev_b32_e32 v220, 16, v77
	v_and_b32_e32 v221, 0xffff0000, v77
	v_lshlrev_b32_e32 v222, 16, v13
	v_and_b32_e32 v223, 0xffff0000, v13
	v_lshlrev_b32_e32 v224, 16, v78
	v_and_b32_e32 v225, 0xffff0000, v78
	v_lshlrev_b32_e32 v226, 16, v14
	v_and_b32_e32 v227, 0xffff0000, v14
	v_lshlrev_b32_e32 v228, 16, v79
	v_and_b32_e32 v229, 0xffff0000, v79
	v_lshlrev_b32_e32 v230, 16, v15
	v_and_b32_e32 v231, 0xffff0000, v15
	v_pk_add_f32 v[218:219], v[216:217], v[218:219] neg_lo:[0,1] neg_hi:[0,1]
	v_pk_add_f32 v[222:223], v[220:221], v[222:223] neg_lo:[0,1] neg_hi:[0,1]
	v_pk_add_f32 v[226:227], v[224:225], v[226:227] neg_lo:[0,1] neg_hi:[0,1]
	v_pk_add_f32 v[230:231], v[228:229], v[230:231] neg_lo:[0,1] neg_hi:[0,1]
	v_pk_add_f32 v[204:205], v[204:205], v[218:219]
	v_pk_add_f32 v[206:207], v[206:207], v[222:223]
	v_pk_add_f32 v[208:209], v[208:209], v[226:227]
	v_pk_add_f32 v[210:211], v[210:211], v[230:231]
	v_fma_f32 v218, s42, v204, -v216
	v_fma_f32 v219, s42, v205, -v217
	v_fma_f32 v222, s42, v206, -v220
	v_fma_f32 v223, s42, v207, -v221
	v_fma_f32 v226, s42, v208, -v224
	v_fma_f32 v227, s42, v209, -v225
	v_fma_f32 v230, s42, v210, -v228
	v_fma_f32 v231, s42, v211, -v229
	v_cvt_pk_bf16_f32 v212, v218, v219
	v_cvt_pk_bf16_f32 v213, v222, v223
	v_cvt_pk_bf16_f32 v214, v226, v227
	v_cvt_pk_bf16_f32 v215, v230, v231
	global_store_dwordx4 v3, v[212:215], s[10:11] sc1
	v_add_u32_e32 v3, 0x2000, v3
	s_waitcnt vmcnt(31)
	s_cselect_b32 s42, 0x3e800000, s43
	v_lshlrev_b32_e32 v216, 16, v80
	v_and_b32_e32 v217, 0xffff0000, v80
	v_lshlrev_b32_e32 v218, 16, v16
	v_and_b32_e32 v219, 0xffff0000, v16
	v_lshlrev_b32_e32 v220, 16, v81
	v_and_b32_e32 v221, 0xffff0000, v81
	v_lshlrev_b32_e32 v222, 16, v17
	v_and_b32_e32 v223, 0xffff0000, v17
	v_lshlrev_b32_e32 v224, 16, v82
	v_and_b32_e32 v225, 0xffff0000, v82
	v_lshlrev_b32_e32 v226, 16, v18
	v_and_b32_e32 v227, 0xffff0000, v18
	v_lshlrev_b32_e32 v228, 16, v83
	v_and_b32_e32 v229, 0xffff0000, v83
	v_lshlrev_b32_e32 v230, 16, v19
	v_and_b32_e32 v231, 0xffff0000, v19
	v_pk_add_f32 v[218:219], v[216:217], v[218:219] neg_lo:[0,1] neg_hi:[0,1]
	v_pk_add_f32 v[222:223], v[220:221], v[222:223] neg_lo:[0,1] neg_hi:[0,1]
	v_pk_add_f32 v[226:227], v[224:225], v[226:227] neg_lo:[0,1] neg_hi:[0,1]
	v_pk_add_f32 v[230:231], v[228:229], v[230:231] neg_lo:[0,1] neg_hi:[0,1]
	v_pk_add_f32 v[204:205], v[204:205], v[218:219]
	v_pk_add_f32 v[206:207], v[206:207], v[222:223]
	v_pk_add_f32 v[208:209], v[208:209], v[226:227]
	v_pk_add_f32 v[210:211], v[210:211], v[230:231]
	v_fma_f32 v218, s42, v204, -v216
	v_fma_f32 v219, s42, v205, -v217
	v_fma_f32 v222, s42, v206, -v220
	v_fma_f32 v223, s42, v207, -v221
	v_fma_f32 v226, s42, v208, -v224
	v_fma_f32 v227, s42, v209, -v225
	v_fma_f32 v230, s42, v210, -v228
	v_fma_f32 v231, s42, v211, -v229
	v_cvt_pk_bf16_f32 v212, v218, v219
	v_cvt_pk_bf16_f32 v213, v222, v223
	v_cvt_pk_bf16_f32 v214, v226, v227
	v_cvt_pk_bf16_f32 v215, v230, v231
	global_store_dwordx4 v3, v[212:215], s[10:11] sc1
	v_add_u32_e32 v3, 0x2000, v3
	s_waitcnt vmcnt(31)
	s_cselect_b32 s42, 0x3e4ccccd, s43
	v_lshlrev_b32_e32 v216, 16, v84
	v_and_b32_e32 v217, 0xffff0000, v84
	v_lshlrev_b32_e32 v218, 16, v20
	v_and_b32_e32 v219, 0xffff0000, v20
	v_lshlrev_b32_e32 v220, 16, v85
	v_and_b32_e32 v221, 0xffff0000, v85
	v_lshlrev_b32_e32 v222, 16, v21
	v_and_b32_e32 v223, 0xffff0000, v21
	v_lshlrev_b32_e32 v224, 16, v86
	v_and_b32_e32 v225, 0xffff0000, v86
	v_lshlrev_b32_e32 v226, 16, v22
	v_and_b32_e32 v227, 0xffff0000, v22
	v_lshlrev_b32_e32 v228, 16, v87
	v_and_b32_e32 v229, 0xffff0000, v87
	v_lshlrev_b32_e32 v230, 16, v23
	v_and_b32_e32 v231, 0xffff0000, v23
	v_pk_add_f32 v[218:219], v[216:217], v[218:219] neg_lo:[0,1] neg_hi:[0,1]
	v_pk_add_f32 v[222:223], v[220:221], v[222:223] neg_lo:[0,1] neg_hi:[0,1]
	v_pk_add_f32 v[226:227], v[224:225], v[226:227] neg_lo:[0,1] neg_hi:[0,1]
	v_pk_add_f32 v[230:231], v[228:229], v[230:231] neg_lo:[0,1] neg_hi:[0,1]
	v_pk_add_f32 v[204:205], v[204:205], v[218:219]
	v_pk_add_f32 v[206:207], v[206:207], v[222:223]
	v_pk_add_f32 v[208:209], v[208:209], v[226:227]
	v_pk_add_f32 v[210:211], v[210:211], v[230:231]
	v_fma_f32 v218, s42, v204, -v216
	v_fma_f32 v219, s42, v205, -v217
	v_fma_f32 v222, s42, v206, -v220
	v_fma_f32 v223, s42, v207, -v221
	v_fma_f32 v226, s42, v208, -v224
	v_fma_f32 v227, s42, v209, -v225
	v_fma_f32 v230, s42, v210, -v228
	v_fma_f32 v231, s42, v211, -v229
	v_cvt_pk_bf16_f32 v212, v218, v219
	v_cvt_pk_bf16_f32 v213, v222, v223
	v_cvt_pk_bf16_f32 v214, v226, v227
	v_cvt_pk_bf16_f32 v215, v230, v231
	global_store_dwordx4 v3, v[212:215], s[10:11] sc1
	v_add_u32_e32 v3, 0x2000, v3
	s_waitcnt vmcnt(31)
; __device__ __forceinline__ unsigned cvt_pk_bf16(float lo, float hi) { unsigned r; asm volatile("v_cvt_pk_bf16_f32 %0, %1, %2" : "=v"(r) : "v"(lo), "v"(hi)); return r; }
; __device__ __forceinline__ float bf_lo(unsigned w) { return __uint_as_float(w << 16); }
; __device__ __forceinline__ float bf_hi(unsigned w) { return __uint_as_float(w & 0xffff0000u); }
; __device__ void phase_pool() {
;     ...
;             for (int k = 0; k < 8; ++k) { const int row = row0 + r0 + k, tl = tl0 + r0 + k;
;                 vv[k] = *(const u32x4*)(uz + (size_t)row * DE2 + col);
;                 ov[k] = (tl >= w) ? *(const u32x4*)(uz + (size_t)(row - w) * DE2 + col) : (u32x4){0u, 0u, 0u, 0u}; }
; #pragma unroll
;             for (int k = 0; k < 8; ++k) { const int row = row0 + r0 + k, tl = tl0 + r0 + k; const u32x4 v = vv[k], o2 = ov[k];
;                 s[0] += bf_lo(v.x) - bf_lo(o2.x); s[1] += bf_hi(v.x) - bf_hi(o2.x); s[2] += bf_lo(v.y) - bf_lo(o2.y); s[3] += bf_hi(v.y) - bf_hi(o2.y);
;                 s[4] += bf_lo(v.z) - bf_lo(o2.z); s[5] += bf_hi(v.z) - bf_hi(o2.z); s[6] += bf_lo(v.w) - bf_lo(o2.w); s[7] += bf_hi(v.w) - bf_hi(o2.w);
;                 const float ic = 1.0f / (float)((tl + 1 < w) ? tl + 1 : w);
;                 u32x4 o;
;                 o.x = cvt_pk_bf16(s[0] * ic - bf_lo(v.x), s[1] * ic - bf_hi(v.x)); o.y = cvt_pk_bf16(s[2] * ic - bf_lo(v.y), s[3] * ic - bf_hi(v.y));
;                 o.z = cvt_pk_bf16(s[4] * ic - bf_lo(v.z), s[5] * ic - bf_hi(v.z)); o.w = cvt_pk_bf16(s[6] * ic - bf_lo(v.w), s[7] * ic - bf_hi(v.w));
;                 *(u32x4*)(pg + (size_t)row * DE + col) = o; }
	s_cselect_b32 s42, 0x3e2aaaab, s43
	v_lshlrev_b32_e32 v216, 16, v88
	v_and_b32_e32 v217, 0xffff0000, v88
	v_lshlrev_b32_e32 v218, 16, v24
	v_and_b32_e32 v219, 0xffff0000, v24
	v_lshlrev_b32_e32 v220, 16, v89
	v_and_b32_e32 v221, 0xffff0000, v89
	v_lshlrev_b32_e32 v222, 16, v25
	v_and_b32_e32 v223, 0xffff0000, v25
	v_lshlrev_b32_e32 v224, 16, v90
	v_and_b32_e32 v225, 0xffff0000, v90
	v_lshlrev_b32_e32 v226, 16, v26
	v_and_b32_e32 v227, 0xffff0000, v26
	v_lshlrev_b32_e32 v228, 16, v91
	v_and_b32_e32 v229, 0xffff0000, v91
	v_lshlrev_b32_e32 v230, 16, v27
	v_and_b32_e32 v231, 0xffff0000, v27
	v_pk_add_f32 v[218:219], v[216:217], v[218:219] neg_lo:[0,1] neg_hi:[0,1]
	v_pk_add_f32 v[222:223], v[220:221], v[222:223] neg_lo:[0,1] neg_hi:[0,1]
	v_pk_add_f32 v[226:227], v[224:225], v[226:227] neg_lo:[0,1] neg_hi:[0,1]
	v_pk_add_f32 v[230:231], v[228:229], v[230:231] neg_lo:[0,1] neg_hi:[0,1]
	v_pk_add_f32 v[204:205], v[204:205], v[218:219]
	v_pk_add_f32 v[206:207], v[206:207], v[222:223]
	v_pk_add_f32 v[208:209], v[208:209], v[226:227]
	v_pk_add_f32 v[210:211], v[210:211], v[230:231]
	v_fma_f32 v218, s42, v204, -v216
	v_fma_f32 v219, s42, v205, -v217
	v_fma_f32 v222, s42, v206, -v220
	v_fma_f32 v223, s42, v207, -v221
	v_fma_f32 v226, s42, v208, -v224
	v_fma_f32 v227, s42, v209, -v225
	v_fma_f32 v230, s42, v210, -v228
	v_fma_f32 v231, s42, v211, -v229
	v_cvt_pk_bf16_f32 v212, v218, v219
	v_cvt_pk_bf16_f32 v213, v222, v223
	v_cvt_pk_bf16_f32 v214, v226, v227
	v_cvt_pk_bf16_f32 v215, v230, v231
	global_store_dwordx4 v3, v[212:215], s[10:11] sc1
	v_add_u32_e32 v3, 0x2000, v3
	s_waitcnt vmcnt(31)
	s_cselect_b32 s42, 0x3e124925, s43
	v_lshlrev_b32_e32 v216, 16, v92
	v_and_b32_e32 v217, 0xffff0000, v92
	v_lshlrev_b32_e32 v218, 16, v28
	v_and_b32_e32 v219, 0xffff0000, v28
	v_lshlrev_b32_e32 v220, 16, v93
	v_and_b32_e32 v221, 0xffff0000, v93
	v_lshlrev_b32_e32 v222, 16, v29
	v_and_b32_e32 v223, 0xffff0000, v29
	v_lshlrev_b32_e32 v224, 16, v94
	v_and_b32_e32 v225, 0xffff0000, v94
	v_lshlrev_b32_e32 v226, 16, v30
	v_and_b32_e32 v227, 0xffff0000, v30
	v_lshlrev_b32_e32 v228, 16, v95
	v_and_b32_e32 v229, 0xffff0000, v95
	v_lshlrev_b32_e32 v230, 16, v31
	v_and_b32_e32 v231, 0xffff0000, v31
	v_pk_add_f32 v[218:219], v[216:217], v[218:219] neg_lo:[0,1] neg_hi:[0,1]
	v_pk_add_f32 v[222:223], v[220:221], v[222:223] neg_lo:[0,1] neg_hi:[0,1]
	v_pk_add_f32 v[226:227], v[224:225], v[226:227] neg_lo:[0,1] neg_hi:[0,1]
	v_pk_add_f32 v[230:231], v[228:229], v[230:231] neg_lo:[0,1] neg_hi:[0,1]
	v_pk_add_f32 v[204:205], v[204:205], v[218:219]
	v_pk_add_f32 v[206:207], v[206:207], v[222:223]
	v_pk_add_f32 v[208:209], v[208:209], v[226:227]
	v_pk_add_f32 v[210:211], v[210:211], v[230:231]
	v_fma_f32 v218, s42, v204, -v216
	v_fma_f32 v219, s42, v205, -v217
	v_fma_f32 v222, s42, v206, -v220
	v_fma_f32 v223, s42, v207, -v221
	v_fma_f32 v226, s42, v208, -v224
	v_fma_f32 v227, s42, v209, -v225
	v_fma_f32 v230, s42, v210, -v228
	v_fma_f32 v231, s42, v211, -v229
	v_cvt_pk_bf16_f32 v212, v218, v219
	v_cvt_pk_bf16_f32 v213, v222, v223
	v_cvt_pk_bf16_f32 v214, v226, v227
	v_cvt_pk_bf16_f32 v215, v230, v231
	global_store_dwordx4 v3, v[212:215], s[10:11] sc1
	v_add_u32_e32 v3, 0x2000, v3
	s_waitcnt vmcnt(31)
	s_cselect_b32 s42, 0x3e000000, s43
	v_lshlrev_b32_e32 v216, 16, v96
	v_and_b32_e32 v217, 0xffff0000, v96
	v_lshlrev_b32_e32 v218, 16, v32
	v_and_b32_e32 v219, 0xffff0000, v32
	v_lshlrev_b32_e32 v220, 16, v97
	v_and_b32_e32 v221, 0xffff0000, v97
	v_lshlrev_b32_e32 v222, 16, v33
	v_and_b32_e32 v223, 0xffff0000, v33
	v_lshlrev_b32_e32 v224, 16, v98
	v_and_b32_e32 v225, 0xffff0000, v98
	v_lshlrev_b32_e32 v226, 16, v34
	v_and_b32_e32 v227, 0xffff0000, v34
	v_lshlrev_b32_e32 v228, 16, v99
	v_and_b32_e32 v229, 0xffff0000, v99
	v_lshlrev_b32_e32 v230, 16, v35
	v_and_b32_e32 v231, 0xffff0000, v35
	v_pk_add_f32 v[218:219], v[216:217], v[218:219] neg_lo:[0,1] neg_hi:[0,1]
	v_pk_add_f32 v[222:223], v[220:221], v[222:223] neg_lo:[0,1] neg_hi:[0,1]
	v_pk_add_f32 v[226:227], v[224:225], v[226:227] neg_lo:[0,1] neg_hi:[0,1]
	v_pk_add_f32 v[230:231], v[228:229], v[230:231] neg_lo:[0,1] neg_hi:[0,1]
	v_pk_add_f32 v[204:205], v[204:205], v[218:219]
	v_pk_add_f32 v[206:207], v[206:207], v[222:223]
	v_pk_add_f32 v[208:209], v[208:209], v[226:227]
	v_pk_add_f32 v[210:211], v[210:211], v[230:231]
	v_fma_f32 v218, s42, v204, -v216
	v_fma_f32 v219, s42, v205, -v217
	v_fma_f32 v222, s42, v206, -v220
	v_fma_f32 v223, s42, v207, -v221
	v_fma_f32 v226, s42, v208, -v224
	v_fma_f32 v227, s42, v209, -v225
	v_fma_f32 v230, s42, v210, -v228
	v_fma_f32 v231, s42, v211, -v229
	v_cvt_pk_bf16_f32 v212, v218, v219
	v_cvt_pk_bf16_f32 v213, v222, v223
	v_cvt_pk_bf16_f32 v214, v226, v227
	v_cvt_pk_bf16_f32 v215, v230, v231
	global_store_dwordx4 v3, v[212:215], s[10:11] sc1
	v_add_u32_e32 v3, 0x2000, v3
	s_waitcnt vmcnt(31)
	s_cselect_b32 s42, 0x3de38e39, s43
	v_lshlrev_b32_e32 v216, 16, v100
	v_and_b32_e32 v217, 0xffff0000, v100
	v_lshlrev_b32_e32 v218, 16, v36
	v_and_b32_e32 v219, 0xffff0000, v36
	v_lshlrev_b32_e32 v220, 16, v101
	v_and_b32_e32 v221, 0xffff0000, v101
	v_lshlrev_b32_e32 v222, 16, v37
	v_and_b32_e32 v223, 0xffff0000, v37
	v_lshlrev_b32_e32 v224, 16, v102
	v_and_b32_e32 v225, 0xffff0000, v102
	v_lshlrev_b32_e32 v226, 16, v38
	v_and_b32_e32 v227, 0xffff0000, v38
	v_lshlrev_b32_e32 v228, 16, v103
	v_and_b32_e32 v229, 0xffff0000, v103
	v_lshlrev_b32_e32 v230, 16, v39
	v_and_b32_e32 v231, 0xffff0000, v39
	v_pk_add_f32 v[218:219], v[216:217], v[218:219] neg_lo:[0,1] neg_hi:[0,1]
	v_pk_add_f32 v[222:223], v[220:221], v[222:223] neg_lo:[0,1] neg_hi:[0,1]
	v_pk_add_f32 v[226:227], v[224:225], v[226:227] neg_lo:[0,1] neg_hi:[0,1]
	v_pk_add_f32 v[230:231], v[228:229], v[230:231] neg_lo:[0,1] neg_hi:[0,1]
	v_pk_add_f32 v[204:205], v[204:205], v[218:219]
	v_pk_add_f32 v[206:207], v[206:207], v[222:223]
	v_pk_add_f32 v[208:209], v[208:209], v[226:227]
	v_pk_add_f32 v[210:211], v[210:211], v[230:231]
	v_fma_f32 v218, s42, v204, -v216
	v_fma_f32 v219, s42, v205, -v217
	v_fma_f32 v222, s42, v206, -v220
	v_fma_f32 v223, s42, v207, -v221
	v_fma_f32 v226, s42, v208, -v224
	v_fma_f32 v227, s42, v209, -v225
	v_fma_f32 v230, s42, v210, -v228
	v_fma_f32 v231, s42, v211, -v229
	v_cvt_pk_bf16_f32 v212, v218, v219
	v_cvt_pk_bf16_f32 v213, v222, v223
	v_cvt_pk_bf16_f32 v214, v226, v227
	v_cvt_pk_bf16_f32 v215, v230, v231
	global_store_dwordx4 v3, v[212:215], s[10:11] sc1
	v_add_u32_e32 v3, 0x2000, v3
	s_waitcnt vmcnt(31)
; __device__ __forceinline__ unsigned cvt_pk_bf16(float lo, float hi) { unsigned r; asm volatile("v_cvt_pk_bf16_f32 %0, %1, %2" : "=v"(r) : "v"(lo), "v"(hi)); return r; }
; __device__ __forceinline__ float bf_lo(unsigned w) { return __uint_as_float(w << 16); }
; __device__ __forceinline__ float bf_hi(unsigned w) { return __uint_as_float(w & 0xffff0000u); }
; __device__ void phase_pool() {
;     ...
;             for (int k = 0; k < 8; ++k) { const int row = row0 + r0 + k, tl = tl0 + r0 + k;
;                 vv[k] = *(const u32x4*)(uz + (size_t)row * DE2 + col);
;                 ov[k] = (tl >= w) ? *(const u32x4*)(uz + (size_t)(row - w) * DE2 + col) : (u32x4){0u, 0u, 0u, 0u}; }
; #pragma unroll
;             for (int k = 0; k < 8; ++k) { const int row = row0 + r0 + k, tl = tl0 + r0 + k; const u32x4 v = vv[k], o2 = ov[k];
;                 s[0] += bf_lo(v.x) - bf_lo(o2.x); s[1] += bf_hi(v.x) - bf_hi(o2.x); s[2] += bf_lo(v.y) - bf_lo(o2.y); s[3] += bf_hi(v.y) - bf_hi(o2.y);
;                 s[4] += bf_lo(v.z) - bf_lo(o2.z); s[5] += bf_hi(v.z) - bf_hi(o2.z); s[6] += bf_lo(v.w) - bf_lo(o2.w); s[7] += bf_hi(v.w) - bf_hi(o2.w);
;                 const float ic = 1.0f / (float)((tl + 1 < w) ? tl + 1 : w);
;                 u32x4 o;
;                 o.x = cvt_pk_bf16(s[0] * ic - bf_lo(v.x), s[1] * ic - bf_hi(v.x)); o.y = cvt_pk_bf16(s[2] * ic - bf_lo(v.y), s[3] * ic - bf_hi(v.y));
;                 o.z = cvt_pk_bf16(s[4] * ic - bf_lo(v.z), s[5] * ic - bf_hi(v.z)); o.w = cvt_pk_bf16(s[6] * ic - bf_lo(v.w), s[7] * ic - bf_hi(v.w));
;                 *(u32x4*)(pg + (size_t)row * DE + col) = o; }
	s_cselect_b32 s42, 0x3dcccccd, s43
	v_lshlrev_b32_e32 v216, 16, v104
	v_and_b32_e32 v217, 0xffff0000, v104
	v_lshlrev_b32_e32 v218, 16, v40
	v_and_b32_e32 v219, 0xffff0000, v40
	v_lshlrev_b32_e32 v220, 16, v105
	v_and_b32_e32 v221, 0xffff0000, v105
	v_lshlrev_b32_e32 v222, 16, v41
	v_and_b32_e32 v223, 0xffff0000, v41
	v_lshlrev_b32_e32 v224, 16, v106
	v_and_b32_e32 v225, 0xffff0000, v106
	v_lshlrev_b32_e32 v226, 16, v42
	v_and_b32_e32 v227, 0xffff0000, v42
	v_lshlrev_b32_e32 v228, 16, v107
	v_and_b32_e32 v229, 0xffff0000, v107
	v_lshlrev_b32_e32 v230, 16, v43
	v_and_b32_e32 v231, 0xffff0000, v43
	v_pk_add_f32 v[218:219], v[216:217], v[218:219] neg_lo:[0,1] neg_hi:[0,1]
	v_pk_add_f32 v[222:223], v[220:221], v[222:223] neg_lo:[0,1] neg_hi:[0,1]
	v_pk_add_f32 v[226:227], v[224:225], v[226:227] neg_lo:[0,1] neg_hi:[0,1]
	v_pk_add_f32 v[230:231], v[228:229], v[230:231] neg_lo:[0,1] neg_hi:[0,1]
	v_pk_add_f32 v[204:205], v[204:205], v[218:219]
	v_pk_add_f32 v[206:207], v[206:207], v[222:223]
	v_pk_add_f32 v[208:209], v[208:209], v[226:227]
	v_pk_add_f32 v[210:211], v[210:211], v[230:231]
	v_fma_f32 v218, s42, v204, -v216
	v_fma_f32 v219, s42, v205, -v217
	v_fma_f32 v222, s42, v206, -v220
	v_fma_f32 v223, s42, v207, -v221
	v_fma_f32 v226, s42, v208, -v224
	v_fma_f32 v227, s42, v209, -v225
	v_fma_f32 v230, s42, v210, -v228
	v_fma_f32 v231, s42, v211, -v229
	v_cvt_pk_bf16_f32 v212, v218, v219
	v_cvt_pk_bf16_f32 v213, v222, v223
	v_cvt_pk_bf16_f32 v214, v226, v227
	v_cvt_pk_bf16_f32 v215, v230, v231
	global_store_dwordx4 v3, v[212:215], s[10:11] sc1
	v_add_u32_e32 v3, 0x2000, v3
	s_waitcnt vmcnt(31)
	s_cselect_b32 s42, 0x3dba2e8c, s43
	v_lshlrev_b32_e32 v216, 16, v108
	v_and_b32_e32 v217, 0xffff0000, v108
	v_lshlrev_b32_e32 v218, 16, v44
	v_and_b32_e32 v219, 0xffff0000, v44
	v_lshlrev_b32_e32 v220, 16, v109
	v_and_b32_e32 v221, 0xffff0000, v109
	v_lshlrev_b32_e32 v222, 16, v45
	v_and_b32_e32 v223, 0xffff0000, v45
	v_lshlrev_b32_e32 v224, 16, v110
	v_and_b32_e32 v225, 0xffff0000, v110
	v_lshlrev_b32_e32 v226, 16, v46
	v_and_b32_e32 v227, 0xffff0000, v46
	v_lshlrev_b32_e32 v228, 16, v111
	v_and_b32_e32 v229, 0xffff0000, v111
	v_lshlrev_b32_e32 v230, 16, v47
	v_and_b32_e32 v231, 0xffff0000, v47
	v_pk_add_f32 v[218:219], v[216:217], v[218:219] neg_lo:[0,1] neg_hi:[0,1]
	v_pk_add_f32 v[222:223], v[220:221], v[222:223] neg_lo:[0,1] neg_hi:[0,1]
	v_pk_add_f32 v[226:227], v[224:225], v[226:227] neg_lo:[0,1] neg_hi:[0,1]
	v_pk_add_f32 v[230:231], v[228:229], v[230:231] neg_lo:[0,1] neg_hi:[0,1]
	v_pk_add_f32 v[204:205], v[204:205], v[218:219]
	v_pk_add_f32 v[206:207], v[206:207], v[222:223]
	v_pk_add_f32 v[208:209], v[208:209], v[226:227]
	v_pk_add_f32 v[210:211], v[210:211], v[230:231]
	v_fma_f32 v218, s42, v204, -v216
	v_fma_f32 v219, s42, v205, -v217
	v_fma_f32 v222, s42, v206, -v220
	v_fma_f32 v223, s42, v207, -v221
	v_fma_f32 v226, s42, v208, -v224
	v_fma_f32 v227, s42, v209, -v225
	v_fma_f32 v230, s42, v210, -v228
	v_fma_f32 v231, s42, v211, -v229
	v_cvt_pk_bf16_f32 v212, v218, v219
	v_cvt_pk_bf16_f32 v213, v222, v223
	v_cvt_pk_bf16_f32 v214, v226, v227
	v_cvt_pk_bf16_f32 v215, v230, v231
	global_store_dwordx4 v3, v[212:215], s[10:11] sc1
	v_add_u32_e32 v3, 0x2000, v3
	s_waitcnt vmcnt(31)
	s_cselect_b32 s42, 0x3daaaaab, s43
	v_lshlrev_b32_e32 v216, 16, v112
	v_and_b32_e32 v217, 0xffff0000, v112
	v_lshlrev_b32_e32 v218, 16, v48
	v_and_b32_e32 v219, 0xffff0000, v48
	v_lshlrev_b32_e32 v220, 16, v113
	v_and_b32_e32 v221, 0xffff0000, v113
	v_lshlrev_b32_e32 v222, 16, v49
	v_and_b32_e32 v223, 0xffff0000, v49
	v_lshlrev_b32_e32 v224, 16, v114
	v_and_b32_e32 v225, 0xffff0000, v114
	v_lshlrev_b32_e32 v226, 16, v50
	v_and_b32_e32 v227, 0xffff0000, v50
	v_lshlrev_b32_e32 v228, 16, v115
	v_and_b32_e32 v229, 0xffff0000, v115
	v_lshlrev_b32_e32 v230, 16, v51
	v_and_b32_e32 v231, 0xffff0000, v51
	v_pk_add_f32 v[218:219], v[216:217], v[218:219] neg_lo:[0,1] neg_hi:[0,1]
	v_pk_add_f32 v[222:223], v[220:221], v[222:223] neg_lo:[0,1] neg_hi:[0,1]
	v_pk_add_f32 v[226:227], v[224:225], v[226:227] neg_lo:[0,1] neg_hi:[0,1]
	v_pk_add_f32 v[230:231], v[228:229], v[230:231] neg_lo:[0,1] neg_hi:[0,1]
	v_pk_add_f32 v[204:205], v[204:205], v[218:219]
	v_pk_add_f32 v[206:207], v[206:207], v[222:223]
	v_pk_add_f32 v[208:209], v[208:209], v[226:227]
	v_pk_add_f32 v[210:211], v[210:211], v[230:231]
	v_fma_f32 v218, s42, v204, -v216
	v_fma_f32 v219, s42, v205, -v217
	v_fma_f32 v222, s42, v206, -v220
	v_fma_f32 v223, s42, v207, -v221
	v_fma_f32 v226, s42, v208, -v224
	v_fma_f32 v227, s42, v209, -v225
	v_fma_f32 v230, s42, v210, -v228
	v_fma_f32 v231, s42, v211, -v229
	v_cvt_pk_bf16_f32 v212, v218, v219
	v_cvt_pk_bf16_f32 v213, v222, v223
	v_cvt_pk_bf16_f32 v214, v226, v227
	v_cvt_pk_bf16_f32 v215, v230, v231
	global_store_dwordx4 v3, v[212:215], s[10:11] sc1
	v_add_u32_e32 v3, 0x2000, v3
	s_waitcnt vmcnt(31)
; __device__ __forceinline__ unsigned cvt_pk_bf16(float lo, float hi) { unsigned r; asm volatile("v_cvt_pk_bf16_f32 %0, %1, %2" : "=v"(r) : "v"(lo), "v"(hi)); return r; }
; __device__ __forceinline__ float bf_lo(unsigned w) { return __uint_as_float(w << 16); }
; __device__ __forceinline__ float bf_hi(unsigned w) { return __uint_as_float(w & 0xffff0000u); }
; __device__ void phase_pool() {
;     ...
;             for (int k = 0; k < 8; ++k) { const int row = row0 + r0 + k, tl = tl0 + r0 + k;
;                 vv[k] = *(const u32x4*)(uz + (size_t)row * DE2 + col);
;                 ov[k] = (tl >= w) ? *(const u32x4*)(uz + (size_t)(row - w) * DE2 + col) : (u32x4){0u, 0u, 0u, 0u}; }
; #pragma unroll
;             for (int k = 0; k < 8; ++k) { const int row = row0 + r0 + k, tl = tl0 + r0 + k; const u32x4 v = vv[k], o2 = ov[k];
;                 s[0] += bf_lo(v.x) - bf_lo(o2.x); s[1] += bf_hi(v.x) - bf_hi(o2.x); s[2] += bf_lo(v.y) - bf_lo(o2.y); s[3] += bf_hi(v.y) - bf_hi(o2.y);
;                 s[4] += bf_lo(v.z) - bf_lo(o2.z); s[5] += bf_hi(v.z) - bf_hi(o2.z); s[6] += bf_lo(v.w) - bf_lo(o2.w); s[7] += bf_hi(v.w) - bf_hi(o2.w);
;                 const float ic = 1.0f / (float)((tl + 1 < w) ? tl + 1 : w);
;                 u32x4 o;
;                 o.x = cvt_pk_bf16(s[0] * ic - bf_lo(v.x), s[1] * ic - bf_hi(v.x)); o.y = cvt_pk_bf16(s[2] * ic - bf_lo(v.y), s[3] * ic - bf_hi(v.y));
;                 o.z = cvt_pk_bf16(s[4] * ic - bf_lo(v.z), s[5] * ic - bf_hi(v.z)); o.w = cvt_pk_bf16(s[6] * ic - bf_lo(v.w), s[7] * ic - bf_hi(v.w));
;                 *(u32x4*)(pg + (size_t)row * DE + col) = o; }
	s_cselect_b32 s42, 0x3d9d89d9, s43
	v_lshlrev_b32_e32 v216, 16, v116
	v_and_b32_e32 v217, 0xffff0000, v116
	v_lshlrev_b32_e32 v218, 16, v52
	v_and_b32_e32 v219, 0xffff0000, v52
	v_lshlrev_b32_e32 v220, 16, v117
	v_and_b32_e32 v221, 0xffff0000, v117
	v_lshlrev_b32_e32 v222, 16, v53
	v_and_b32_e32 v223, 0xffff0000, v53
	v_lshlrev_b32_e32 v224, 16, v118
	v_and_b32_e32 v225, 0xffff0000, v118
	v_lshlrev_b32_e32 v226, 16, v54
	v_and_b32_e32 v227, 0xffff0000, v54
	v_lshlrev_b32_e32 v228, 16, v119
	v_and_b32_e32 v229, 0xffff0000, v119
	v_lshlrev_b32_e32 v230, 16, v55
	v_and_b32_e32 v231, 0xffff0000, v55
	v_pk_add_f32 v[218:219], v[216:217], v[218:219] neg_lo:[0,1] neg_hi:[0,1]
	v_pk_add_f32 v[222:223], v[220:221], v[222:223] neg_lo:[0,1] neg_hi:[0,1]
	v_pk_add_f32 v[226:227], v[224:225], v[226:227] neg_lo:[0,1] neg_hi:[0,1]
	v_pk_add_f32 v[230:231], v[228:229], v[230:231] neg_lo:[0,1] neg_hi:[0,1]
	v_pk_add_f32 v[204:205], v[204:205], v[218:219]
	v_pk_add_f32 v[206:207], v[206:207], v[222:223]
	v_pk_add_f32 v[208:209], v[208:209], v[226:227]
	v_pk_add_f32 v[210:211], v[210:211], v[230:231]
	v_fma_f32 v218, s42, v204, -v216
	v_fma_f32 v219, s42, v205, -v217
	v_fma_f32 v222, s42, v206, -v220
	v_fma_f32 v223, s42, v207, -v221
	v_fma_f32 v226, s42, v208, -v224
	v_fma_f32 v227, s42, v209, -v225
	v_fma_f32 v230, s42, v210, -v228
	v_fma_f32 v231, s42, v211, -v229
	v_cvt_pk_bf16_f32 v212, v218, v219
	v_cvt_pk_bf16_f32 v213, v222, v223
	v_cvt_pk_bf16_f32 v214, v226, v227
	v_cvt_pk_bf16_f32 v215, v230, v231
	global_store_dwordx4 v3, v[212:215], s[10:11] sc1
	v_add_u32_e32 v3, 0x2000, v3
	s_waitcnt vmcnt(31)
	s_cselect_b32 s42, 0x3d924925, s43
	v_lshlrev_b32_e32 v216, 16, v120
	v_and_b32_e32 v217, 0xffff0000, v120
	v_lshlrev_b32_e32 v218, 16, v56
	v_and_b32_e32 v219, 0xffff0000, v56
	v_lshlrev_b32_e32 v220, 16, v121
	v_and_b32_e32 v221, 0xffff0000, v121
	v_lshlrev_b32_e32 v222, 16, v57
	v_and_b32_e32 v223, 0xffff0000, v57
	v_lshlrev_b32_e32 v224, 16, v122
	v_and_b32_e32 v225, 0xffff0000, v122
	v_lshlrev_b32_e32 v226, 16, v58
	v_and_b32_e32 v227, 0xffff0000, v58
	v_lshlrev_b32_e32 v228, 16, v123
	v_and_b32_e32 v229, 0xffff0000, v123
	v_lshlrev_b32_e32 v230, 16, v59
	v_and_b32_e32 v231, 0xffff0000, v59
	v_pk_add_f32 v[218:219], v[216:217], v[218:219] neg_lo:[0,1] neg_hi:[0,1]
	v_pk_add_f32 v[222:223], v[220:221], v[222:223] neg_lo:[0,1] neg_hi:[0,1]
	v_pk_add_f32 v[226:227], v[224:225], v[226:227] neg_lo:[0,1] neg_hi:[0,1]
	v_pk_add_f32 v[230:231], v[228:229], v[230:231] neg_lo:[0,1] neg_hi:[0,1]
	v_pk_add_f32 v[204:205], v[204:205], v[218:219]
	v_pk_add_f32 v[206:207], v[206:207], v[222:223]
	v_pk_add_f32 v[208:209], v[208:209], v[226:227]
	v_pk_add_f32 v[210:211], v[210:211], v[230:231]
	v_fma_f32 v218, s42, v204, -v216
	v_fma_f32 v219, s42, v205, -v217
	v_fma_f32 v222, s42, v206, -v220
	v_fma_f32 v223, s42, v207, -v221
	v_fma_f32 v226, s42, v208, -v224
	v_fma_f32 v227, s42, v209, -v225
	v_fma_f32 v230, s42, v210, -v228
	v_fma_f32 v231, s42, v211, -v229
	v_cvt_pk_bf16_f32 v212, v218, v219
	v_cvt_pk_bf16_f32 v213, v222, v223
	v_cvt_pk_bf16_f32 v214, v226, v227
	v_cvt_pk_bf16_f32 v215, v230, v231
	global_store_dwordx4 v3, v[212:215], s[10:11] sc1
	v_add_u32_e32 v3, 0x2000, v3
	s_waitcnt vmcnt(31)
	s_cselect_b32 s42, 0x3d888889, s43
	v_lshlrev_b32_e32 v216, 16, v124
	v_and_b32_e32 v217, 0xffff0000, v124
	v_lshlrev_b32_e32 v218, 16, v60
	v_and_b32_e32 v219, 0xffff0000, v60
	v_lshlrev_b32_e32 v220, 16, v125
	v_and_b32_e32 v221, 0xffff0000, v125
	v_lshlrev_b32_e32 v222, 16, v61
	v_and_b32_e32 v223, 0xffff0000, v61
	v_lshlrev_b32_e32 v224, 16, v126
	v_and_b32_e32 v225, 0xffff0000, v126
	v_lshlrev_b32_e32 v226, 16, v62
	v_and_b32_e32 v227, 0xffff0000, v62
	v_lshlrev_b32_e32 v228, 16, v127
	v_and_b32_e32 v229, 0xffff0000, v127
	v_lshlrev_b32_e32 v230, 16, v63
	v_and_b32_e32 v231, 0xffff0000, v63
	v_pk_add_f32 v[218:219], v[216:217], v[218:219] neg_lo:[0,1] neg_hi:[0,1]
	v_pk_add_f32 v[222:223], v[220:221], v[222:223] neg_lo:[0,1] neg_hi:[0,1]
	v_pk_add_f32 v[226:227], v[224:225], v[226:227] neg_lo:[0,1] neg_hi:[0,1]
	v_pk_add_f32 v[230:231], v[228:229], v[230:231] neg_lo:[0,1] neg_hi:[0,1]
	v_pk_add_f32 v[204:205], v[204:205], v[218:219]
	v_pk_add_f32 v[206:207], v[206:207], v[222:223]
	v_pk_add_f32 v[208:209], v[208:209], v[226:227]
	v_pk_add_f32 v[210:211], v[210:211], v[230:231]
	v_fma_f32 v218, s42, v204, -v216
	v_fma_f32 v219, s42, v205, -v217
	v_fma_f32 v222, s42, v206, -v220
	v_fma_f32 v223, s42, v207, -v221
	v_fma_f32 v226, s42, v208, -v224
	v_fma_f32 v227, s42, v209, -v225
	v_fma_f32 v230, s42, v210, -v228
	v_fma_f32 v231, s42, v211, -v229
	v_cvt_pk_bf16_f32 v212, v218, v219
	v_cvt_pk_bf16_f32 v213, v222, v223
	v_cvt_pk_bf16_f32 v214, v226, v227
	v_cvt_pk_bf16_f32 v215, v230, v231
	global_store_dwordx4 v3, v[212:215], s[10:11] sc1
	v_add_u32_e32 v3, 0x2000, v3
	s_waitcnt vmcnt(31)
; __device__ __forceinline__ unsigned cvt_pk_bf16(float lo, float hi) { unsigned r; asm volatile("v_cvt_pk_bf16_f32 %0, %1, %2" : "=v"(r) : "v"(lo), "v"(hi)); return r; }
; __device__ __forceinline__ float bf_lo(unsigned w) { return __uint_as_float(w << 16); }
; __device__ __forceinline__ float bf_hi(unsigned w) { return __uint_as_float(w & 0xffff0000u); }
; __device__ void phase_pool() {
;     ...
;             for (int k = 0; k < 8; ++k) { const int row = row0 + r0 + k, tl = tl0 + r0 + k;
;                 vv[k] = *(const u32x4*)(uz + (size_t)row * DE2 + col);
;                 ov[k] = (tl >= w) ? *(const u32x4*)(uz + (size_t)(row - w) * DE2 + col) : (u32x4){0u, 0u, 0u, 0u}; }
; #pragma unroll
;             for (int k = 0; k < 8; ++k) { const int row = row0 + r0 + k, tl = tl0 + r0 + k; const u32x4 v = vv[k], o2 = ov[k];
;                 s[0] += bf_lo(v.x) - bf_lo(o2.x); s[1] += bf_hi(v.x) - bf_hi(o2.x); s[2] += bf_lo(v.y) - bf_lo(o2.y); s[3] += bf_hi(v.y) - bf_hi(o2.y);
;                 s[4] += bf_lo(v.z) - bf_lo(o2.z); s[5] += bf_hi(v.z) - bf_hi(o2.z); s[6] += bf_lo(v.w) - bf_lo(o2.w); s[7] += bf_hi(v.w) - bf_hi(o2.w);
;                 const float ic = 1.0f / (float)((tl + 1 < w) ? tl + 1 : w);
;                 u32x4 o;
;                 o.x = cvt_pk_bf16(s[0] * ic - bf_lo(v.x), s[1] * ic - bf_hi(v.x)); o.y = cvt_pk_bf16(s[2] * ic - bf_lo(v.y), s[3] * ic - bf_hi(v.y));
;                 o.z = cvt_pk_bf16(s[4] * ic - bf_lo(v.z), s[5] * ic - bf_hi(v.z)); o.w = cvt_pk_bf16(s[6] * ic - bf_lo(v.w), s[7] * ic - bf_hi(v.w));
;                 *(u32x4*)(pg + (size_t)row * DE + col) = o; }
	v_lshlrev_b32_e32 v216, 16, v128
	v_and_b32_e32 v217, 0xffff0000, v128
	v_lshlrev_b32_e32 v218, 16, v64
	v_and_b32_e32 v219, 0xffff0000, v64
	v_lshlrev_b32_e32 v220, 16, v129
	v_and_b32_e32 v221, 0xffff0000, v129
	v_lshlrev_b32_e32 v222, 16, v65
	v_and_b32_e32 v223, 0xffff0000, v65
	v_lshlrev_b32_e32 v224, 16, v130
	v_and_b32_e32 v225, 0xffff0000, v130
	v_lshlrev_b32_e32 v226, 16, v66
	v_and_b32_e32 v227, 0xffff0000, v66
	v_lshlrev_b32_e32 v228, 16, v131
	v_and_b32_e32 v229, 0xffff0000, v131
	v_lshlrev_b32_e32 v230, 16, v67
	v_and_b32_e32 v231, 0xffff0000, v67
	v_pk_add_f32 v[218:219], v[216:217], v[218:219] neg_lo:[0,1] neg_hi:[0,1]
	v_pk_add_f32 v[222:223], v[220:221], v[222:223] neg_lo:[0,1] neg_hi:[0,1]
	v_pk_add_f32 v[226:227], v[224:225], v[226:227] neg_lo:[0,1] neg_hi:[0,1]
	v_pk_add_f32 v[230:231], v[228:229], v[230:231] neg_lo:[0,1] neg_hi:[0,1]
	v_pk_add_f32 v[204:205], v[204:205], v[218:219]
	v_pk_add_f32 v[206:207], v[206:207], v[222:223]
	v_pk_add_f32 v[208:209], v[208:209], v[226:227]
	v_pk_add_f32 v[210:211], v[210:211], v[230:231]
	v_fma_f32 v218, s43, v204, -v216
	v_fma_f32 v219, s43, v205, -v217
	v_fma_f32 v222, s43, v206, -v220
	v_fma_f32 v223, s43, v207, -v221
	v_fma_f32 v226, s43, v208, -v224
	v_fma_f32 v227, s43, v209, -v225
	v_fma_f32 v230, s43, v210, -v228
	v_fma_f32 v231, s43, v211, -v229
	v_cvt_pk_bf16_f32 v212, v218, v219
	v_cvt_pk_bf16_f32 v213, v222, v223
	v_cvt_pk_bf16_f32 v214, v226, v227
	v_cvt_pk_bf16_f32 v215, v230, v231
	global_store_dwordx4 v3, v[212:215], s[10:11] sc1
	v_add_u32_e32 v3, 0x2000, v3
	s_waitcnt vmcnt(31)
	v_lshlrev_b32_e32 v216, 16, v132
	v_and_b32_e32 v217, 0xffff0000, v132
	v_lshlrev_b32_e32 v218, 16, v68
	v_and_b32_e32 v219, 0xffff0000, v68
	v_lshlrev_b32_e32 v220, 16, v133
	v_and_b32_e32 v221, 0xffff0000, v133
	v_lshlrev_b32_e32 v222, 16, v69
	v_and_b32_e32 v223, 0xffff0000, v69
	v_lshlrev_b32_e32 v224, 16, v134
	v_and_b32_e32 v225, 0xffff0000, v134
	v_lshlrev_b32_e32 v226, 16, v70
	v_and_b32_e32 v227, 0xffff0000, v70
	v_lshlrev_b32_e32 v228, 16, v135
	v_and_b32_e32 v229, 0xffff0000, v135
	v_lshlrev_b32_e32 v230, 16, v71
	v_and_b32_e32 v231, 0xffff0000, v71
	v_pk_add_f32 v[218:219], v[216:217], v[218:219] neg_lo:[0,1] neg_hi:[0,1]
	v_pk_add_f32 v[222:223], v[220:221], v[222:223] neg_lo:[0,1] neg_hi:[0,1]
	v_pk_add_f32 v[226:227], v[224:225], v[226:227] neg_lo:[0,1] neg_hi:[0,1]
	v_pk_add_f32 v[230:231], v[228:229], v[230:231] neg_lo:[0,1] neg_hi:[0,1]
	v_pk_add_f32 v[204:205], v[204:205], v[218:219]
	v_pk_add_f32 v[206:207], v[206:207], v[222:223]
	v_pk_add_f32 v[208:209], v[208:209], v[226:227]
	v_pk_add_f32 v[210:211], v[210:211], v[230:231]
	v_fma_f32 v218, s43, v204, -v216
	v_fma_f32 v219, s43, v205, -v217
	v_fma_f32 v222, s43, v206, -v220
	v_fma_f32 v223, s43, v207, -v221
	v_fma_f32 v226, s43, v208, -v224
	v_fma_f32 v227, s43, v209, -v225
	v_fma_f32 v230, s43, v210, -v228
	v_fma_f32 v231, s43, v211, -v229
	v_cvt_pk_bf16_f32 v212, v218, v219
	v_cvt_pk_bf16_f32 v213, v222, v223
	v_cvt_pk_bf16_f32 v214, v226, v227
	v_cvt_pk_bf16_f32 v215, v230, v231
	global_store_dwordx4 v3, v[212:215], s[10:11] sc1
	v_add_u32_e32 v3, 0x2000, v3
	s_waitcnt vmcnt(31)
	v_lshlrev_b32_e32 v216, 16, v136
	v_and_b32_e32 v217, 0xffff0000, v136
	v_lshlrev_b32_e32 v218, 16, v72
	v_and_b32_e32 v219, 0xffff0000, v72
	v_lshlrev_b32_e32 v220, 16, v137
	v_and_b32_e32 v221, 0xffff0000, v137
	v_lshlrev_b32_e32 v222, 16, v73
	v_and_b32_e32 v223, 0xffff0000, v73
	v_lshlrev_b32_e32 v224, 16, v138
	v_and_b32_e32 v225, 0xffff0000, v138
	v_lshlrev_b32_e32 v226, 16, v74
	v_and_b32_e32 v227, 0xffff0000, v74
	v_lshlrev_b32_e32 v228, 16, v139
	v_and_b32_e32 v229, 0xffff0000, v139
	v_lshlrev_b32_e32 v230, 16, v75
	v_and_b32_e32 v231, 0xffff0000, v75
	v_pk_add_f32 v[218:219], v[216:217], v[218:219] neg_lo:[0,1] neg_hi:[0,1]
	v_pk_add_f32 v[222:223], v[220:221], v[222:223] neg_lo:[0,1] neg_hi:[0,1]
	v_pk_add_f32 v[226:227], v[224:225], v[226:227] neg_lo:[0,1] neg_hi:[0,1]
	v_pk_add_f32 v[230:231], v[228:229], v[230:231] neg_lo:[0,1] neg_hi:[0,1]
	v_pk_add_f32 v[204:205], v[204:205], v[218:219]
	v_pk_add_f32 v[206:207], v[206:207], v[222:223]
	v_pk_add_f32 v[208:209], v[208:209], v[226:227]
	v_pk_add_f32 v[210:211], v[210:211], v[230:231]
	v_fma_f32 v218, s43, v204, -v216
	v_fma_f32 v219, s43, v205, -v217
	v_fma_f32 v222, s43, v206, -v220
	v_fma_f32 v223, s43, v207, -v221
	v_fma_f32 v226, s43, v208, -v224
	v_fma_f32 v227, s43, v209, -v225
	v_fma_f32 v230, s43, v210, -v228
	v_fma_f32 v231, s43, v211, -v229
	v_cvt_pk_bf16_f32 v212, v218, v219
	v_cvt_pk_bf16_f32 v213, v222, v223
	v_cvt_pk_bf16_f32 v214, v226, v227
	v_cvt_pk_bf16_f32 v215, v230, v231
	global_store_dwordx4 v3, v[212:215], s[10:11] sc1
	v_add_u32_e32 v3, 0x2000, v3
	s_waitcnt vmcnt(31)
	v_lshlrev_b32_e32 v216, 16, v140
	v_and_b32_e32 v217, 0xffff0000, v140
	v_lshlrev_b32_e32 v218, 16, v76
	v_and_b32_e32 v219, 0xffff0000, v76
	v_lshlrev_b32_e32 v220, 16, v141
	v_and_b32_e32 v221, 0xffff0000, v141
	v_lshlrev_b32_e32 v222, 16, v77
	v_and_b32_e32 v223, 0xffff0000, v77
	v_lshlrev_b32_e32 v224, 16, v142
	v_and_b32_e32 v225, 0xffff0000, v142
	v_lshlrev_b32_e32 v226, 16, v78
	v_and_b32_e32 v227, 0xffff0000, v78
	v_lshlrev_b32_e32 v228, 16, v143
	v_and_b32_e32 v229, 0xffff0000, v143
	v_lshlrev_b32_e32 v230, 16, v79
	v_and_b32_e32 v231, 0xffff0000, v79
	v_pk_add_f32 v[218:219], v[216:217], v[218:219] neg_lo:[0,1] neg_hi:[0,1]
	v_pk_add_f32 v[222:223], v[220:221], v[222:223] neg_lo:[0,1] neg_hi:[0,1]
	v_pk_add_f32 v[226:227], v[224:225], v[226:227] neg_lo:[0,1] neg_hi:[0,1]
	v_pk_add_f32 v[230:231], v[228:229], v[230:231] neg_lo:[0,1] neg_hi:[0,1]
	v_pk_add_f32 v[204:205], v[204:205], v[218:219]
	v_pk_add_f32 v[206:207], v[206:207], v[222:223]
	v_pk_add_f32 v[208:209], v[208:209], v[226:227]
	v_pk_add_f32 v[210:211], v[210:211], v[230:231]
	v_fma_f32 v218, s43, v204, -v216
	v_fma_f32 v219, s43, v205, -v217
	v_fma_f32 v222, s43, v206, -v220
	v_fma_f32 v223, s43, v207, -v221
	v_fma_f32 v226, s43, v208, -v224
	v_fma_f32 v227, s43, v209, -v225
	v_fma_f32 v230, s43, v210, -v228
	v_fma_f32 v231, s43, v211, -v229
	v_cvt_pk_bf16_f32 v212, v218, v219
	v_cvt_pk_bf16_f32 v213, v222, v223
	v_cvt_pk_bf16_f32 v214, v226, v227
	v_cvt_pk_bf16_f32 v215, v230, v231
	global_store_dwordx4 v3, v[212:215], s[10:11] sc1
	v_add_u32_e32 v3, 0x2000, v3
	s_waitcnt vmcnt(31)
; __device__ __forceinline__ unsigned cvt_pk_bf16(float lo, float hi) { unsigned r; asm volatile("v_cvt_pk_bf16_f32 %0, %1, %2" : "=v"(r) : "v"(lo), "v"(hi)); return r; }
; __device__ __forceinline__ float bf_lo(unsigned w) { return __uint_as_float(w << 16); }
; __device__ __forceinline__ float bf_hi(unsigned w) { return __uint_as_float(w & 0xffff0000u); }
; __device__ void phase_pool() {
;     ...
;             for (int k = 0; k < 8; ++k) { const int row = row0 + r0 + k, tl = tl0 + r0 + k;
;                 vv[k] = *(const u32x4*)(uz + (size_t)row * DE2 + col);
;                 ov[k] = (tl >= w) ? *(const u32x4*)(uz + (size_t)(row - w) * DE2 + col) : (u32x4){0u, 0u, 0u, 0u}; }
; #pragma unroll
;             for (int k = 0; k < 8; ++k) { const int row = row0 + r0 + k, tl = tl0 + r0 + k; const u32x4 v = vv[k], o2 = ov[k];
;                 s[0] += bf_lo(v.x) - bf_lo(o2.x); s[1] += bf_hi(v.x) - bf_hi(o2.x); s[2] += bf_lo(v.y) - bf_lo(o2.y); s[3] += bf_hi(v.y) - bf_hi(o2.y);
;                 s[4] += bf_lo(v.z) - bf_lo(o2.z); s[5] += bf_hi(v.z) - bf_hi(o2.z); s[6] += bf_lo(v.w) - bf_lo(o2.w); s[7] += bf_hi(v.w) - bf_hi(o2.w);
;                 const float ic = 1.0f / (float)((tl + 1 < w) ? tl + 1 : w);
;                 u32x4 o;
;                 o.x = cvt_pk_bf16(s[0] * ic - bf_lo(v.x), s[1] * ic - bf_hi(v.x)); o.y = cvt_pk_bf16(s[2] * ic - bf_lo(v.y), s[3] * ic - bf_hi(v.y));
;                 o.z = cvt_pk_bf16(s[4] * ic - bf_lo(v.z), s[5] * ic - bf_hi(v.z)); o.w = cvt_pk_bf16(s[6] * ic - bf_lo(v.w), s[7] * ic - bf_hi(v.w));
;                 *(u32x4*)(pg + (size_t)row * DE + col) = o; }
	v_lshlrev_b32_e32 v216, 16, v144
	v_and_b32_e32 v217, 0xffff0000, v144
	v_lshlrev_b32_e32 v218, 16, v80
	v_and_b32_e32 v219, 0xffff0000, v80
	v_lshlrev_b32_e32 v220, 16, v145
	v_and_b32_e32 v221, 0xffff0000, v145
	v_lshlrev_b32_e32 v222, 16, v81
	v_and_b32_e32 v223, 0xffff0000, v81
	v_lshlrev_b32_e32 v224, 16, v146
	v_and_b32_e32 v225, 0xffff0000, v146
	v_lshlrev_b32_e32 v226, 16, v82
	v_and_b32_e32 v227, 0xffff0000, v82
	v_lshlrev_b32_e32 v228, 16, v147
	v_and_b32_e32 v229, 0xffff0000, v147
	v_lshlrev_b32_e32 v230, 16, v83
	v_and_b32_e32 v231, 0xffff0000, v83
	v_pk_add_f32 v[218:219], v[216:217], v[218:219] neg_lo:[0,1] neg_hi:[0,1]
	v_pk_add_f32 v[222:223], v[220:221], v[222:223] neg_lo:[0,1] neg_hi:[0,1]
	v_pk_add_f32 v[226:227], v[224:225], v[226:227] neg_lo:[0,1] neg_hi:[0,1]
	v_pk_add_f32 v[230:231], v[228:229], v[230:231] neg_lo:[0,1] neg_hi:[0,1]
	v_pk_add_f32 v[204:205], v[204:205], v[218:219]
	v_pk_add_f32 v[206:207], v[206:207], v[222:223]
	v_pk_add_f32 v[208:209], v[208:209], v[226:227]
	v_pk_add_f32 v[210:211], v[210:211], v[230:231]
	v_fma_f32 v218, s43, v204, -v216
	v_fma_f32 v219, s43, v205, -v217
	v_fma_f32 v222, s43, v206, -v220
	v_fma_f32 v223, s43, v207, -v221
	v_fma_f32 v226, s43, v208, -v224
	v_fma_f32 v227, s43, v209, -v225
	v_fma_f32 v230, s43, v210, -v228
	v_fma_f32 v231, s43, v211, -v229
	v_cvt_pk_bf16_f32 v212, v218, v219
	v_cvt_pk_bf16_f32 v213, v222, v223
	v_cvt_pk_bf16_f32 v214, v226, v227
	v_cvt_pk_bf16_f32 v215, v230, v231
	global_store_dwordx4 v3, v[212:215], s[10:11] sc1
	v_add_u32_e32 v3, 0x2000, v3
	s_waitcnt vmcnt(31)
	v_lshlrev_b32_e32 v216, 16, v148
	v_and_b32_e32 v217, 0xffff0000, v148
	v_lshlrev_b32_e32 v218, 16, v84
	v_and_b32_e32 v219, 0xffff0000, v84
	v_lshlrev_b32_e32 v220, 16, v149
	v_and_b32_e32 v221, 0xffff0000, v149
	v_lshlrev_b32_e32 v222, 16, v85
	v_and_b32_e32 v223, 0xffff0000, v85
	v_lshlrev_b32_e32 v224, 16, v150
	v_and_b32_e32 v225, 0xffff0000, v150
	v_lshlrev_b32_e32 v226, 16, v86
	v_and_b32_e32 v227, 0xffff0000, v86
	v_lshlrev_b32_e32 v228, 16, v151
	v_and_b32_e32 v229, 0xffff0000, v151
	v_lshlrev_b32_e32 v230, 16, v87
	v_and_b32_e32 v231, 0xffff0000, v87
	v_pk_add_f32 v[218:219], v[216:217], v[218:219] neg_lo:[0,1] neg_hi:[0,1]
	v_pk_add_f32 v[222:223], v[220:221], v[222:223] neg_lo:[0,1] neg_hi:[0,1]
	v_pk_add_f32 v[226:227], v[224:225], v[226:227] neg_lo:[0,1] neg_hi:[0,1]
	v_pk_add_f32 v[230:231], v[228:229], v[230:231] neg_lo:[0,1] neg_hi:[0,1]
	v_pk_add_f32 v[204:205], v[204:205], v[218:219]
	v_pk_add_f32 v[206:207], v[206:207], v[222:223]
	v_pk_add_f32 v[208:209], v[208:209], v[226:227]
	v_pk_add_f32 v[210:211], v[210:211], v[230:231]
	v_fma_f32 v218, s43, v204, -v216
	v_fma_f32 v219, s43, v205, -v217
	v_fma_f32 v222, s43, v206, -v220
	v_fma_f32 v223, s43, v207, -v221
	v_fma_f32 v226, s43, v208, -v224
	v_fma_f32 v227, s43, v209, -v225
	v_fma_f32 v230, s43, v210, -v228
	v_fma_f32 v231, s43, v211, -v229
	v_cvt_pk_bf16_f32 v212, v218, v219
	v_cvt_pk_bf16_f32 v213, v222, v223
	v_cvt_pk_bf16_f32 v214, v226, v227
	v_cvt_pk_bf16_f32 v215, v230, v231
	global_store_dwordx4 v3, v[212:215], s[10:11] sc1
	v_add_u32_e32 v3, 0x2000, v3
	s_waitcnt vmcnt(31)
	v_lshlrev_b32_e32 v216, 16, v152
	v_and_b32_e32 v217, 0xffff0000, v152
	v_lshlrev_b32_e32 v218, 16, v88
	v_and_b32_e32 v219, 0xffff0000, v88
	v_lshlrev_b32_e32 v220, 16, v153
	v_and_b32_e32 v221, 0xffff0000, v153
	v_lshlrev_b32_e32 v222, 16, v89
	v_and_b32_e32 v223, 0xffff0000, v89
	v_lshlrev_b32_e32 v224, 16, v154
	v_and_b32_e32 v225, 0xffff0000, v154
	v_lshlrev_b32_e32 v226, 16, v90
	v_and_b32_e32 v227, 0xffff0000, v90
	v_lshlrev_b32_e32 v228, 16, v155
	v_and_b32_e32 v229, 0xffff0000, v155
	v_lshlrev_b32_e32 v230, 16, v91
	v_and_b32_e32 v231, 0xffff0000, v91
	v_pk_add_f32 v[218:219], v[216:217], v[218:219] neg_lo:[0,1] neg_hi:[0,1]
	v_pk_add_f32 v[222:223], v[220:221], v[222:223] neg_lo:[0,1] neg_hi:[0,1]
	v_pk_add_f32 v[226:227], v[224:225], v[226:227] neg_lo:[0,1] neg_hi:[0,1]
	v_pk_add_f32 v[230:231], v[228:229], v[230:231] neg_lo:[0,1] neg_hi:[0,1]
	v_pk_add_f32 v[204:205], v[204:205], v[218:219]
	v_pk_add_f32 v[206:207], v[206:207], v[222:223]
	v_pk_add_f32 v[208:209], v[208:209], v[226:227]
	v_pk_add_f32 v[210:211], v[210:211], v[230:231]
	v_fma_f32 v218, s43, v204, -v216
	v_fma_f32 v219, s43, v205, -v217
	v_fma_f32 v222, s43, v206, -v220
	v_fma_f32 v223, s43, v207, -v221
	v_fma_f32 v226, s43, v208, -v224
	v_fma_f32 v227, s43, v209, -v225
	v_fma_f32 v230, s43, v210, -v228
	v_fma_f32 v231, s43, v211, -v229
	v_cvt_pk_bf16_f32 v212, v218, v219
	v_cvt_pk_bf16_f32 v213, v222, v223
	v_cvt_pk_bf16_f32 v214, v226, v227
	v_cvt_pk_bf16_f32 v215, v230, v231
	global_store_dwordx4 v3, v[212:215], s[10:11] sc1
	v_add_u32_e32 v3, 0x2000, v3
	s_waitcnt vmcnt(31)
	v_lshlrev_b32_e32 v216, 16, v156
	v_and_b32_e32 v217, 0xffff0000, v156
	v_lshlrev_b32_e32 v218, 16, v92
	v_and_b32_e32 v219, 0xffff0000, v92
	v_lshlrev_b32_e32 v220, 16, v157
	v_and_b32_e32 v221, 0xffff0000, v157
	v_lshlrev_b32_e32 v222, 16, v93
	v_and_b32_e32 v223, 0xffff0000, v93
	v_lshlrev_b32_e32 v224, 16, v158
	v_and_b32_e32 v225, 0xffff0000, v158
	v_lshlrev_b32_e32 v226, 16, v94
	v_and_b32_e32 v227, 0xffff0000, v94
	v_lshlrev_b32_e32 v228, 16, v159
	v_and_b32_e32 v229, 0xffff0000, v159
	v_lshlrev_b32_e32 v230, 16, v95
	v_and_b32_e32 v231, 0xffff0000, v95
	v_pk_add_f32 v[218:219], v[216:217], v[218:219] neg_lo:[0,1] neg_hi:[0,1]
	v_pk_add_f32 v[222:223], v[220:221], v[222:223] neg_lo:[0,1] neg_hi:[0,1]
	v_pk_add_f32 v[226:227], v[224:225], v[226:227] neg_lo:[0,1] neg_hi:[0,1]
	v_pk_add_f32 v[230:231], v[228:229], v[230:231] neg_lo:[0,1] neg_hi:[0,1]
	v_pk_add_f32 v[204:205], v[204:205], v[218:219]
	v_pk_add_f32 v[206:207], v[206:207], v[222:223]
	v_pk_add_f32 v[208:209], v[208:209], v[226:227]
	v_pk_add_f32 v[210:211], v[210:211], v[230:231]
	v_fma_f32 v218, s43, v204, -v216
	v_fma_f32 v219, s43, v205, -v217
	v_fma_f32 v222, s43, v206, -v220
	v_fma_f32 v223, s43, v207, -v221
	v_fma_f32 v226, s43, v208, -v224
	v_fma_f32 v227, s43, v209, -v225
	v_fma_f32 v230, s43, v210, -v228
	v_fma_f32 v231, s43, v211, -v229
	v_cvt_pk_bf16_f32 v212, v218, v219
	v_cvt_pk_bf16_f32 v213, v222, v223
	v_cvt_pk_bf16_f32 v214, v226, v227
	v_cvt_pk_bf16_f32 v215, v230, v231
	global_store_dwordx4 v3, v[212:215], s[10:11] sc1
	v_add_u32_e32 v3, 0x2000, v3
	s_waitcnt vmcnt(31)
; __device__ __forceinline__ unsigned cvt_pk_bf16(float lo, float hi) { unsigned r; asm volatile("v_cvt_pk_bf16_f32 %0, %1, %2" : "=v"(r) : "v"(lo), "v"(hi)); return r; }
; __device__ __forceinline__ float bf_lo(unsigned w) { return __uint_as_float(w << 16); }
; __device__ __forceinline__ float bf_hi(unsigned w) { return __uint_as_float(w & 0xffff0000u); }
; __device__ void phase_pool() {
;     ...
;             for (int k = 0; k < 8; ++k) { const int row = row0 + r0 + k, tl = tl0 + r0 + k;
;                 vv[k] = *(const u32x4*)(uz + (size_t)row * DE2 + col);
;                 ov[k] = (tl >= w) ? *(const u32x4*)(uz + (size_t)(row - w) * DE2 + col) : (u32x4){0u, 0u, 0u, 0u}; }
; #pragma unroll
;             for (int k = 0; k < 8; ++k) { const int row = row0 + r0 + k, tl = tl0 + r0 + k; const u32x4 v = vv[k], o2 = ov[k];
;                 s[0] += bf_lo(v.x) - bf_lo(o2.x); s[1] += bf_hi(v.x) - bf_hi(o2.x); s[2] += bf_lo(v.y) - bf_lo(o2.y); s[3] += bf_hi(v.y) - bf_hi(o2.y);
;                 s[4] += bf_lo(v.z) - bf_lo(o2.z); s[5] += bf_hi(v.z) - bf_hi(o2.z); s[6] += bf_lo(v.w) - bf_lo(o2.w); s[7] += bf_hi(v.w) - bf_hi(o2.w);
;                 const float ic = 1.0f / (float)((tl + 1 < w) ? tl + 1 : w);
;                 u32x4 o;
;                 o.x = cvt_pk_bf16(s[0] * ic - bf_lo(v.x), s[1] * ic - bf_hi(v.x)); o.y = cvt_pk_bf16(s[2] * ic - bf_lo(v.y), s[3] * ic - bf_hi(v.y));
;                 o.z = cvt_pk_bf16(s[4] * ic - bf_lo(v.z), s[5] * ic - bf_hi(v.z)); o.w = cvt_pk_bf16(s[6] * ic - bf_lo(v.w), s[7] * ic - bf_hi(v.w));
;                 *(u32x4*)(pg + (size_t)row * DE + col) = o; }
	v_lshlrev_b32_e32 v216, 16, v160
	v_and_b32_e32 v217, 0xffff0000, v160
	v_lshlrev_b32_e32 v218, 16, v96
	v_and_b32_e32 v219, 0xffff0000, v96
	v_lshlrev_b32_e32 v220, 16, v161
	v_and_b32_e32 v221, 0xffff0000, v161
	v_lshlrev_b32_e32 v222, 16, v97
	v_and_b32_e32 v223, 0xffff0000, v97
	v_lshlrev_b32_e32 v224, 16, v162
	v_and_b32_e32 v225, 0xffff0000, v162
	v_lshlrev_b32_e32 v226, 16, v98
	v_and_b32_e32 v227, 0xffff0000, v98
	v_lshlrev_b32_e32 v228, 16, v163
	v_and_b32_e32 v229, 0xffff0000, v163
	v_lshlrev_b32_e32 v230, 16, v99
	v_and_b32_e32 v231, 0xffff0000, v99
	v_pk_add_f32 v[218:219], v[216:217], v[218:219] neg_lo:[0,1] neg_hi:[0,1]
	v_pk_add_f32 v[222:223], v[220:221], v[222:223] neg_lo:[0,1] neg_hi:[0,1]
	v_pk_add_f32 v[226:227], v[224:225], v[226:227] neg_lo:[0,1] neg_hi:[0,1]
	v_pk_add_f32 v[230:231], v[228:229], v[230:231] neg_lo:[0,1] neg_hi:[0,1]
	v_pk_add_f32 v[204:205], v[204:205], v[218:219]
	v_pk_add_f32 v[206:207], v[206:207], v[222:223]
	v_pk_add_f32 v[208:209], v[208:209], v[226:227]
	v_pk_add_f32 v[210:211], v[210:211], v[230:231]
	v_fma_f32 v218, s43, v204, -v216
	v_fma_f32 v219, s43, v205, -v217
	v_fma_f32 v222, s43, v206, -v220
	v_fma_f32 v223, s43, v207, -v221
	v_fma_f32 v226, s43, v208, -v224
	v_fma_f32 v227, s43, v209, -v225
	v_fma_f32 v230, s43, v210, -v228
	v_fma_f32 v231, s43, v211, -v229
	v_cvt_pk_bf16_f32 v212, v218, v219
	v_cvt_pk_bf16_f32 v213, v222, v223
	v_cvt_pk_bf16_f32 v214, v226, v227
	v_cvt_pk_bf16_f32 v215, v230, v231
	global_store_dwordx4 v3, v[212:215], s[10:11] sc1
	v_add_u32_e32 v3, 0x2000, v3
	s_waitcnt vmcnt(31)
	v_lshlrev_b32_e32 v216, 16, v164
	v_and_b32_e32 v217, 0xffff0000, v164
	v_lshlrev_b32_e32 v218, 16, v100
	v_and_b32_e32 v219, 0xffff0000, v100
	v_lshlrev_b32_e32 v220, 16, v165
	v_and_b32_e32 v221, 0xffff0000, v165
	v_lshlrev_b32_e32 v222, 16, v101
	v_and_b32_e32 v223, 0xffff0000, v101
	v_lshlrev_b32_e32 v224, 16, v166
	v_and_b32_e32 v225, 0xffff0000, v166
	v_lshlrev_b32_e32 v226, 16, v102
	v_and_b32_e32 v227, 0xffff0000, v102
	v_lshlrev_b32_e32 v228, 16, v167
	v_and_b32_e32 v229, 0xffff0000, v167
	v_lshlrev_b32_e32 v230, 16, v103
	v_and_b32_e32 v231, 0xffff0000, v103
	v_pk_add_f32 v[218:219], v[216:217], v[218:219] neg_lo:[0,1] neg_hi:[0,1]
	v_pk_add_f32 v[222:223], v[220:221], v[222:223] neg_lo:[0,1] neg_hi:[0,1]
	v_pk_add_f32 v[226:227], v[224:225], v[226:227] neg_lo:[0,1] neg_hi:[0,1]
	v_pk_add_f32 v[230:231], v[228:229], v[230:231] neg_lo:[0,1] neg_hi:[0,1]
	v_pk_add_f32 v[204:205], v[204:205], v[218:219]
	v_pk_add_f32 v[206:207], v[206:207], v[222:223]
	v_pk_add_f32 v[208:209], v[208:209], v[226:227]
	v_pk_add_f32 v[210:211], v[210:211], v[230:231]
	v_fma_f32 v218, s43, v204, -v216
	v_fma_f32 v219, s43, v205, -v217
	v_fma_f32 v222, s43, v206, -v220
	v_fma_f32 v223, s43, v207, -v221
	v_fma_f32 v226, s43, v208, -v224
	v_fma_f32 v227, s43, v209, -v225
	v_fma_f32 v230, s43, v210, -v228
	v_fma_f32 v231, s43, v211, -v229
	v_cvt_pk_bf16_f32 v212, v218, v219
	v_cvt_pk_bf16_f32 v213, v222, v223
	v_cvt_pk_bf16_f32 v214, v226, v227
	v_cvt_pk_bf16_f32 v215, v230, v231
	global_store_dwordx4 v3, v[212:215], s[10:11] sc1
	v_add_u32_e32 v3, 0x2000, v3
	s_waitcnt vmcnt(31)
	v_lshlrev_b32_e32 v216, 16, v168
	v_and_b32_e32 v217, 0xffff0000, v168
	v_lshlrev_b32_e32 v218, 16, v104
	v_and_b32_e32 v219, 0xffff0000, v104
	v_lshlrev_b32_e32 v220, 16, v169
	v_and_b32_e32 v221, 0xffff0000, v169
	v_lshlrev_b32_e32 v222, 16, v105
	v_and_b32_e32 v223, 0xffff0000, v105
	v_lshlrev_b32_e32 v224, 16, v170
	v_and_b32_e32 v225, 0xffff0000, v170
	v_lshlrev_b32_e32 v226, 16, v106
	v_and_b32_e32 v227, 0xffff0000, v106
	v_lshlrev_b32_e32 v228, 16, v171
	v_and_b32_e32 v229, 0xffff0000, v171
	v_lshlrev_b32_e32 v230, 16, v107
	v_and_b32_e32 v231, 0xffff0000, v107
	v_pk_add_f32 v[218:219], v[216:217], v[218:219] neg_lo:[0,1] neg_hi:[0,1]
	v_pk_add_f32 v[222:223], v[220:221], v[222:223] neg_lo:[0,1] neg_hi:[0,1]
	v_pk_add_f32 v[226:227], v[224:225], v[226:227] neg_lo:[0,1] neg_hi:[0,1]
	v_pk_add_f32 v[230:231], v[228:229], v[230:231] neg_lo:[0,1] neg_hi:[0,1]
	v_pk_add_f32 v[204:205], v[204:205], v[218:219]
	v_pk_add_f32 v[206:207], v[206:207], v[222:223]
	v_pk_add_f32 v[208:209], v[208:209], v[226:227]
	v_pk_add_f32 v[210:211], v[210:211], v[230:231]
	v_fma_f32 v218, s43, v204, -v216
	v_fma_f32 v219, s43, v205, -v217
	v_fma_f32 v222, s43, v206, -v220
	v_fma_f32 v223, s43, v207, -v221
	v_fma_f32 v226, s43, v208, -v224
	v_fma_f32 v227, s43, v209, -v225
	v_fma_f32 v230, s43, v210, -v228
	v_fma_f32 v231, s43, v211, -v229
	v_cvt_pk_bf16_f32 v212, v218, v219
	v_cvt_pk_bf16_f32 v213, v222, v223
	v_cvt_pk_bf16_f32 v214, v226, v227
	v_cvt_pk_bf16_f32 v215, v230, v231
	global_store_dwordx4 v3, v[212:215], s[10:11] sc1
	v_add_u32_e32 v3, 0x2000, v3
	s_waitcnt vmcnt(31)
	v_lshlrev_b32_e32 v216, 16, v172
	v_and_b32_e32 v217, 0xffff0000, v172
	v_lshlrev_b32_e32 v218, 16, v108
	v_and_b32_e32 v219, 0xffff0000, v108
	v_lshlrev_b32_e32 v220, 16, v173
	v_and_b32_e32 v221, 0xffff0000, v173
	v_lshlrev_b32_e32 v222, 16, v109
	v_and_b32_e32 v223, 0xffff0000, v109
	v_lshlrev_b32_e32 v224, 16, v174
	v_and_b32_e32 v225, 0xffff0000, v174
	v_lshlrev_b32_e32 v226, 16, v110
	v_and_b32_e32 v227, 0xffff0000, v110
	v_lshlrev_b32_e32 v228, 16, v175
	v_and_b32_e32 v229, 0xffff0000, v175
	v_lshlrev_b32_e32 v230, 16, v111
	v_and_b32_e32 v231, 0xffff0000, v111
	v_pk_add_f32 v[218:219], v[216:217], v[218:219] neg_lo:[0,1] neg_hi:[0,1]
	v_pk_add_f32 v[222:223], v[220:221], v[222:223] neg_lo:[0,1] neg_hi:[0,1]
	v_pk_add_f32 v[226:227], v[224:225], v[226:227] neg_lo:[0,1] neg_hi:[0,1]
	v_pk_add_f32 v[230:231], v[228:229], v[230:231] neg_lo:[0,1] neg_hi:[0,1]
	v_pk_add_f32 v[204:205], v[204:205], v[218:219]
	v_pk_add_f32 v[206:207], v[206:207], v[222:223]
	v_pk_add_f32 v[208:209], v[208:209], v[226:227]
	v_pk_add_f32 v[210:211], v[210:211], v[230:231]
	v_fma_f32 v218, s43, v204, -v216
	v_fma_f32 v219, s43, v205, -v217
	v_fma_f32 v222, s43, v206, -v220
	v_fma_f32 v223, s43, v207, -v221
	v_fma_f32 v226, s43, v208, -v224
	v_fma_f32 v227, s43, v209, -v225
	v_fma_f32 v230, s43, v210, -v228
	v_fma_f32 v231, s43, v211, -v229
	v_cvt_pk_bf16_f32 v212, v218, v219
	v_cvt_pk_bf16_f32 v213, v222, v223
	v_cvt_pk_bf16_f32 v214, v226, v227
	v_cvt_pk_bf16_f32 v215, v230, v231
	global_store_dwordx4 v3, v[212:215], s[10:11] sc1
	v_add_u32_e32 v3, 0x2000, v3
	s_waitcnt vmcnt(31)
; __device__ __forceinline__ unsigned cvt_pk_bf16(float lo, float hi) { unsigned r; asm volatile("v_cvt_pk_bf16_f32 %0, %1, %2" : "=v"(r) : "v"(lo), "v"(hi)); return r; }
; __device__ __forceinline__ float bf_lo(unsigned w) { return __uint_as_float(w << 16); }
; __device__ __forceinline__ float bf_hi(unsigned w) { return __uint_as_float(w & 0xffff0000u); }
; __device__ void phase_pool() {
;     ...
;             for (int k = 0; k < 8; ++k) { const int row = row0 + r0 + k, tl = tl0 + r0 + k;
;                 vv[k] = *(const u32x4*)(uz + (size_t)row * DE2 + col);
;                 ov[k] = (tl >= w) ? *(const u32x4*)(uz + (size_t)(row - w) * DE2 + col) : (u32x4){0u, 0u, 0u, 0u}; }
; #pragma unroll
;             for (int k = 0; k < 8; ++k) { const int row = row0 + r0 + k, tl = tl0 + r0 + k; const u32x4 v = vv[k], o2 = ov[k];
;                 s[0] += bf_lo(v.x) - bf_lo(o2.x); s[1] += bf_hi(v.x) - bf_hi(o2.x); s[2] += bf_lo(v.y) - bf_lo(o2.y); s[3] += bf_hi(v.y) - bf_hi(o2.y);
;                 s[4] += bf_lo(v.z) - bf_lo(o2.z); s[5] += bf_hi(v.z) - bf_hi(o2.z); s[6] += bf_lo(v.w) - bf_lo(o2.w); s[7] += bf_hi(v.w) - bf_hi(o2.w);
;                 const float ic = 1.0f / (float)((tl + 1 < w) ? tl + 1 : w);
;                 u32x4 o;
;                 o.x = cvt_pk_bf16(s[0] * ic - bf_lo(v.x), s[1] * ic - bf_hi(v.x)); o.y = cvt_pk_bf16(s[2] * ic - bf_lo(v.y), s[3] * ic - bf_hi(v.y));
;                 o.z = cvt_pk_bf16(s[4] * ic - bf_lo(v.z), s[5] * ic - bf_hi(v.z)); o.w = cvt_pk_bf16(s[6] * ic - bf_lo(v.w), s[7] * ic - bf_hi(v.w));
;                 *(u32x4*)(pg + (size_t)row * DE + col) = o; }
	v_lshlrev_b32_e32 v216, 16, v184
	v_and_b32_e32 v217, 0xffff0000, v184
	v_lshlrev_b32_e32 v218, 16, v112
	v_and_b32_e32 v219, 0xffff0000, v112
	v_lshlrev_b32_e32 v220, 16, v185
	v_and_b32_e32 v221, 0xffff0000, v185
	v_lshlrev_b32_e32 v222, 16, v113
	v_and_b32_e32 v223, 0xffff0000, v113
	v_lshlrev_b32_e32 v224, 16, v186
	v_and_b32_e32 v225, 0xffff0000, v186
	v_lshlrev_b32_e32 v226, 16, v114
	v_and_b32_e32 v227, 0xffff0000, v114
	v_lshlrev_b32_e32 v228, 16, v187
	v_and_b32_e32 v229, 0xffff0000, v187
	v_lshlrev_b32_e32 v230, 16, v115
	v_and_b32_e32 v231, 0xffff0000, v115
	v_pk_add_f32 v[218:219], v[216:217], v[218:219] neg_lo:[0,1] neg_hi:[0,1]
	v_pk_add_f32 v[222:223], v[220:221], v[222:223] neg_lo:[0,1] neg_hi:[0,1]
	v_pk_add_f32 v[226:227], v[224:225], v[226:227] neg_lo:[0,1] neg_hi:[0,1]
	v_pk_add_f32 v[230:231], v[228:229], v[230:231] neg_lo:[0,1] neg_hi:[0,1]
	v_pk_add_f32 v[204:205], v[204:205], v[218:219]
	v_pk_add_f32 v[206:207], v[206:207], v[222:223]
	v_pk_add_f32 v[208:209], v[208:209], v[226:227]
	v_pk_add_f32 v[210:211], v[210:211], v[230:231]
	v_fma_f32 v218, s43, v204, -v216
	v_fma_f32 v219, s43, v205, -v217
	v_fma_f32 v222, s43, v206, -v220
	v_fma_f32 v223, s43, v207, -v221
	v_fma_f32 v226, s43, v208, -v224
	v_fma_f32 v227, s43, v209, -v225
	v_fma_f32 v230, s43, v210, -v228
	v_fma_f32 v231, s43, v211, -v229
	v_cvt_pk_bf16_f32 v212, v218, v219
	v_cvt_pk_bf16_f32 v213, v222, v223
	v_cvt_pk_bf16_f32 v214, v226, v227
	v_cvt_pk_bf16_f32 v215, v230, v231
	global_store_dwordx4 v3, v[212:215], s[10:11] sc1
	v_add_u32_e32 v3, 0x2000, v3
	s_waitcnt vmcnt(31)
	v_lshlrev_b32_e32 v216, 16, v188
	v_and_b32_e32 v217, 0xffff0000, v188
	v_lshlrev_b32_e32 v218, 16, v116
	v_and_b32_e32 v219, 0xffff0000, v116
	v_lshlrev_b32_e32 v220, 16, v189
	v_and_b32_e32 v221, 0xffff0000, v189
	v_lshlrev_b32_e32 v222, 16, v117
	v_and_b32_e32 v223, 0xffff0000, v117
	v_lshlrev_b32_e32 v224, 16, v190
	v_and_b32_e32 v225, 0xffff0000, v190
	v_lshlrev_b32_e32 v226, 16, v118
	v_and_b32_e32 v227, 0xffff0000, v118
	v_lshlrev_b32_e32 v228, 16, v191
	v_and_b32_e32 v229, 0xffff0000, v191
	v_lshlrev_b32_e32 v230, 16, v119
	v_and_b32_e32 v231, 0xffff0000, v119
	v_pk_add_f32 v[218:219], v[216:217], v[218:219] neg_lo:[0,1] neg_hi:[0,1]
	v_pk_add_f32 v[222:223], v[220:221], v[222:223] neg_lo:[0,1] neg_hi:[0,1]
	v_pk_add_f32 v[226:227], v[224:225], v[226:227] neg_lo:[0,1] neg_hi:[0,1]
	v_pk_add_f32 v[230:231], v[228:229], v[230:231] neg_lo:[0,1] neg_hi:[0,1]
	v_pk_add_f32 v[204:205], v[204:205], v[218:219]
	v_pk_add_f32 v[206:207], v[206:207], v[222:223]
	v_pk_add_f32 v[208:209], v[208:209], v[226:227]
	v_pk_add_f32 v[210:211], v[210:211], v[230:231]
	v_fma_f32 v218, s43, v204, -v216
	v_fma_f32 v219, s43, v205, -v217
	v_fma_f32 v222, s43, v206, -v220
	v_fma_f32 v223, s43, v207, -v221
	v_fma_f32 v226, s43, v208, -v224
	v_fma_f32 v227, s43, v209, -v225
	v_fma_f32 v230, s43, v210, -v228
	v_fma_f32 v231, s43, v211, -v229
	v_cvt_pk_bf16_f32 v212, v218, v219
	v_cvt_pk_bf16_f32 v213, v222, v223
	v_cvt_pk_bf16_f32 v214, v226, v227
	v_cvt_pk_bf16_f32 v215, v230, v231
	global_store_dwordx4 v3, v[212:215], s[10:11] sc1
	v_add_u32_e32 v3, 0x2000, v3
	s_waitcnt vmcnt(31)
; __device__ __forceinline__ unsigned cvt_pk_bf16(float lo, float hi) { unsigned r; asm volatile("v_cvt_pk_bf16_f32 %0, %1, %2" : "=v"(r) : "v"(lo), "v"(hi)); return r; }
; __device__ __forceinline__ float bf_lo(unsigned w) { return __uint_as_float(w << 16); }
; __device__ __forceinline__ float bf_hi(unsigned w) { return __uint_as_float(w & 0xffff0000u); }
; __device__ void phase_pool() {
;     ...
;             for (int k = 0; k < 8; ++k) { const int row = row0 + r0 + k, tl = tl0 + r0 + k;
;                 vv[k] = *(const u32x4*)(uz + (size_t)row * DE2 + col);
;                 ov[k] = (tl >= w) ? *(const u32x4*)(uz + (size_t)(row - w) * DE2 + col) : (u32x4){0u, 0u, 0u, 0u}; }
; #pragma unroll
;             for (int k = 0; k < 8; ++k) { const int row = row0 + r0 + k, tl = tl0 + r0 + k; const u32x4 v = vv[k], o2 = ov[k];
;                 s[0] += bf_lo(v.x) - bf_lo(o2.x); s[1] += bf_hi(v.x) - bf_hi(o2.x); s[2] += bf_lo(v.y) - bf_lo(o2.y); s[3] += bf_hi(v.y) - bf_hi(o2.y);
;                 s[4] += bf_lo(v.z) - bf_lo(o2.z); s[5] += bf_hi(v.z) - bf_hi(o2.z); s[6] += bf_lo(v.w) - bf_lo(o2.w); s[7] += bf_hi(v.w) - bf_hi(o2.w);
;                 const float ic = 1.0f / (float)((tl + 1 < w) ? tl + 1 : w);
;                 u32x4 o;
;                 o.x = cvt_pk_bf16(s[0] * ic - bf_lo(v.x), s[1] * ic - bf_hi(v.x)); o.y = cvt_pk_bf16(s[2] * ic - bf_lo(v.y), s[3] * ic - bf_hi(v.y));
;                 o.z = cvt_pk_bf16(s[4] * ic - bf_lo(v.z), s[5] * ic - bf_hi(v.z)); o.w = cvt_pk_bf16(s[6] * ic - bf_lo(v.w), s[7] * ic - bf_hi(v.w));
;                 *(u32x4*)(pg + (size_t)row * DE + col) = o; }
	v_lshlrev_b32_e32 v216, 16, v192
	v_and_b32_e32 v217, 0xffff0000, v192
	v_lshlrev_b32_e32 v218, 16, v120
	v_and_b32_e32 v219, 0xffff0000, v120
	v_lshlrev_b32_e32 v220, 16, v193
	v_and_b32_e32 v221, 0xffff0000, v193
	v_lshlrev_b32_e32 v222, 16, v121
	v_and_b32_e32 v223, 0xffff0000, v121
	v_lshlrev_b32_e32 v224, 16, v194
	v_and_b32_e32 v225, 0xffff0000, v194
	v_lshlrev_b32_e32 v226, 16, v122
	v_and_b32_e32 v227, 0xffff0000, v122
	v_lshlrev_b32_e32 v228, 16, v195
	v_and_b32_e32 v229, 0xffff0000, v195
	v_lshlrev_b32_e32 v230, 16, v123
	v_and_b32_e32 v231, 0xffff0000, v123
	v_pk_add_f32 v[218:219], v[216:217], v[218:219] neg_lo:[0,1] neg_hi:[0,1]
	v_pk_add_f32 v[222:223], v[220:221], v[222:223] neg_lo:[0,1] neg_hi:[0,1]
	v_pk_add_f32 v[226:227], v[224:225], v[226:227] neg_lo:[0,1] neg_hi:[0,1]
	v_pk_add_f32 v[230:231], v[228:229], v[230:231] neg_lo:[0,1] neg_hi:[0,1]
	v_pk_add_f32 v[204:205], v[204:205], v[218:219]
	v_pk_add_f32 v[206:207], v[206:207], v[222:223]
	v_pk_add_f32 v[208:209], v[208:209], v[226:227]
	v_pk_add_f32 v[210:211], v[210:211], v[230:231]
	v_fma_f32 v218, s43, v204, -v216
	v_fma_f32 v219, s43, v205, -v217
	v_fma_f32 v222, s43, v206, -v220
	v_fma_f32 v223, s43, v207, -v221
	v_fma_f32 v226, s43, v208, -v224
	v_fma_f32 v227, s43, v209, -v225
	v_fma_f32 v230, s43, v210, -v228
	v_fma_f32 v231, s43, v211, -v229
	v_cvt_pk_bf16_f32 v212, v218, v219
	v_cvt_pk_bf16_f32 v213, v222, v223
	v_cvt_pk_bf16_f32 v214, v226, v227
	v_cvt_pk_bf16_f32 v215, v230, v231
	global_store_dwordx4 v3, v[212:215], s[10:11] sc1
	v_add_u32_e32 v3, 0x2000, v3
	s_waitcnt vmcnt(31)
	v_lshlrev_b32_e32 v216, 16, v196
	v_and_b32_e32 v217, 0xffff0000, v196
	v_lshlrev_b32_e32 v218, 16, v124
	v_and_b32_e32 v219, 0xffff0000, v124
	v_lshlrev_b32_e32 v220, 16, v197
	v_and_b32_e32 v221, 0xffff0000, v197
	v_lshlrev_b32_e32 v222, 16, v125
	v_and_b32_e32 v223, 0xffff0000, v125
	v_lshlrev_b32_e32 v224, 16, v198
	v_and_b32_e32 v225, 0xffff0000, v198
	v_lshlrev_b32_e32 v226, 16, v126
	v_and_b32_e32 v227, 0xffff0000, v126
	v_lshlrev_b32_e32 v228, 16, v199
	v_and_b32_e32 v229, 0xffff0000, v199
	v_lshlrev_b32_e32 v230, 16, v127
	v_and_b32_e32 v231, 0xffff0000, v127
	v_pk_add_f32 v[218:219], v[216:217], v[218:219] neg_lo:[0,1] neg_hi:[0,1]
	v_pk_add_f32 v[222:223], v[220:221], v[222:223] neg_lo:[0,1] neg_hi:[0,1]
	v_pk_add_f32 v[226:227], v[224:225], v[226:227] neg_lo:[0,1] neg_hi:[0,1]
	v_pk_add_f32 v[230:231], v[228:229], v[230:231] neg_lo:[0,1] neg_hi:[0,1]
	v_pk_add_f32 v[204:205], v[204:205], v[218:219]
	v_pk_add_f32 v[206:207], v[206:207], v[222:223]
	v_pk_add_f32 v[208:209], v[208:209], v[226:227]
	v_pk_add_f32 v[210:211], v[210:211], v[230:231]
	v_fma_f32 v218, s43, v204, -v216
	v_fma_f32 v219, s43, v205, -v217
	v_fma_f32 v222, s43, v206, -v220
	v_fma_f32 v223, s43, v207, -v221
	v_fma_f32 v226, s43, v208, -v224
	v_fma_f32 v227, s43, v209, -v225
	v_fma_f32 v230, s43, v210, -v228
	v_fma_f32 v231, s43, v211, -v229
	v_cvt_pk_bf16_f32 v212, v218, v219
	v_cvt_pk_bf16_f32 v213, v222, v223
	v_cvt_pk_bf16_f32 v214, v226, v227
	v_cvt_pk_bf16_f32 v215, v230, v231
	global_store_dwordx4 v3, v[212:215], s[10:11] sc1
	v_add_u32_e32 v3, 0x2000, v3
	s_waitcnt vmcnt(31)
	v_lshlrev_b32_e32 v216, 16, v200
	v_and_b32_e32 v217, 0xffff0000, v200
	v_lshlrev_b32_e32 v218, 16, v128
	v_and_b32_e32 v219, 0xffff0000, v128
	v_lshlrev_b32_e32 v220, 16, v201
	v_and_b32_e32 v221, 0xffff0000, v201
	v_lshlrev_b32_e32 v222, 16, v129
	v_and_b32_e32 v223, 0xffff0000, v129
	v_lshlrev_b32_e32 v224, 16, v202
	v_and_b32_e32 v225, 0xffff0000, v202
	v_lshlrev_b32_e32 v226, 16, v130
	v_and_b32_e32 v227, 0xffff0000, v130
	v_lshlrev_b32_e32 v228, 16, v203
	v_and_b32_e32 v229, 0xffff0000, v203
	v_lshlrev_b32_e32 v230, 16, v131
	v_and_b32_e32 v231, 0xffff0000, v131
	v_pk_add_f32 v[218:219], v[216:217], v[218:219] neg_lo:[0,1] neg_hi:[0,1]
	v_pk_add_f32 v[222:223], v[220:221], v[222:223] neg_lo:[0,1] neg_hi:[0,1]
	v_pk_add_f32 v[226:227], v[224:225], v[226:227] neg_lo:[0,1] neg_hi:[0,1]
	v_pk_add_f32 v[230:231], v[228:229], v[230:231] neg_lo:[0,1] neg_hi:[0,1]
	v_pk_add_f32 v[204:205], v[204:205], v[218:219]
	v_pk_add_f32 v[206:207], v[206:207], v[222:223]
	v_pk_add_f32 v[208:209], v[208:209], v[226:227]
	v_pk_add_f32 v[210:211], v[210:211], v[230:231]
	v_fma_f32 v218, s43, v204, -v216
	v_fma_f32 v219, s43, v205, -v217
	v_fma_f32 v222, s43, v206, -v220
	v_fma_f32 v223, s43, v207, -v221
	v_fma_f32 v226, s43, v208, -v224
	v_fma_f32 v227, s43, v209, -v225
	v_fma_f32 v230, s43, v210, -v228
	v_fma_f32 v231, s43, v211, -v229
	v_cvt_pk_bf16_f32 v212, v218, v219
	v_cvt_pk_bf16_f32 v213, v222, v223
	v_cvt_pk_bf16_f32 v214, v226, v227
	v_cvt_pk_bf16_f32 v215, v230, v231
	global_store_dwordx4 v3, v[212:215], s[10:11] sc1
	s_branch .LBB0_441
